# nt hint also on the GEMM1 epilogue output stores
# speedup vs baseline: 1.0060x; 1.0040x over previous
; __device__ __forceinline__ float log_sigmoid_f(float x) { return fminf(x, 0.f) - log1pf(__expf(-fabsf(x))); }
;     __device__ __forceinline__ void operator()(const f32x4 (&acc)[2][2][4][2], const Unit& u, int wr, int wc, int fr, int fq) const {
;     ...
;                         if (pm == 0) dst = o_lfs + (size_t)row * 16; else { const int t = row - G_ROWP; if (t < G_TP) dst = o_lfp + (size_t)t * 16; }
; #pragma unroll
;                         for (int n = 0; n < 2; ++n) { const int c = 8 * fq + 4 * n; const f32x4 bv = *(const f32x4*)(b_f + c); const f32x4 x = acc[ai][0][m][n] * s + bv; f32x4 lf;
;                             lf[0] = log_sigmoid_f(x[0]); lf[1] = log_sigmoid_f(x[1]); lf[2] = log_sigmoid_f(x[2]); lf[3] = log_sigmoid_f(x[3]);
.LBB0_375:
	global_load_dwordx4 v[130:133], v[158:159], off
	v_cmp_ne_u64_e32 vcc, 0, v[136:137]
	v_lshl_add_u64 v[138:139], v[162:163], 0, v[138:139]
	s_waitcnt vmcnt(0)
	v_pk_fma_f32 v[140:141], v[126:127], v[200:201], v[130:131] op_sel_hi:[1,0,1]
	s_nop 0
	v_mul_f32_e64 v131, |v140|, s34
	v_exp_f32_e32 v150, v131
	v_min_f32_e32 v130, 0, v140
	v_pk_fma_f32 v[132:133], v[128:129], v[200:201], v[132:133] op_sel_hi:[1,0,1]
	v_add_f32_e32 v131, 1.0, v150
	v_add_f32_e32 v140, -1.0, v131
	v_sub_f32_e32 v173, v140, v131
	v_add_f32_e32 v173, 1.0, v173
	v_sub_f32_e32 v140, v150, v140
	v_add_f32_e32 v173, v140, v173
	v_frexp_mant_f32_e32 v140, v131
	v_cvt_f64_f32_e32 v[202:203], v131
	v_cmp_gt_f32_e64 s[10:11], s35, v140
	v_frexp_exp_i32_f64_e32 v140, v[202:203]
	s_nop 0
	v_subbrev_co_u32_e64 v179, s[10:11], 0, v140, s[10:11]
	v_sub_u32_e32 v183, 0, v179
	v_ldexp_f32 v140, v131, v183
	v_min_f32_e32 v131, 0, v141
	v_mul_f32_e64 v141, |v141|, s34
	v_ldexp_f32 v202, v173, v183
	v_exp_f32_e32 v173, v141
	s_nop 0
	v_add_f32_e32 v141, 1.0, v173
	v_add_f32_e32 v183, -1.0, v141
	v_sub_f32_e32 v187, v183, v141
	v_add_f32_e32 v187, 1.0, v187
	v_sub_f32_e32 v183, v173, v183
	v_add_f32_e32 v187, v183, v187
	v_frexp_mant_f32_e32 v183, v141
	v_cvt_f64_f32_e32 v[204:205], v141
	v_cmp_gt_f32_e64 s[10:11], s35, v183
	v_frexp_exp_i32_f64_e32 v183, v[204:205]
	v_cmp_lt_f32_e64 s[12:13], |v173|, s5
	v_subbrev_co_u32_e64 v183, s[10:11], 0, v183, s[10:11]
	v_sub_u32_e32 v191, 0, v183
	v_ldexp_f32 v141, v141, v191
	v_pk_add_f32 v[204:205], v[140:141], 1.0 op_sel_hi:[1,0]
	v_ldexp_f32 v203, v187, v191
	v_pk_add_f32 v[206:207], v[204:205], -1.0 op_sel_hi:[1,0]
	v_pk_add_f32 v[212:213], v[140:141], -1.0 op_sel_hi:[1,0]
	v_pk_add_f32 v[206:207], v[140:141], v[206:207] neg_lo:[0,1] neg_hi:[0,1]
	v_pk_add_f32 v[214:215], v[212:213], 1.0 op_sel_hi:[1,0]
	v_pk_add_f32 v[206:207], v[202:203], v[206:207]
	v_pk_add_f32 v[140:141], v[140:141], v[214:215] neg_lo:[0,1] neg_hi:[0,1]
	v_pk_add_f32 v[208:209], v[204:205], v[206:207]
	v_pk_add_f32 v[140:141], v[202:203], v[140:141]
	v_rcp_f32_e32 v210, v208
	v_rcp_f32_e32 v211, v209
	v_pk_add_f32 v[202:203], v[212:213], v[140:141]
	v_pk_add_f32 v[204:205], v[208:209], v[204:205] neg_lo:[0,1] neg_hi:[0,1]
	v_pk_add_f32 v[212:213], v[202:203], v[212:213] neg_lo:[0,1] neg_hi:[0,1]
	v_pk_add_f32 v[204:205], v[206:207], v[204:205] neg_lo:[0,1] neg_hi:[0,1]
	v_pk_mul_f32 v[206:207], v[202:203], v[210:211]
	v_pk_add_f32 v[140:141], v[140:141], v[212:213] neg_lo:[0,1] neg_hi:[0,1]
	v_pk_mul_f32 v[212:213], v[208:209], v[206:207]
	v_cmp_neq_f32_e64 s[10:11], s4, v150
	v_pk_fma_f32 v[214:215], v[206:207], v[208:209], v[212:213] neg_lo:[0,0,1] neg_hi:[0,0,1]
	s_nop 0
	v_pk_fma_f32 v[214:215], v[206:207], v[204:205], v[214:215]
	s_nop 0
	v_pk_add_f32 v[216:217], v[212:213], v[214:215]
	s_nop 0
	v_pk_add_f32 v[218:219], v[202:203], v[216:217] neg_lo:[0,1] neg_hi:[0,1]
	v_pk_add_f32 v[212:213], v[216:217], v[212:213] neg_lo:[0,1] neg_hi:[0,1]
	v_pk_add_f32 v[202:203], v[202:203], v[218:219] neg_lo:[0,1] neg_hi:[0,1]
	s_nop 0
	v_pk_add_f32 v[202:203], v[202:203], v[216:217] neg_lo:[0,1] neg_hi:[0,1]
	s_nop 0
	v_pk_add_f32 v[140:141], v[140:141], v[202:203]
	v_pk_add_f32 v[202:203], v[212:213], v[214:215] neg_lo:[0,1] neg_hi:[0,1]
	s_nop 0
	v_pk_add_f32 v[140:141], v[202:203], v[140:141]
	s_nop 0
	v_pk_add_f32 v[202:203], v[218:219], v[140:141]
	s_nop 0
	v_pk_mul_f32 v[212:213], v[210:211], v[202:203]
	s_nop 0
	v_pk_mul_f32 v[214:215], v[208:209], v[212:213]
	s_nop 0
	v_pk_fma_f32 v[208:209], v[212:213], v[208:209], v[214:215] neg_lo:[0,0,1] neg_hi:[0,0,1]
	s_nop 0
	v_pk_fma_f32 v[204:205], v[212:213], v[204:205], v[208:209]
	v_pk_add_f32 v[208:209], v[218:219], v[202:203] neg_lo:[0,1] neg_hi:[0,1]
	s_nop 0
	v_pk_add_f32 v[140:141], v[140:141], v[208:209]
	v_pk_add_f32 v[208:209], v[214:215], v[204:205]
	s_nop 0
	v_pk_add_f32 v[216:217], v[202:203], v[208:209] neg_lo:[0,1] neg_hi:[0,1]
	v_pk_add_f32 v[214:215], v[208:209], v[214:215] neg_lo:[0,1] neg_hi:[0,1]
	v_pk_add_f32 v[202:203], v[202:203], v[216:217] neg_lo:[0,1] neg_hi:[0,1]
	s_nop 0
	v_pk_add_f32 v[202:203], v[202:203], v[208:209] neg_lo:[0,1] neg_hi:[0,1]
	s_nop 0
	v_pk_add_f32 v[140:141], v[140:141], v[202:203]
	v_pk_add_f32 v[202:203], v[214:215], v[204:205] neg_lo:[0,1] neg_hi:[0,1]
	s_nop 0
	v_pk_add_f32 v[140:141], v[202:203], v[140:141]
	v_pk_add_f32 v[202:203], v[206:207], v[212:213]
	v_pk_add_f32 v[140:141], v[216:217], v[140:141]
	v_pk_add_f32 v[204:205], v[202:203], v[206:207] neg_lo:[0,1] neg_hi:[0,1]
	v_pk_mul_f32 v[140:141], v[210:211], v[140:141]
	v_pk_add_f32 v[204:205], v[212:213], v[204:205] neg_lo:[0,1] neg_hi:[0,1]
	s_nop 0
	v_pk_add_f32 v[140:141], v[204:205], v[140:141]
	s_nop 0
	v_pk_add_f32 v[206:207], v[202:203], v[140:141]
	s_nop 0
	v_pk_add_f32 v[202:203], v[206:207], v[202:203] neg_lo:[0,1] neg_hi:[0,1]
	v_pk_mul_f32 v[208:209], v[206:207], v[206:207]
	v_pk_add_f32 v[202:203], v[140:141], v[202:203] neg_lo:[0,1] neg_hi:[0,1]
	v_mov_b64_e32 v[140:141], s[50:51]
	v_pk_fma_f32 v[210:211], v[208:209], s[52:53], v[140:141] op_sel_hi:[1,0,0]
	v_ldexp_f32 v204, v206, 1
	v_pk_fma_f32 v[210:211], v[208:209], v[210:211], s[54:55] op_sel_hi:[1,1,0]
	v_ldexp_f32 v205, v207, 1
	v_pk_mul_f32 v[206:207], v[206:207], v[208:209]
	v_cvt_f32_i32_e32 v209, v183
	v_cvt_f32_i32_e32 v208, v179
	v_pk_mul_f32 v[216:217], v[206:207], v[210:211]
	v_ldexp_f32 v215, v203, 1
	v_pk_add_f32 v[206:207], v[204:205], v[216:217]
	v_pk_mul_f32 v[212:213], v[208:209], s[64:65] op_sel_hi:[1,0]
	v_pk_add_f32 v[204:205], v[206:207], v[204:205] neg_lo:[0,1] neg_hi:[0,1]
	v_ldexp_f32 v202, v202, 1
; __device__ __forceinline__ float log_sigmoid_f(float x) { return fminf(x, 0.f) - log1pf(__expf(-fabsf(x))); }
;     __device__ __forceinline__ void operator()(const f32x4 (&acc)[2][2][4][2], const Unit& u, int wr, int wc, int fr, int fq) const {
;     ...
;                             lf[0] = log_sigmoid_f(x[0]); lf[1] = log_sigmoid_f(x[1]); lf[2] = log_sigmoid_f(x[2]); lf[3] = log_sigmoid_f(x[3]);
	v_pk_fma_f32 v[210:211], v[208:209], s[64:65], v[212:213] op_sel_hi:[1,0,1] neg_lo:[0,0,1] neg_hi:[0,0,1]
	v_pk_add_f32 v[218:219], v[216:217], v[204:205] neg_lo:[0,1] neg_hi:[0,1]
	v_mov_b32_e32 v203, v215
	v_pk_fma_f32 v[208:209], v[208:209], s[66:67], v[210:211] op_sel_hi:[1,0,1]
	v_pk_add_f32 v[216:217], v[202:203], v[218:219]
	v_mov_b32_e32 v204, v212
	v_mov_b32_e32 v205, v219
	v_mov_b32_e32 v214, v208
	v_mov_b32_e32 v203, v217
	v_mov_b32_e32 v219, v207
	v_pk_add_f32 v[210:211], v[212:213], v[208:209]
	v_pk_add_f32 v[204:205], v[204:205], v[214:215]
	v_pk_add_f32 v[214:215], v[202:203], v[218:219]
	v_pk_add_f32 v[218:219], v[206:207], v[216:217]
	v_mov_b32_e32 v226, v206
	v_pk_add_f32 v[202:203], v[210:211], v[218:219]
	v_mov_b32_e32 v224, v218
	v_mov_b32_e32 v225, v203
	v_mov_b32_e32 v227, v211
	v_pk_add_f32 v[224:225], v[224:225], v[226:227] neg_lo:[0,1] neg_hi:[0,1]
	v_mov_b32_e32 v220, v202
	v_mov_b32_e32 v221, v211
	v_mov_b32_e32 v222, v210
	v_mov_b32_e32 v223, v213
	v_mov_b32_e32 v226, v210
	v_mov_b32_e32 v227, v203
	v_mov_b32_e32 v213, v225
	v_pk_add_f32 v[220:221], v[220:221], v[222:223] neg_lo:[0,1] neg_hi:[0,1]
	v_mov_b32_e32 v222, v218
	v_mov_b32_e32 v223, v209
	v_pk_add_f32 v[212:213], v[226:227], v[212:213] neg_lo:[0,1] neg_hi:[0,1]
	v_pk_add_f32 v[222:223], v[222:223], v[220:221] neg_lo:[0,1] neg_hi:[0,1]
	v_mov_b32_e32 v226, v212
	v_mov_b32_e32 v227, v221
	v_mov_b32_e32 v236, v202
	v_mov_b32_e32 v237, v219
	v_mov_b32_e32 v221, v207
	v_pk_add_f32 v[226:227], v[208:209], v[226:227] neg_lo:[0,1] neg_hi:[0,1]
	v_pk_add_f32 v[220:221], v[236:237], v[220:221] neg_lo:[0,1] neg_hi:[0,1]
	v_mov_b32_e32 v209, v211
	v_pk_add_f32 v[204:205], v[204:205], v[220:221] neg_lo:[0,1] neg_hi:[0,1]
	v_pk_add_f32 v[208:209], v[208:209], v[212:213] neg_lo:[0,1] neg_hi:[0,1]
	v_pk_add_f32 v[210:211], v[214:215], v[224:225] neg_lo:[0,1] neg_hi:[0,1]
	v_pk_add_f32 v[214:215], v[222:223], v[204:205]
	v_pk_add_f32 v[212:213], v[210:211], v[208:209]
	v_mov_b32_e32 v209, v223
	v_mov_b32_e32 v211, v205
	v_pk_add_f32 v[204:205], v[208:209], v[210:211]
	v_pk_add_f32 v[206:207], v[218:219], v[206:207] neg_lo:[0,1] neg_hi:[0,1]
	v_pk_add_f32 v[204:205], v[204:205], v[226:227] neg_lo:[0,1] neg_hi:[0,1]
	v_mov_b32_e32 v210, v212
	v_mov_b32_e32 v211, v215
	v_pk_add_f32 v[206:207], v[216:217], v[206:207] neg_lo:[0,1] neg_hi:[0,1]
	v_pk_add_f32 v[210:211], v[210:211], v[204:205] neg_lo:[0,1] neg_hi:[0,1]
	v_pk_add_f32 v[204:205], v[206:207], v[204:205] neg_lo:[0,1] neg_hi:[0,1]
	v_pk_add_f32 v[208:209], v[208:209], v[210:211] neg_lo:[0,1] neg_hi:[0,1]
	v_pk_add_f32 v[206:207], v[214:215], v[212:213]
	v_pk_add_f32 v[204:205], v[204:205], v[208:209]
	v_pk_add_f32 v[208:209], v[202:203], v[206:207]
	s_nop 0
	v_pk_add_f32 v[202:203], v[208:209], v[202:203] neg_lo:[0,1] neg_hi:[0,1]
	s_nop 0
	v_pk_add_f32 v[202:203], v[206:207], v[202:203] neg_lo:[0,1] neg_hi:[0,1]
	s_nop 0
	v_pk_add_f32 v[202:203], v[204:205], v[202:203]
	s_nop 0
	v_pk_add_f32 v[202:203], v[208:209], v[202:203]
	s_nop 0
	v_cndmask_b32_e64 v179, v231, v202, s[10:11]
	v_cmp_neq_f32_e64 s[10:11], s4, v173
	s_nop 1
	v_cndmask_b32_e64 v183, v231, v203, s[10:11]
	v_cmp_ngt_f32_e64 s[10:11], -1.0, v173
	s_nop 1
	v_cndmask_b32_e64 v183, v232, v183, s[10:11]
	v_cmp_ngt_f32_e64 s[10:11], -1.0, v150
	s_nop 1
	v_cndmask_b32_e64 v179, v232, v179, s[10:11]
	v_cmp_neq_f32_e64 s[10:11], -1.0, v150
	s_nop 1
	v_cndmask_b32_e64 v179, v233, v179, s[10:11]
	v_cmp_neq_f32_e64 s[10:11], -1.0, v173
	s_nop 1
	v_cndmask_b32_e64 v183, v233, v183, s[10:11]
	v_cmp_lt_f32_e64 s[10:11], |v150|, s5
	v_cndmask_b32_e64 v203, v183, v173, s[12:13]
	s_nop 0
	v_cndmask_b32_e64 v202, v179, v150, s[10:11]
	v_pk_add_f32 v[130:131], v[130:131], v[202:203] neg_lo:[0,1] neg_hi:[0,1]
	v_min_f32_e32 v202, 0, v132
	v_mul_f32_e64 v132, |v132|, s34
	v_exp_f32_e32 v150, v132
	v_min_f32_e32 v203, 0, v133
	v_mul_f32_e64 v133, |v133|, s34
	v_add_f32_e32 v132, 1.0, v150
	v_add_f32_e32 v173, -1.0, v132
	v_sub_f32_e32 v179, v173, v132
	v_add_f32_e32 v179, 1.0, v179
	v_sub_f32_e32 v173, v150, v173
	v_add_f32_e32 v173, v173, v179
	v_frexp_mant_f32_e32 v179, v132
	v_cvt_f64_f32_e32 v[204:205], v132
	v_cmp_gt_f32_e64 s[10:11], s35, v179
	v_frexp_exp_i32_f64_e32 v179, v[204:205]
	s_nop 0
	v_subbrev_co_u32_e64 v179, s[10:11], 0, v179, s[10:11]
	v_sub_u32_e32 v183, 0, v179
	v_ldexp_f32 v204, v173, v183
	v_exp_f32_e32 v173, v133
	v_ldexp_f32 v132, v132, v183
	v_add_f32_e32 v133, 1.0, v173
	v_add_f32_e32 v183, -1.0, v133
	v_sub_f32_e32 v187, v183, v133
	v_add_f32_e32 v187, 1.0, v187
	v_sub_f32_e32 v183, v173, v183
	v_add_f32_e32 v183, v183, v187
	v_frexp_mant_f32_e32 v187, v133
	v_cvt_f64_f32_e32 v[206:207], v133
	v_cmp_gt_f32_e64 s[10:11], s35, v187
	v_frexp_exp_i32_f64_e32 v187, v[206:207]
	v_cmp_lt_f32_e64 s[12:13], |v173|, s5
	v_subbrev_co_u32_e64 v187, s[10:11], 0, v187, s[10:11]
	v_sub_u32_e32 v191, 0, v187
	v_ldexp_f32 v133, v133, v191
	v_pk_add_f32 v[206:207], v[132:133], 1.0 op_sel_hi:[1,0]
	v_ldexp_f32 v205, v183, v191
	v_pk_add_f32 v[208:209], v[206:207], -1.0 op_sel_hi:[1,0]
	v_pk_add_f32 v[214:215], v[132:133], -1.0 op_sel_hi:[1,0]
	v_pk_add_f32 v[208:209], v[132:133], v[208:209] neg_lo:[0,1] neg_hi:[0,1]
	v_pk_add_f32 v[216:217], v[214:215], 1.0 op_sel_hi:[1,0]
	v_pk_add_f32 v[208:209], v[204:205], v[208:209]
	v_pk_add_f32 v[132:133], v[132:133], v[216:217] neg_lo:[0,1] neg_hi:[0,1]
	v_pk_add_f32 v[210:211], v[206:207], v[208:209]
	v_pk_add_f32 v[132:133], v[204:205], v[132:133]
	v_rcp_f32_e32 v212, v210
	v_rcp_f32_e32 v213, v211
	v_pk_add_f32 v[204:205], v[214:215], v[132:133]
	v_pk_add_f32 v[206:207], v[210:211], v[206:207] neg_lo:[0,1] neg_hi:[0,1]
; __device__ __forceinline__ float log_sigmoid_f(float x) { return fminf(x, 0.f) - log1pf(__expf(-fabsf(x))); }
;     __device__ __forceinline__ void operator()(const f32x4 (&acc)[2][2][4][2], const Unit& u, int wr, int wc, int fr, int fq) const {
;     ...
;                             lf[0] = log_sigmoid_f(x[0]); lf[1] = log_sigmoid_f(x[1]); lf[2] = log_sigmoid_f(x[2]); lf[3] = log_sigmoid_f(x[3]);
	v_pk_add_f32 v[214:215], v[204:205], v[214:215] neg_lo:[0,1] neg_hi:[0,1]
	v_pk_add_f32 v[206:207], v[208:209], v[206:207] neg_lo:[0,1] neg_hi:[0,1]
	v_pk_mul_f32 v[208:209], v[204:205], v[212:213]
	v_pk_add_f32 v[132:133], v[132:133], v[214:215] neg_lo:[0,1] neg_hi:[0,1]
	v_pk_mul_f32 v[214:215], v[210:211], v[208:209]
	v_cmp_neq_f32_e64 s[10:11], s4, v150
	v_pk_fma_f32 v[216:217], v[208:209], v[210:211], v[214:215] neg_lo:[0,0,1] neg_hi:[0,0,1]
	s_nop 0
	v_pk_fma_f32 v[216:217], v[208:209], v[206:207], v[216:217]
	s_nop 0
	v_pk_add_f32 v[218:219], v[214:215], v[216:217]
	s_nop 0
	v_pk_add_f32 v[220:221], v[204:205], v[218:219] neg_lo:[0,1] neg_hi:[0,1]
	v_pk_add_f32 v[214:215], v[218:219], v[214:215] neg_lo:[0,1] neg_hi:[0,1]
	v_pk_add_f32 v[204:205], v[204:205], v[220:221] neg_lo:[0,1] neg_hi:[0,1]
	s_nop 0
	v_pk_add_f32 v[204:205], v[204:205], v[218:219] neg_lo:[0,1] neg_hi:[0,1]
	s_nop 0
	v_pk_add_f32 v[132:133], v[132:133], v[204:205]
	v_pk_add_f32 v[204:205], v[214:215], v[216:217] neg_lo:[0,1] neg_hi:[0,1]
	s_nop 0
	v_pk_add_f32 v[132:133], v[204:205], v[132:133]
	s_nop 0
	v_pk_add_f32 v[204:205], v[220:221], v[132:133]
	s_nop 0
	v_pk_mul_f32 v[214:215], v[212:213], v[204:205]
	s_nop 0
	v_pk_mul_f32 v[216:217], v[210:211], v[214:215]
	s_nop 0
	v_pk_fma_f32 v[210:211], v[214:215], v[210:211], v[216:217] neg_lo:[0,0,1] neg_hi:[0,0,1]
	s_nop 0
	v_pk_fma_f32 v[206:207], v[214:215], v[206:207], v[210:211]
	v_pk_add_f32 v[210:211], v[220:221], v[204:205] neg_lo:[0,1] neg_hi:[0,1]
	s_nop 0
	v_pk_add_f32 v[132:133], v[132:133], v[210:211]
	v_pk_add_f32 v[210:211], v[216:217], v[206:207]
	s_nop 0
	v_pk_add_f32 v[218:219], v[204:205], v[210:211] neg_lo:[0,1] neg_hi:[0,1]
	v_pk_add_f32 v[216:217], v[210:211], v[216:217] neg_lo:[0,1] neg_hi:[0,1]
	v_pk_add_f32 v[204:205], v[204:205], v[218:219] neg_lo:[0,1] neg_hi:[0,1]
	s_nop 0
	v_pk_add_f32 v[204:205], v[204:205], v[210:211] neg_lo:[0,1] neg_hi:[0,1]
	s_nop 0
	v_pk_add_f32 v[132:133], v[132:133], v[204:205]
	v_pk_add_f32 v[204:205], v[216:217], v[206:207] neg_lo:[0,1] neg_hi:[0,1]
	s_nop 0
	v_pk_add_f32 v[132:133], v[204:205], v[132:133]
	v_pk_add_f32 v[204:205], v[208:209], v[214:215]
	v_pk_add_f32 v[132:133], v[218:219], v[132:133]
	v_pk_add_f32 v[206:207], v[204:205], v[208:209] neg_lo:[0,1] neg_hi:[0,1]
	v_pk_mul_f32 v[132:133], v[212:213], v[132:133]
	v_pk_add_f32 v[206:207], v[214:215], v[206:207] neg_lo:[0,1] neg_hi:[0,1]
	s_nop 0
	v_pk_add_f32 v[132:133], v[206:207], v[132:133]
	s_nop 0
	v_pk_add_f32 v[206:207], v[204:205], v[132:133]
	s_nop 0
	v_pk_mul_f32 v[208:209], v[206:207], v[206:207]
	v_pk_add_f32 v[204:205], v[206:207], v[204:205] neg_lo:[0,1] neg_hi:[0,1]
	v_pk_fma_f32 v[140:141], v[208:209], s[52:53], v[140:141] op_sel_hi:[1,0,0]
	v_pk_add_f32 v[132:133], v[132:133], v[204:205] neg_lo:[0,1] neg_hi:[0,1]
	v_ldexp_f32 v204, v206, 1
	v_pk_fma_f32 v[140:141], v[208:209], v[140:141], s[54:55] op_sel_hi:[1,1,0]
	v_ldexp_f32 v205, v207, 1
	v_pk_mul_f32 v[206:207], v[206:207], v[208:209]
	v_cvt_f32_i32_e32 v209, v187
	v_cvt_f32_i32_e32 v208, v179
	v_pk_mul_f32 v[140:141], v[206:207], v[140:141]
	v_ldexp_f32 v211, v133, 1
	v_pk_add_f32 v[206:207], v[204:205], v[140:141]
	v_pk_mul_f32 v[212:213], v[208:209], s[64:65] op_sel_hi:[1,0]
	v_pk_add_f32 v[204:205], v[206:207], v[204:205] neg_lo:[0,1] neg_hi:[0,1]
	v_pk_fma_f32 v[214:215], v[208:209], s[64:65], v[212:213] op_sel_hi:[1,0,1] neg_lo:[0,0,1] neg_hi:[0,0,1]
	v_pk_add_f32 v[140:141], v[140:141], v[204:205] neg_lo:[0,1] neg_hi:[0,1]
	v_pk_fma_f32 v[208:209], v[208:209], s[66:67], v[214:215] op_sel_hi:[1,0,1]
	v_ldexp_f32 v132, v132, 1
	v_mov_b32_e32 v204, v212
	v_mov_b32_e32 v205, v141
	v_mov_b32_e32 v210, v208
	v_mov_b32_e32 v133, v211
	v_pk_add_f32 v[204:205], v[204:205], v[210:211]
	v_pk_add_f32 v[210:211], v[132:133], v[140:141]
	v_mov_b32_e32 v141, v207
	v_mov_b32_e32 v133, v211
	v_pk_add_f32 v[214:215], v[212:213], v[208:209]
	v_pk_add_f32 v[132:133], v[132:133], v[140:141]
	v_pk_add_f32 v[140:141], v[206:207], v[210:211]
	v_mov_b32_e32 v224, v206
	v_pk_add_f32 v[216:217], v[214:215], v[140:141]
	v_mov_b32_e32 v222, v140
	v_mov_b32_e32 v223, v217
	v_mov_b32_e32 v225, v215
	v_pk_add_f32 v[222:223], v[222:223], v[224:225] neg_lo:[0,1] neg_hi:[0,1]
	v_mov_b32_e32 v218, v216
	v_mov_b32_e32 v219, v215
	v_mov_b32_e32 v220, v214
	v_mov_b32_e32 v221, v213
	v_mov_b32_e32 v224, v214
	v_mov_b32_e32 v225, v217
	v_mov_b32_e32 v213, v223
	v_pk_add_f32 v[218:219], v[218:219], v[220:221] neg_lo:[0,1] neg_hi:[0,1]
	v_mov_b32_e32 v220, v140
	v_mov_b32_e32 v221, v209
	v_pk_add_f32 v[212:213], v[224:225], v[212:213] neg_lo:[0,1] neg_hi:[0,1]
	v_pk_add_f32 v[220:221], v[220:221], v[218:219] neg_lo:[0,1] neg_hi:[0,1]
	v_mov_b32_e32 v224, v212
	v_mov_b32_e32 v225, v219
	v_mov_b32_e32 v226, v216
	v_mov_b32_e32 v227, v141
	v_mov_b32_e32 v219, v207
	v_pk_add_f32 v[224:225], v[208:209], v[224:225] neg_lo:[0,1] neg_hi:[0,1]
	v_pk_add_f32 v[218:219], v[226:227], v[218:219] neg_lo:[0,1] neg_hi:[0,1]
	v_mov_b32_e32 v209, v215
	v_pk_add_f32 v[140:141], v[140:141], v[206:207] neg_lo:[0,1] neg_hi:[0,1]
	v_pk_add_f32 v[204:205], v[204:205], v[218:219] neg_lo:[0,1] neg_hi:[0,1]
	v_pk_add_f32 v[206:207], v[208:209], v[212:213] neg_lo:[0,1] neg_hi:[0,1]
	v_pk_add_f32 v[132:133], v[132:133], v[222:223] neg_lo:[0,1] neg_hi:[0,1]
	v_pk_add_f32 v[140:141], v[210:211], v[140:141] neg_lo:[0,1] neg_hi:[0,1]
	v_pk_add_f32 v[208:209], v[132:133], v[206:207]
	v_mov_b32_e32 v207, v221
	v_mov_b32_e32 v133, v205
	v_pk_add_f32 v[210:211], v[220:221], v[204:205]
	v_pk_add_f32 v[132:133], v[206:207], v[132:133]
	v_mov_b32_e32 v204, v208
; __device__ __forceinline__ float log_sigmoid_f(float x) { return fminf(x, 0.f) - log1pf(__expf(-fabsf(x))); }
;     __device__ __forceinline__ void operator()(const f32x4 (&acc)[2][2][4][2], const Unit& u, int wr, int wc, int fr, int fq) const {
;     ...
;                         for (int n = 0; n < 2; ++n) { const int c = 8 * fq + 4 * n; const f32x4 bv = *(const f32x4*)(b_f + c); const f32x4 x = acc[ai][0][m][n] * s + bv; f32x4 lf;
;                             lf[0] = log_sigmoid_f(x[0]); lf[1] = log_sigmoid_f(x[1]); lf[2] = log_sigmoid_f(x[2]); lf[3] = log_sigmoid_f(x[3]);
;                             *(f32x4*)(LF + (size_t)row * 16 + c) = lf; if (dst) *(f32x4*)(dst + c) = lf; } }
	v_pk_add_f32 v[132:133], v[132:133], v[224:225] neg_lo:[0,1] neg_hi:[0,1]
	v_mov_b32_e32 v205, v211
	v_pk_add_f32 v[204:205], v[204:205], v[132:133] neg_lo:[0,1] neg_hi:[0,1]
	v_pk_add_f32 v[132:133], v[140:141], v[132:133] neg_lo:[0,1] neg_hi:[0,1]
	v_pk_add_f32 v[204:205], v[206:207], v[204:205] neg_lo:[0,1] neg_hi:[0,1]
	v_pk_add_f32 v[140:141], v[210:211], v[208:209]
	v_pk_add_f32 v[132:133], v[132:133], v[204:205]
	v_pk_add_f32 v[204:205], v[216:217], v[140:141]
	s_nop 0
	v_pk_add_f32 v[206:207], v[204:205], v[216:217] neg_lo:[0,1] neg_hi:[0,1]
	s_nop 0
	v_pk_add_f32 v[140:141], v[140:141], v[206:207] neg_lo:[0,1] neg_hi:[0,1]
	s_nop 0
	v_pk_add_f32 v[132:133], v[132:133], v[140:141]
	s_nop 0
	v_pk_add_f32 v[132:133], v[204:205], v[132:133]
	s_nop 0
	v_cndmask_b32_e64 v132, v231, v132, s[10:11]
	v_cmp_neq_f32_e64 s[10:11], s4, v173
	s_nop 1
	v_cndmask_b32_e64 v133, v231, v133, s[10:11]
	v_cmp_ngt_f32_e64 s[10:11], -1.0, v173
	s_nop 1
	v_cndmask_b32_e64 v133, v232, v133, s[10:11]
	v_cmp_ngt_f32_e64 s[10:11], -1.0, v150
	s_nop 1
	v_cndmask_b32_e64 v132, v232, v132, s[10:11]
	v_cmp_neq_f32_e64 s[10:11], -1.0, v150
	s_nop 1
	v_cndmask_b32_e64 v132, v233, v132, s[10:11]
	v_cmp_neq_f32_e64 s[10:11], -1.0, v173
	s_nop 1
	v_cndmask_b32_e64 v133, v233, v133, s[10:11]
	v_cmp_lt_f32_e64 s[10:11], |v150|, s5
	v_cndmask_b32_e64 v133, v133, v173, s[12:13]
	s_nop 0
	v_cndmask_b32_e64 v132, v132, v150, s[10:11]
	v_pk_add_f32 v[132:133], v[202:203], v[132:133] neg_lo:[0,1] neg_hi:[0,1]
	v_lshlrev_b32_e32 v150, 2, v152
	global_store_dwordx4 v[138:139], v[130:133], off nt
	s_and_saveexec_b64 s[10:11], vcc
	s_cbranch_execz .LBB0_377
	v_lshl_add_u64 v[140:141], v[136:137], 0, v[150:151]
	global_store_dwordx4 v[140:141], v[130:133], off nt
.LBB0_377:
	s_or_b64 exec, exec, s[10:11]
	global_load_dwordx4 v[130:133], v[158:159], off offset:16
	v_mov_b32_e32 v201, v200
	v_mov_b32_e32 v140, v200
	v_mov_b32_e32 v141, v200
	s_waitcnt vmcnt(0)
	v_pk_fma_f32 v[132:133], v[124:125], v[140:141], v[132:133]
	v_pk_fma_f32 v[140:141], v[122:123], v[200:201], v[130:131]
	s_nop 0
	v_mul_f32_e64 v131, |v140|, s34
	v_exp_f32_e32 v173, v131
	v_min_f32_e32 v130, 0, v140
	v_add_f32_e32 v131, 1.0, v173
	v_add_f32_e32 v140, -1.0, v131
	v_sub_f32_e32 v179, v140, v131
	v_add_f32_e32 v179, 1.0, v179
	v_sub_f32_e32 v140, v173, v140
	v_add_f32_e32 v179, v140, v179
	v_frexp_mant_f32_e32 v140, v131
	v_cvt_f64_f32_e32 v[202:203], v131
	v_cmp_gt_f32_e64 s[10:11], s35, v140
	v_frexp_exp_i32_f64_e32 v140, v[202:203]
	s_nop 0
	v_subbrev_co_u32_e64 v183, s[10:11], 0, v140, s[10:11]
	v_sub_u32_e32 v187, 0, v183
	v_ldexp_f32 v140, v131, v187
	v_min_f32_e32 v131, 0, v141
	v_mul_f32_e64 v141, |v141|, s34
	v_ldexp_f32 v202, v179, v187
	v_exp_f32_e32 v179, v141
	s_nop 0
	v_add_f32_e32 v141, 1.0, v179
	v_add_f32_e32 v187, -1.0, v141
	v_sub_f32_e32 v191, v187, v141
	v_add_f32_e32 v191, 1.0, v191
	v_sub_f32_e32 v187, v179, v187
	v_add_f32_e32 v191, v187, v191
	v_frexp_mant_f32_e32 v187, v141
	v_cvt_f64_f32_e32 v[204:205], v141
	v_cmp_gt_f32_e64 s[10:11], s35, v187
	v_frexp_exp_i32_f64_e32 v187, v[204:205]
	v_cmp_lt_f32_e64 s[12:13], |v179|, s5
	v_subbrev_co_u32_e64 v187, s[10:11], 0, v187, s[10:11]
	v_sub_u32_e32 v195, 0, v187
	v_ldexp_f32 v141, v141, v195
	v_pk_add_f32 v[204:205], v[140:141], 1.0 op_sel_hi:[1,0]
	v_ldexp_f32 v203, v191, v195
	v_pk_add_f32 v[206:207], v[204:205], -1.0 op_sel_hi:[1,0]
	v_pk_add_f32 v[212:213], v[140:141], -1.0 op_sel_hi:[1,0]
	v_pk_add_f32 v[206:207], v[140:141], v[206:207] neg_lo:[0,1] neg_hi:[0,1]
	v_pk_add_f32 v[214:215], v[212:213], 1.0 op_sel_hi:[1,0]
	v_pk_add_f32 v[206:207], v[202:203], v[206:207]
	v_pk_add_f32 v[140:141], v[140:141], v[214:215] neg_lo:[0,1] neg_hi:[0,1]
	v_pk_add_f32 v[208:209], v[204:205], v[206:207]
	v_pk_add_f32 v[140:141], v[202:203], v[140:141]
	v_rcp_f32_e32 v210, v208
	v_rcp_f32_e32 v211, v209
	v_pk_add_f32 v[202:203], v[212:213], v[140:141]
	v_pk_add_f32 v[204:205], v[208:209], v[204:205] neg_lo:[0,1] neg_hi:[0,1]
	v_pk_add_f32 v[212:213], v[202:203], v[212:213] neg_lo:[0,1] neg_hi:[0,1]
	v_pk_add_f32 v[204:205], v[206:207], v[204:205] neg_lo:[0,1] neg_hi:[0,1]
	v_pk_mul_f32 v[206:207], v[202:203], v[210:211]
	v_pk_add_f32 v[140:141], v[140:141], v[212:213] neg_lo:[0,1] neg_hi:[0,1]
	v_pk_mul_f32 v[212:213], v[208:209], v[206:207]
	v_cmp_neq_f32_e64 s[10:11], s4, v173
	v_pk_fma_f32 v[214:215], v[206:207], v[208:209], v[212:213] neg_lo:[0,0,1] neg_hi:[0,0,1]
	s_nop 0
	v_pk_fma_f32 v[214:215], v[206:207], v[204:205], v[214:215]
	s_nop 0
	v_pk_add_f32 v[216:217], v[212:213], v[214:215]
	s_nop 0
	v_pk_add_f32 v[218:219], v[202:203], v[216:217] neg_lo:[0,1] neg_hi:[0,1]
	v_pk_add_f32 v[212:213], v[216:217], v[212:213] neg_lo:[0,1] neg_hi:[0,1]
	v_pk_add_f32 v[202:203], v[202:203], v[218:219] neg_lo:[0,1] neg_hi:[0,1]
	s_nop 0
	v_pk_add_f32 v[202:203], v[202:203], v[216:217] neg_lo:[0,1] neg_hi:[0,1]
	s_nop 0
	v_pk_add_f32 v[140:141], v[140:141], v[202:203]
	v_pk_add_f32 v[202:203], v[212:213], v[214:215] neg_lo:[0,1] neg_hi:[0,1]
	s_nop 0
	v_pk_add_f32 v[140:141], v[202:203], v[140:141]
	s_nop 0
	v_pk_add_f32 v[202:203], v[218:219], v[140:141]
	s_nop 0
	v_pk_mul_f32 v[212:213], v[210:211], v[202:203]
	s_nop 0
	v_pk_mul_f32 v[214:215], v[208:209], v[212:213]
	s_nop 0
	v_pk_fma_f32 v[208:209], v[212:213], v[208:209], v[214:215] neg_lo:[0,0,1] neg_hi:[0,0,1]
	s_nop 0
	v_pk_fma_f32 v[204:205], v[212:213], v[204:205], v[208:209]
	v_pk_add_f32 v[208:209], v[218:219], v[202:203] neg_lo:[0,1] neg_hi:[0,1]
	s_nop 0
	v_pk_add_f32 v[140:141], v[140:141], v[208:209]
	v_pk_add_f32 v[208:209], v[214:215], v[204:205]
	s_nop 0
; __device__ __forceinline__ float log_sigmoid_f(float x) { return fminf(x, 0.f) - log1pf(__expf(-fabsf(x))); }
;     __device__ __forceinline__ void operator()(const f32x4 (&acc)[2][2][4][2], const Unit& u, int wr, int wc, int fr, int fq) const {
;     ...
;                             lf[0] = log_sigmoid_f(x[0]); lf[1] = log_sigmoid_f(x[1]); lf[2] = log_sigmoid_f(x[2]); lf[3] = log_sigmoid_f(x[3]);
	v_pk_add_f32 v[216:217], v[202:203], v[208:209] neg_lo:[0,1] neg_hi:[0,1]
	v_pk_add_f32 v[214:215], v[208:209], v[214:215] neg_lo:[0,1] neg_hi:[0,1]
	v_pk_add_f32 v[202:203], v[202:203], v[216:217] neg_lo:[0,1] neg_hi:[0,1]
	s_nop 0
	v_pk_add_f32 v[202:203], v[202:203], v[208:209] neg_lo:[0,1] neg_hi:[0,1]
	s_nop 0
	v_pk_add_f32 v[140:141], v[140:141], v[202:203]
	v_pk_add_f32 v[202:203], v[214:215], v[204:205] neg_lo:[0,1] neg_hi:[0,1]
	s_nop 0
	v_pk_add_f32 v[140:141], v[202:203], v[140:141]
	v_pk_add_f32 v[202:203], v[206:207], v[212:213]
	v_pk_add_f32 v[140:141], v[216:217], v[140:141]
	v_pk_add_f32 v[204:205], v[202:203], v[206:207] neg_lo:[0,1] neg_hi:[0,1]
	v_pk_mul_f32 v[140:141], v[210:211], v[140:141]
	v_pk_add_f32 v[204:205], v[212:213], v[204:205] neg_lo:[0,1] neg_hi:[0,1]
	v_cvt_f32_i32_e32 v213, v187
	v_pk_add_f32 v[140:141], v[204:205], v[140:141]
	v_cvt_f32_i32_e32 v212, v183
	v_pk_add_f32 v[206:207], v[202:203], v[140:141]
	s_nop 0
	v_pk_add_f32 v[202:203], v[206:207], v[202:203] neg_lo:[0,1] neg_hi:[0,1]
	v_pk_mul_f32 v[208:209], v[206:207], v[206:207]
	v_pk_add_f32 v[202:203], v[140:141], v[202:203] neg_lo:[0,1] neg_hi:[0,1]
	v_mov_b64_e32 v[140:141], s[50:51]
	v_pk_fma_f32 v[210:211], v[208:209], s[52:53], v[140:141] op_sel_hi:[1,0,0]
	v_ldexp_f32 v204, v206, 1
	v_pk_fma_f32 v[210:211], v[208:209], v[210:211], s[54:55] op_sel_hi:[1,1,0]
	v_ldexp_f32 v205, v207, 1
	v_pk_mul_f32 v[206:207], v[206:207], v[208:209]
	v_ldexp_f32 v215, v203, 1
	v_pk_mul_f32 v[216:217], v[206:207], v[210:211]
	v_pk_mul_f32 v[208:209], v[212:213], s[64:65] op_sel_hi:[1,0]
	v_pk_add_f32 v[206:207], v[204:205], v[216:217]
	v_ldexp_f32 v202, v202, 1
	v_pk_add_f32 v[204:205], v[206:207], v[204:205] neg_lo:[0,1] neg_hi:[0,1]
	v_pk_fma_f32 v[210:211], v[212:213], s[64:65], v[208:209] op_sel_hi:[1,0,1] neg_lo:[0,0,1] neg_hi:[0,0,1]
	v_pk_add_f32 v[218:219], v[216:217], v[204:205] neg_lo:[0,1] neg_hi:[0,1]
	v_mov_b32_e32 v203, v215
	v_pk_fma_f32 v[210:211], v[212:213], s[66:67], v[210:211] op_sel_hi:[1,0,1]
	v_pk_add_f32 v[216:217], v[202:203], v[218:219]
	v_mov_b32_e32 v204, v208
	v_mov_b32_e32 v205, v219
	v_mov_b32_e32 v214, v210
	v_mov_b32_e32 v203, v217
	v_mov_b32_e32 v219, v207
	v_pk_add_f32 v[212:213], v[208:209], v[210:211]
	v_pk_add_f32 v[204:205], v[204:205], v[214:215]
	v_pk_add_f32 v[214:215], v[202:203], v[218:219]
	v_pk_add_f32 v[218:219], v[206:207], v[216:217]
	v_mov_b32_e32 v226, v206
	v_pk_add_f32 v[202:203], v[212:213], v[218:219]
	v_mov_b32_e32 v224, v218
	v_mov_b32_e32 v225, v203
	v_mov_b32_e32 v227, v213
	v_pk_add_f32 v[224:225], v[224:225], v[226:227] neg_lo:[0,1] neg_hi:[0,1]
	v_mov_b32_e32 v220, v202
	v_mov_b32_e32 v221, v213
	v_mov_b32_e32 v222, v212
	v_mov_b32_e32 v223, v209
	v_mov_b32_e32 v226, v212
	v_mov_b32_e32 v227, v203
	v_mov_b32_e32 v209, v225
	v_pk_add_f32 v[220:221], v[220:221], v[222:223] neg_lo:[0,1] neg_hi:[0,1]
	v_mov_b32_e32 v222, v218
	v_mov_b32_e32 v223, v211
	v_pk_add_f32 v[208:209], v[226:227], v[208:209] neg_lo:[0,1] neg_hi:[0,1]
	v_pk_add_f32 v[222:223], v[222:223], v[220:221] neg_lo:[0,1] neg_hi:[0,1]
	v_mov_b32_e32 v226, v208
	v_mov_b32_e32 v227, v221
	v_mov_b32_e32 v236, v202
	v_mov_b32_e32 v237, v219
	v_mov_b32_e32 v221, v207
	v_pk_add_f32 v[226:227], v[210:211], v[226:227] neg_lo:[0,1] neg_hi:[0,1]
	v_pk_add_f32 v[220:221], v[236:237], v[220:221] neg_lo:[0,1] neg_hi:[0,1]
	v_mov_b32_e32 v211, v213
	v_pk_add_f32 v[204:205], v[204:205], v[220:221] neg_lo:[0,1] neg_hi:[0,1]
	v_pk_add_f32 v[208:209], v[210:211], v[208:209] neg_lo:[0,1] neg_hi:[0,1]
	v_pk_add_f32 v[210:211], v[214:215], v[224:225] neg_lo:[0,1] neg_hi:[0,1]
	v_pk_add_f32 v[214:215], v[222:223], v[204:205]
	v_pk_add_f32 v[212:213], v[210:211], v[208:209]
	v_mov_b32_e32 v209, v223
	v_mov_b32_e32 v211, v205
	v_pk_add_f32 v[204:205], v[208:209], v[210:211]
	v_pk_add_f32 v[206:207], v[218:219], v[206:207] neg_lo:[0,1] neg_hi:[0,1]
	v_pk_add_f32 v[204:205], v[204:205], v[226:227] neg_lo:[0,1] neg_hi:[0,1]
	v_mov_b32_e32 v210, v212
	v_mov_b32_e32 v211, v215
	v_pk_add_f32 v[206:207], v[216:217], v[206:207] neg_lo:[0,1] neg_hi:[0,1]
	v_pk_add_f32 v[210:211], v[210:211], v[204:205] neg_lo:[0,1] neg_hi:[0,1]
	v_pk_add_f32 v[204:205], v[206:207], v[204:205] neg_lo:[0,1] neg_hi:[0,1]
	v_pk_add_f32 v[208:209], v[208:209], v[210:211] neg_lo:[0,1] neg_hi:[0,1]
	v_pk_add_f32 v[206:207], v[214:215], v[212:213]
	v_pk_add_f32 v[204:205], v[204:205], v[208:209]
	v_pk_add_f32 v[208:209], v[202:203], v[206:207]
	s_nop 0
	v_pk_add_f32 v[202:203], v[208:209], v[202:203] neg_lo:[0,1] neg_hi:[0,1]
	s_nop 0
	v_pk_add_f32 v[202:203], v[206:207], v[202:203] neg_lo:[0,1] neg_hi:[0,1]
	s_nop 0
	v_pk_add_f32 v[202:203], v[204:205], v[202:203]
	s_nop 0
	v_pk_add_f32 v[202:203], v[208:209], v[202:203]
	s_nop 0
	v_cndmask_b32_e64 v183, v231, v202, s[10:11]
	v_cmp_neq_f32_e64 s[10:11], s4, v179
	s_nop 1
	v_cndmask_b32_e64 v187, v231, v203, s[10:11]
	v_cmp_ngt_f32_e64 s[10:11], -1.0, v179
	s_nop 1
	v_cndmask_b32_e64 v187, v232, v187, s[10:11]
	v_cmp_ngt_f32_e64 s[10:11], -1.0, v173
	s_nop 1
	v_cndmask_b32_e64 v183, v232, v183, s[10:11]
	v_cmp_neq_f32_e64 s[10:11], -1.0, v173
	s_nop 1
	v_cndmask_b32_e64 v183, v233, v183, s[10:11]
	v_cmp_neq_f32_e64 s[10:11], -1.0, v179
	s_nop 1
	v_cndmask_b32_e64 v187, v233, v187, s[10:11]
	v_cmp_lt_f32_e64 s[10:11], |v173|, s5
	v_cndmask_b32_e64 v203, v187, v179, s[12:13]
	s_nop 0
	v_cndmask_b32_e64 v202, v183, v173, s[10:11]
	v_pk_add_f32 v[130:131], v[130:131], v[202:203] neg_lo:[0,1] neg_hi:[0,1]
	v_min_f32_e32 v202, 0, v132
	v_mul_f32_e64 v132, |v132|, s34
	v_exp_f32_e32 v173, v132
	v_min_f32_e32 v203, 0, v133
	v_mul_f32_e64 v133, |v133|, s34
; __device__ __forceinline__ float log_sigmoid_f(float x) { return fminf(x, 0.f) - log1pf(__expf(-fabsf(x))); }
;     __device__ __forceinline__ void operator()(const f32x4 (&acc)[2][2][4][2], const Unit& u, int wr, int wc, int fr, int fq) const {
;     ...
;                             lf[0] = log_sigmoid_f(x[0]); lf[1] = log_sigmoid_f(x[1]); lf[2] = log_sigmoid_f(x[2]); lf[3] = log_sigmoid_f(x[3]);
	v_add_f32_e32 v132, 1.0, v173
	v_add_f32_e32 v179, -1.0, v132
	v_sub_f32_e32 v183, v179, v132
	v_add_f32_e32 v183, 1.0, v183
	v_sub_f32_e32 v179, v173, v179
	v_add_f32_e32 v179, v179, v183
	v_frexp_mant_f32_e32 v183, v132
	v_cvt_f64_f32_e32 v[204:205], v132
	v_cmp_gt_f32_e64 s[10:11], s35, v183
	v_frexp_exp_i32_f64_e32 v183, v[204:205]
	s_nop 0
	v_subbrev_co_u32_e64 v183, s[10:11], 0, v183, s[10:11]
	v_sub_u32_e32 v187, 0, v183
	v_ldexp_f32 v204, v179, v187
	v_exp_f32_e32 v179, v133
	v_ldexp_f32 v132, v132, v187
	v_add_f32_e32 v133, 1.0, v179
	v_add_f32_e32 v187, -1.0, v133
	v_sub_f32_e32 v191, v187, v133
	v_add_f32_e32 v191, 1.0, v191
	v_sub_f32_e32 v187, v179, v187
	v_add_f32_e32 v187, v187, v191
	v_frexp_mant_f32_e32 v191, v133
	v_cvt_f64_f32_e32 v[206:207], v133
	v_cmp_gt_f32_e64 s[10:11], s35, v191
	v_frexp_exp_i32_f64_e32 v191, v[206:207]
	v_cmp_lt_f32_e64 s[12:13], |v179|, s5
	v_subbrev_co_u32_e64 v191, s[10:11], 0, v191, s[10:11]
	v_sub_u32_e32 v195, 0, v191
	v_ldexp_f32 v133, v133, v195
	v_pk_add_f32 v[206:207], v[132:133], 1.0 op_sel_hi:[1,0]
	v_ldexp_f32 v205, v187, v195
	v_pk_add_f32 v[208:209], v[206:207], -1.0 op_sel_hi:[1,0]
	v_pk_add_f32 v[214:215], v[132:133], -1.0 op_sel_hi:[1,0]
	v_pk_add_f32 v[208:209], v[132:133], v[208:209] neg_lo:[0,1] neg_hi:[0,1]
	v_pk_add_f32 v[216:217], v[214:215], 1.0 op_sel_hi:[1,0]
	v_pk_add_f32 v[208:209], v[204:205], v[208:209]
	v_pk_add_f32 v[132:133], v[132:133], v[216:217] neg_lo:[0,1] neg_hi:[0,1]
	v_pk_add_f32 v[210:211], v[206:207], v[208:209]
	v_pk_add_f32 v[132:133], v[204:205], v[132:133]
	v_rcp_f32_e32 v212, v210
	v_rcp_f32_e32 v213, v211
	v_pk_add_f32 v[204:205], v[214:215], v[132:133]
	v_pk_add_f32 v[206:207], v[210:211], v[206:207] neg_lo:[0,1] neg_hi:[0,1]
	v_pk_add_f32 v[214:215], v[204:205], v[214:215] neg_lo:[0,1] neg_hi:[0,1]
	v_pk_add_f32 v[206:207], v[208:209], v[206:207] neg_lo:[0,1] neg_hi:[0,1]
	v_pk_mul_f32 v[208:209], v[204:205], v[212:213]
	v_pk_add_f32 v[132:133], v[132:133], v[214:215] neg_lo:[0,1] neg_hi:[0,1]
	v_pk_mul_f32 v[214:215], v[210:211], v[208:209]
	v_cmp_neq_f32_e64 s[10:11], s4, v173
	v_pk_fma_f32 v[216:217], v[208:209], v[210:211], v[214:215] neg_lo:[0,0,1] neg_hi:[0,0,1]
	s_nop 0
	v_pk_fma_f32 v[216:217], v[208:209], v[206:207], v[216:217]
	s_nop 0
	v_pk_add_f32 v[218:219], v[214:215], v[216:217]
	s_nop 0
	v_pk_add_f32 v[220:221], v[204:205], v[218:219] neg_lo:[0,1] neg_hi:[0,1]
	v_pk_add_f32 v[214:215], v[218:219], v[214:215] neg_lo:[0,1] neg_hi:[0,1]
	v_pk_add_f32 v[204:205], v[204:205], v[220:221] neg_lo:[0,1] neg_hi:[0,1]
	s_nop 0
	v_pk_add_f32 v[204:205], v[204:205], v[218:219] neg_lo:[0,1] neg_hi:[0,1]
	s_nop 0
	v_pk_add_f32 v[132:133], v[132:133], v[204:205]
	v_pk_add_f32 v[204:205], v[214:215], v[216:217] neg_lo:[0,1] neg_hi:[0,1]
	s_nop 0
	v_pk_add_f32 v[132:133], v[204:205], v[132:133]
	s_nop 0
	v_pk_add_f32 v[204:205], v[220:221], v[132:133]
	s_nop 0
	v_pk_mul_f32 v[214:215], v[212:213], v[204:205]
	s_nop 0
	v_pk_mul_f32 v[216:217], v[210:211], v[214:215]
	s_nop 0
	v_pk_fma_f32 v[210:211], v[214:215], v[210:211], v[216:217] neg_lo:[0,0,1] neg_hi:[0,0,1]
	s_nop 0
	v_pk_fma_f32 v[206:207], v[214:215], v[206:207], v[210:211]
	v_pk_add_f32 v[210:211], v[220:221], v[204:205] neg_lo:[0,1] neg_hi:[0,1]
	s_nop 0
	v_pk_add_f32 v[132:133], v[132:133], v[210:211]
	v_pk_add_f32 v[210:211], v[216:217], v[206:207]
	s_nop 0
	v_pk_add_f32 v[218:219], v[204:205], v[210:211] neg_lo:[0,1] neg_hi:[0,1]
	v_pk_add_f32 v[216:217], v[210:211], v[216:217] neg_lo:[0,1] neg_hi:[0,1]
	v_pk_add_f32 v[204:205], v[204:205], v[218:219] neg_lo:[0,1] neg_hi:[0,1]
	s_nop 0
	v_pk_add_f32 v[204:205], v[204:205], v[210:211] neg_lo:[0,1] neg_hi:[0,1]
	s_nop 0
	v_pk_add_f32 v[132:133], v[132:133], v[204:205]
	v_pk_add_f32 v[204:205], v[216:217], v[206:207] neg_lo:[0,1] neg_hi:[0,1]
	s_nop 0
	v_pk_add_f32 v[132:133], v[204:205], v[132:133]
	v_pk_add_f32 v[204:205], v[208:209], v[214:215]
	v_pk_add_f32 v[132:133], v[218:219], v[132:133]
	v_pk_add_f32 v[206:207], v[204:205], v[208:209] neg_lo:[0,1] neg_hi:[0,1]
	v_pk_mul_f32 v[132:133], v[212:213], v[132:133]
	v_pk_add_f32 v[206:207], v[214:215], v[206:207] neg_lo:[0,1] neg_hi:[0,1]
	s_nop 0
	v_pk_add_f32 v[132:133], v[206:207], v[132:133]
	s_nop 0
	v_pk_add_f32 v[206:207], v[204:205], v[132:133]
	s_nop 0
	v_pk_mul_f32 v[208:209], v[206:207], v[206:207]
	v_pk_add_f32 v[204:205], v[206:207], v[204:205] neg_lo:[0,1] neg_hi:[0,1]
	v_pk_fma_f32 v[140:141], v[208:209], s[52:53], v[140:141] op_sel_hi:[1,0,0]
	v_pk_add_f32 v[132:133], v[132:133], v[204:205] neg_lo:[0,1] neg_hi:[0,1]
; __device__ __forceinline__ float log_sigmoid_f(float x) { return fminf(x, 0.f) - log1pf(__expf(-fabsf(x))); }
;     __device__ __forceinline__ void operator()(const f32x4 (&acc)[2][2][4][2], const Unit& u, int wr, int wc, int fr, int fq) const {
;     ...
;                         for (int n = 0; n < 2; ++n) { const int c = 8 * fq + 4 * n; const f32x4 bv = *(const f32x4*)(b_f + c); const f32x4 x = acc[ai][0][m][n] * s + bv; f32x4 lf;
;                             lf[0] = log_sigmoid_f(x[0]); lf[1] = log_sigmoid_f(x[1]); lf[2] = log_sigmoid_f(x[2]); lf[3] = log_sigmoid_f(x[3]);
;                             *(f32x4*)(LF + (size_t)row * 16 + c) = lf; if (dst) *(f32x4*)(dst + c) = lf; } }
	v_ldexp_f32 v204, v206, 1
	v_pk_fma_f32 v[140:141], v[208:209], v[140:141], s[54:55] op_sel_hi:[1,1,0]
	v_ldexp_f32 v205, v207, 1
	v_pk_mul_f32 v[206:207], v[206:207], v[208:209]
	v_cvt_f32_i32_e32 v209, v191
	v_cvt_f32_i32_e32 v208, v183
	v_pk_mul_f32 v[140:141], v[206:207], v[140:141]
	v_ldexp_f32 v211, v133, 1
	v_pk_add_f32 v[206:207], v[204:205], v[140:141]
	v_pk_mul_f32 v[212:213], v[208:209], s[64:65] op_sel_hi:[1,0]
	v_pk_add_f32 v[204:205], v[206:207], v[204:205] neg_lo:[0,1] neg_hi:[0,1]
	v_pk_fma_f32 v[214:215], v[208:209], s[64:65], v[212:213] op_sel_hi:[1,0,1] neg_lo:[0,0,1] neg_hi:[0,0,1]
	v_pk_add_f32 v[140:141], v[140:141], v[204:205] neg_lo:[0,1] neg_hi:[0,1]
	v_pk_fma_f32 v[208:209], v[208:209], s[66:67], v[214:215] op_sel_hi:[1,0,1]
	v_ldexp_f32 v132, v132, 1
	v_mov_b32_e32 v204, v212
	v_mov_b32_e32 v205, v141
	v_mov_b32_e32 v210, v208
	v_mov_b32_e32 v133, v211
	v_pk_add_f32 v[204:205], v[204:205], v[210:211]
	v_pk_add_f32 v[210:211], v[132:133], v[140:141]
	v_mov_b32_e32 v141, v207
	v_mov_b32_e32 v133, v211
	v_pk_add_f32 v[214:215], v[212:213], v[208:209]
	v_pk_add_f32 v[132:133], v[132:133], v[140:141]
	v_pk_add_f32 v[140:141], v[206:207], v[210:211]
	v_mov_b32_e32 v224, v206
	v_pk_add_f32 v[216:217], v[214:215], v[140:141]
	v_mov_b32_e32 v222, v140
	v_mov_b32_e32 v223, v217
	v_mov_b32_e32 v225, v215
	v_pk_add_f32 v[222:223], v[222:223], v[224:225] neg_lo:[0,1] neg_hi:[0,1]
	v_mov_b32_e32 v218, v216
	v_mov_b32_e32 v219, v215
	v_mov_b32_e32 v220, v214
	v_mov_b32_e32 v221, v213
	v_mov_b32_e32 v224, v214
	v_mov_b32_e32 v225, v217
	v_mov_b32_e32 v213, v223
	v_pk_add_f32 v[218:219], v[218:219], v[220:221] neg_lo:[0,1] neg_hi:[0,1]
	v_mov_b32_e32 v220, v140
	v_mov_b32_e32 v221, v209
	v_pk_add_f32 v[212:213], v[224:225], v[212:213] neg_lo:[0,1] neg_hi:[0,1]
	v_pk_add_f32 v[220:221], v[220:221], v[218:219] neg_lo:[0,1] neg_hi:[0,1]
	v_mov_b32_e32 v224, v212
	v_mov_b32_e32 v225, v219
	v_mov_b32_e32 v226, v216
	v_mov_b32_e32 v227, v141
	v_mov_b32_e32 v219, v207
	v_pk_add_f32 v[224:225], v[208:209], v[224:225] neg_lo:[0,1] neg_hi:[0,1]
	v_pk_add_f32 v[218:219], v[226:227], v[218:219] neg_lo:[0,1] neg_hi:[0,1]
	v_mov_b32_e32 v209, v215
	v_pk_add_f32 v[140:141], v[140:141], v[206:207] neg_lo:[0,1] neg_hi:[0,1]
	v_pk_add_f32 v[204:205], v[204:205], v[218:219] neg_lo:[0,1] neg_hi:[0,1]
	v_pk_add_f32 v[206:207], v[208:209], v[212:213] neg_lo:[0,1] neg_hi:[0,1]
	v_pk_add_f32 v[132:133], v[132:133], v[222:223] neg_lo:[0,1] neg_hi:[0,1]
	v_pk_add_f32 v[140:141], v[210:211], v[140:141] neg_lo:[0,1] neg_hi:[0,1]
	v_pk_add_f32 v[208:209], v[132:133], v[206:207]
	v_mov_b32_e32 v207, v221
	v_mov_b32_e32 v133, v205
	v_pk_add_f32 v[210:211], v[220:221], v[204:205]
	v_pk_add_f32 v[132:133], v[206:207], v[132:133]
	v_mov_b32_e32 v204, v208
	v_pk_add_f32 v[132:133], v[132:133], v[224:225] neg_lo:[0,1] neg_hi:[0,1]
	v_mov_b32_e32 v205, v211
	v_pk_add_f32 v[204:205], v[204:205], v[132:133] neg_lo:[0,1] neg_hi:[0,1]
	v_pk_add_f32 v[132:133], v[140:141], v[132:133] neg_lo:[0,1] neg_hi:[0,1]
	v_pk_add_f32 v[204:205], v[206:207], v[204:205] neg_lo:[0,1] neg_hi:[0,1]
	v_pk_add_f32 v[140:141], v[210:211], v[208:209]
	v_pk_add_f32 v[132:133], v[132:133], v[204:205]
	v_pk_add_f32 v[204:205], v[216:217], v[140:141]
	s_nop 0
	v_pk_add_f32 v[206:207], v[204:205], v[216:217] neg_lo:[0,1] neg_hi:[0,1]
	s_nop 0
	v_pk_add_f32 v[140:141], v[140:141], v[206:207] neg_lo:[0,1] neg_hi:[0,1]
	s_nop 0
	v_pk_add_f32 v[132:133], v[132:133], v[140:141]
	s_nop 0
	v_pk_add_f32 v[132:133], v[204:205], v[132:133]
	s_nop 0
	v_cndmask_b32_e64 v132, v231, v132, s[10:11]
	v_cmp_neq_f32_e64 s[10:11], s4, v179
	s_nop 1
	v_cndmask_b32_e64 v133, v231, v133, s[10:11]
	v_cmp_ngt_f32_e64 s[10:11], -1.0, v179
	s_nop 1
	v_cndmask_b32_e64 v133, v232, v133, s[10:11]
	v_cmp_ngt_f32_e64 s[10:11], -1.0, v173
	s_nop 1
	v_cndmask_b32_e64 v132, v232, v132, s[10:11]
	v_cmp_neq_f32_e64 s[10:11], -1.0, v173
	s_nop 1
	v_cndmask_b32_e64 v132, v233, v132, s[10:11]
	v_cmp_neq_f32_e64 s[10:11], -1.0, v179
	s_nop 1
	v_cndmask_b32_e64 v133, v233, v133, s[10:11]
	v_cmp_lt_f32_e64 s[10:11], |v173|, s5
	v_cndmask_b32_e64 v133, v133, v179, s[12:13]
	s_nop 0
	v_cndmask_b32_e64 v132, v132, v173, s[10:11]
	v_pk_add_f32 v[132:133], v[202:203], v[132:133] neg_lo:[0,1] neg_hi:[0,1]
	global_store_dwordx4 v[138:139], v[130:133], off offset:16 nt
	s_and_saveexec_b64 s[10:11], vcc
	s_cbranch_execz .LBB0_379
	v_lshl_add_u64 v[136:137], v[136:137], 0, v[150:151]
	global_store_dwordx4 v[136:137], v[130:133], off offset:16 nt

; __device__ __forceinline__ float log_sigmoid_f(float x) { return fminf(x, 0.f) - log1pf(__expf(-fabsf(x))); }
;     __device__ __forceinline__ void operator()(const f32x4 (&acc)[2][2][4][2], const Unit& u, int wr, int wc, int fr, int fq) const {
;     ...
;                         if (pm == 0) dst = o_lfs + (size_t)row * 16; else { const int t = row - G_ROWP; if (t < G_TP) dst = o_lfp + (size_t)t * 16; }
; #pragma unroll
;                         for (int n = 0; n < 2; ++n) { const int c = 8 * fq + 4 * n; const f32x4 bv = *(const f32x4*)(b_f + c); const f32x4 x = acc[ai][0][m][n] * s + bv; f32x4 lf;
;                             lf[0] = log_sigmoid_f(x[0]); lf[1] = log_sigmoid_f(x[1]); lf[2] = log_sigmoid_f(x[2]); lf[3] = log_sigmoid_f(x[3]);
.LBB0_382:
	global_load_dwordx4 v[130:133], v[158:159], off
	v_cmp_ne_u64_e32 vcc, 0, v[136:137]
	v_lshl_add_u64 v[138:139], v[162:163], 0, v[138:139]
	s_waitcnt vmcnt(0)
	v_pk_fma_f32 v[140:141], v[110:111], v[198:199], v[130:131] op_sel_hi:[1,0,1]
	s_nop 0
	v_mul_f32_e64 v131, |v140|, s34
	v_exp_f32_e32 v173, v131
	v_min_f32_e32 v130, 0, v140
	v_pk_fma_f32 v[132:133], v[112:113], v[198:199], v[132:133] op_sel_hi:[1,0,1]
	v_add_f32_e32 v131, 1.0, v173
	v_add_f32_e32 v140, -1.0, v131
	v_sub_f32_e32 v179, v140, v131
	v_add_f32_e32 v179, 1.0, v179
	v_sub_f32_e32 v140, v173, v140
	v_add_f32_e32 v179, v140, v179
	v_frexp_mant_f32_e32 v140, v131
	v_cvt_f64_f32_e32 v[202:203], v131
	v_cmp_gt_f32_e64 s[12:13], s35, v140
	v_frexp_exp_i32_f64_e32 v140, v[202:203]
	s_nop 0
	v_subbrev_co_u32_e64 v183, s[12:13], 0, v140, s[12:13]
	v_sub_u32_e32 v187, 0, v183
	v_ldexp_f32 v140, v131, v187
	v_min_f32_e32 v131, 0, v141
	v_mul_f32_e64 v141, |v141|, s34
	v_ldexp_f32 v202, v179, v187
	v_exp_f32_e32 v179, v141
	s_nop 0
	v_add_f32_e32 v141, 1.0, v179
	v_add_f32_e32 v187, -1.0, v141
	v_sub_f32_e32 v191, v187, v141
	v_add_f32_e32 v191, 1.0, v191
	v_sub_f32_e32 v187, v179, v187
	v_add_f32_e32 v191, v187, v191
	v_frexp_mant_f32_e32 v187, v141
	v_cvt_f64_f32_e32 v[204:205], v141
	v_cmp_gt_f32_e64 s[12:13], s35, v187
	v_frexp_exp_i32_f64_e32 v187, v[204:205]
	v_cmp_lt_f32_e64 s[14:15], |v179|, s5
	v_subbrev_co_u32_e64 v187, s[12:13], 0, v187, s[12:13]
	v_sub_u32_e32 v195, 0, v187
	v_ldexp_f32 v141, v141, v195
	v_pk_add_f32 v[204:205], v[140:141], 1.0 op_sel_hi:[1,0]
	v_ldexp_f32 v203, v191, v195
	v_pk_add_f32 v[206:207], v[204:205], -1.0 op_sel_hi:[1,0]
	v_pk_add_f32 v[212:213], v[140:141], -1.0 op_sel_hi:[1,0]
	v_pk_add_f32 v[206:207], v[140:141], v[206:207] neg_lo:[0,1] neg_hi:[0,1]
	v_pk_add_f32 v[214:215], v[212:213], 1.0 op_sel_hi:[1,0]
	v_pk_add_f32 v[206:207], v[202:203], v[206:207]
	v_pk_add_f32 v[140:141], v[140:141], v[214:215] neg_lo:[0,1] neg_hi:[0,1]
	v_pk_add_f32 v[208:209], v[204:205], v[206:207]
	v_pk_add_f32 v[140:141], v[202:203], v[140:141]
	v_rcp_f32_e32 v210, v208
	v_rcp_f32_e32 v211, v209
	v_pk_add_f32 v[202:203], v[212:213], v[140:141]
	v_pk_add_f32 v[204:205], v[208:209], v[204:205] neg_lo:[0,1] neg_hi:[0,1]
	v_pk_add_f32 v[212:213], v[202:203], v[212:213] neg_lo:[0,1] neg_hi:[0,1]
	v_pk_add_f32 v[204:205], v[206:207], v[204:205] neg_lo:[0,1] neg_hi:[0,1]
	v_pk_mul_f32 v[206:207], v[202:203], v[210:211]
	v_pk_add_f32 v[140:141], v[140:141], v[212:213] neg_lo:[0,1] neg_hi:[0,1]
	v_pk_mul_f32 v[212:213], v[208:209], v[206:207]
	v_cmp_neq_f32_e64 s[12:13], s4, v173
	v_pk_fma_f32 v[214:215], v[206:207], v[208:209], v[212:213] neg_lo:[0,0,1] neg_hi:[0,0,1]
	s_nop 0
	v_pk_fma_f32 v[214:215], v[206:207], v[204:205], v[214:215]
	s_nop 0
	v_pk_add_f32 v[216:217], v[212:213], v[214:215]
	s_nop 0
	v_pk_add_f32 v[218:219], v[202:203], v[216:217] neg_lo:[0,1] neg_hi:[0,1]
	v_pk_add_f32 v[212:213], v[216:217], v[212:213] neg_lo:[0,1] neg_hi:[0,1]
	v_pk_add_f32 v[202:203], v[202:203], v[218:219] neg_lo:[0,1] neg_hi:[0,1]
	s_nop 0
	v_pk_add_f32 v[202:203], v[202:203], v[216:217] neg_lo:[0,1] neg_hi:[0,1]
	s_nop 0
	v_pk_add_f32 v[140:141], v[140:141], v[202:203]
	v_pk_add_f32 v[202:203], v[212:213], v[214:215] neg_lo:[0,1] neg_hi:[0,1]
	s_nop 0
	v_pk_add_f32 v[140:141], v[202:203], v[140:141]
	s_nop 0
	v_pk_add_f32 v[202:203], v[218:219], v[140:141]
	s_nop 0
	v_pk_mul_f32 v[212:213], v[210:211], v[202:203]
	s_nop 0
	v_pk_mul_f32 v[214:215], v[208:209], v[212:213]
	s_nop 0
	v_pk_fma_f32 v[208:209], v[212:213], v[208:209], v[214:215] neg_lo:[0,0,1] neg_hi:[0,0,1]
	s_nop 0
	v_pk_fma_f32 v[204:205], v[212:213], v[204:205], v[208:209]
	v_pk_add_f32 v[208:209], v[218:219], v[202:203] neg_lo:[0,1] neg_hi:[0,1]
	s_nop 0
	v_pk_add_f32 v[140:141], v[140:141], v[208:209]
	v_pk_add_f32 v[208:209], v[214:215], v[204:205]
	s_nop 0
	v_pk_add_f32 v[216:217], v[202:203], v[208:209] neg_lo:[0,1] neg_hi:[0,1]
	v_pk_add_f32 v[214:215], v[208:209], v[214:215] neg_lo:[0,1] neg_hi:[0,1]
	v_pk_add_f32 v[202:203], v[202:203], v[216:217] neg_lo:[0,1] neg_hi:[0,1]
	s_nop 0
	v_pk_add_f32 v[202:203], v[202:203], v[208:209] neg_lo:[0,1] neg_hi:[0,1]
	s_nop 0
	v_pk_add_f32 v[140:141], v[140:141], v[202:203]
	v_pk_add_f32 v[202:203], v[214:215], v[204:205] neg_lo:[0,1] neg_hi:[0,1]
	s_nop 0
	v_pk_add_f32 v[140:141], v[202:203], v[140:141]
	v_pk_add_f32 v[202:203], v[206:207], v[212:213]
	v_pk_add_f32 v[140:141], v[216:217], v[140:141]
	v_pk_add_f32 v[204:205], v[202:203], v[206:207] neg_lo:[0,1] neg_hi:[0,1]
	v_pk_mul_f32 v[140:141], v[210:211], v[140:141]
	v_pk_add_f32 v[204:205], v[212:213], v[204:205] neg_lo:[0,1] neg_hi:[0,1]
	s_nop 0
	v_pk_add_f32 v[140:141], v[204:205], v[140:141]
	s_nop 0
	v_pk_add_f32 v[206:207], v[202:203], v[140:141]
	s_nop 0
	v_pk_add_f32 v[202:203], v[206:207], v[202:203] neg_lo:[0,1] neg_hi:[0,1]
	v_pk_mul_f32 v[208:209], v[206:207], v[206:207]
	v_pk_add_f32 v[202:203], v[140:141], v[202:203] neg_lo:[0,1] neg_hi:[0,1]
	v_mov_b64_e32 v[140:141], s[50:51]
	v_pk_fma_f32 v[210:211], v[208:209], s[52:53], v[140:141] op_sel_hi:[1,0,0]
	v_ldexp_f32 v204, v206, 1
	v_pk_fma_f32 v[210:211], v[208:209], v[210:211], s[54:55] op_sel_hi:[1,1,0]
	v_ldexp_f32 v205, v207, 1
	v_pk_mul_f32 v[206:207], v[206:207], v[208:209]
	v_cvt_f32_i32_e32 v209, v187
	v_cvt_f32_i32_e32 v208, v183
	v_pk_mul_f32 v[216:217], v[206:207], v[210:211]
	v_ldexp_f32 v215, v203, 1
	v_pk_add_f32 v[206:207], v[204:205], v[216:217]
	v_pk_mul_f32 v[212:213], v[208:209], s[64:65] op_sel_hi:[1,0]
	v_pk_add_f32 v[204:205], v[206:207], v[204:205] neg_lo:[0,1] neg_hi:[0,1]
	v_ldexp_f32 v202, v202, 1
; __device__ __forceinline__ float log_sigmoid_f(float x) { return fminf(x, 0.f) - log1pf(__expf(-fabsf(x))); }
;     __device__ __forceinline__ void operator()(const f32x4 (&acc)[2][2][4][2], const Unit& u, int wr, int wc, int fr, int fq) const {
;     ...
;                             lf[0] = log_sigmoid_f(x[0]); lf[1] = log_sigmoid_f(x[1]); lf[2] = log_sigmoid_f(x[2]); lf[3] = log_sigmoid_f(x[3]);
	v_pk_fma_f32 v[210:211], v[208:209], s[64:65], v[212:213] op_sel_hi:[1,0,1] neg_lo:[0,0,1] neg_hi:[0,0,1]
	v_pk_add_f32 v[218:219], v[216:217], v[204:205] neg_lo:[0,1] neg_hi:[0,1]
	v_mov_b32_e32 v203, v215
	v_pk_fma_f32 v[208:209], v[208:209], s[66:67], v[210:211] op_sel_hi:[1,0,1]
	v_pk_add_f32 v[216:217], v[202:203], v[218:219]
	v_mov_b32_e32 v204, v212
	v_mov_b32_e32 v205, v219
	v_mov_b32_e32 v214, v208
	v_mov_b32_e32 v203, v217
	v_mov_b32_e32 v219, v207
	v_pk_add_f32 v[210:211], v[212:213], v[208:209]
	v_pk_add_f32 v[204:205], v[204:205], v[214:215]
	v_pk_add_f32 v[214:215], v[202:203], v[218:219]
	v_pk_add_f32 v[218:219], v[206:207], v[216:217]
	v_mov_b32_e32 v226, v206
	v_pk_add_f32 v[202:203], v[210:211], v[218:219]
	v_mov_b32_e32 v224, v218
	v_mov_b32_e32 v225, v203
	v_mov_b32_e32 v227, v211
	v_pk_add_f32 v[224:225], v[224:225], v[226:227] neg_lo:[0,1] neg_hi:[0,1]
	v_mov_b32_e32 v220, v202
	v_mov_b32_e32 v221, v211
	v_mov_b32_e32 v222, v210
	v_mov_b32_e32 v223, v213
	v_mov_b32_e32 v226, v210
	v_mov_b32_e32 v227, v203
	v_mov_b32_e32 v213, v225
	v_pk_add_f32 v[220:221], v[220:221], v[222:223] neg_lo:[0,1] neg_hi:[0,1]
	v_mov_b32_e32 v222, v218
	v_mov_b32_e32 v223, v209
	v_pk_add_f32 v[212:213], v[226:227], v[212:213] neg_lo:[0,1] neg_hi:[0,1]
	v_pk_add_f32 v[222:223], v[222:223], v[220:221] neg_lo:[0,1] neg_hi:[0,1]
	v_mov_b32_e32 v226, v212
	v_mov_b32_e32 v227, v221
	v_mov_b32_e32 v236, v202
	v_mov_b32_e32 v237, v219
	v_mov_b32_e32 v221, v207
	v_pk_add_f32 v[226:227], v[208:209], v[226:227] neg_lo:[0,1] neg_hi:[0,1]
	v_pk_add_f32 v[220:221], v[236:237], v[220:221] neg_lo:[0,1] neg_hi:[0,1]
	v_mov_b32_e32 v209, v211
	v_pk_add_f32 v[204:205], v[204:205], v[220:221] neg_lo:[0,1] neg_hi:[0,1]
	v_pk_add_f32 v[208:209], v[208:209], v[212:213] neg_lo:[0,1] neg_hi:[0,1]
	v_pk_add_f32 v[210:211], v[214:215], v[224:225] neg_lo:[0,1] neg_hi:[0,1]
	v_pk_add_f32 v[214:215], v[222:223], v[204:205]
	v_pk_add_f32 v[212:213], v[210:211], v[208:209]
	v_mov_b32_e32 v209, v223
	v_mov_b32_e32 v211, v205
	v_pk_add_f32 v[204:205], v[208:209], v[210:211]
	v_pk_add_f32 v[206:207], v[218:219], v[206:207] neg_lo:[0,1] neg_hi:[0,1]
	v_pk_add_f32 v[204:205], v[204:205], v[226:227] neg_lo:[0,1] neg_hi:[0,1]
	v_mov_b32_e32 v210, v212
	v_mov_b32_e32 v211, v215
	v_pk_add_f32 v[206:207], v[216:217], v[206:207] neg_lo:[0,1] neg_hi:[0,1]
	v_pk_add_f32 v[210:211], v[210:211], v[204:205] neg_lo:[0,1] neg_hi:[0,1]
	v_pk_add_f32 v[204:205], v[206:207], v[204:205] neg_lo:[0,1] neg_hi:[0,1]
	v_pk_add_f32 v[208:209], v[208:209], v[210:211] neg_lo:[0,1] neg_hi:[0,1]
	v_pk_add_f32 v[206:207], v[214:215], v[212:213]
	v_pk_add_f32 v[204:205], v[204:205], v[208:209]
	v_pk_add_f32 v[208:209], v[202:203], v[206:207]
	s_nop 0
	v_pk_add_f32 v[202:203], v[208:209], v[202:203] neg_lo:[0,1] neg_hi:[0,1]
	s_nop 0
	v_pk_add_f32 v[202:203], v[206:207], v[202:203] neg_lo:[0,1] neg_hi:[0,1]
	s_nop 0
	v_pk_add_f32 v[202:203], v[204:205], v[202:203]
	s_nop 0
	v_pk_add_f32 v[202:203], v[208:209], v[202:203]
	s_nop 0
	v_cndmask_b32_e64 v183, v231, v202, s[12:13]
	v_cmp_neq_f32_e64 s[12:13], s4, v179
	s_nop 1
	v_cndmask_b32_e64 v187, v231, v203, s[12:13]
	v_cmp_ngt_f32_e64 s[12:13], -1.0, v179
	s_nop 1
	v_cndmask_b32_e64 v187, v232, v187, s[12:13]
	v_cmp_ngt_f32_e64 s[12:13], -1.0, v173
	s_nop 1
	v_cndmask_b32_e64 v183, v232, v183, s[12:13]
	v_cmp_neq_f32_e64 s[12:13], -1.0, v173
	s_nop 1
	v_cndmask_b32_e64 v183, v233, v183, s[12:13]
	v_cmp_neq_f32_e64 s[12:13], -1.0, v179
	s_nop 1
	v_cndmask_b32_e64 v187, v233, v187, s[12:13]
	v_cmp_lt_f32_e64 s[12:13], |v173|, s5
	v_cndmask_b32_e64 v203, v187, v179, s[14:15]
	s_nop 0
	v_cndmask_b32_e64 v202, v183, v173, s[12:13]
	v_pk_add_f32 v[130:131], v[130:131], v[202:203] neg_lo:[0,1] neg_hi:[0,1]
	v_min_f32_e32 v202, 0, v132
	v_mul_f32_e64 v132, |v132|, s34
	v_exp_f32_e32 v173, v132
	v_min_f32_e32 v203, 0, v133
	v_mul_f32_e64 v133, |v133|, s34
	v_add_f32_e32 v132, 1.0, v173
	v_add_f32_e32 v179, -1.0, v132
	v_sub_f32_e32 v183, v179, v132
	v_add_f32_e32 v183, 1.0, v183
	v_sub_f32_e32 v179, v173, v179
	v_add_f32_e32 v179, v179, v183
	v_frexp_mant_f32_e32 v183, v132
	v_cvt_f64_f32_e32 v[204:205], v132
	v_cmp_gt_f32_e64 s[12:13], s35, v183
	v_frexp_exp_i32_f64_e32 v183, v[204:205]
	s_nop 0
	v_subbrev_co_u32_e64 v183, s[12:13], 0, v183, s[12:13]
	v_sub_u32_e32 v187, 0, v183
	v_ldexp_f32 v204, v179, v187
	v_exp_f32_e32 v179, v133
	v_ldexp_f32 v132, v132, v187
	v_add_f32_e32 v133, 1.0, v179
	v_add_f32_e32 v187, -1.0, v133
	v_sub_f32_e32 v191, v187, v133
	v_add_f32_e32 v191, 1.0, v191
	v_sub_f32_e32 v187, v179, v187
	v_add_f32_e32 v187, v187, v191
	v_frexp_mant_f32_e32 v191, v133
	v_cvt_f64_f32_e32 v[206:207], v133
	v_cmp_gt_f32_e64 s[12:13], s35, v191
	v_frexp_exp_i32_f64_e32 v191, v[206:207]
	v_cmp_lt_f32_e64 s[14:15], |v179|, s5
	v_subbrev_co_u32_e64 v191, s[12:13], 0, v191, s[12:13]
	v_sub_u32_e32 v195, 0, v191
	v_ldexp_f32 v133, v133, v195
	v_pk_add_f32 v[206:207], v[132:133], 1.0 op_sel_hi:[1,0]
	v_ldexp_f32 v205, v187, v195
	v_pk_add_f32 v[208:209], v[206:207], -1.0 op_sel_hi:[1,0]
	v_pk_add_f32 v[214:215], v[132:133], -1.0 op_sel_hi:[1,0]
	v_pk_add_f32 v[208:209], v[132:133], v[208:209] neg_lo:[0,1] neg_hi:[0,1]
	v_pk_add_f32 v[216:217], v[214:215], 1.0 op_sel_hi:[1,0]
	v_pk_add_f32 v[208:209], v[204:205], v[208:209]
	v_pk_add_f32 v[132:133], v[132:133], v[216:217] neg_lo:[0,1] neg_hi:[0,1]
	v_pk_add_f32 v[210:211], v[206:207], v[208:209]
	v_pk_add_f32 v[132:133], v[204:205], v[132:133]
	v_rcp_f32_e32 v212, v210
	v_rcp_f32_e32 v213, v211
	v_pk_add_f32 v[204:205], v[214:215], v[132:133]
	v_pk_add_f32 v[206:207], v[210:211], v[206:207] neg_lo:[0,1] neg_hi:[0,1]
; __device__ __forceinline__ float log_sigmoid_f(float x) { return fminf(x, 0.f) - log1pf(__expf(-fabsf(x))); }
;     __device__ __forceinline__ void operator()(const f32x4 (&acc)[2][2][4][2], const Unit& u, int wr, int wc, int fr, int fq) const {
;     ...
;                         for (int n = 0; n < 2; ++n) { const int c = 8 * fq + 4 * n; const f32x4 bv = *(const f32x4*)(b_f + c); const f32x4 x = acc[ai][0][m][n] * s + bv; f32x4 lf;
;                             lf[0] = log_sigmoid_f(x[0]); lf[1] = log_sigmoid_f(x[1]); lf[2] = log_sigmoid_f(x[2]); lf[3] = log_sigmoid_f(x[3]);
	v_pk_add_f32 v[214:215], v[204:205], v[214:215] neg_lo:[0,1] neg_hi:[0,1]
	v_pk_add_f32 v[206:207], v[208:209], v[206:207] neg_lo:[0,1] neg_hi:[0,1]
	v_pk_mul_f32 v[208:209], v[204:205], v[212:213]
	v_pk_add_f32 v[132:133], v[132:133], v[214:215] neg_lo:[0,1] neg_hi:[0,1]
	v_pk_mul_f32 v[214:215], v[210:211], v[208:209]
	v_cmp_neq_f32_e64 s[12:13], s4, v173
	v_pk_fma_f32 v[216:217], v[208:209], v[210:211], v[214:215] neg_lo:[0,0,1] neg_hi:[0,0,1]
	s_nop 0
	v_pk_fma_f32 v[216:217], v[208:209], v[206:207], v[216:217]
	s_nop 0
	v_pk_add_f32 v[218:219], v[214:215], v[216:217]
	s_nop 0
	v_pk_add_f32 v[220:221], v[204:205], v[218:219] neg_lo:[0,1] neg_hi:[0,1]
	v_pk_add_f32 v[214:215], v[218:219], v[214:215] neg_lo:[0,1] neg_hi:[0,1]
	v_pk_add_f32 v[204:205], v[204:205], v[220:221] neg_lo:[0,1] neg_hi:[0,1]
	s_nop 0
	v_pk_add_f32 v[204:205], v[204:205], v[218:219] neg_lo:[0,1] neg_hi:[0,1]
	s_nop 0
	v_pk_add_f32 v[132:133], v[132:133], v[204:205]
	v_pk_add_f32 v[204:205], v[214:215], v[216:217] neg_lo:[0,1] neg_hi:[0,1]
	s_nop 0
	v_pk_add_f32 v[132:133], v[204:205], v[132:133]
	s_nop 0
	v_pk_add_f32 v[204:205], v[220:221], v[132:133]
	s_nop 0
	v_pk_mul_f32 v[214:215], v[212:213], v[204:205]
	s_nop 0
	v_pk_mul_f32 v[216:217], v[210:211], v[214:215]
	s_nop 0
	v_pk_fma_f32 v[210:211], v[214:215], v[210:211], v[216:217] neg_lo:[0,0,1] neg_hi:[0,0,1]
	s_nop 0
	v_pk_fma_f32 v[206:207], v[214:215], v[206:207], v[210:211]
	v_pk_add_f32 v[210:211], v[220:221], v[204:205] neg_lo:[0,1] neg_hi:[0,1]
	s_nop 0
	v_pk_add_f32 v[132:133], v[132:133], v[210:211]
	v_pk_add_f32 v[210:211], v[216:217], v[206:207]
	s_nop 0
	v_pk_add_f32 v[218:219], v[204:205], v[210:211] neg_lo:[0,1] neg_hi:[0,1]
	v_pk_add_f32 v[216:217], v[210:211], v[216:217] neg_lo:[0,1] neg_hi:[0,1]
	v_pk_add_f32 v[204:205], v[204:205], v[218:219] neg_lo:[0,1] neg_hi:[0,1]
	s_nop 0
	v_pk_add_f32 v[204:205], v[204:205], v[210:211] neg_lo:[0,1] neg_hi:[0,1]
	s_nop 0
	v_pk_add_f32 v[132:133], v[132:133], v[204:205]
	v_pk_add_f32 v[204:205], v[216:217], v[206:207] neg_lo:[0,1] neg_hi:[0,1]
	s_nop 0
	v_pk_add_f32 v[132:133], v[204:205], v[132:133]
	v_pk_add_f32 v[204:205], v[208:209], v[214:215]
	v_pk_add_f32 v[132:133], v[218:219], v[132:133]
	v_pk_add_f32 v[206:207], v[204:205], v[208:209] neg_lo:[0,1] neg_hi:[0,1]
	v_pk_mul_f32 v[132:133], v[212:213], v[132:133]
	v_pk_add_f32 v[206:207], v[214:215], v[206:207] neg_lo:[0,1] neg_hi:[0,1]
	s_nop 0
	v_pk_add_f32 v[132:133], v[206:207], v[132:133]
	s_nop 0
	v_pk_add_f32 v[206:207], v[204:205], v[132:133]
	s_nop 0
	v_pk_mul_f32 v[208:209], v[206:207], v[206:207]
	v_pk_add_f32 v[204:205], v[206:207], v[204:205] neg_lo:[0,1] neg_hi:[0,1]
	v_pk_fma_f32 v[140:141], v[208:209], s[52:53], v[140:141] op_sel_hi:[1,0,0]
	v_pk_add_f32 v[132:133], v[132:133], v[204:205] neg_lo:[0,1] neg_hi:[0,1]
	v_ldexp_f32 v204, v206, 1
	v_pk_fma_f32 v[140:141], v[208:209], v[140:141], s[54:55] op_sel_hi:[1,1,0]
	v_ldexp_f32 v205, v207, 1
	v_pk_mul_f32 v[206:207], v[206:207], v[208:209]
	v_cvt_f32_i32_e32 v209, v191
	v_cvt_f32_i32_e32 v208, v183
	v_pk_mul_f32 v[140:141], v[206:207], v[140:141]
	v_ldexp_f32 v211, v133, 1
	v_pk_add_f32 v[206:207], v[204:205], v[140:141]
	v_pk_mul_f32 v[212:213], v[208:209], s[64:65] op_sel_hi:[1,0]
	v_pk_add_f32 v[204:205], v[206:207], v[204:205] neg_lo:[0,1] neg_hi:[0,1]
	v_pk_fma_f32 v[214:215], v[208:209], s[64:65], v[212:213] op_sel_hi:[1,0,1] neg_lo:[0,0,1] neg_hi:[0,0,1]
	v_pk_add_f32 v[140:141], v[140:141], v[204:205] neg_lo:[0,1] neg_hi:[0,1]
	v_pk_fma_f32 v[208:209], v[208:209], s[66:67], v[214:215] op_sel_hi:[1,0,1]
	v_ldexp_f32 v132, v132, 1
	v_mov_b32_e32 v204, v212
	v_mov_b32_e32 v205, v141
	v_mov_b32_e32 v210, v208
	v_mov_b32_e32 v133, v211
	v_pk_add_f32 v[204:205], v[204:205], v[210:211]
	v_pk_add_f32 v[210:211], v[132:133], v[140:141]
	v_mov_b32_e32 v141, v207
	v_mov_b32_e32 v133, v211
	v_pk_add_f32 v[214:215], v[212:213], v[208:209]
	v_pk_add_f32 v[132:133], v[132:133], v[140:141]
	v_pk_add_f32 v[140:141], v[206:207], v[210:211]
	v_mov_b32_e32 v224, v206
	v_pk_add_f32 v[216:217], v[214:215], v[140:141]
	v_mov_b32_e32 v222, v140
	v_mov_b32_e32 v223, v217
	v_mov_b32_e32 v225, v215
	v_pk_add_f32 v[222:223], v[222:223], v[224:225] neg_lo:[0,1] neg_hi:[0,1]
	v_mov_b32_e32 v218, v216
	v_mov_b32_e32 v219, v215
	v_mov_b32_e32 v220, v214
	v_mov_b32_e32 v221, v213
	v_mov_b32_e32 v224, v214
	v_mov_b32_e32 v225, v217
	v_mov_b32_e32 v213, v223
	v_pk_add_f32 v[218:219], v[218:219], v[220:221] neg_lo:[0,1] neg_hi:[0,1]
	v_mov_b32_e32 v220, v140
	v_mov_b32_e32 v221, v209
	v_pk_add_f32 v[212:213], v[224:225], v[212:213] neg_lo:[0,1] neg_hi:[0,1]
	v_pk_add_f32 v[220:221], v[220:221], v[218:219] neg_lo:[0,1] neg_hi:[0,1]
	v_mov_b32_e32 v224, v212
	v_mov_b32_e32 v225, v219
	v_mov_b32_e32 v226, v216
	v_mov_b32_e32 v227, v141
	v_mov_b32_e32 v219, v207
	v_pk_add_f32 v[224:225], v[208:209], v[224:225] neg_lo:[0,1] neg_hi:[0,1]
	v_pk_add_f32 v[218:219], v[226:227], v[218:219] neg_lo:[0,1] neg_hi:[0,1]
	v_mov_b32_e32 v209, v215
	v_pk_add_f32 v[140:141], v[140:141], v[206:207] neg_lo:[0,1] neg_hi:[0,1]
	v_pk_add_f32 v[204:205], v[204:205], v[218:219] neg_lo:[0,1] neg_hi:[0,1]
	v_pk_add_f32 v[206:207], v[208:209], v[212:213] neg_lo:[0,1] neg_hi:[0,1]
	v_pk_add_f32 v[132:133], v[132:133], v[222:223] neg_lo:[0,1] neg_hi:[0,1]
	v_pk_add_f32 v[140:141], v[210:211], v[140:141] neg_lo:[0,1] neg_hi:[0,1]
	v_pk_add_f32 v[208:209], v[132:133], v[206:207]
	v_mov_b32_e32 v207, v221
	v_mov_b32_e32 v133, v205
	v_pk_add_f32 v[210:211], v[220:221], v[204:205]
	v_pk_add_f32 v[132:133], v[206:207], v[132:133]
	v_mov_b32_e32 v204, v208
; __device__ __forceinline__ float log_sigmoid_f(float x) { return fminf(x, 0.f) - log1pf(__expf(-fabsf(x))); }
;     __device__ __forceinline__ void operator()(const f32x4 (&acc)[2][2][4][2], const Unit& u, int wr, int wc, int fr, int fq) const {
;     ...
;                         for (int n = 0; n < 2; ++n) { const int c = 8 * fq + 4 * n; const f32x4 bv = *(const f32x4*)(b_f + c); const f32x4 x = acc[ai][0][m][n] * s + bv; f32x4 lf;
;                             lf[0] = log_sigmoid_f(x[0]); lf[1] = log_sigmoid_f(x[1]); lf[2] = log_sigmoid_f(x[2]); lf[3] = log_sigmoid_f(x[3]);
;                             *(f32x4*)(LF + (size_t)row * 16 + c) = lf; if (dst) *(f32x4*)(dst + c) = lf; } }
	v_pk_add_f32 v[132:133], v[132:133], v[224:225] neg_lo:[0,1] neg_hi:[0,1]
	v_mov_b32_e32 v205, v211
	v_pk_add_f32 v[204:205], v[204:205], v[132:133] neg_lo:[0,1] neg_hi:[0,1]
	v_pk_add_f32 v[132:133], v[140:141], v[132:133] neg_lo:[0,1] neg_hi:[0,1]
	v_pk_add_f32 v[204:205], v[206:207], v[204:205] neg_lo:[0,1] neg_hi:[0,1]
	v_pk_add_f32 v[140:141], v[210:211], v[208:209]
	v_pk_add_f32 v[132:133], v[132:133], v[204:205]
	v_pk_add_f32 v[204:205], v[216:217], v[140:141]
	s_nop 0
	v_pk_add_f32 v[206:207], v[204:205], v[216:217] neg_lo:[0,1] neg_hi:[0,1]
	s_nop 0
	v_pk_add_f32 v[140:141], v[140:141], v[206:207] neg_lo:[0,1] neg_hi:[0,1]
	s_nop 0
	v_pk_add_f32 v[132:133], v[132:133], v[140:141]
	s_nop 0
	v_pk_add_f32 v[132:133], v[204:205], v[132:133]
	s_nop 0
	v_cndmask_b32_e64 v132, v231, v132, s[12:13]
	v_cmp_neq_f32_e64 s[12:13], s4, v179
	s_nop 1
	v_cndmask_b32_e64 v133, v231, v133, s[12:13]
	v_cmp_ngt_f32_e64 s[12:13], -1.0, v179
	s_nop 1
	v_cndmask_b32_e64 v133, v232, v133, s[12:13]
	v_cmp_ngt_f32_e64 s[12:13], -1.0, v173
	s_nop 1
	v_cndmask_b32_e64 v132, v232, v132, s[12:13]
	v_cmp_neq_f32_e64 s[12:13], -1.0, v173
	s_nop 1
	v_cndmask_b32_e64 v132, v233, v132, s[12:13]
	v_cmp_neq_f32_e64 s[12:13], -1.0, v179
	s_nop 1
	v_cndmask_b32_e64 v133, v233, v133, s[12:13]
	v_cmp_lt_f32_e64 s[12:13], |v173|, s5
	v_cndmask_b32_e64 v133, v133, v179, s[14:15]
	s_nop 0
	v_cndmask_b32_e64 v132, v132, v173, s[12:13]
	v_pk_add_f32 v[132:133], v[202:203], v[132:133] neg_lo:[0,1] neg_hi:[0,1]
	global_store_dwordx4 v[138:139], v[130:133], off nt
	s_and_saveexec_b64 s[12:13], vcc
	s_cbranch_execz .LBB0_384
	v_lshl_add_u64 v[140:141], v[136:137], 0, v[150:151]
	global_store_dwordx4 v[140:141], v[130:133], off nt
.LBB0_384:
	s_or_b64 exec, exec, s[12:13]
	global_load_dwordx4 v[130:133], v[158:159], off offset:16
	v_mov_b32_e32 v199, v198
	v_mov_b32_e32 v140, v198
	v_mov_b32_e32 v141, v198
	s_waitcnt vmcnt(0)
	v_pk_fma_f32 v[132:133], v[108:109], v[140:141], v[132:133]
	v_pk_fma_f32 v[140:141], v[106:107], v[198:199], v[130:131]
	s_nop 0
	v_mul_f32_e64 v131, |v140|, s34
	v_exp_f32_e32 v173, v131
	v_min_f32_e32 v130, 0, v140
	v_add_f32_e32 v131, 1.0, v173
	v_add_f32_e32 v140, -1.0, v131
	v_sub_f32_e32 v179, v140, v131
	v_add_f32_e32 v179, 1.0, v179
	v_sub_f32_e32 v140, v173, v140
	v_add_f32_e32 v179, v140, v179
	v_frexp_mant_f32_e32 v140, v131
	v_cvt_f64_f32_e32 v[202:203], v131
	v_cmp_gt_f32_e64 s[12:13], s35, v140
	v_frexp_exp_i32_f64_e32 v140, v[202:203]
	s_nop 0
	v_subbrev_co_u32_e64 v183, s[12:13], 0, v140, s[12:13]
	v_sub_u32_e32 v187, 0, v183
	v_ldexp_f32 v140, v131, v187
	v_min_f32_e32 v131, 0, v141
	v_mul_f32_e64 v141, |v141|, s34
	v_ldexp_f32 v202, v179, v187
	v_exp_f32_e32 v179, v141
	s_nop 0
	v_add_f32_e32 v141, 1.0, v179
	v_add_f32_e32 v187, -1.0, v141
	v_sub_f32_e32 v191, v187, v141
	v_add_f32_e32 v191, 1.0, v191
	v_sub_f32_e32 v187, v179, v187
	v_add_f32_e32 v191, v187, v191
	v_frexp_mant_f32_e32 v187, v141
	v_cvt_f64_f32_e32 v[204:205], v141
	v_cmp_gt_f32_e64 s[12:13], s35, v187
	v_frexp_exp_i32_f64_e32 v187, v[204:205]
	v_cmp_lt_f32_e64 s[14:15], |v179|, s5
	v_subbrev_co_u32_e64 v187, s[12:13], 0, v187, s[12:13]
	v_sub_u32_e32 v195, 0, v187
	v_ldexp_f32 v141, v141, v195
	v_pk_add_f32 v[204:205], v[140:141], 1.0 op_sel_hi:[1,0]
	v_ldexp_f32 v203, v191, v195
	v_pk_add_f32 v[206:207], v[204:205], -1.0 op_sel_hi:[1,0]
	v_pk_add_f32 v[212:213], v[140:141], -1.0 op_sel_hi:[1,0]
	v_pk_add_f32 v[206:207], v[140:141], v[206:207] neg_lo:[0,1] neg_hi:[0,1]
	v_pk_add_f32 v[214:215], v[212:213], 1.0 op_sel_hi:[1,0]
	v_pk_add_f32 v[206:207], v[202:203], v[206:207]
	v_pk_add_f32 v[140:141], v[140:141], v[214:215] neg_lo:[0,1] neg_hi:[0,1]
	v_pk_add_f32 v[208:209], v[204:205], v[206:207]
	v_pk_add_f32 v[140:141], v[202:203], v[140:141]
	v_rcp_f32_e32 v210, v208
	v_rcp_f32_e32 v211, v209
	v_pk_add_f32 v[202:203], v[212:213], v[140:141]
	v_pk_add_f32 v[204:205], v[208:209], v[204:205] neg_lo:[0,1] neg_hi:[0,1]
	v_pk_add_f32 v[212:213], v[202:203], v[212:213] neg_lo:[0,1] neg_hi:[0,1]
	v_pk_add_f32 v[204:205], v[206:207], v[204:205] neg_lo:[0,1] neg_hi:[0,1]
	v_pk_mul_f32 v[206:207], v[202:203], v[210:211]
	v_pk_add_f32 v[140:141], v[140:141], v[212:213] neg_lo:[0,1] neg_hi:[0,1]
	v_pk_mul_f32 v[212:213], v[208:209], v[206:207]
	v_cmp_neq_f32_e64 s[12:13], s4, v173
	v_pk_fma_f32 v[214:215], v[206:207], v[208:209], v[212:213] neg_lo:[0,0,1] neg_hi:[0,0,1]
	s_nop 0
	v_pk_fma_f32 v[214:215], v[206:207], v[204:205], v[214:215]
	s_nop 0
	v_pk_add_f32 v[216:217], v[212:213], v[214:215]
	s_nop 0
	v_pk_add_f32 v[218:219], v[202:203], v[216:217] neg_lo:[0,1] neg_hi:[0,1]
	v_pk_add_f32 v[212:213], v[216:217], v[212:213] neg_lo:[0,1] neg_hi:[0,1]
	v_pk_add_f32 v[202:203], v[202:203], v[218:219] neg_lo:[0,1] neg_hi:[0,1]
	s_nop 0
	v_pk_add_f32 v[202:203], v[202:203], v[216:217] neg_lo:[0,1] neg_hi:[0,1]
	s_nop 0
	v_pk_add_f32 v[140:141], v[140:141], v[202:203]
	v_pk_add_f32 v[202:203], v[212:213], v[214:215] neg_lo:[0,1] neg_hi:[0,1]
	s_nop 0
	v_pk_add_f32 v[140:141], v[202:203], v[140:141]
	s_nop 0
	v_pk_add_f32 v[202:203], v[218:219], v[140:141]
	s_nop 0
	v_pk_mul_f32 v[212:213], v[210:211], v[202:203]
	s_nop 0
	v_pk_mul_f32 v[214:215], v[208:209], v[212:213]
	s_nop 0
	v_pk_fma_f32 v[208:209], v[212:213], v[208:209], v[214:215] neg_lo:[0,0,1] neg_hi:[0,0,1]
	s_nop 0
	v_pk_fma_f32 v[204:205], v[212:213], v[204:205], v[208:209]
	v_pk_add_f32 v[208:209], v[218:219], v[202:203] neg_lo:[0,1] neg_hi:[0,1]
	s_nop 0
	v_pk_add_f32 v[140:141], v[140:141], v[208:209]
	v_pk_add_f32 v[208:209], v[214:215], v[204:205]
	s_nop 0
	v_pk_add_f32 v[216:217], v[202:203], v[208:209] neg_lo:[0,1] neg_hi:[0,1]
; __device__ __forceinline__ float log_sigmoid_f(float x) { return fminf(x, 0.f) - log1pf(__expf(-fabsf(x))); }
;     __device__ __forceinline__ void operator()(const f32x4 (&acc)[2][2][4][2], const Unit& u, int wr, int wc, int fr, int fq) const {
;     ...
;                         for (int n = 0; n < 2; ++n) { const int c = 8 * fq + 4 * n; const f32x4 bv = *(const f32x4*)(b_f + c); const f32x4 x = acc[ai][0][m][n] * s + bv; f32x4 lf;
;                             lf[0] = log_sigmoid_f(x[0]); lf[1] = log_sigmoid_f(x[1]); lf[2] = log_sigmoid_f(x[2]); lf[3] = log_sigmoid_f(x[3]);
	v_pk_add_f32 v[214:215], v[208:209], v[214:215] neg_lo:[0,1] neg_hi:[0,1]
	v_pk_add_f32 v[202:203], v[202:203], v[216:217] neg_lo:[0,1] neg_hi:[0,1]
	s_nop 0
	v_pk_add_f32 v[202:203], v[202:203], v[208:209] neg_lo:[0,1] neg_hi:[0,1]
	s_nop 0
	v_pk_add_f32 v[140:141], v[140:141], v[202:203]
	v_pk_add_f32 v[202:203], v[214:215], v[204:205] neg_lo:[0,1] neg_hi:[0,1]
	s_nop 0
	v_pk_add_f32 v[140:141], v[202:203], v[140:141]
	v_pk_add_f32 v[202:203], v[206:207], v[212:213]
	v_pk_add_f32 v[140:141], v[216:217], v[140:141]
	v_pk_add_f32 v[204:205], v[202:203], v[206:207] neg_lo:[0,1] neg_hi:[0,1]
	v_pk_mul_f32 v[140:141], v[210:211], v[140:141]
	v_pk_add_f32 v[204:205], v[212:213], v[204:205] neg_lo:[0,1] neg_hi:[0,1]
	v_cvt_f32_i32_e32 v213, v187
	v_pk_add_f32 v[140:141], v[204:205], v[140:141]
	v_cvt_f32_i32_e32 v212, v183
	v_pk_add_f32 v[206:207], v[202:203], v[140:141]
	s_nop 0
	v_pk_add_f32 v[202:203], v[206:207], v[202:203] neg_lo:[0,1] neg_hi:[0,1]
	v_pk_mul_f32 v[208:209], v[206:207], v[206:207]
	v_pk_add_f32 v[202:203], v[140:141], v[202:203] neg_lo:[0,1] neg_hi:[0,1]
	v_mov_b64_e32 v[140:141], s[50:51]
	v_pk_fma_f32 v[210:211], v[208:209], s[52:53], v[140:141] op_sel_hi:[1,0,0]
	v_ldexp_f32 v204, v206, 1
	v_pk_fma_f32 v[210:211], v[208:209], v[210:211], s[54:55] op_sel_hi:[1,1,0]
	v_ldexp_f32 v205, v207, 1
	v_pk_mul_f32 v[206:207], v[206:207], v[208:209]
	v_ldexp_f32 v215, v203, 1
	v_pk_mul_f32 v[216:217], v[206:207], v[210:211]
	v_pk_mul_f32 v[208:209], v[212:213], s[64:65] op_sel_hi:[1,0]
	v_pk_add_f32 v[206:207], v[204:205], v[216:217]
	v_ldexp_f32 v202, v202, 1
	v_pk_add_f32 v[204:205], v[206:207], v[204:205] neg_lo:[0,1] neg_hi:[0,1]
	v_pk_fma_f32 v[210:211], v[212:213], s[64:65], v[208:209] op_sel_hi:[1,0,1] neg_lo:[0,0,1] neg_hi:[0,0,1]
	v_pk_add_f32 v[218:219], v[216:217], v[204:205] neg_lo:[0,1] neg_hi:[0,1]
	v_mov_b32_e32 v203, v215
	v_pk_fma_f32 v[210:211], v[212:213], s[66:67], v[210:211] op_sel_hi:[1,0,1]
	v_pk_add_f32 v[216:217], v[202:203], v[218:219]
	v_mov_b32_e32 v204, v208
	v_mov_b32_e32 v205, v219
	v_mov_b32_e32 v214, v210
	v_mov_b32_e32 v203, v217
	v_mov_b32_e32 v219, v207
	v_pk_add_f32 v[212:213], v[208:209], v[210:211]
	v_pk_add_f32 v[204:205], v[204:205], v[214:215]
	v_pk_add_f32 v[214:215], v[202:203], v[218:219]
	v_pk_add_f32 v[218:219], v[206:207], v[216:217]
	v_mov_b32_e32 v226, v206
	v_pk_add_f32 v[202:203], v[212:213], v[218:219]
	v_mov_b32_e32 v224, v218
	v_mov_b32_e32 v225, v203
	v_mov_b32_e32 v227, v213
	v_pk_add_f32 v[224:225], v[224:225], v[226:227] neg_lo:[0,1] neg_hi:[0,1]
	v_mov_b32_e32 v220, v202
	v_mov_b32_e32 v221, v213
	v_mov_b32_e32 v222, v212
	v_mov_b32_e32 v223, v209
	v_mov_b32_e32 v226, v212
	v_mov_b32_e32 v227, v203
	v_mov_b32_e32 v209, v225
	v_pk_add_f32 v[220:221], v[220:221], v[222:223] neg_lo:[0,1] neg_hi:[0,1]
	v_mov_b32_e32 v222, v218
	v_mov_b32_e32 v223, v211
	v_pk_add_f32 v[208:209], v[226:227], v[208:209] neg_lo:[0,1] neg_hi:[0,1]
	v_pk_add_f32 v[222:223], v[222:223], v[220:221] neg_lo:[0,1] neg_hi:[0,1]
	v_mov_b32_e32 v226, v208
	v_mov_b32_e32 v227, v221
	v_mov_b32_e32 v236, v202
	v_mov_b32_e32 v237, v219
	v_mov_b32_e32 v221, v207
	v_pk_add_f32 v[226:227], v[210:211], v[226:227] neg_lo:[0,1] neg_hi:[0,1]
	v_pk_add_f32 v[220:221], v[236:237], v[220:221] neg_lo:[0,1] neg_hi:[0,1]
	v_mov_b32_e32 v211, v213
	v_pk_add_f32 v[204:205], v[204:205], v[220:221] neg_lo:[0,1] neg_hi:[0,1]
	v_pk_add_f32 v[208:209], v[210:211], v[208:209] neg_lo:[0,1] neg_hi:[0,1]
	v_pk_add_f32 v[210:211], v[214:215], v[224:225] neg_lo:[0,1] neg_hi:[0,1]
	v_pk_add_f32 v[214:215], v[222:223], v[204:205]
	v_pk_add_f32 v[212:213], v[210:211], v[208:209]
	v_mov_b32_e32 v209, v223
	v_mov_b32_e32 v211, v205
	v_pk_add_f32 v[204:205], v[208:209], v[210:211]
	v_pk_add_f32 v[206:207], v[218:219], v[206:207] neg_lo:[0,1] neg_hi:[0,1]
	v_pk_add_f32 v[204:205], v[204:205], v[226:227] neg_lo:[0,1] neg_hi:[0,1]
	v_mov_b32_e32 v210, v212
	v_mov_b32_e32 v211, v215
	v_pk_add_f32 v[206:207], v[216:217], v[206:207] neg_lo:[0,1] neg_hi:[0,1]
	v_pk_add_f32 v[210:211], v[210:211], v[204:205] neg_lo:[0,1] neg_hi:[0,1]
	v_pk_add_f32 v[204:205], v[206:207], v[204:205] neg_lo:[0,1] neg_hi:[0,1]
	v_pk_add_f32 v[208:209], v[208:209], v[210:211] neg_lo:[0,1] neg_hi:[0,1]
	v_pk_add_f32 v[206:207], v[214:215], v[212:213]
	v_pk_add_f32 v[204:205], v[204:205], v[208:209]
	v_pk_add_f32 v[208:209], v[202:203], v[206:207]
	s_nop 0
	v_pk_add_f32 v[202:203], v[208:209], v[202:203] neg_lo:[0,1] neg_hi:[0,1]
	s_nop 0
	v_pk_add_f32 v[202:203], v[206:207], v[202:203] neg_lo:[0,1] neg_hi:[0,1]
	s_nop 0
	v_pk_add_f32 v[202:203], v[204:205], v[202:203]
	s_nop 0
	v_pk_add_f32 v[202:203], v[208:209], v[202:203]
	s_nop 0
	v_cndmask_b32_e64 v183, v231, v202, s[12:13]
	v_cmp_neq_f32_e64 s[12:13], s4, v179
	s_nop 1
	v_cndmask_b32_e64 v187, v231, v203, s[12:13]
	v_cmp_ngt_f32_e64 s[12:13], -1.0, v179
	s_nop 1
	v_cndmask_b32_e64 v187, v232, v187, s[12:13]
	v_cmp_ngt_f32_e64 s[12:13], -1.0, v173
	s_nop 1
	v_cndmask_b32_e64 v183, v232, v183, s[12:13]
	v_cmp_neq_f32_e64 s[12:13], -1.0, v173
	s_nop 1
	v_cndmask_b32_e64 v183, v233, v183, s[12:13]
	v_cmp_neq_f32_e64 s[12:13], -1.0, v179
	s_nop 1
	v_cndmask_b32_e64 v187, v233, v187, s[12:13]
	v_cmp_lt_f32_e64 s[12:13], |v173|, s5
	v_cndmask_b32_e64 v203, v187, v179, s[14:15]
	s_nop 0
	v_cndmask_b32_e64 v202, v183, v173, s[12:13]
	v_pk_add_f32 v[130:131], v[130:131], v[202:203] neg_lo:[0,1] neg_hi:[0,1]
	v_min_f32_e32 v202, 0, v132
	v_mul_f32_e64 v132, |v132|, s34
	v_exp_f32_e32 v173, v132
	v_min_f32_e32 v203, 0, v133
	v_mul_f32_e64 v133, |v133|, s34
	v_add_f32_e32 v132, 1.0, v173
	v_add_f32_e32 v179, -1.0, v132
; __device__ __forceinline__ float log_sigmoid_f(float x) { return fminf(x, 0.f) - log1pf(__expf(-fabsf(x))); }
;     __device__ __forceinline__ void operator()(const f32x4 (&acc)[2][2][4][2], const Unit& u, int wr, int wc, int fr, int fq) const {
;     ...
;                         for (int n = 0; n < 2; ++n) { const int c = 8 * fq + 4 * n; const f32x4 bv = *(const f32x4*)(b_f + c); const f32x4 x = acc[ai][0][m][n] * s + bv; f32x4 lf;
;                             lf[0] = log_sigmoid_f(x[0]); lf[1] = log_sigmoid_f(x[1]); lf[2] = log_sigmoid_f(x[2]); lf[3] = log_sigmoid_f(x[3]);
	v_sub_f32_e32 v183, v179, v132
	v_add_f32_e32 v183, 1.0, v183
	v_sub_f32_e32 v179, v173, v179
	v_add_f32_e32 v179, v179, v183
	v_frexp_mant_f32_e32 v183, v132
	v_cvt_f64_f32_e32 v[204:205], v132
	v_cmp_gt_f32_e64 s[12:13], s35, v183
	v_frexp_exp_i32_f64_e32 v183, v[204:205]
	s_nop 0
	v_subbrev_co_u32_e64 v183, s[12:13], 0, v183, s[12:13]
	v_sub_u32_e32 v187, 0, v183
	v_ldexp_f32 v204, v179, v187
	v_exp_f32_e32 v179, v133
	v_ldexp_f32 v132, v132, v187
	v_add_f32_e32 v133, 1.0, v179
	v_add_f32_e32 v187, -1.0, v133
	v_sub_f32_e32 v191, v187, v133
	v_add_f32_e32 v191, 1.0, v191
	v_sub_f32_e32 v187, v179, v187
	v_add_f32_e32 v187, v187, v191
	v_frexp_mant_f32_e32 v191, v133
	v_cvt_f64_f32_e32 v[206:207], v133
	v_cmp_gt_f32_e64 s[12:13], s35, v191
	v_frexp_exp_i32_f64_e32 v191, v[206:207]
	v_cmp_lt_f32_e64 s[14:15], |v179|, s5
	v_subbrev_co_u32_e64 v191, s[12:13], 0, v191, s[12:13]
	v_sub_u32_e32 v195, 0, v191
	v_ldexp_f32 v133, v133, v195
	v_pk_add_f32 v[206:207], v[132:133], 1.0 op_sel_hi:[1,0]
	v_ldexp_f32 v205, v187, v195
	v_pk_add_f32 v[208:209], v[206:207], -1.0 op_sel_hi:[1,0]
	v_pk_add_f32 v[214:215], v[132:133], -1.0 op_sel_hi:[1,0]
	v_pk_add_f32 v[208:209], v[132:133], v[208:209] neg_lo:[0,1] neg_hi:[0,1]
	v_pk_add_f32 v[216:217], v[214:215], 1.0 op_sel_hi:[1,0]
	v_pk_add_f32 v[208:209], v[204:205], v[208:209]
	v_pk_add_f32 v[132:133], v[132:133], v[216:217] neg_lo:[0,1] neg_hi:[0,1]
	v_pk_add_f32 v[210:211], v[206:207], v[208:209]
	v_pk_add_f32 v[132:133], v[204:205], v[132:133]
	v_rcp_f32_e32 v212, v210
	v_rcp_f32_e32 v213, v211
	v_pk_add_f32 v[204:205], v[214:215], v[132:133]
	v_pk_add_f32 v[206:207], v[210:211], v[206:207] neg_lo:[0,1] neg_hi:[0,1]
	v_pk_add_f32 v[214:215], v[204:205], v[214:215] neg_lo:[0,1] neg_hi:[0,1]
	v_pk_add_f32 v[206:207], v[208:209], v[206:207] neg_lo:[0,1] neg_hi:[0,1]
	v_pk_mul_f32 v[208:209], v[204:205], v[212:213]
	v_pk_add_f32 v[132:133], v[132:133], v[214:215] neg_lo:[0,1] neg_hi:[0,1]
	v_pk_mul_f32 v[214:215], v[210:211], v[208:209]
	v_cmp_neq_f32_e64 s[12:13], s4, v173
	v_pk_fma_f32 v[216:217], v[208:209], v[210:211], v[214:215] neg_lo:[0,0,1] neg_hi:[0,0,1]
	s_nop 0
	v_pk_fma_f32 v[216:217], v[208:209], v[206:207], v[216:217]
	s_nop 0
	v_pk_add_f32 v[218:219], v[214:215], v[216:217]
	s_nop 0
	v_pk_add_f32 v[220:221], v[204:205], v[218:219] neg_lo:[0,1] neg_hi:[0,1]
	v_pk_add_f32 v[214:215], v[218:219], v[214:215] neg_lo:[0,1] neg_hi:[0,1]
	v_pk_add_f32 v[204:205], v[204:205], v[220:221] neg_lo:[0,1] neg_hi:[0,1]
	s_nop 0
	v_pk_add_f32 v[204:205], v[204:205], v[218:219] neg_lo:[0,1] neg_hi:[0,1]
	s_nop 0
	v_pk_add_f32 v[132:133], v[132:133], v[204:205]
	v_pk_add_f32 v[204:205], v[214:215], v[216:217] neg_lo:[0,1] neg_hi:[0,1]
	s_nop 0
	v_pk_add_f32 v[132:133], v[204:205], v[132:133]
	s_nop 0
	v_pk_add_f32 v[204:205], v[220:221], v[132:133]
	s_nop 0
	v_pk_mul_f32 v[214:215], v[212:213], v[204:205]
	s_nop 0
	v_pk_mul_f32 v[216:217], v[210:211], v[214:215]
	s_nop 0
	v_pk_fma_f32 v[210:211], v[214:215], v[210:211], v[216:217] neg_lo:[0,0,1] neg_hi:[0,0,1]
	s_nop 0
	v_pk_fma_f32 v[206:207], v[214:215], v[206:207], v[210:211]
	v_pk_add_f32 v[210:211], v[220:221], v[204:205] neg_lo:[0,1] neg_hi:[0,1]
	s_nop 0
	v_pk_add_f32 v[132:133], v[132:133], v[210:211]
	v_pk_add_f32 v[210:211], v[216:217], v[206:207]
	s_nop 0
	v_pk_add_f32 v[218:219], v[204:205], v[210:211] neg_lo:[0,1] neg_hi:[0,1]
	v_pk_add_f32 v[216:217], v[210:211], v[216:217] neg_lo:[0,1] neg_hi:[0,1]
	v_pk_add_f32 v[204:205], v[204:205], v[218:219] neg_lo:[0,1] neg_hi:[0,1]
	s_nop 0
	v_pk_add_f32 v[204:205], v[204:205], v[210:211] neg_lo:[0,1] neg_hi:[0,1]
	s_nop 0
	v_pk_add_f32 v[132:133], v[132:133], v[204:205]
	v_pk_add_f32 v[204:205], v[216:217], v[206:207] neg_lo:[0,1] neg_hi:[0,1]
	s_nop 0
	v_pk_add_f32 v[132:133], v[204:205], v[132:133]
	v_pk_add_f32 v[204:205], v[208:209], v[214:215]
	v_pk_add_f32 v[132:133], v[218:219], v[132:133]
	v_pk_add_f32 v[206:207], v[204:205], v[208:209] neg_lo:[0,1] neg_hi:[0,1]
	v_pk_mul_f32 v[132:133], v[212:213], v[132:133]
	v_pk_add_f32 v[206:207], v[214:215], v[206:207] neg_lo:[0,1] neg_hi:[0,1]
	s_nop 0
	v_pk_add_f32 v[132:133], v[206:207], v[132:133]
	s_nop 0
	v_pk_add_f32 v[206:207], v[204:205], v[132:133]
	s_nop 0
	v_pk_mul_f32 v[208:209], v[206:207], v[206:207]
	v_pk_add_f32 v[204:205], v[206:207], v[204:205] neg_lo:[0,1] neg_hi:[0,1]
	v_pk_fma_f32 v[140:141], v[208:209], s[52:53], v[140:141] op_sel_hi:[1,0,0]
	v_pk_add_f32 v[132:133], v[132:133], v[204:205] neg_lo:[0,1] neg_hi:[0,1]
; __device__ __forceinline__ float log_sigmoid_f(float x) { return fminf(x, 0.f) - log1pf(__expf(-fabsf(x))); }
;     __device__ __forceinline__ void operator()(const f32x4 (&acc)[2][2][4][2], const Unit& u, int wr, int wc, int fr, int fq) const {
;     ...
;                         for (int n = 0; n < 2; ++n) { const int c = 8 * fq + 4 * n; const f32x4 bv = *(const f32x4*)(b_f + c); const f32x4 x = acc[ai][0][m][n] * s + bv; f32x4 lf;
;                             lf[0] = log_sigmoid_f(x[0]); lf[1] = log_sigmoid_f(x[1]); lf[2] = log_sigmoid_f(x[2]); lf[3] = log_sigmoid_f(x[3]);
;                             *(f32x4*)(LF + (size_t)row * 16 + c) = lf; if (dst) *(f32x4*)(dst + c) = lf; } }
	v_ldexp_f32 v204, v206, 1
	v_pk_fma_f32 v[140:141], v[208:209], v[140:141], s[54:55] op_sel_hi:[1,1,0]
	v_ldexp_f32 v205, v207, 1
	v_pk_mul_f32 v[206:207], v[206:207], v[208:209]
	v_cvt_f32_i32_e32 v209, v191
	v_cvt_f32_i32_e32 v208, v183
	v_pk_mul_f32 v[140:141], v[206:207], v[140:141]
	v_ldexp_f32 v211, v133, 1
	v_pk_add_f32 v[206:207], v[204:205], v[140:141]
	v_pk_mul_f32 v[212:213], v[208:209], s[64:65] op_sel_hi:[1,0]
	v_pk_add_f32 v[204:205], v[206:207], v[204:205] neg_lo:[0,1] neg_hi:[0,1]
	v_pk_fma_f32 v[214:215], v[208:209], s[64:65], v[212:213] op_sel_hi:[1,0,1] neg_lo:[0,0,1] neg_hi:[0,0,1]
	v_pk_add_f32 v[140:141], v[140:141], v[204:205] neg_lo:[0,1] neg_hi:[0,1]
	v_pk_fma_f32 v[208:209], v[208:209], s[66:67], v[214:215] op_sel_hi:[1,0,1]
	v_ldexp_f32 v132, v132, 1
	v_mov_b32_e32 v204, v212
	v_mov_b32_e32 v205, v141
	v_mov_b32_e32 v210, v208
	v_mov_b32_e32 v133, v211
	v_pk_add_f32 v[204:205], v[204:205], v[210:211]
	v_pk_add_f32 v[210:211], v[132:133], v[140:141]
	v_mov_b32_e32 v141, v207
	v_mov_b32_e32 v133, v211
	v_pk_add_f32 v[214:215], v[212:213], v[208:209]
	v_pk_add_f32 v[132:133], v[132:133], v[140:141]
	v_pk_add_f32 v[140:141], v[206:207], v[210:211]
	v_mov_b32_e32 v224, v206
	v_pk_add_f32 v[216:217], v[214:215], v[140:141]
	v_mov_b32_e32 v222, v140
	v_mov_b32_e32 v223, v217
	v_mov_b32_e32 v225, v215
	v_pk_add_f32 v[222:223], v[222:223], v[224:225] neg_lo:[0,1] neg_hi:[0,1]
	v_mov_b32_e32 v218, v216
	v_mov_b32_e32 v219, v215
	v_mov_b32_e32 v220, v214
	v_mov_b32_e32 v221, v213
	v_mov_b32_e32 v224, v214
	v_mov_b32_e32 v225, v217
	v_mov_b32_e32 v213, v223
	v_pk_add_f32 v[218:219], v[218:219], v[220:221] neg_lo:[0,1] neg_hi:[0,1]
	v_mov_b32_e32 v220, v140
	v_mov_b32_e32 v221, v209
	v_pk_add_f32 v[212:213], v[224:225], v[212:213] neg_lo:[0,1] neg_hi:[0,1]
	v_pk_add_f32 v[220:221], v[220:221], v[218:219] neg_lo:[0,1] neg_hi:[0,1]
	v_mov_b32_e32 v224, v212
	v_mov_b32_e32 v225, v219
	v_mov_b32_e32 v226, v216
	v_mov_b32_e32 v227, v141
	v_mov_b32_e32 v219, v207
	v_pk_add_f32 v[224:225], v[208:209], v[224:225] neg_lo:[0,1] neg_hi:[0,1]
	v_pk_add_f32 v[218:219], v[226:227], v[218:219] neg_lo:[0,1] neg_hi:[0,1]
	v_mov_b32_e32 v209, v215
	v_pk_add_f32 v[140:141], v[140:141], v[206:207] neg_lo:[0,1] neg_hi:[0,1]
	v_pk_add_f32 v[204:205], v[204:205], v[218:219] neg_lo:[0,1] neg_hi:[0,1]
	v_pk_add_f32 v[206:207], v[208:209], v[212:213] neg_lo:[0,1] neg_hi:[0,1]
	v_pk_add_f32 v[132:133], v[132:133], v[222:223] neg_lo:[0,1] neg_hi:[0,1]
	v_pk_add_f32 v[140:141], v[210:211], v[140:141] neg_lo:[0,1] neg_hi:[0,1]
	v_pk_add_f32 v[208:209], v[132:133], v[206:207]
	v_mov_b32_e32 v207, v221
	v_mov_b32_e32 v133, v205
	v_pk_add_f32 v[210:211], v[220:221], v[204:205]
	v_pk_add_f32 v[132:133], v[206:207], v[132:133]
	v_mov_b32_e32 v204, v208
	v_pk_add_f32 v[132:133], v[132:133], v[224:225] neg_lo:[0,1] neg_hi:[0,1]
	v_mov_b32_e32 v205, v211
	v_pk_add_f32 v[204:205], v[204:205], v[132:133] neg_lo:[0,1] neg_hi:[0,1]
	v_pk_add_f32 v[132:133], v[140:141], v[132:133] neg_lo:[0,1] neg_hi:[0,1]
	v_pk_add_f32 v[204:205], v[206:207], v[204:205] neg_lo:[0,1] neg_hi:[0,1]
	v_pk_add_f32 v[140:141], v[210:211], v[208:209]
	v_pk_add_f32 v[132:133], v[132:133], v[204:205]
	v_pk_add_f32 v[204:205], v[216:217], v[140:141]
	s_nop 0
	v_pk_add_f32 v[206:207], v[204:205], v[216:217] neg_lo:[0,1] neg_hi:[0,1]
	s_nop 0
	v_pk_add_f32 v[140:141], v[140:141], v[206:207] neg_lo:[0,1] neg_hi:[0,1]
	s_nop 0
	v_pk_add_f32 v[132:133], v[132:133], v[140:141]
	s_nop 0
	v_pk_add_f32 v[132:133], v[204:205], v[132:133]
	s_nop 0
	v_cndmask_b32_e64 v132, v231, v132, s[12:13]
	v_cmp_neq_f32_e64 s[12:13], s4, v179
	s_nop 1
	v_cndmask_b32_e64 v133, v231, v133, s[12:13]
	v_cmp_ngt_f32_e64 s[12:13], -1.0, v179
	s_nop 1
	v_cndmask_b32_e64 v133, v232, v133, s[12:13]
	v_cmp_ngt_f32_e64 s[12:13], -1.0, v173
	s_nop 1
	v_cndmask_b32_e64 v132, v232, v132, s[12:13]
	v_cmp_neq_f32_e64 s[12:13], -1.0, v173
	s_nop 1
	v_cndmask_b32_e64 v132, v233, v132, s[12:13]
	v_cmp_neq_f32_e64 s[12:13], -1.0, v179
	s_nop 1
	v_cndmask_b32_e64 v133, v233, v133, s[12:13]
	v_cmp_lt_f32_e64 s[12:13], |v173|, s5
	v_cndmask_b32_e64 v133, v133, v179, s[14:15]
	s_nop 0
	v_cndmask_b32_e64 v132, v132, v173, s[12:13]
	v_pk_add_f32 v[132:133], v[202:203], v[132:133] neg_lo:[0,1] neg_hi:[0,1]
	global_store_dwordx4 v[138:139], v[130:133], off offset:16 nt
	s_and_saveexec_b64 s[12:13], vcc
	s_cbranch_execz .LBB0_386
	v_lshl_add_u64 v[136:137], v[136:137], 0, v[150:151]
	global_store_dwordx4 v[136:137], v[130:133], off offset:16 nt

; __device__ __forceinline__ float log_sigmoid_f(float x) { return fminf(x, 0.f) - log1pf(__expf(-fabsf(x))); }
;     __device__ __forceinline__ void operator()(const f32x4 (&acc)[2][2][4][2], const Unit& u, int wr, int wc, int fr, int fq) const {
;     ...
;                         if (pm == 0) dst = o_lfs + (size_t)row * 16; else { const int t = row - G_ROWP; if (t < G_TP) dst = o_lfp + (size_t)t * 16; }
; #pragma unroll
;                         for (int n = 0; n < 2; ++n) { const int c = 8 * fq + 4 * n; const f32x4 bv = *(const f32x4*)(b_f + c); const f32x4 x = acc[ai][0][m][n] * s + bv; f32x4 lf;
;                             lf[0] = log_sigmoid_f(x[0]); lf[1] = log_sigmoid_f(x[1]); lf[2] = log_sigmoid_f(x[2]); lf[3] = log_sigmoid_f(x[3]);
.LBB0_389:
	global_load_dwordx4 v[130:133], v[158:159], off
	v_cmp_ne_u64_e32 vcc, 0, v[136:137]
	v_lshl_add_u64 v[138:139], v[162:163], 0, v[138:139]
	s_waitcnt vmcnt(0)
	v_pk_fma_f32 v[140:141], v[94:95], v[194:195], v[130:131] op_sel_hi:[1,0,1]
	s_nop 0
	v_mul_f32_e64 v131, |v140|, s34
	v_exp_f32_e32 v173, v131
	v_min_f32_e32 v130, 0, v140
	v_pk_fma_f32 v[132:133], v[96:97], v[194:195], v[132:133] op_sel_hi:[1,0,1]
	v_add_f32_e32 v131, 1.0, v173
	v_add_f32_e32 v140, -1.0, v131
	v_sub_f32_e32 v179, v140, v131
	v_add_f32_e32 v179, 1.0, v179
	v_sub_f32_e32 v140, v173, v140
	v_add_f32_e32 v179, v140, v179
	v_frexp_mant_f32_e32 v140, v131
	v_cvt_f64_f32_e32 v[202:203], v131
	v_cmp_gt_f32_e64 s[12:13], s35, v140
	v_frexp_exp_i32_f64_e32 v140, v[202:203]
	s_nop 0
	v_subbrev_co_u32_e64 v183, s[12:13], 0, v140, s[12:13]
	v_sub_u32_e32 v187, 0, v183
	v_ldexp_f32 v140, v131, v187
	v_min_f32_e32 v131, 0, v141
	v_mul_f32_e64 v141, |v141|, s34
	v_ldexp_f32 v202, v179, v187
	v_exp_f32_e32 v179, v141
	s_nop 0
	v_add_f32_e32 v141, 1.0, v179
	v_add_f32_e32 v187, -1.0, v141
	v_sub_f32_e32 v191, v187, v141
	v_add_f32_e32 v191, 1.0, v191
	v_sub_f32_e32 v187, v179, v187
	v_add_f32_e32 v191, v187, v191
	v_frexp_mant_f32_e32 v187, v141
	v_cvt_f64_f32_e32 v[204:205], v141
	v_cmp_gt_f32_e64 s[12:13], s35, v187
	v_frexp_exp_i32_f64_e32 v187, v[204:205]
	v_cmp_lt_f32_e64 s[14:15], |v179|, s5
	v_subbrev_co_u32_e64 v187, s[12:13], 0, v187, s[12:13]
	v_sub_u32_e32 v195, 0, v187
	v_ldexp_f32 v141, v141, v195
	v_pk_add_f32 v[204:205], v[140:141], 1.0 op_sel_hi:[1,0]
	v_ldexp_f32 v203, v191, v195
	v_pk_add_f32 v[206:207], v[204:205], -1.0 op_sel_hi:[1,0]
	v_pk_add_f32 v[212:213], v[140:141], -1.0 op_sel_hi:[1,0]
	v_pk_add_f32 v[206:207], v[140:141], v[206:207] neg_lo:[0,1] neg_hi:[0,1]
	v_pk_add_f32 v[214:215], v[212:213], 1.0 op_sel_hi:[1,0]
	v_pk_add_f32 v[206:207], v[202:203], v[206:207]
	v_pk_add_f32 v[140:141], v[140:141], v[214:215] neg_lo:[0,1] neg_hi:[0,1]
	v_pk_add_f32 v[208:209], v[204:205], v[206:207]
	v_pk_add_f32 v[140:141], v[202:203], v[140:141]
	v_rcp_f32_e32 v210, v208
	v_rcp_f32_e32 v211, v209
	v_pk_add_f32 v[202:203], v[212:213], v[140:141]
	v_pk_add_f32 v[204:205], v[208:209], v[204:205] neg_lo:[0,1] neg_hi:[0,1]
	v_pk_add_f32 v[212:213], v[202:203], v[212:213] neg_lo:[0,1] neg_hi:[0,1]
	v_pk_add_f32 v[204:205], v[206:207], v[204:205] neg_lo:[0,1] neg_hi:[0,1]
	v_pk_mul_f32 v[206:207], v[202:203], v[210:211]
	v_pk_add_f32 v[140:141], v[140:141], v[212:213] neg_lo:[0,1] neg_hi:[0,1]
	v_pk_mul_f32 v[212:213], v[208:209], v[206:207]
	v_cmp_neq_f32_e64 s[12:13], s4, v173
	v_pk_fma_f32 v[214:215], v[206:207], v[208:209], v[212:213] neg_lo:[0,0,1] neg_hi:[0,0,1]
	s_nop 0
	v_pk_fma_f32 v[214:215], v[206:207], v[204:205], v[214:215]
	s_nop 0
	v_pk_add_f32 v[216:217], v[212:213], v[214:215]
	s_nop 0
	v_pk_add_f32 v[218:219], v[202:203], v[216:217] neg_lo:[0,1] neg_hi:[0,1]
	v_pk_add_f32 v[212:213], v[216:217], v[212:213] neg_lo:[0,1] neg_hi:[0,1]
	v_pk_add_f32 v[202:203], v[202:203], v[218:219] neg_lo:[0,1] neg_hi:[0,1]
	s_nop 0
	v_pk_add_f32 v[202:203], v[202:203], v[216:217] neg_lo:[0,1] neg_hi:[0,1]
	s_nop 0
	v_pk_add_f32 v[140:141], v[140:141], v[202:203]
	v_pk_add_f32 v[202:203], v[212:213], v[214:215] neg_lo:[0,1] neg_hi:[0,1]
	s_nop 0
	v_pk_add_f32 v[140:141], v[202:203], v[140:141]
	s_nop 0
	v_pk_add_f32 v[202:203], v[218:219], v[140:141]
	s_nop 0
	v_pk_mul_f32 v[212:213], v[210:211], v[202:203]
	s_nop 0
	v_pk_mul_f32 v[214:215], v[208:209], v[212:213]
	s_nop 0
	v_pk_fma_f32 v[208:209], v[212:213], v[208:209], v[214:215] neg_lo:[0,0,1] neg_hi:[0,0,1]
	s_nop 0
	v_pk_fma_f32 v[204:205], v[212:213], v[204:205], v[208:209]
	v_pk_add_f32 v[208:209], v[218:219], v[202:203] neg_lo:[0,1] neg_hi:[0,1]
	s_nop 0
	v_pk_add_f32 v[140:141], v[140:141], v[208:209]
	v_pk_add_f32 v[208:209], v[214:215], v[204:205]
	s_nop 0
	v_pk_add_f32 v[216:217], v[202:203], v[208:209] neg_lo:[0,1] neg_hi:[0,1]
	v_pk_add_f32 v[214:215], v[208:209], v[214:215] neg_lo:[0,1] neg_hi:[0,1]
	v_pk_add_f32 v[202:203], v[202:203], v[216:217] neg_lo:[0,1] neg_hi:[0,1]
	s_nop 0
	v_pk_add_f32 v[202:203], v[202:203], v[208:209] neg_lo:[0,1] neg_hi:[0,1]
	s_nop 0
	v_pk_add_f32 v[140:141], v[140:141], v[202:203]
	v_pk_add_f32 v[202:203], v[214:215], v[204:205] neg_lo:[0,1] neg_hi:[0,1]
	s_nop 0
	v_pk_add_f32 v[140:141], v[202:203], v[140:141]
	v_pk_add_f32 v[202:203], v[206:207], v[212:213]
	v_pk_add_f32 v[140:141], v[216:217], v[140:141]
	v_pk_add_f32 v[204:205], v[202:203], v[206:207] neg_lo:[0,1] neg_hi:[0,1]
	v_pk_mul_f32 v[140:141], v[210:211], v[140:141]
	v_pk_add_f32 v[204:205], v[212:213], v[204:205] neg_lo:[0,1] neg_hi:[0,1]
	s_nop 0
	v_pk_add_f32 v[140:141], v[204:205], v[140:141]
	s_nop 0
	v_pk_add_f32 v[206:207], v[202:203], v[140:141]
	s_nop 0
	v_pk_add_f32 v[202:203], v[206:207], v[202:203] neg_lo:[0,1] neg_hi:[0,1]
	v_pk_mul_f32 v[208:209], v[206:207], v[206:207]
	v_pk_add_f32 v[202:203], v[140:141], v[202:203] neg_lo:[0,1] neg_hi:[0,1]
	v_mov_b64_e32 v[140:141], s[50:51]
	v_pk_fma_f32 v[210:211], v[208:209], s[52:53], v[140:141] op_sel_hi:[1,0,0]
	v_ldexp_f32 v204, v206, 1
	v_pk_fma_f32 v[210:211], v[208:209], v[210:211], s[54:55] op_sel_hi:[1,1,0]
	v_ldexp_f32 v205, v207, 1
	v_pk_mul_f32 v[206:207], v[206:207], v[208:209]
	v_cvt_f32_i32_e32 v209, v187
	v_cvt_f32_i32_e32 v208, v183
	v_pk_mul_f32 v[216:217], v[206:207], v[210:211]
	v_ldexp_f32 v215, v203, 1
	v_pk_add_f32 v[206:207], v[204:205], v[216:217]
	v_pk_mul_f32 v[212:213], v[208:209], s[64:65] op_sel_hi:[1,0]
	v_pk_add_f32 v[204:205], v[206:207], v[204:205] neg_lo:[0,1] neg_hi:[0,1]
	v_ldexp_f32 v202, v202, 1
; __device__ __forceinline__ float log_sigmoid_f(float x) { return fminf(x, 0.f) - log1pf(__expf(-fabsf(x))); }
;     __device__ __forceinline__ void operator()(const f32x4 (&acc)[2][2][4][2], const Unit& u, int wr, int wc, int fr, int fq) const {
;     ...
;                         for (int n = 0; n < 2; ++n) { const int c = 8 * fq + 4 * n; const f32x4 bv = *(const f32x4*)(b_f + c); const f32x4 x = acc[ai][0][m][n] * s + bv; f32x4 lf;
;                             lf[0] = log_sigmoid_f(x[0]); lf[1] = log_sigmoid_f(x[1]); lf[2] = log_sigmoid_f(x[2]); lf[3] = log_sigmoid_f(x[3]);
	v_pk_fma_f32 v[210:211], v[208:209], s[64:65], v[212:213] op_sel_hi:[1,0,1] neg_lo:[0,0,1] neg_hi:[0,0,1]
	v_pk_add_f32 v[218:219], v[216:217], v[204:205] neg_lo:[0,1] neg_hi:[0,1]
	v_mov_b32_e32 v203, v215
	v_pk_fma_f32 v[208:209], v[208:209], s[66:67], v[210:211] op_sel_hi:[1,0,1]
	v_pk_add_f32 v[216:217], v[202:203], v[218:219]
	v_mov_b32_e32 v204, v212
	v_mov_b32_e32 v205, v219
	v_mov_b32_e32 v214, v208
	v_mov_b32_e32 v203, v217
	v_mov_b32_e32 v219, v207
	v_pk_add_f32 v[210:211], v[212:213], v[208:209]
	v_pk_add_f32 v[204:205], v[204:205], v[214:215]
	v_pk_add_f32 v[214:215], v[202:203], v[218:219]
	v_pk_add_f32 v[218:219], v[206:207], v[216:217]
	v_mov_b32_e32 v226, v206
	v_pk_add_f32 v[202:203], v[210:211], v[218:219]
	v_mov_b32_e32 v224, v218
	v_mov_b32_e32 v225, v203
	v_mov_b32_e32 v227, v211
	v_pk_add_f32 v[224:225], v[224:225], v[226:227] neg_lo:[0,1] neg_hi:[0,1]
	v_mov_b32_e32 v220, v202
	v_mov_b32_e32 v221, v211
	v_mov_b32_e32 v222, v210
	v_mov_b32_e32 v223, v213
	v_mov_b32_e32 v226, v210
	v_mov_b32_e32 v227, v203
	v_mov_b32_e32 v213, v225
	v_pk_add_f32 v[220:221], v[220:221], v[222:223] neg_lo:[0,1] neg_hi:[0,1]
	v_mov_b32_e32 v222, v218
	v_mov_b32_e32 v223, v209
	v_pk_add_f32 v[212:213], v[226:227], v[212:213] neg_lo:[0,1] neg_hi:[0,1]
	v_pk_add_f32 v[222:223], v[222:223], v[220:221] neg_lo:[0,1] neg_hi:[0,1]
	v_mov_b32_e32 v226, v212
	v_mov_b32_e32 v227, v221
	v_mov_b32_e32 v236, v202
	v_mov_b32_e32 v237, v219
	v_mov_b32_e32 v221, v207
	v_pk_add_f32 v[226:227], v[208:209], v[226:227] neg_lo:[0,1] neg_hi:[0,1]
	v_pk_add_f32 v[220:221], v[236:237], v[220:221] neg_lo:[0,1] neg_hi:[0,1]
	v_mov_b32_e32 v209, v211
	v_pk_add_f32 v[204:205], v[204:205], v[220:221] neg_lo:[0,1] neg_hi:[0,1]
	v_pk_add_f32 v[208:209], v[208:209], v[212:213] neg_lo:[0,1] neg_hi:[0,1]
	v_pk_add_f32 v[210:211], v[214:215], v[224:225] neg_lo:[0,1] neg_hi:[0,1]
	v_pk_add_f32 v[214:215], v[222:223], v[204:205]
	v_pk_add_f32 v[212:213], v[210:211], v[208:209]
	v_mov_b32_e32 v209, v223
	v_mov_b32_e32 v211, v205
	v_pk_add_f32 v[204:205], v[208:209], v[210:211]
	v_pk_add_f32 v[206:207], v[218:219], v[206:207] neg_lo:[0,1] neg_hi:[0,1]
	v_pk_add_f32 v[204:205], v[204:205], v[226:227] neg_lo:[0,1] neg_hi:[0,1]
	v_mov_b32_e32 v210, v212
	v_mov_b32_e32 v211, v215
	v_pk_add_f32 v[206:207], v[216:217], v[206:207] neg_lo:[0,1] neg_hi:[0,1]
	v_pk_add_f32 v[210:211], v[210:211], v[204:205] neg_lo:[0,1] neg_hi:[0,1]
	v_pk_add_f32 v[204:205], v[206:207], v[204:205] neg_lo:[0,1] neg_hi:[0,1]
	v_pk_add_f32 v[208:209], v[208:209], v[210:211] neg_lo:[0,1] neg_hi:[0,1]
	v_pk_add_f32 v[206:207], v[214:215], v[212:213]
	v_pk_add_f32 v[204:205], v[204:205], v[208:209]
	v_pk_add_f32 v[208:209], v[202:203], v[206:207]
	s_nop 0
	v_pk_add_f32 v[202:203], v[208:209], v[202:203] neg_lo:[0,1] neg_hi:[0,1]
	s_nop 0
	v_pk_add_f32 v[202:203], v[206:207], v[202:203] neg_lo:[0,1] neg_hi:[0,1]
	s_nop 0
	v_pk_add_f32 v[202:203], v[204:205], v[202:203]
	s_nop 0
	v_pk_add_f32 v[202:203], v[208:209], v[202:203]
	s_nop 0
	v_cndmask_b32_e64 v183, v231, v202, s[12:13]
	v_cmp_neq_f32_e64 s[12:13], s4, v179
	s_nop 1
	v_cndmask_b32_e64 v187, v231, v203, s[12:13]
	v_cmp_ngt_f32_e64 s[12:13], -1.0, v179
	s_nop 1
	v_cndmask_b32_e64 v187, v232, v187, s[12:13]
	v_cmp_ngt_f32_e64 s[12:13], -1.0, v173
	s_nop 1
	v_cndmask_b32_e64 v183, v232, v183, s[12:13]
	v_cmp_neq_f32_e64 s[12:13], -1.0, v173
	s_nop 1
	v_cndmask_b32_e64 v183, v233, v183, s[12:13]
	v_cmp_neq_f32_e64 s[12:13], -1.0, v179
	s_nop 1
	v_cndmask_b32_e64 v187, v233, v187, s[12:13]
	v_cmp_lt_f32_e64 s[12:13], |v173|, s5
	v_cndmask_b32_e64 v203, v187, v179, s[14:15]
	s_nop 0
	v_cndmask_b32_e64 v202, v183, v173, s[12:13]
	v_pk_add_f32 v[130:131], v[130:131], v[202:203] neg_lo:[0,1] neg_hi:[0,1]
	v_min_f32_e32 v202, 0, v132
	v_mul_f32_e64 v132, |v132|, s34
	v_exp_f32_e32 v173, v132
	v_min_f32_e32 v203, 0, v133
	v_mul_f32_e64 v133, |v133|, s34
	v_add_f32_e32 v132, 1.0, v173
	v_add_f32_e32 v179, -1.0, v132
	v_sub_f32_e32 v183, v179, v132
	v_add_f32_e32 v183, 1.0, v183
	v_sub_f32_e32 v179, v173, v179
	v_add_f32_e32 v179, v179, v183
	v_frexp_mant_f32_e32 v183, v132
	v_cvt_f64_f32_e32 v[204:205], v132
	v_cmp_gt_f32_e64 s[12:13], s35, v183
	v_frexp_exp_i32_f64_e32 v183, v[204:205]
	s_nop 0
	v_subbrev_co_u32_e64 v183, s[12:13], 0, v183, s[12:13]
	v_sub_u32_e32 v187, 0, v183
	v_ldexp_f32 v204, v179, v187
	v_exp_f32_e32 v179, v133
	v_ldexp_f32 v132, v132, v187
	v_add_f32_e32 v133, 1.0, v179
	v_add_f32_e32 v187, -1.0, v133
	v_sub_f32_e32 v191, v187, v133
	v_add_f32_e32 v191, 1.0, v191
	v_sub_f32_e32 v187, v179, v187
	v_add_f32_e32 v187, v187, v191
	v_frexp_mant_f32_e32 v191, v133
	v_cvt_f64_f32_e32 v[206:207], v133
	v_cmp_gt_f32_e64 s[12:13], s35, v191
	v_frexp_exp_i32_f64_e32 v191, v[206:207]
	v_cmp_lt_f32_e64 s[14:15], |v179|, s5
	v_subbrev_co_u32_e64 v191, s[12:13], 0, v191, s[12:13]
	v_sub_u32_e32 v195, 0, v191
	v_ldexp_f32 v133, v133, v195
	v_pk_add_f32 v[206:207], v[132:133], 1.0 op_sel_hi:[1,0]
	v_ldexp_f32 v205, v187, v195
	v_pk_add_f32 v[208:209], v[206:207], -1.0 op_sel_hi:[1,0]
	v_pk_add_f32 v[214:215], v[132:133], -1.0 op_sel_hi:[1,0]
	v_pk_add_f32 v[208:209], v[132:133], v[208:209] neg_lo:[0,1] neg_hi:[0,1]
	v_pk_add_f32 v[216:217], v[214:215], 1.0 op_sel_hi:[1,0]
	v_pk_add_f32 v[208:209], v[204:205], v[208:209]
	v_pk_add_f32 v[132:133], v[132:133], v[216:217] neg_lo:[0,1] neg_hi:[0,1]
	v_pk_add_f32 v[210:211], v[206:207], v[208:209]
	v_pk_add_f32 v[132:133], v[204:205], v[132:133]
	v_rcp_f32_e32 v212, v210
	v_rcp_f32_e32 v213, v211
	v_pk_add_f32 v[204:205], v[214:215], v[132:133]
	v_pk_add_f32 v[206:207], v[210:211], v[206:207] neg_lo:[0,1] neg_hi:[0,1]
; __device__ __forceinline__ float log_sigmoid_f(float x) { return fminf(x, 0.f) - log1pf(__expf(-fabsf(x))); }
;     __device__ __forceinline__ void operator()(const f32x4 (&acc)[2][2][4][2], const Unit& u, int wr, int wc, int fr, int fq) const {
;     ...
;                         for (int n = 0; n < 2; ++n) { const int c = 8 * fq + 4 * n; const f32x4 bv = *(const f32x4*)(b_f + c); const f32x4 x = acc[ai][0][m][n] * s + bv; f32x4 lf;
;                             lf[0] = log_sigmoid_f(x[0]); lf[1] = log_sigmoid_f(x[1]); lf[2] = log_sigmoid_f(x[2]); lf[3] = log_sigmoid_f(x[3]);
	v_pk_add_f32 v[214:215], v[204:205], v[214:215] neg_lo:[0,1] neg_hi:[0,1]
	v_pk_add_f32 v[206:207], v[208:209], v[206:207] neg_lo:[0,1] neg_hi:[0,1]
	v_pk_mul_f32 v[208:209], v[204:205], v[212:213]
	v_pk_add_f32 v[132:133], v[132:133], v[214:215] neg_lo:[0,1] neg_hi:[0,1]
	v_pk_mul_f32 v[214:215], v[210:211], v[208:209]
	v_cmp_neq_f32_e64 s[12:13], s4, v173
	v_pk_fma_f32 v[216:217], v[208:209], v[210:211], v[214:215] neg_lo:[0,0,1] neg_hi:[0,0,1]
	s_nop 0
	v_pk_fma_f32 v[216:217], v[208:209], v[206:207], v[216:217]
	s_nop 0
	v_pk_add_f32 v[218:219], v[214:215], v[216:217]
	s_nop 0
	v_pk_add_f32 v[220:221], v[204:205], v[218:219] neg_lo:[0,1] neg_hi:[0,1]
	v_pk_add_f32 v[214:215], v[218:219], v[214:215] neg_lo:[0,1] neg_hi:[0,1]
	v_pk_add_f32 v[204:205], v[204:205], v[220:221] neg_lo:[0,1] neg_hi:[0,1]
	s_nop 0
	v_pk_add_f32 v[204:205], v[204:205], v[218:219] neg_lo:[0,1] neg_hi:[0,1]
	s_nop 0
	v_pk_add_f32 v[132:133], v[132:133], v[204:205]
	v_pk_add_f32 v[204:205], v[214:215], v[216:217] neg_lo:[0,1] neg_hi:[0,1]
	s_nop 0
	v_pk_add_f32 v[132:133], v[204:205], v[132:133]
	s_nop 0
	v_pk_add_f32 v[204:205], v[220:221], v[132:133]
	s_nop 0
	v_pk_mul_f32 v[214:215], v[212:213], v[204:205]
	s_nop 0
	v_pk_mul_f32 v[216:217], v[210:211], v[214:215]
	s_nop 0
	v_pk_fma_f32 v[210:211], v[214:215], v[210:211], v[216:217] neg_lo:[0,0,1] neg_hi:[0,0,1]
	s_nop 0
	v_pk_fma_f32 v[206:207], v[214:215], v[206:207], v[210:211]
	v_pk_add_f32 v[210:211], v[220:221], v[204:205] neg_lo:[0,1] neg_hi:[0,1]
	s_nop 0
	v_pk_add_f32 v[132:133], v[132:133], v[210:211]
	v_pk_add_f32 v[210:211], v[216:217], v[206:207]
	s_nop 0
	v_pk_add_f32 v[218:219], v[204:205], v[210:211] neg_lo:[0,1] neg_hi:[0,1]
	v_pk_add_f32 v[216:217], v[210:211], v[216:217] neg_lo:[0,1] neg_hi:[0,1]
	v_pk_add_f32 v[204:205], v[204:205], v[218:219] neg_lo:[0,1] neg_hi:[0,1]
	s_nop 0
	v_pk_add_f32 v[204:205], v[204:205], v[210:211] neg_lo:[0,1] neg_hi:[0,1]
	s_nop 0
	v_pk_add_f32 v[132:133], v[132:133], v[204:205]
	v_pk_add_f32 v[204:205], v[216:217], v[206:207] neg_lo:[0,1] neg_hi:[0,1]
	s_nop 0
	v_pk_add_f32 v[132:133], v[204:205], v[132:133]
	v_pk_add_f32 v[204:205], v[208:209], v[214:215]
	v_pk_add_f32 v[132:133], v[218:219], v[132:133]
	v_pk_add_f32 v[206:207], v[204:205], v[208:209] neg_lo:[0,1] neg_hi:[0,1]
	v_pk_mul_f32 v[132:133], v[212:213], v[132:133]
	v_pk_add_f32 v[206:207], v[214:215], v[206:207] neg_lo:[0,1] neg_hi:[0,1]
	s_nop 0
	v_pk_add_f32 v[132:133], v[206:207], v[132:133]
	s_nop 0
	v_pk_add_f32 v[206:207], v[204:205], v[132:133]
	s_nop 0
	v_pk_mul_f32 v[208:209], v[206:207], v[206:207]
	v_pk_add_f32 v[204:205], v[206:207], v[204:205] neg_lo:[0,1] neg_hi:[0,1]
	v_pk_fma_f32 v[140:141], v[208:209], s[52:53], v[140:141] op_sel_hi:[1,0,0]
	v_pk_add_f32 v[132:133], v[132:133], v[204:205] neg_lo:[0,1] neg_hi:[0,1]
	v_ldexp_f32 v204, v206, 1
	v_pk_fma_f32 v[140:141], v[208:209], v[140:141], s[54:55] op_sel_hi:[1,1,0]
	v_ldexp_f32 v205, v207, 1
	v_pk_mul_f32 v[206:207], v[206:207], v[208:209]
	v_cvt_f32_i32_e32 v209, v191
	v_cvt_f32_i32_e32 v208, v183
	v_pk_mul_f32 v[140:141], v[206:207], v[140:141]
	v_ldexp_f32 v211, v133, 1
	v_pk_add_f32 v[206:207], v[204:205], v[140:141]
	v_pk_mul_f32 v[212:213], v[208:209], s[64:65] op_sel_hi:[1,0]
	v_pk_add_f32 v[204:205], v[206:207], v[204:205] neg_lo:[0,1] neg_hi:[0,1]
	v_pk_fma_f32 v[214:215], v[208:209], s[64:65], v[212:213] op_sel_hi:[1,0,1] neg_lo:[0,0,1] neg_hi:[0,0,1]
	v_pk_add_f32 v[140:141], v[140:141], v[204:205] neg_lo:[0,1] neg_hi:[0,1]
	v_pk_fma_f32 v[208:209], v[208:209], s[66:67], v[214:215] op_sel_hi:[1,0,1]
	v_ldexp_f32 v132, v132, 1
	v_mov_b32_e32 v204, v212
	v_mov_b32_e32 v205, v141
	v_mov_b32_e32 v210, v208
	v_mov_b32_e32 v133, v211
	v_pk_add_f32 v[204:205], v[204:205], v[210:211]
	v_pk_add_f32 v[210:211], v[132:133], v[140:141]
	v_mov_b32_e32 v141, v207
	v_mov_b32_e32 v133, v211
	v_pk_add_f32 v[214:215], v[212:213], v[208:209]
	v_pk_add_f32 v[132:133], v[132:133], v[140:141]
	v_pk_add_f32 v[140:141], v[206:207], v[210:211]
	v_mov_b32_e32 v224, v206
	v_pk_add_f32 v[216:217], v[214:215], v[140:141]
	v_mov_b32_e32 v222, v140
	v_mov_b32_e32 v223, v217
	v_mov_b32_e32 v225, v215
	v_pk_add_f32 v[222:223], v[222:223], v[224:225] neg_lo:[0,1] neg_hi:[0,1]
	v_mov_b32_e32 v218, v216
	v_mov_b32_e32 v219, v215
	v_mov_b32_e32 v220, v214
	v_mov_b32_e32 v221, v213
	v_mov_b32_e32 v224, v214
	v_mov_b32_e32 v225, v217
	v_mov_b32_e32 v213, v223
	v_pk_add_f32 v[218:219], v[218:219], v[220:221] neg_lo:[0,1] neg_hi:[0,1]
	v_mov_b32_e32 v220, v140
	v_mov_b32_e32 v221, v209
	v_pk_add_f32 v[212:213], v[224:225], v[212:213] neg_lo:[0,1] neg_hi:[0,1]
	v_pk_add_f32 v[220:221], v[220:221], v[218:219] neg_lo:[0,1] neg_hi:[0,1]
	v_mov_b32_e32 v224, v212
	v_mov_b32_e32 v225, v219
	v_mov_b32_e32 v226, v216
	v_mov_b32_e32 v227, v141
	v_mov_b32_e32 v219, v207
	v_pk_add_f32 v[224:225], v[208:209], v[224:225] neg_lo:[0,1] neg_hi:[0,1]
	v_pk_add_f32 v[218:219], v[226:227], v[218:219] neg_lo:[0,1] neg_hi:[0,1]
	v_mov_b32_e32 v209, v215
	v_pk_add_f32 v[140:141], v[140:141], v[206:207] neg_lo:[0,1] neg_hi:[0,1]
	v_pk_add_f32 v[204:205], v[204:205], v[218:219] neg_lo:[0,1] neg_hi:[0,1]
	v_pk_add_f32 v[206:207], v[208:209], v[212:213] neg_lo:[0,1] neg_hi:[0,1]
	v_pk_add_f32 v[132:133], v[132:133], v[222:223] neg_lo:[0,1] neg_hi:[0,1]
	v_pk_add_f32 v[140:141], v[210:211], v[140:141] neg_lo:[0,1] neg_hi:[0,1]
	v_pk_add_f32 v[208:209], v[132:133], v[206:207]
	v_mov_b32_e32 v207, v221
	v_mov_b32_e32 v133, v205
	v_pk_add_f32 v[210:211], v[220:221], v[204:205]
	v_pk_add_f32 v[132:133], v[206:207], v[132:133]
	v_mov_b32_e32 v204, v208
; __device__ __forceinline__ float log_sigmoid_f(float x) { return fminf(x, 0.f) - log1pf(__expf(-fabsf(x))); }
;     __device__ __forceinline__ void operator()(const f32x4 (&acc)[2][2][4][2], const Unit& u, int wr, int wc, int fr, int fq) const {
;     ...
;                         for (int n = 0; n < 2; ++n) { const int c = 8 * fq + 4 * n; const f32x4 bv = *(const f32x4*)(b_f + c); const f32x4 x = acc[ai][0][m][n] * s + bv; f32x4 lf;
;                             lf[0] = log_sigmoid_f(x[0]); lf[1] = log_sigmoid_f(x[1]); lf[2] = log_sigmoid_f(x[2]); lf[3] = log_sigmoid_f(x[3]);
;                             *(f32x4*)(LF + (size_t)row * 16 + c) = lf; if (dst) *(f32x4*)(dst + c) = lf; } }
	v_pk_add_f32 v[132:133], v[132:133], v[224:225] neg_lo:[0,1] neg_hi:[0,1]
	v_mov_b32_e32 v205, v211
	v_pk_add_f32 v[204:205], v[204:205], v[132:133] neg_lo:[0,1] neg_hi:[0,1]
	v_pk_add_f32 v[132:133], v[140:141], v[132:133] neg_lo:[0,1] neg_hi:[0,1]
	v_pk_add_f32 v[204:205], v[206:207], v[204:205] neg_lo:[0,1] neg_hi:[0,1]
	v_pk_add_f32 v[140:141], v[210:211], v[208:209]
	v_pk_add_f32 v[132:133], v[132:133], v[204:205]
	v_pk_add_f32 v[204:205], v[216:217], v[140:141]
	s_nop 0
	v_pk_add_f32 v[206:207], v[204:205], v[216:217] neg_lo:[0,1] neg_hi:[0,1]
	s_nop 0
	v_pk_add_f32 v[140:141], v[140:141], v[206:207] neg_lo:[0,1] neg_hi:[0,1]
	s_nop 0
	v_pk_add_f32 v[132:133], v[132:133], v[140:141]
	s_nop 0
	v_pk_add_f32 v[132:133], v[204:205], v[132:133]
	s_nop 0
	v_cndmask_b32_e64 v132, v231, v132, s[12:13]
	v_cmp_neq_f32_e64 s[12:13], s4, v179
	s_nop 1
	v_cndmask_b32_e64 v133, v231, v133, s[12:13]
	v_cmp_ngt_f32_e64 s[12:13], -1.0, v179
	s_nop 1
	v_cndmask_b32_e64 v133, v232, v133, s[12:13]
	v_cmp_ngt_f32_e64 s[12:13], -1.0, v173
	s_nop 1
	v_cndmask_b32_e64 v132, v232, v132, s[12:13]
	v_cmp_neq_f32_e64 s[12:13], -1.0, v173
	s_nop 1
	v_cndmask_b32_e64 v132, v233, v132, s[12:13]
	v_cmp_neq_f32_e64 s[12:13], -1.0, v179
	s_nop 1
	v_cndmask_b32_e64 v133, v233, v133, s[12:13]
	v_cmp_lt_f32_e64 s[12:13], |v173|, s5
	v_cndmask_b32_e64 v133, v133, v179, s[14:15]
	s_nop 0
	v_cndmask_b32_e64 v132, v132, v173, s[12:13]
	v_pk_add_f32 v[132:133], v[202:203], v[132:133] neg_lo:[0,1] neg_hi:[0,1]
	global_store_dwordx4 v[138:139], v[130:133], off nt
	s_and_saveexec_b64 s[12:13], vcc
	s_cbranch_execz .LBB0_391
	v_lshl_add_u64 v[140:141], v[136:137], 0, v[150:151]
	global_store_dwordx4 v[140:141], v[130:133], off nt
.LBB0_391:
	s_or_b64 exec, exec, s[12:13]
	global_load_dwordx4 v[130:133], v[158:159], off offset:16
	v_mov_b32_e32 v195, v194
	v_mov_b32_e32 v140, v194
	v_mov_b32_e32 v141, v194
	s_waitcnt vmcnt(0)
	v_pk_fma_f32 v[132:133], v[92:93], v[140:141], v[132:133]
	v_pk_fma_f32 v[140:141], v[90:91], v[194:195], v[130:131]
	s_nop 0
	v_mul_f32_e64 v131, |v140|, s34
	v_exp_f32_e32 v173, v131
	v_min_f32_e32 v130, 0, v140
	v_add_f32_e32 v131, 1.0, v173
	v_add_f32_e32 v140, -1.0, v131
	v_sub_f32_e32 v179, v140, v131
	v_add_f32_e32 v179, 1.0, v179
	v_sub_f32_e32 v140, v173, v140
	v_add_f32_e32 v179, v140, v179
	v_frexp_mant_f32_e32 v140, v131
	v_cvt_f64_f32_e32 v[202:203], v131
	v_cmp_gt_f32_e64 s[12:13], s35, v140
	v_frexp_exp_i32_f64_e32 v140, v[202:203]
	s_nop 0
	v_subbrev_co_u32_e64 v183, s[12:13], 0, v140, s[12:13]
	v_sub_u32_e32 v187, 0, v183
	v_ldexp_f32 v140, v131, v187
	v_min_f32_e32 v131, 0, v141
	v_mul_f32_e64 v141, |v141|, s34
	v_ldexp_f32 v202, v179, v187
	v_exp_f32_e32 v179, v141
	s_nop 0
	v_add_f32_e32 v141, 1.0, v179
	v_add_f32_e32 v187, -1.0, v141
	v_sub_f32_e32 v191, v187, v141
	v_add_f32_e32 v191, 1.0, v191
	v_sub_f32_e32 v187, v179, v187
	v_add_f32_e32 v191, v187, v191
	v_frexp_mant_f32_e32 v187, v141
	v_cvt_f64_f32_e32 v[204:205], v141
	v_cmp_gt_f32_e64 s[12:13], s35, v187
	v_frexp_exp_i32_f64_e32 v187, v[204:205]
	v_cmp_lt_f32_e64 s[14:15], |v179|, s5
	v_subbrev_co_u32_e64 v187, s[12:13], 0, v187, s[12:13]
	v_sub_u32_e32 v195, 0, v187
	v_ldexp_f32 v141, v141, v195
	v_pk_add_f32 v[204:205], v[140:141], 1.0 op_sel_hi:[1,0]
	v_ldexp_f32 v203, v191, v195
	v_pk_add_f32 v[206:207], v[204:205], -1.0 op_sel_hi:[1,0]
	v_pk_add_f32 v[212:213], v[140:141], -1.0 op_sel_hi:[1,0]
	v_pk_add_f32 v[206:207], v[140:141], v[206:207] neg_lo:[0,1] neg_hi:[0,1]
	v_pk_add_f32 v[214:215], v[212:213], 1.0 op_sel_hi:[1,0]
	v_pk_add_f32 v[206:207], v[202:203], v[206:207]
	v_pk_add_f32 v[140:141], v[140:141], v[214:215] neg_lo:[0,1] neg_hi:[0,1]
	v_pk_add_f32 v[208:209], v[204:205], v[206:207]
	v_pk_add_f32 v[140:141], v[202:203], v[140:141]
	v_rcp_f32_e32 v210, v208
	v_rcp_f32_e32 v211, v209
	v_pk_add_f32 v[202:203], v[212:213], v[140:141]
	v_pk_add_f32 v[204:205], v[208:209], v[204:205] neg_lo:[0,1] neg_hi:[0,1]
	v_pk_add_f32 v[212:213], v[202:203], v[212:213] neg_lo:[0,1] neg_hi:[0,1]
	v_pk_add_f32 v[204:205], v[206:207], v[204:205] neg_lo:[0,1] neg_hi:[0,1]
	v_pk_mul_f32 v[206:207], v[202:203], v[210:211]
	v_pk_add_f32 v[140:141], v[140:141], v[212:213] neg_lo:[0,1] neg_hi:[0,1]
	v_pk_mul_f32 v[212:213], v[208:209], v[206:207]
	v_cmp_neq_f32_e64 s[12:13], s4, v173
	v_pk_fma_f32 v[214:215], v[206:207], v[208:209], v[212:213] neg_lo:[0,0,1] neg_hi:[0,0,1]
	s_nop 0
	v_pk_fma_f32 v[214:215], v[206:207], v[204:205], v[214:215]
	s_nop 0
	v_pk_add_f32 v[216:217], v[212:213], v[214:215]
	s_nop 0
	v_pk_add_f32 v[218:219], v[202:203], v[216:217] neg_lo:[0,1] neg_hi:[0,1]
	v_pk_add_f32 v[212:213], v[216:217], v[212:213] neg_lo:[0,1] neg_hi:[0,1]
	v_pk_add_f32 v[202:203], v[202:203], v[218:219] neg_lo:[0,1] neg_hi:[0,1]
	s_nop 0
	v_pk_add_f32 v[202:203], v[202:203], v[216:217] neg_lo:[0,1] neg_hi:[0,1]
	s_nop 0
	v_pk_add_f32 v[140:141], v[140:141], v[202:203]
	v_pk_add_f32 v[202:203], v[212:213], v[214:215] neg_lo:[0,1] neg_hi:[0,1]
	s_nop 0
	v_pk_add_f32 v[140:141], v[202:203], v[140:141]
	s_nop 0
	v_pk_add_f32 v[202:203], v[218:219], v[140:141]
	s_nop 0
	v_pk_mul_f32 v[212:213], v[210:211], v[202:203]
	s_nop 0
	v_pk_mul_f32 v[214:215], v[208:209], v[212:213]
	s_nop 0
	v_pk_fma_f32 v[208:209], v[212:213], v[208:209], v[214:215] neg_lo:[0,0,1] neg_hi:[0,0,1]
	s_nop 0
	v_pk_fma_f32 v[204:205], v[212:213], v[204:205], v[208:209]
	v_pk_add_f32 v[208:209], v[218:219], v[202:203] neg_lo:[0,1] neg_hi:[0,1]
	s_nop 0
	v_pk_add_f32 v[140:141], v[140:141], v[208:209]
	v_pk_add_f32 v[208:209], v[214:215], v[204:205]
	s_nop 0
	v_pk_add_f32 v[216:217], v[202:203], v[208:209] neg_lo:[0,1] neg_hi:[0,1]
; __device__ __forceinline__ float log_sigmoid_f(float x) { return fminf(x, 0.f) - log1pf(__expf(-fabsf(x))); }
;     __device__ __forceinline__ void operator()(const f32x4 (&acc)[2][2][4][2], const Unit& u, int wr, int wc, int fr, int fq) const {
;     ...
;                         for (int n = 0; n < 2; ++n) { const int c = 8 * fq + 4 * n; const f32x4 bv = *(const f32x4*)(b_f + c); const f32x4 x = acc[ai][0][m][n] * s + bv; f32x4 lf;
;                             lf[0] = log_sigmoid_f(x[0]); lf[1] = log_sigmoid_f(x[1]); lf[2] = log_sigmoid_f(x[2]); lf[3] = log_sigmoid_f(x[3]);
	v_pk_add_f32 v[214:215], v[208:209], v[214:215] neg_lo:[0,1] neg_hi:[0,1]
	v_pk_add_f32 v[202:203], v[202:203], v[216:217] neg_lo:[0,1] neg_hi:[0,1]
	s_nop 0
	v_pk_add_f32 v[202:203], v[202:203], v[208:209] neg_lo:[0,1] neg_hi:[0,1]
	s_nop 0
	v_pk_add_f32 v[140:141], v[140:141], v[202:203]
	v_pk_add_f32 v[202:203], v[214:215], v[204:205] neg_lo:[0,1] neg_hi:[0,1]
	s_nop 0
	v_pk_add_f32 v[140:141], v[202:203], v[140:141]
	v_pk_add_f32 v[202:203], v[206:207], v[212:213]
	v_pk_add_f32 v[140:141], v[216:217], v[140:141]
	v_pk_add_f32 v[204:205], v[202:203], v[206:207] neg_lo:[0,1] neg_hi:[0,1]
	v_pk_mul_f32 v[140:141], v[210:211], v[140:141]
	v_pk_add_f32 v[204:205], v[212:213], v[204:205] neg_lo:[0,1] neg_hi:[0,1]
	v_cvt_f32_i32_e32 v213, v187
	v_pk_add_f32 v[140:141], v[204:205], v[140:141]
	v_cvt_f32_i32_e32 v212, v183
	v_pk_add_f32 v[206:207], v[202:203], v[140:141]
	s_nop 0
	v_pk_add_f32 v[202:203], v[206:207], v[202:203] neg_lo:[0,1] neg_hi:[0,1]
	v_pk_mul_f32 v[208:209], v[206:207], v[206:207]
	v_pk_add_f32 v[202:203], v[140:141], v[202:203] neg_lo:[0,1] neg_hi:[0,1]
	v_mov_b64_e32 v[140:141], s[50:51]
	v_pk_fma_f32 v[210:211], v[208:209], s[52:53], v[140:141] op_sel_hi:[1,0,0]
	v_ldexp_f32 v204, v206, 1
	v_pk_fma_f32 v[210:211], v[208:209], v[210:211], s[54:55] op_sel_hi:[1,1,0]
	v_ldexp_f32 v205, v207, 1
	v_pk_mul_f32 v[206:207], v[206:207], v[208:209]
	v_ldexp_f32 v215, v203, 1
	v_pk_mul_f32 v[216:217], v[206:207], v[210:211]
	v_pk_mul_f32 v[208:209], v[212:213], s[64:65] op_sel_hi:[1,0]
	v_pk_add_f32 v[206:207], v[204:205], v[216:217]
	v_ldexp_f32 v202, v202, 1
	v_pk_add_f32 v[204:205], v[206:207], v[204:205] neg_lo:[0,1] neg_hi:[0,1]
	v_pk_fma_f32 v[210:211], v[212:213], s[64:65], v[208:209] op_sel_hi:[1,0,1] neg_lo:[0,0,1] neg_hi:[0,0,1]
	v_pk_add_f32 v[218:219], v[216:217], v[204:205] neg_lo:[0,1] neg_hi:[0,1]
	v_mov_b32_e32 v203, v215
	v_pk_fma_f32 v[210:211], v[212:213], s[66:67], v[210:211] op_sel_hi:[1,0,1]
	v_pk_add_f32 v[216:217], v[202:203], v[218:219]
	v_mov_b32_e32 v204, v208
	v_mov_b32_e32 v205, v219
	v_mov_b32_e32 v214, v210
	v_mov_b32_e32 v203, v217
	v_mov_b32_e32 v219, v207
	v_pk_add_f32 v[212:213], v[208:209], v[210:211]
	v_pk_add_f32 v[204:205], v[204:205], v[214:215]
	v_pk_add_f32 v[214:215], v[202:203], v[218:219]
	v_pk_add_f32 v[218:219], v[206:207], v[216:217]
	v_mov_b32_e32 v226, v206
	v_pk_add_f32 v[202:203], v[212:213], v[218:219]
	v_mov_b32_e32 v224, v218
	v_mov_b32_e32 v225, v203
	v_mov_b32_e32 v227, v213
	v_pk_add_f32 v[224:225], v[224:225], v[226:227] neg_lo:[0,1] neg_hi:[0,1]
	v_mov_b32_e32 v220, v202
	v_mov_b32_e32 v221, v213
	v_mov_b32_e32 v222, v212
	v_mov_b32_e32 v223, v209
	v_mov_b32_e32 v226, v212
	v_mov_b32_e32 v227, v203
	v_mov_b32_e32 v209, v225
	v_pk_add_f32 v[220:221], v[220:221], v[222:223] neg_lo:[0,1] neg_hi:[0,1]
	v_mov_b32_e32 v222, v218
	v_mov_b32_e32 v223, v211
	v_pk_add_f32 v[208:209], v[226:227], v[208:209] neg_lo:[0,1] neg_hi:[0,1]
	v_pk_add_f32 v[222:223], v[222:223], v[220:221] neg_lo:[0,1] neg_hi:[0,1]
	v_mov_b32_e32 v226, v208
	v_mov_b32_e32 v227, v221
	v_mov_b32_e32 v236, v202
	v_mov_b32_e32 v237, v219
	v_mov_b32_e32 v221, v207
	v_pk_add_f32 v[226:227], v[210:211], v[226:227] neg_lo:[0,1] neg_hi:[0,1]
	v_pk_add_f32 v[220:221], v[236:237], v[220:221] neg_lo:[0,1] neg_hi:[0,1]
	v_mov_b32_e32 v211, v213
	v_pk_add_f32 v[204:205], v[204:205], v[220:221] neg_lo:[0,1] neg_hi:[0,1]
	v_pk_add_f32 v[208:209], v[210:211], v[208:209] neg_lo:[0,1] neg_hi:[0,1]
	v_pk_add_f32 v[210:211], v[214:215], v[224:225] neg_lo:[0,1] neg_hi:[0,1]
	v_pk_add_f32 v[214:215], v[222:223], v[204:205]
	v_pk_add_f32 v[212:213], v[210:211], v[208:209]
	v_mov_b32_e32 v209, v223
	v_mov_b32_e32 v211, v205
	v_pk_add_f32 v[204:205], v[208:209], v[210:211]
	v_pk_add_f32 v[206:207], v[218:219], v[206:207] neg_lo:[0,1] neg_hi:[0,1]
	v_pk_add_f32 v[204:205], v[204:205], v[226:227] neg_lo:[0,1] neg_hi:[0,1]
	v_mov_b32_e32 v210, v212
	v_mov_b32_e32 v211, v215
	v_pk_add_f32 v[206:207], v[216:217], v[206:207] neg_lo:[0,1] neg_hi:[0,1]
	v_pk_add_f32 v[210:211], v[210:211], v[204:205] neg_lo:[0,1] neg_hi:[0,1]
	v_pk_add_f32 v[204:205], v[206:207], v[204:205] neg_lo:[0,1] neg_hi:[0,1]
	v_pk_add_f32 v[208:209], v[208:209], v[210:211] neg_lo:[0,1] neg_hi:[0,1]
	v_pk_add_f32 v[206:207], v[214:215], v[212:213]
	v_pk_add_f32 v[204:205], v[204:205], v[208:209]
	v_pk_add_f32 v[208:209], v[202:203], v[206:207]
	s_nop 0
	v_pk_add_f32 v[202:203], v[208:209], v[202:203] neg_lo:[0,1] neg_hi:[0,1]
	s_nop 0
	v_pk_add_f32 v[202:203], v[206:207], v[202:203] neg_lo:[0,1] neg_hi:[0,1]
	s_nop 0
	v_pk_add_f32 v[202:203], v[204:205], v[202:203]
	s_nop 0
	v_pk_add_f32 v[202:203], v[208:209], v[202:203]
	s_nop 0
	v_cndmask_b32_e64 v183, v231, v202, s[12:13]
	v_cmp_neq_f32_e64 s[12:13], s4, v179
	s_nop 1
	v_cndmask_b32_e64 v187, v231, v203, s[12:13]
	v_cmp_ngt_f32_e64 s[12:13], -1.0, v179
	s_nop 1
	v_cndmask_b32_e64 v187, v232, v187, s[12:13]
	v_cmp_ngt_f32_e64 s[12:13], -1.0, v173
	s_nop 1
	v_cndmask_b32_e64 v183, v232, v183, s[12:13]
	v_cmp_neq_f32_e64 s[12:13], -1.0, v173
	s_nop 1
	v_cndmask_b32_e64 v183, v233, v183, s[12:13]
	v_cmp_neq_f32_e64 s[12:13], -1.0, v179
	s_nop 1
	v_cndmask_b32_e64 v187, v233, v187, s[12:13]
	v_cmp_lt_f32_e64 s[12:13], |v173|, s5
	v_cndmask_b32_e64 v203, v187, v179, s[14:15]
	s_nop 0
	v_cndmask_b32_e64 v202, v183, v173, s[12:13]
	v_pk_add_f32 v[130:131], v[130:131], v[202:203] neg_lo:[0,1] neg_hi:[0,1]
	v_min_f32_e32 v202, 0, v132
	v_mul_f32_e64 v132, |v132|, s34
	v_exp_f32_e32 v173, v132
	v_min_f32_e32 v203, 0, v133
	v_mul_f32_e64 v133, |v133|, s34
	v_add_f32_e32 v132, 1.0, v173
	v_add_f32_e32 v179, -1.0, v132
; __device__ __forceinline__ float log_sigmoid_f(float x) { return fminf(x, 0.f) - log1pf(__expf(-fabsf(x))); }
;     __device__ __forceinline__ void operator()(const f32x4 (&acc)[2][2][4][2], const Unit& u, int wr, int wc, int fr, int fq) const {
;     ...
;                         for (int n = 0; n < 2; ++n) { const int c = 8 * fq + 4 * n; const f32x4 bv = *(const f32x4*)(b_f + c); const f32x4 x = acc[ai][0][m][n] * s + bv; f32x4 lf;
;                             lf[0] = log_sigmoid_f(x[0]); lf[1] = log_sigmoid_f(x[1]); lf[2] = log_sigmoid_f(x[2]); lf[3] = log_sigmoid_f(x[3]);
	v_sub_f32_e32 v183, v179, v132
	v_add_f32_e32 v183, 1.0, v183
	v_sub_f32_e32 v179, v173, v179
	v_add_f32_e32 v179, v179, v183
	v_frexp_mant_f32_e32 v183, v132
	v_cvt_f64_f32_e32 v[204:205], v132
	v_cmp_gt_f32_e64 s[12:13], s35, v183
	v_frexp_exp_i32_f64_e32 v183, v[204:205]
	s_nop 0
	v_subbrev_co_u32_e64 v183, s[12:13], 0, v183, s[12:13]
	v_sub_u32_e32 v187, 0, v183
	v_ldexp_f32 v204, v179, v187
	v_exp_f32_e32 v179, v133
	v_ldexp_f32 v132, v132, v187
	v_add_f32_e32 v133, 1.0, v179
	v_add_f32_e32 v187, -1.0, v133
	v_sub_f32_e32 v191, v187, v133
	v_add_f32_e32 v191, 1.0, v191
	v_sub_f32_e32 v187, v179, v187
	v_add_f32_e32 v187, v187, v191
	v_frexp_mant_f32_e32 v191, v133
	v_cvt_f64_f32_e32 v[206:207], v133
	v_cmp_gt_f32_e64 s[12:13], s35, v191
	v_frexp_exp_i32_f64_e32 v191, v[206:207]
	v_cmp_lt_f32_e64 s[14:15], |v179|, s5
	v_subbrev_co_u32_e64 v191, s[12:13], 0, v191, s[12:13]
	v_sub_u32_e32 v195, 0, v191
	v_ldexp_f32 v133, v133, v195
	v_pk_add_f32 v[206:207], v[132:133], 1.0 op_sel_hi:[1,0]
	v_ldexp_f32 v205, v187, v195
	v_pk_add_f32 v[208:209], v[206:207], -1.0 op_sel_hi:[1,0]
	v_pk_add_f32 v[214:215], v[132:133], -1.0 op_sel_hi:[1,0]
	v_pk_add_f32 v[208:209], v[132:133], v[208:209] neg_lo:[0,1] neg_hi:[0,1]
	v_pk_add_f32 v[216:217], v[214:215], 1.0 op_sel_hi:[1,0]
	v_pk_add_f32 v[208:209], v[204:205], v[208:209]
	v_pk_add_f32 v[132:133], v[132:133], v[216:217] neg_lo:[0,1] neg_hi:[0,1]
	v_pk_add_f32 v[210:211], v[206:207], v[208:209]
	v_pk_add_f32 v[132:133], v[204:205], v[132:133]
	v_rcp_f32_e32 v212, v210
	v_rcp_f32_e32 v213, v211
	v_pk_add_f32 v[204:205], v[214:215], v[132:133]
	v_pk_add_f32 v[206:207], v[210:211], v[206:207] neg_lo:[0,1] neg_hi:[0,1]
	v_pk_add_f32 v[214:215], v[204:205], v[214:215] neg_lo:[0,1] neg_hi:[0,1]
	v_pk_add_f32 v[206:207], v[208:209], v[206:207] neg_lo:[0,1] neg_hi:[0,1]
	v_pk_mul_f32 v[208:209], v[204:205], v[212:213]
	v_pk_add_f32 v[132:133], v[132:133], v[214:215] neg_lo:[0,1] neg_hi:[0,1]
	v_pk_mul_f32 v[214:215], v[210:211], v[208:209]
	v_cmp_neq_f32_e64 s[12:13], s4, v173
	v_pk_fma_f32 v[216:217], v[208:209], v[210:211], v[214:215] neg_lo:[0,0,1] neg_hi:[0,0,1]
	s_nop 0
	v_pk_fma_f32 v[216:217], v[208:209], v[206:207], v[216:217]
	s_nop 0
	v_pk_add_f32 v[218:219], v[214:215], v[216:217]
	s_nop 0
	v_pk_add_f32 v[220:221], v[204:205], v[218:219] neg_lo:[0,1] neg_hi:[0,1]
	v_pk_add_f32 v[214:215], v[218:219], v[214:215] neg_lo:[0,1] neg_hi:[0,1]
	v_pk_add_f32 v[204:205], v[204:205], v[220:221] neg_lo:[0,1] neg_hi:[0,1]
	s_nop 0
	v_pk_add_f32 v[204:205], v[204:205], v[218:219] neg_lo:[0,1] neg_hi:[0,1]
	s_nop 0
	v_pk_add_f32 v[132:133], v[132:133], v[204:205]
	v_pk_add_f32 v[204:205], v[214:215], v[216:217] neg_lo:[0,1] neg_hi:[0,1]
	s_nop 0
	v_pk_add_f32 v[132:133], v[204:205], v[132:133]
	s_nop 0
	v_pk_add_f32 v[204:205], v[220:221], v[132:133]
	s_nop 0
	v_pk_mul_f32 v[214:215], v[212:213], v[204:205]
	s_nop 0
	v_pk_mul_f32 v[216:217], v[210:211], v[214:215]
	s_nop 0
	v_pk_fma_f32 v[210:211], v[214:215], v[210:211], v[216:217] neg_lo:[0,0,1] neg_hi:[0,0,1]
	s_nop 0
	v_pk_fma_f32 v[206:207], v[214:215], v[206:207], v[210:211]
	v_pk_add_f32 v[210:211], v[220:221], v[204:205] neg_lo:[0,1] neg_hi:[0,1]
	s_nop 0
	v_pk_add_f32 v[132:133], v[132:133], v[210:211]
	v_pk_add_f32 v[210:211], v[216:217], v[206:207]
	s_nop 0
	v_pk_add_f32 v[218:219], v[204:205], v[210:211] neg_lo:[0,1] neg_hi:[0,1]
	v_pk_add_f32 v[216:217], v[210:211], v[216:217] neg_lo:[0,1] neg_hi:[0,1]
	v_pk_add_f32 v[204:205], v[204:205], v[218:219] neg_lo:[0,1] neg_hi:[0,1]
	s_nop 0
	v_pk_add_f32 v[204:205], v[204:205], v[210:211] neg_lo:[0,1] neg_hi:[0,1]
	s_nop 0
	v_pk_add_f32 v[132:133], v[132:133], v[204:205]
	v_pk_add_f32 v[204:205], v[216:217], v[206:207] neg_lo:[0,1] neg_hi:[0,1]
	s_nop 0
	v_pk_add_f32 v[132:133], v[204:205], v[132:133]
	v_pk_add_f32 v[204:205], v[208:209], v[214:215]
	v_pk_add_f32 v[132:133], v[218:219], v[132:133]
	v_pk_add_f32 v[206:207], v[204:205], v[208:209] neg_lo:[0,1] neg_hi:[0,1]
	v_pk_mul_f32 v[132:133], v[212:213], v[132:133]
	v_pk_add_f32 v[206:207], v[214:215], v[206:207] neg_lo:[0,1] neg_hi:[0,1]
	s_nop 0
	v_pk_add_f32 v[132:133], v[206:207], v[132:133]
	s_nop 0
	v_pk_add_f32 v[206:207], v[204:205], v[132:133]
	s_nop 0
	v_pk_mul_f32 v[208:209], v[206:207], v[206:207]
	v_pk_add_f32 v[204:205], v[206:207], v[204:205] neg_lo:[0,1] neg_hi:[0,1]
	v_pk_fma_f32 v[140:141], v[208:209], s[52:53], v[140:141] op_sel_hi:[1,0,0]
	v_pk_add_f32 v[132:133], v[132:133], v[204:205] neg_lo:[0,1] neg_hi:[0,1]
; __device__ __forceinline__ float log_sigmoid_f(float x) { return fminf(x, 0.f) - log1pf(__expf(-fabsf(x))); }
;     __device__ __forceinline__ void operator()(const f32x4 (&acc)[2][2][4][2], const Unit& u, int wr, int wc, int fr, int fq) const {
;     ...
;                         for (int n = 0; n < 2; ++n) { const int c = 8 * fq + 4 * n; const f32x4 bv = *(const f32x4*)(b_f + c); const f32x4 x = acc[ai][0][m][n] * s + bv; f32x4 lf;
;                             lf[0] = log_sigmoid_f(x[0]); lf[1] = log_sigmoid_f(x[1]); lf[2] = log_sigmoid_f(x[2]); lf[3] = log_sigmoid_f(x[3]);
;                             *(f32x4*)(LF + (size_t)row * 16 + c) = lf; if (dst) *(f32x4*)(dst + c) = lf; } }
	v_ldexp_f32 v204, v206, 1
	v_pk_fma_f32 v[140:141], v[208:209], v[140:141], s[54:55] op_sel_hi:[1,1,0]
	v_ldexp_f32 v205, v207, 1
	v_pk_mul_f32 v[206:207], v[206:207], v[208:209]
	v_cvt_f32_i32_e32 v209, v191
	v_cvt_f32_i32_e32 v208, v183
	v_pk_mul_f32 v[140:141], v[206:207], v[140:141]
	v_ldexp_f32 v211, v133, 1
	v_pk_add_f32 v[206:207], v[204:205], v[140:141]
	v_pk_mul_f32 v[212:213], v[208:209], s[64:65] op_sel_hi:[1,0]
	v_pk_add_f32 v[204:205], v[206:207], v[204:205] neg_lo:[0,1] neg_hi:[0,1]
	v_pk_fma_f32 v[214:215], v[208:209], s[64:65], v[212:213] op_sel_hi:[1,0,1] neg_lo:[0,0,1] neg_hi:[0,0,1]
	v_pk_add_f32 v[140:141], v[140:141], v[204:205] neg_lo:[0,1] neg_hi:[0,1]
	v_pk_fma_f32 v[208:209], v[208:209], s[66:67], v[214:215] op_sel_hi:[1,0,1]
	v_ldexp_f32 v132, v132, 1
	v_mov_b32_e32 v204, v212
	v_mov_b32_e32 v205, v141
	v_mov_b32_e32 v210, v208
	v_mov_b32_e32 v133, v211
	v_pk_add_f32 v[204:205], v[204:205], v[210:211]
	v_pk_add_f32 v[210:211], v[132:133], v[140:141]
	v_mov_b32_e32 v141, v207
	v_mov_b32_e32 v133, v211
	v_pk_add_f32 v[214:215], v[212:213], v[208:209]
	v_pk_add_f32 v[132:133], v[132:133], v[140:141]
	v_pk_add_f32 v[140:141], v[206:207], v[210:211]
	v_mov_b32_e32 v224, v206
	v_pk_add_f32 v[216:217], v[214:215], v[140:141]
	v_mov_b32_e32 v222, v140
	v_mov_b32_e32 v223, v217
	v_mov_b32_e32 v225, v215
	v_pk_add_f32 v[222:223], v[222:223], v[224:225] neg_lo:[0,1] neg_hi:[0,1]
	v_mov_b32_e32 v218, v216
	v_mov_b32_e32 v219, v215
	v_mov_b32_e32 v220, v214
	v_mov_b32_e32 v221, v213
	v_mov_b32_e32 v224, v214
	v_mov_b32_e32 v225, v217
	v_mov_b32_e32 v213, v223
	v_pk_add_f32 v[218:219], v[218:219], v[220:221] neg_lo:[0,1] neg_hi:[0,1]
	v_mov_b32_e32 v220, v140
	v_mov_b32_e32 v221, v209
	v_pk_add_f32 v[212:213], v[224:225], v[212:213] neg_lo:[0,1] neg_hi:[0,1]
	v_pk_add_f32 v[220:221], v[220:221], v[218:219] neg_lo:[0,1] neg_hi:[0,1]
	v_mov_b32_e32 v224, v212
	v_mov_b32_e32 v225, v219
	v_mov_b32_e32 v226, v216
	v_mov_b32_e32 v227, v141
	v_mov_b32_e32 v219, v207
	v_pk_add_f32 v[224:225], v[208:209], v[224:225] neg_lo:[0,1] neg_hi:[0,1]
	v_pk_add_f32 v[218:219], v[226:227], v[218:219] neg_lo:[0,1] neg_hi:[0,1]
	v_mov_b32_e32 v209, v215
	v_pk_add_f32 v[140:141], v[140:141], v[206:207] neg_lo:[0,1] neg_hi:[0,1]
	v_pk_add_f32 v[204:205], v[204:205], v[218:219] neg_lo:[0,1] neg_hi:[0,1]
	v_pk_add_f32 v[206:207], v[208:209], v[212:213] neg_lo:[0,1] neg_hi:[0,1]
	v_pk_add_f32 v[132:133], v[132:133], v[222:223] neg_lo:[0,1] neg_hi:[0,1]
	v_pk_add_f32 v[140:141], v[210:211], v[140:141] neg_lo:[0,1] neg_hi:[0,1]
	v_pk_add_f32 v[208:209], v[132:133], v[206:207]
	v_mov_b32_e32 v207, v221
	v_mov_b32_e32 v133, v205
	v_pk_add_f32 v[210:211], v[220:221], v[204:205]
	v_pk_add_f32 v[132:133], v[206:207], v[132:133]
	v_mov_b32_e32 v204, v208
	v_pk_add_f32 v[132:133], v[132:133], v[224:225] neg_lo:[0,1] neg_hi:[0,1]
	v_mov_b32_e32 v205, v211
	v_pk_add_f32 v[204:205], v[204:205], v[132:133] neg_lo:[0,1] neg_hi:[0,1]
	v_pk_add_f32 v[132:133], v[140:141], v[132:133] neg_lo:[0,1] neg_hi:[0,1]
	v_pk_add_f32 v[204:205], v[206:207], v[204:205] neg_lo:[0,1] neg_hi:[0,1]
	v_pk_add_f32 v[140:141], v[210:211], v[208:209]
	v_pk_add_f32 v[132:133], v[132:133], v[204:205]
	v_pk_add_f32 v[204:205], v[216:217], v[140:141]
	s_nop 0
	v_pk_add_f32 v[206:207], v[204:205], v[216:217] neg_lo:[0,1] neg_hi:[0,1]
	s_nop 0
	v_pk_add_f32 v[140:141], v[140:141], v[206:207] neg_lo:[0,1] neg_hi:[0,1]
	s_nop 0
	v_pk_add_f32 v[132:133], v[132:133], v[140:141]
	s_nop 0
	v_pk_add_f32 v[132:133], v[204:205], v[132:133]
	s_nop 0
	v_cndmask_b32_e64 v132, v231, v132, s[12:13]
	v_cmp_neq_f32_e64 s[12:13], s4, v179
	s_nop 1
	v_cndmask_b32_e64 v133, v231, v133, s[12:13]
	v_cmp_ngt_f32_e64 s[12:13], -1.0, v179
	s_nop 1
	v_cndmask_b32_e64 v133, v232, v133, s[12:13]
	v_cmp_ngt_f32_e64 s[12:13], -1.0, v173
	s_nop 1
	v_cndmask_b32_e64 v132, v232, v132, s[12:13]
	v_cmp_neq_f32_e64 s[12:13], -1.0, v173
	s_nop 1
	v_cndmask_b32_e64 v132, v233, v132, s[12:13]
	v_cmp_neq_f32_e64 s[12:13], -1.0, v179
	s_nop 1
	v_cndmask_b32_e64 v133, v233, v133, s[12:13]
	v_cmp_lt_f32_e64 s[12:13], |v173|, s5
	v_cndmask_b32_e64 v133, v133, v179, s[14:15]
	s_nop 0
	v_cndmask_b32_e64 v132, v132, v173, s[12:13]
	v_pk_add_f32 v[132:133], v[202:203], v[132:133] neg_lo:[0,1] neg_hi:[0,1]
	global_store_dwordx4 v[138:139], v[130:133], off offset:16 nt
	s_and_saveexec_b64 s[12:13], vcc
	s_cbranch_execz .LBB0_393
	v_lshl_add_u64 v[136:137], v[136:137], 0, v[150:151]
	global_store_dwordx4 v[136:137], v[130:133], off offset:16 nt

; __device__ __forceinline__ float log_sigmoid_f(float x) { return fminf(x, 0.f) - log1pf(__expf(-fabsf(x))); }
;     __device__ __forceinline__ void operator()(const f32x4 (&acc)[2][2][4][2], const Unit& u, int wr, int wc, int fr, int fq) const {
;     ...
;                         if (pm == 0) dst = o_lfs + (size_t)row * 16; else { const int t = row - G_ROWP; if (t < G_TP) dst = o_lfp + (size_t)t * 16; }
; #pragma unroll
;                         for (int n = 0; n < 2; ++n) { const int c = 8 * fq + 4 * n; const f32x4 bv = *(const f32x4*)(b_f + c); const f32x4 x = acc[ai][0][m][n] * s + bv; f32x4 lf;
;                             lf[0] = log_sigmoid_f(x[0]); lf[1] = log_sigmoid_f(x[1]); lf[2] = log_sigmoid_f(x[2]); lf[3] = log_sigmoid_f(x[3]);
.LBB0_396:
	global_load_dwordx4 v[130:133], v[158:159], off
	v_cmp_ne_u64_e32 vcc, 0, v[134:135]
	v_lshl_add_u64 v[136:137], v[162:163], 0, v[136:137]
	s_waitcnt vmcnt(0)
	v_pk_fma_f32 v[138:139], v[78:79], v[190:191], v[130:131] op_sel_hi:[1,0,1]
	s_nop 0
	v_mul_f32_e64 v131, |v138|, s34
	v_exp_f32_e32 v173, v131
	v_min_f32_e32 v130, 0, v138
	v_pk_fma_f32 v[132:133], v[80:81], v[190:191], v[132:133] op_sel_hi:[1,0,1]
	v_add_f32_e32 v131, 1.0, v173
	v_add_f32_e32 v138, -1.0, v131
	v_sub_f32_e32 v140, v138, v131
	v_add_f32_e32 v140, 1.0, v140
	v_sub_f32_e32 v138, v173, v138
	v_add_f32_e32 v179, v138, v140
	v_frexp_mant_f32_e32 v138, v131
	v_cvt_f64_f32_e32 v[140:141], v131
	v_cmp_gt_f32_e64 s[12:13], s35, v138
	v_frexp_exp_i32_f64_e32 v138, v[140:141]
	s_nop 0
	v_subbrev_co_u32_e64 v183, s[12:13], 0, v138, s[12:13]
	v_sub_u32_e32 v140, 0, v183
	v_ldexp_f32 v138, v131, v140
	v_min_f32_e32 v131, 0, v139
	v_mul_f32_e64 v139, |v139|, s34
	v_ldexp_f32 v140, v179, v140
	v_exp_f32_e32 v179, v139
	s_nop 0
	v_add_f32_e32 v139, 1.0, v179
	v_add_f32_e32 v141, -1.0, v139
	v_sub_f32_e32 v187, v141, v139
	v_add_f32_e32 v187, 1.0, v187
	v_sub_f32_e32 v141, v179, v141
	v_add_f32_e32 v141, v141, v187
	v_frexp_mant_f32_e32 v187, v139
	v_cvt_f64_f32_e32 v[202:203], v139
	v_cmp_gt_f32_e64 s[12:13], s35, v187
	v_frexp_exp_i32_f64_e32 v187, v[202:203]
	v_cmp_lt_f32_e64 s[14:15], |v179|, s5
	v_subbrev_co_u32_e64 v187, s[12:13], 0, v187, s[12:13]
	v_sub_u32_e32 v191, 0, v187
	v_ldexp_f32 v139, v139, v191
	v_pk_add_f32 v[202:203], v[138:139], 1.0 op_sel_hi:[1,0]
	v_ldexp_f32 v141, v141, v191
	v_pk_add_f32 v[204:205], v[202:203], -1.0 op_sel_hi:[1,0]
	v_pk_add_f32 v[210:211], v[138:139], -1.0 op_sel_hi:[1,0]
	v_pk_add_f32 v[204:205], v[138:139], v[204:205] neg_lo:[0,1] neg_hi:[0,1]
	v_pk_add_f32 v[212:213], v[210:211], 1.0 op_sel_hi:[1,0]
	v_pk_add_f32 v[204:205], v[140:141], v[204:205]
	v_pk_add_f32 v[138:139], v[138:139], v[212:213] neg_lo:[0,1] neg_hi:[0,1]
	v_pk_add_f32 v[206:207], v[202:203], v[204:205]
	v_pk_add_f32 v[138:139], v[140:141], v[138:139]
	v_rcp_f32_e32 v208, v206
	v_rcp_f32_e32 v209, v207
	v_pk_add_f32 v[140:141], v[210:211], v[138:139]
	v_pk_add_f32 v[202:203], v[206:207], v[202:203] neg_lo:[0,1] neg_hi:[0,1]
	v_pk_add_f32 v[210:211], v[140:141], v[210:211] neg_lo:[0,1] neg_hi:[0,1]
	v_pk_add_f32 v[202:203], v[204:205], v[202:203] neg_lo:[0,1] neg_hi:[0,1]
	v_pk_mul_f32 v[204:205], v[140:141], v[208:209]
	v_pk_add_f32 v[138:139], v[138:139], v[210:211] neg_lo:[0,1] neg_hi:[0,1]
	v_pk_mul_f32 v[210:211], v[206:207], v[204:205]
	v_cmp_neq_f32_e64 s[12:13], s4, v173
	v_pk_fma_f32 v[212:213], v[204:205], v[206:207], v[210:211] neg_lo:[0,0,1] neg_hi:[0,0,1]
	s_nop 0
	v_pk_fma_f32 v[212:213], v[204:205], v[202:203], v[212:213]
	s_nop 0
	v_pk_add_f32 v[214:215], v[210:211], v[212:213]
	s_nop 0
	v_pk_add_f32 v[216:217], v[140:141], v[214:215] neg_lo:[0,1] neg_hi:[0,1]
	v_pk_add_f32 v[210:211], v[214:215], v[210:211] neg_lo:[0,1] neg_hi:[0,1]
	v_pk_add_f32 v[140:141], v[140:141], v[216:217] neg_lo:[0,1] neg_hi:[0,1]
	s_nop 0
	v_pk_add_f32 v[140:141], v[140:141], v[214:215] neg_lo:[0,1] neg_hi:[0,1]
	s_nop 0
	v_pk_add_f32 v[138:139], v[138:139], v[140:141]
	v_pk_add_f32 v[140:141], v[210:211], v[212:213] neg_lo:[0,1] neg_hi:[0,1]
	s_nop 0
	v_pk_add_f32 v[138:139], v[140:141], v[138:139]
	s_nop 0
	v_pk_add_f32 v[140:141], v[216:217], v[138:139]
	s_nop 0
	v_pk_mul_f32 v[210:211], v[208:209], v[140:141]
	s_nop 0
	v_pk_mul_f32 v[212:213], v[206:207], v[210:211]
	s_nop 0
	v_pk_fma_f32 v[206:207], v[210:211], v[206:207], v[212:213] neg_lo:[0,0,1] neg_hi:[0,0,1]
	s_nop 0
	v_pk_fma_f32 v[202:203], v[210:211], v[202:203], v[206:207]
	v_pk_add_f32 v[206:207], v[216:217], v[140:141] neg_lo:[0,1] neg_hi:[0,1]
	s_nop 0
	v_pk_add_f32 v[138:139], v[138:139], v[206:207]
	v_pk_add_f32 v[206:207], v[212:213], v[202:203]
	s_nop 0
	v_pk_add_f32 v[214:215], v[140:141], v[206:207] neg_lo:[0,1] neg_hi:[0,1]
	v_pk_add_f32 v[212:213], v[206:207], v[212:213] neg_lo:[0,1] neg_hi:[0,1]
	v_pk_add_f32 v[140:141], v[140:141], v[214:215] neg_lo:[0,1] neg_hi:[0,1]
	s_nop 0
	v_pk_add_f32 v[140:141], v[140:141], v[206:207] neg_lo:[0,1] neg_hi:[0,1]
	s_nop 0
	v_pk_add_f32 v[138:139], v[138:139], v[140:141]
	v_pk_add_f32 v[140:141], v[212:213], v[202:203] neg_lo:[0,1] neg_hi:[0,1]
	s_nop 0
	v_pk_add_f32 v[138:139], v[140:141], v[138:139]
	v_pk_add_f32 v[140:141], v[204:205], v[210:211]
	v_pk_add_f32 v[138:139], v[214:215], v[138:139]
	v_pk_add_f32 v[202:203], v[140:141], v[204:205] neg_lo:[0,1] neg_hi:[0,1]
	v_pk_mul_f32 v[138:139], v[208:209], v[138:139]
	v_pk_add_f32 v[202:203], v[210:211], v[202:203] neg_lo:[0,1] neg_hi:[0,1]
	s_nop 0
	v_pk_add_f32 v[138:139], v[202:203], v[138:139]
	s_nop 0
	v_pk_add_f32 v[204:205], v[140:141], v[138:139]
	s_nop 0
	v_pk_add_f32 v[140:141], v[204:205], v[140:141] neg_lo:[0,1] neg_hi:[0,1]
	v_pk_mul_f32 v[206:207], v[204:205], v[204:205]
	v_pk_add_f32 v[140:141], v[138:139], v[140:141] neg_lo:[0,1] neg_hi:[0,1]
	v_mov_b64_e32 v[138:139], s[50:51]
	v_pk_fma_f32 v[208:209], v[206:207], s[52:53], v[138:139] op_sel_hi:[1,0,0]
	v_ldexp_f32 v202, v204, 1
	v_pk_fma_f32 v[208:209], v[206:207], v[208:209], s[54:55] op_sel_hi:[1,1,0]
	v_ldexp_f32 v203, v205, 1
	v_pk_mul_f32 v[204:205], v[204:205], v[206:207]
	v_cvt_f32_i32_e32 v207, v187
	v_cvt_f32_i32_e32 v206, v183
	v_pk_mul_f32 v[214:215], v[204:205], v[208:209]
	v_ldexp_f32 v213, v141, 1
	v_pk_add_f32 v[204:205], v[202:203], v[214:215]
	v_pk_mul_f32 v[210:211], v[206:207], s[64:65] op_sel_hi:[1,0]
	v_pk_add_f32 v[202:203], v[204:205], v[202:203] neg_lo:[0,1] neg_hi:[0,1]
	v_ldexp_f32 v140, v140, 1
; __device__ __forceinline__ float log_sigmoid_f(float x) { return fminf(x, 0.f) - log1pf(__expf(-fabsf(x))); }
;     __device__ __forceinline__ void operator()(const f32x4 (&acc)[2][2][4][2], const Unit& u, int wr, int wc, int fr, int fq) const {
;     ...
;                         for (int n = 0; n < 2; ++n) { const int c = 8 * fq + 4 * n; const f32x4 bv = *(const f32x4*)(b_f + c); const f32x4 x = acc[ai][0][m][n] * s + bv; f32x4 lf;
;                             lf[0] = log_sigmoid_f(x[0]); lf[1] = log_sigmoid_f(x[1]); lf[2] = log_sigmoid_f(x[2]); lf[3] = log_sigmoid_f(x[3]);
	v_pk_fma_f32 v[208:209], v[206:207], s[64:65], v[210:211] op_sel_hi:[1,0,1] neg_lo:[0,0,1] neg_hi:[0,0,1]
	v_pk_add_f32 v[216:217], v[214:215], v[202:203] neg_lo:[0,1] neg_hi:[0,1]
	v_mov_b32_e32 v141, v213
	v_pk_fma_f32 v[206:207], v[206:207], s[66:67], v[208:209] op_sel_hi:[1,0,1]
	v_pk_add_f32 v[214:215], v[140:141], v[216:217]
	v_mov_b32_e32 v202, v210
	v_mov_b32_e32 v203, v217
	v_mov_b32_e32 v212, v206
	v_mov_b32_e32 v141, v215
	v_mov_b32_e32 v217, v205
	v_pk_add_f32 v[208:209], v[210:211], v[206:207]
	v_pk_add_f32 v[202:203], v[202:203], v[212:213]
	v_pk_add_f32 v[212:213], v[140:141], v[216:217]
	v_pk_add_f32 v[216:217], v[204:205], v[214:215]
	v_mov_b32_e32 v224, v204
	v_pk_add_f32 v[140:141], v[208:209], v[216:217]
	v_mov_b32_e32 v222, v216
	v_mov_b32_e32 v223, v141
	v_mov_b32_e32 v225, v209
	v_pk_add_f32 v[222:223], v[222:223], v[224:225] neg_lo:[0,1] neg_hi:[0,1]
	v_mov_b32_e32 v218, v140
	v_mov_b32_e32 v219, v209
	v_mov_b32_e32 v220, v208
	v_mov_b32_e32 v221, v211
	v_mov_b32_e32 v224, v208
	v_mov_b32_e32 v225, v141
	v_mov_b32_e32 v211, v223
	v_pk_add_f32 v[218:219], v[218:219], v[220:221] neg_lo:[0,1] neg_hi:[0,1]
	v_mov_b32_e32 v220, v216
	v_mov_b32_e32 v221, v207
	v_pk_add_f32 v[210:211], v[224:225], v[210:211] neg_lo:[0,1] neg_hi:[0,1]
	v_pk_add_f32 v[220:221], v[220:221], v[218:219] neg_lo:[0,1] neg_hi:[0,1]
	v_mov_b32_e32 v224, v210
	v_mov_b32_e32 v225, v219
	v_mov_b32_e32 v226, v140
	v_mov_b32_e32 v227, v217
	v_mov_b32_e32 v219, v205
	v_pk_add_f32 v[224:225], v[206:207], v[224:225] neg_lo:[0,1] neg_hi:[0,1]
	v_pk_add_f32 v[218:219], v[226:227], v[218:219] neg_lo:[0,1] neg_hi:[0,1]
	v_mov_b32_e32 v207, v209
	v_pk_add_f32 v[202:203], v[202:203], v[218:219] neg_lo:[0,1] neg_hi:[0,1]
	v_pk_add_f32 v[206:207], v[206:207], v[210:211] neg_lo:[0,1] neg_hi:[0,1]
	v_pk_add_f32 v[208:209], v[212:213], v[222:223] neg_lo:[0,1] neg_hi:[0,1]
	v_pk_add_f32 v[212:213], v[220:221], v[202:203]
	v_pk_add_f32 v[210:211], v[208:209], v[206:207]
	v_mov_b32_e32 v207, v221
	v_mov_b32_e32 v209, v203
	v_pk_add_f32 v[202:203], v[206:207], v[208:209]
	v_pk_add_f32 v[204:205], v[216:217], v[204:205] neg_lo:[0,1] neg_hi:[0,1]
	v_pk_add_f32 v[202:203], v[202:203], v[224:225] neg_lo:[0,1] neg_hi:[0,1]
	v_mov_b32_e32 v208, v210
	v_mov_b32_e32 v209, v213
	v_pk_add_f32 v[204:205], v[214:215], v[204:205] neg_lo:[0,1] neg_hi:[0,1]
	v_pk_add_f32 v[208:209], v[208:209], v[202:203] neg_lo:[0,1] neg_hi:[0,1]
	v_pk_add_f32 v[202:203], v[204:205], v[202:203] neg_lo:[0,1] neg_hi:[0,1]
	v_pk_add_f32 v[206:207], v[206:207], v[208:209] neg_lo:[0,1] neg_hi:[0,1]
	v_pk_add_f32 v[204:205], v[212:213], v[210:211]
	v_pk_add_f32 v[202:203], v[202:203], v[206:207]
	v_pk_add_f32 v[206:207], v[140:141], v[204:205]
	s_nop 0
	v_pk_add_f32 v[140:141], v[206:207], v[140:141] neg_lo:[0,1] neg_hi:[0,1]
	s_nop 0
	v_pk_add_f32 v[140:141], v[204:205], v[140:141] neg_lo:[0,1] neg_hi:[0,1]
	s_nop 0
	v_pk_add_f32 v[140:141], v[202:203], v[140:141]
	s_nop 0
	v_pk_add_f32 v[140:141], v[206:207], v[140:141]
	s_nop 0
	v_cndmask_b32_e64 v140, v231, v140, s[12:13]
	v_cmp_neq_f32_e64 s[12:13], s4, v179
	s_nop 1
	v_cndmask_b32_e64 v141, v231, v141, s[12:13]
	v_cmp_ngt_f32_e64 s[12:13], -1.0, v179
	s_nop 1
	v_cndmask_b32_e64 v141, v232, v141, s[12:13]
	v_cmp_ngt_f32_e64 s[12:13], -1.0, v173
	s_nop 1
	v_cndmask_b32_e64 v140, v232, v140, s[12:13]
	v_cmp_neq_f32_e64 s[12:13], -1.0, v173
	s_nop 1
	v_cndmask_b32_e64 v140, v233, v140, s[12:13]
	v_cmp_neq_f32_e64 s[12:13], -1.0, v179
	s_nop 1
	v_cndmask_b32_e64 v141, v233, v141, s[12:13]
	v_cmp_lt_f32_e64 s[12:13], |v173|, s5
	v_cndmask_b32_e64 v141, v141, v179, s[14:15]
	s_nop 0
	v_cndmask_b32_e64 v140, v140, v173, s[12:13]
	v_pk_add_f32 v[130:131], v[130:131], v[140:141] neg_lo:[0,1] neg_hi:[0,1]
	v_min_f32_e32 v140, 0, v132
	v_mul_f32_e64 v132, |v132|, s34
	v_exp_f32_e32 v173, v132
	s_nop 0
	v_add_f32_e32 v132, 1.0, v173
	v_add_f32_e32 v141, -1.0, v132
	v_sub_f32_e32 v179, v141, v132
	v_add_f32_e32 v179, 1.0, v179
	v_sub_f32_e32 v141, v173, v141
	v_add_f32_e32 v141, v141, v179
	v_frexp_mant_f32_e32 v179, v132
	v_cvt_f64_f32_e32 v[202:203], v132
	v_cmp_gt_f32_e64 s[12:13], s35, v179
	v_frexp_exp_i32_f64_e32 v179, v[202:203]
	s_nop 0
	v_subbrev_co_u32_e64 v179, s[12:13], 0, v179, s[12:13]
	v_sub_u32_e32 v183, 0, v179
	v_ldexp_f32 v202, v141, v183
	v_min_f32_e32 v141, 0, v133
	v_mul_f32_e64 v133, |v133|, s34
	v_ldexp_f32 v132, v132, v183
	v_exp_f32_e32 v183, v133
	s_nop 0
	v_add_f32_e32 v133, 1.0, v183
	v_add_f32_e32 v187, -1.0, v133
	v_sub_f32_e32 v191, v187, v133
	v_add_f32_e32 v191, 1.0, v191
	v_sub_f32_e32 v187, v183, v187
	v_add_f32_e32 v187, v187, v191
	v_frexp_mant_f32_e32 v191, v133
	v_cvt_f64_f32_e32 v[204:205], v133
	v_cmp_gt_f32_e64 s[12:13], s35, v191
	v_frexp_exp_i32_f64_e32 v191, v[204:205]
	v_cmp_lt_f32_e64 s[14:15], |v183|, s5
	v_subbrev_co_u32_e64 v191, s[12:13], 0, v191, s[12:13]
	v_sub_u32_e32 v195, 0, v191
	v_ldexp_f32 v133, v133, v195
	v_pk_add_f32 v[204:205], v[132:133], 1.0 op_sel_hi:[1,0]
	v_ldexp_f32 v203, v187, v195
	v_pk_add_f32 v[206:207], v[204:205], -1.0 op_sel_hi:[1,0]
	v_pk_add_f32 v[212:213], v[132:133], -1.0 op_sel_hi:[1,0]
	v_pk_add_f32 v[206:207], v[132:133], v[206:207] neg_lo:[0,1] neg_hi:[0,1]
	v_pk_add_f32 v[214:215], v[212:213], 1.0 op_sel_hi:[1,0]
	v_pk_add_f32 v[206:207], v[202:203], v[206:207]
	v_pk_add_f32 v[132:133], v[132:133], v[214:215] neg_lo:[0,1] neg_hi:[0,1]
	v_pk_add_f32 v[208:209], v[204:205], v[206:207]
	v_pk_add_f32 v[132:133], v[202:203], v[132:133]
	v_rcp_f32_e32 v210, v208
	v_rcp_f32_e32 v211, v209
	v_pk_add_f32 v[202:203], v[212:213], v[132:133]
	v_pk_add_f32 v[204:205], v[208:209], v[204:205] neg_lo:[0,1] neg_hi:[0,1]
; __device__ __forceinline__ float log_sigmoid_f(float x) { return fminf(x, 0.f) - log1pf(__expf(-fabsf(x))); }
;     __device__ __forceinline__ void operator()(const f32x4 (&acc)[2][2][4][2], const Unit& u, int wr, int wc, int fr, int fq) const {
;     ...
;                         for (int n = 0; n < 2; ++n) { const int c = 8 * fq + 4 * n; const f32x4 bv = *(const f32x4*)(b_f + c); const f32x4 x = acc[ai][0][m][n] * s + bv; f32x4 lf;
;                             lf[0] = log_sigmoid_f(x[0]); lf[1] = log_sigmoid_f(x[1]); lf[2] = log_sigmoid_f(x[2]); lf[3] = log_sigmoid_f(x[3]);
	v_pk_add_f32 v[212:213], v[202:203], v[212:213] neg_lo:[0,1] neg_hi:[0,1]
	v_pk_add_f32 v[204:205], v[206:207], v[204:205] neg_lo:[0,1] neg_hi:[0,1]
	v_pk_mul_f32 v[206:207], v[202:203], v[210:211]
	v_pk_add_f32 v[132:133], v[132:133], v[212:213] neg_lo:[0,1] neg_hi:[0,1]
	v_pk_mul_f32 v[212:213], v[208:209], v[206:207]
	v_cmp_neq_f32_e64 s[12:13], s4, v173
	v_pk_fma_f32 v[214:215], v[206:207], v[208:209], v[212:213] neg_lo:[0,0,1] neg_hi:[0,0,1]
	s_nop 0
	v_pk_fma_f32 v[214:215], v[206:207], v[204:205], v[214:215]
	s_nop 0
	v_pk_add_f32 v[216:217], v[212:213], v[214:215]
	s_nop 0
	v_pk_add_f32 v[218:219], v[202:203], v[216:217] neg_lo:[0,1] neg_hi:[0,1]
	v_pk_add_f32 v[212:213], v[216:217], v[212:213] neg_lo:[0,1] neg_hi:[0,1]
	v_pk_add_f32 v[202:203], v[202:203], v[218:219] neg_lo:[0,1] neg_hi:[0,1]
	s_nop 0
	v_pk_add_f32 v[202:203], v[202:203], v[216:217] neg_lo:[0,1] neg_hi:[0,1]
	s_nop 0
	v_pk_add_f32 v[132:133], v[132:133], v[202:203]
	v_pk_add_f32 v[202:203], v[212:213], v[214:215] neg_lo:[0,1] neg_hi:[0,1]
	s_nop 0
	v_pk_add_f32 v[132:133], v[202:203], v[132:133]
	s_nop 0
	v_pk_add_f32 v[202:203], v[218:219], v[132:133]
	s_nop 0
	v_pk_mul_f32 v[212:213], v[210:211], v[202:203]
	s_nop 0
	v_pk_mul_f32 v[214:215], v[208:209], v[212:213]
	s_nop 0
	v_pk_fma_f32 v[208:209], v[212:213], v[208:209], v[214:215] neg_lo:[0,0,1] neg_hi:[0,0,1]
	s_nop 0
	v_pk_fma_f32 v[204:205], v[212:213], v[204:205], v[208:209]
	v_pk_add_f32 v[208:209], v[218:219], v[202:203] neg_lo:[0,1] neg_hi:[0,1]
	s_nop 0
	v_pk_add_f32 v[132:133], v[132:133], v[208:209]
	v_pk_add_f32 v[208:209], v[214:215], v[204:205]
	s_nop 0
	v_pk_add_f32 v[216:217], v[202:203], v[208:209] neg_lo:[0,1] neg_hi:[0,1]
	v_pk_add_f32 v[214:215], v[208:209], v[214:215] neg_lo:[0,1] neg_hi:[0,1]
	v_pk_add_f32 v[202:203], v[202:203], v[216:217] neg_lo:[0,1] neg_hi:[0,1]
	s_nop 0
	v_pk_add_f32 v[202:203], v[202:203], v[208:209] neg_lo:[0,1] neg_hi:[0,1]
	s_nop 0
	v_pk_add_f32 v[132:133], v[132:133], v[202:203]
	v_pk_add_f32 v[202:203], v[214:215], v[204:205] neg_lo:[0,1] neg_hi:[0,1]
	s_nop 0
	v_pk_add_f32 v[132:133], v[202:203], v[132:133]
	v_pk_add_f32 v[202:203], v[206:207], v[212:213]
	v_pk_add_f32 v[132:133], v[216:217], v[132:133]
	v_pk_add_f32 v[204:205], v[202:203], v[206:207] neg_lo:[0,1] neg_hi:[0,1]
	v_pk_mul_f32 v[132:133], v[210:211], v[132:133]
	v_pk_add_f32 v[204:205], v[212:213], v[204:205] neg_lo:[0,1] neg_hi:[0,1]
	s_nop 0
	v_pk_add_f32 v[132:133], v[204:205], v[132:133]
	s_nop 0
	v_pk_add_f32 v[204:205], v[202:203], v[132:133]
	s_nop 0
	v_pk_mul_f32 v[206:207], v[204:205], v[204:205]
	v_pk_add_f32 v[202:203], v[204:205], v[202:203] neg_lo:[0,1] neg_hi:[0,1]
	v_pk_fma_f32 v[138:139], v[206:207], s[52:53], v[138:139] op_sel_hi:[1,0,0]
	v_pk_add_f32 v[132:133], v[132:133], v[202:203] neg_lo:[0,1] neg_hi:[0,1]
	v_ldexp_f32 v202, v204, 1
	v_pk_fma_f32 v[138:139], v[206:207], v[138:139], s[54:55] op_sel_hi:[1,1,0]
	v_ldexp_f32 v203, v205, 1
	v_pk_mul_f32 v[204:205], v[204:205], v[206:207]
	v_cvt_f32_i32_e32 v207, v191
	v_cvt_f32_i32_e32 v206, v179
	v_pk_mul_f32 v[138:139], v[204:205], v[138:139]
	v_ldexp_f32 v209, v133, 1
	v_pk_add_f32 v[204:205], v[202:203], v[138:139]
	v_pk_mul_f32 v[210:211], v[206:207], s[64:65] op_sel_hi:[1,0]
	v_pk_add_f32 v[202:203], v[204:205], v[202:203] neg_lo:[0,1] neg_hi:[0,1]
	v_pk_fma_f32 v[212:213], v[206:207], s[64:65], v[210:211] op_sel_hi:[1,0,1] neg_lo:[0,0,1] neg_hi:[0,0,1]
	v_pk_add_f32 v[138:139], v[138:139], v[202:203] neg_lo:[0,1] neg_hi:[0,1]
	v_pk_fma_f32 v[206:207], v[206:207], s[66:67], v[212:213] op_sel_hi:[1,0,1]
	v_ldexp_f32 v132, v132, 1
	v_mov_b32_e32 v202, v210
	v_mov_b32_e32 v203, v139
	v_mov_b32_e32 v208, v206
	v_mov_b32_e32 v133, v209
	v_pk_add_f32 v[202:203], v[202:203], v[208:209]
	v_pk_add_f32 v[208:209], v[132:133], v[138:139]
	v_mov_b32_e32 v139, v205
	v_mov_b32_e32 v133, v209
	v_pk_add_f32 v[212:213], v[210:211], v[206:207]
	v_pk_add_f32 v[132:133], v[132:133], v[138:139]
	v_pk_add_f32 v[138:139], v[204:205], v[208:209]
	v_mov_b32_e32 v222, v204
	v_pk_add_f32 v[214:215], v[212:213], v[138:139]
	v_mov_b32_e32 v220, v138
	v_mov_b32_e32 v221, v215
	v_mov_b32_e32 v223, v213
	v_pk_add_f32 v[220:221], v[220:221], v[222:223] neg_lo:[0,1] neg_hi:[0,1]
	v_mov_b32_e32 v216, v214
	v_mov_b32_e32 v217, v213
	v_mov_b32_e32 v218, v212
	v_mov_b32_e32 v219, v211
	v_mov_b32_e32 v222, v212
	v_mov_b32_e32 v223, v215
	v_mov_b32_e32 v211, v221
	v_pk_add_f32 v[216:217], v[216:217], v[218:219] neg_lo:[0,1] neg_hi:[0,1]
	v_mov_b32_e32 v218, v138
	v_mov_b32_e32 v219, v207
	v_pk_add_f32 v[210:211], v[222:223], v[210:211] neg_lo:[0,1] neg_hi:[0,1]
	v_pk_add_f32 v[218:219], v[218:219], v[216:217] neg_lo:[0,1] neg_hi:[0,1]
	v_mov_b32_e32 v222, v210
	v_mov_b32_e32 v223, v217
	v_mov_b32_e32 v224, v214
	v_mov_b32_e32 v225, v139
	v_mov_b32_e32 v217, v205
	v_pk_add_f32 v[222:223], v[206:207], v[222:223] neg_lo:[0,1] neg_hi:[0,1]
	v_pk_add_f32 v[216:217], v[224:225], v[216:217] neg_lo:[0,1] neg_hi:[0,1]
	v_mov_b32_e32 v207, v213
	v_pk_add_f32 v[138:139], v[138:139], v[204:205] neg_lo:[0,1] neg_hi:[0,1]
	v_pk_add_f32 v[202:203], v[202:203], v[216:217] neg_lo:[0,1] neg_hi:[0,1]
	v_pk_add_f32 v[204:205], v[206:207], v[210:211] neg_lo:[0,1] neg_hi:[0,1]
	v_pk_add_f32 v[132:133], v[132:133], v[220:221] neg_lo:[0,1] neg_hi:[0,1]
	v_pk_add_f32 v[138:139], v[208:209], v[138:139] neg_lo:[0,1] neg_hi:[0,1]
	v_pk_add_f32 v[206:207], v[132:133], v[204:205]
	v_mov_b32_e32 v205, v219
	v_mov_b32_e32 v133, v203
	v_pk_add_f32 v[208:209], v[218:219], v[202:203]
	v_pk_add_f32 v[132:133], v[204:205], v[132:133]
	v_mov_b32_e32 v202, v206
; __device__ __forceinline__ float log_sigmoid_f(float x) { return fminf(x, 0.f) - log1pf(__expf(-fabsf(x))); }
;     __device__ __forceinline__ void operator()(const f32x4 (&acc)[2][2][4][2], const Unit& u, int wr, int wc, int fr, int fq) const {
;     ...
;                         for (int n = 0; n < 2; ++n) { const int c = 8 * fq + 4 * n; const f32x4 bv = *(const f32x4*)(b_f + c); const f32x4 x = acc[ai][0][m][n] * s + bv; f32x4 lf;
;                             lf[0] = log_sigmoid_f(x[0]); lf[1] = log_sigmoid_f(x[1]); lf[2] = log_sigmoid_f(x[2]); lf[3] = log_sigmoid_f(x[3]);
;                             *(f32x4*)(LF + (size_t)row * 16 + c) = lf; if (dst) *(f32x4*)(dst + c) = lf; } }
	v_pk_add_f32 v[132:133], v[132:133], v[222:223] neg_lo:[0,1] neg_hi:[0,1]
	v_mov_b32_e32 v203, v209
	v_pk_add_f32 v[202:203], v[202:203], v[132:133] neg_lo:[0,1] neg_hi:[0,1]
	v_pk_add_f32 v[132:133], v[138:139], v[132:133] neg_lo:[0,1] neg_hi:[0,1]
	v_pk_add_f32 v[202:203], v[204:205], v[202:203] neg_lo:[0,1] neg_hi:[0,1]
	v_pk_add_f32 v[138:139], v[208:209], v[206:207]
	v_pk_add_f32 v[132:133], v[132:133], v[202:203]
	v_pk_add_f32 v[202:203], v[214:215], v[138:139]
	s_nop 0
	v_pk_add_f32 v[204:205], v[202:203], v[214:215] neg_lo:[0,1] neg_hi:[0,1]
	s_nop 0
	v_pk_add_f32 v[138:139], v[138:139], v[204:205] neg_lo:[0,1] neg_hi:[0,1]
	s_nop 0
	v_pk_add_f32 v[132:133], v[132:133], v[138:139]
	s_nop 0
	v_pk_add_f32 v[132:133], v[202:203], v[132:133]
	s_nop 0
	v_cndmask_b32_e64 v132, v231, v132, s[12:13]
	v_cmp_neq_f32_e64 s[12:13], s4, v183
	s_nop 1
	v_cndmask_b32_e64 v133, v231, v133, s[12:13]
	v_cmp_ngt_f32_e64 s[12:13], -1.0, v183
	s_nop 1
	v_cndmask_b32_e64 v133, v232, v133, s[12:13]
	v_cmp_ngt_f32_e64 s[12:13], -1.0, v173
	s_nop 1
	v_cndmask_b32_e64 v132, v232, v132, s[12:13]
	v_cmp_neq_f32_e64 s[12:13], -1.0, v173
	s_nop 1
	v_cndmask_b32_e64 v132, v233, v132, s[12:13]
	v_cmp_neq_f32_e64 s[12:13], -1.0, v183
	s_nop 1
	v_cndmask_b32_e64 v133, v233, v133, s[12:13]
	v_cmp_lt_f32_e64 s[12:13], |v173|, s5
	v_cndmask_b32_e64 v133, v133, v183, s[14:15]
	s_nop 0
	v_cndmask_b32_e64 v132, v132, v173, s[12:13]
	v_pk_add_f32 v[132:133], v[140:141], v[132:133] neg_lo:[0,1] neg_hi:[0,1]
	global_store_dwordx4 v[136:137], v[130:133], off nt
	s_and_saveexec_b64 s[12:13], vcc
	s_cbranch_execz .LBB0_398
	v_lshl_add_u64 v[138:139], v[134:135], 0, v[150:151]
	global_store_dwordx4 v[138:139], v[130:133], off nt
.LBB0_398:
	s_or_b64 exec, exec, s[12:13]
	global_load_dwordx4 v[130:133], v[158:159], off offset:16
	v_mov_b32_e32 v191, v190
	v_mov_b32_e32 v138, v190
	v_mov_b32_e32 v139, v190
	s_waitcnt vmcnt(0)
	v_pk_fma_f32 v[132:133], v[76:77], v[138:139], v[132:133]
	v_pk_fma_f32 v[138:139], v[74:75], v[190:191], v[130:131]
	s_nop 0
	v_mul_f32_e64 v131, |v138|, s34
	v_exp_f32_e32 v173, v131
	v_min_f32_e32 v130, 0, v138
	v_add_f32_e32 v131, 1.0, v173
	v_add_f32_e32 v138, -1.0, v131
	v_sub_f32_e32 v140, v138, v131
	v_add_f32_e32 v140, 1.0, v140
	v_sub_f32_e32 v138, v173, v138
	v_add_f32_e32 v179, v138, v140
	v_frexp_mant_f32_e32 v138, v131
	v_cvt_f64_f32_e32 v[140:141], v131
	v_cmp_gt_f32_e64 s[12:13], s35, v138
	v_frexp_exp_i32_f64_e32 v138, v[140:141]
	s_nop 0
	v_subbrev_co_u32_e64 v183, s[12:13], 0, v138, s[12:13]
	v_sub_u32_e32 v140, 0, v183
	v_ldexp_f32 v138, v131, v140
	v_min_f32_e32 v131, 0, v139
	v_mul_f32_e64 v139, |v139|, s34
	v_ldexp_f32 v140, v179, v140
	v_exp_f32_e32 v179, v139
	s_nop 0
	v_add_f32_e32 v139, 1.0, v179
	v_add_f32_e32 v141, -1.0, v139
	v_sub_f32_e32 v187, v141, v139
	v_add_f32_e32 v187, 1.0, v187
	v_sub_f32_e32 v141, v179, v141
	v_add_f32_e32 v141, v141, v187
	v_frexp_mant_f32_e32 v187, v139
	v_cvt_f64_f32_e32 v[202:203], v139
	v_cmp_gt_f32_e64 s[12:13], s35, v187
	v_frexp_exp_i32_f64_e32 v187, v[202:203]
	v_cmp_lt_f32_e64 s[14:15], |v179|, s5
	v_subbrev_co_u32_e64 v187, s[12:13], 0, v187, s[12:13]
	v_sub_u32_e32 v191, 0, v187
	v_ldexp_f32 v139, v139, v191
	v_pk_add_f32 v[202:203], v[138:139], 1.0 op_sel_hi:[1,0]
	v_ldexp_f32 v141, v141, v191
	v_pk_add_f32 v[204:205], v[202:203], -1.0 op_sel_hi:[1,0]
	v_pk_add_f32 v[210:211], v[138:139], -1.0 op_sel_hi:[1,0]
	v_pk_add_f32 v[204:205], v[138:139], v[204:205] neg_lo:[0,1] neg_hi:[0,1]
	v_pk_add_f32 v[212:213], v[210:211], 1.0 op_sel_hi:[1,0]
	v_pk_add_f32 v[204:205], v[140:141], v[204:205]
	v_pk_add_f32 v[138:139], v[138:139], v[212:213] neg_lo:[0,1] neg_hi:[0,1]
	v_pk_add_f32 v[206:207], v[202:203], v[204:205]
	v_pk_add_f32 v[138:139], v[140:141], v[138:139]
	v_rcp_f32_e32 v208, v206
	v_rcp_f32_e32 v209, v207
	v_pk_add_f32 v[140:141], v[210:211], v[138:139]
	v_pk_add_f32 v[202:203], v[206:207], v[202:203] neg_lo:[0,1] neg_hi:[0,1]
	v_pk_add_f32 v[210:211], v[140:141], v[210:211] neg_lo:[0,1] neg_hi:[0,1]
	v_pk_add_f32 v[202:203], v[204:205], v[202:203] neg_lo:[0,1] neg_hi:[0,1]
	v_pk_mul_f32 v[204:205], v[140:141], v[208:209]
	v_pk_add_f32 v[138:139], v[138:139], v[210:211] neg_lo:[0,1] neg_hi:[0,1]
	v_pk_mul_f32 v[210:211], v[206:207], v[204:205]
	v_cmp_neq_f32_e64 s[12:13], s4, v173
	v_pk_fma_f32 v[212:213], v[204:205], v[206:207], v[210:211] neg_lo:[0,0,1] neg_hi:[0,0,1]
	s_nop 0
	v_pk_fma_f32 v[212:213], v[204:205], v[202:203], v[212:213]
	s_nop 0
	v_pk_add_f32 v[214:215], v[210:211], v[212:213]
	s_nop 0
	v_pk_add_f32 v[216:217], v[140:141], v[214:215] neg_lo:[0,1] neg_hi:[0,1]
	v_pk_add_f32 v[210:211], v[214:215], v[210:211] neg_lo:[0,1] neg_hi:[0,1]
	v_pk_add_f32 v[140:141], v[140:141], v[216:217] neg_lo:[0,1] neg_hi:[0,1]
	s_nop 0
	v_pk_add_f32 v[140:141], v[140:141], v[214:215] neg_lo:[0,1] neg_hi:[0,1]
	s_nop 0
	v_pk_add_f32 v[138:139], v[138:139], v[140:141]
	v_pk_add_f32 v[140:141], v[210:211], v[212:213] neg_lo:[0,1] neg_hi:[0,1]
	s_nop 0
	v_pk_add_f32 v[138:139], v[140:141], v[138:139]
	s_nop 0
	v_pk_add_f32 v[140:141], v[216:217], v[138:139]
	s_nop 0
	v_pk_mul_f32 v[210:211], v[208:209], v[140:141]
	s_nop 0
	v_pk_mul_f32 v[212:213], v[206:207], v[210:211]
	s_nop 0
	v_pk_fma_f32 v[206:207], v[210:211], v[206:207], v[212:213] neg_lo:[0,0,1] neg_hi:[0,0,1]
	s_nop 0
	v_pk_fma_f32 v[202:203], v[210:211], v[202:203], v[206:207]
	v_pk_add_f32 v[206:207], v[216:217], v[140:141] neg_lo:[0,1] neg_hi:[0,1]
	s_nop 0
	v_pk_add_f32 v[138:139], v[138:139], v[206:207]
	v_pk_add_f32 v[206:207], v[212:213], v[202:203]
	s_nop 0
	v_pk_add_f32 v[214:215], v[140:141], v[206:207] neg_lo:[0,1] neg_hi:[0,1]
; __device__ __forceinline__ float log_sigmoid_f(float x) { return fminf(x, 0.f) - log1pf(__expf(-fabsf(x))); }
;     __device__ __forceinline__ void operator()(const f32x4 (&acc)[2][2][4][2], const Unit& u, int wr, int wc, int fr, int fq) const {
;     ...
;                         for (int n = 0; n < 2; ++n) { const int c = 8 * fq + 4 * n; const f32x4 bv = *(const f32x4*)(b_f + c); const f32x4 x = acc[ai][0][m][n] * s + bv; f32x4 lf;
;                             lf[0] = log_sigmoid_f(x[0]); lf[1] = log_sigmoid_f(x[1]); lf[2] = log_sigmoid_f(x[2]); lf[3] = log_sigmoid_f(x[3]);
	v_pk_add_f32 v[212:213], v[206:207], v[212:213] neg_lo:[0,1] neg_hi:[0,1]
	v_pk_add_f32 v[140:141], v[140:141], v[214:215] neg_lo:[0,1] neg_hi:[0,1]
	s_nop 0
	v_pk_add_f32 v[140:141], v[140:141], v[206:207] neg_lo:[0,1] neg_hi:[0,1]
	s_nop 0
	v_pk_add_f32 v[138:139], v[138:139], v[140:141]
	v_pk_add_f32 v[140:141], v[212:213], v[202:203] neg_lo:[0,1] neg_hi:[0,1]
	s_nop 0
	v_pk_add_f32 v[138:139], v[140:141], v[138:139]
	v_pk_add_f32 v[140:141], v[204:205], v[210:211]
	v_pk_add_f32 v[138:139], v[214:215], v[138:139]
	v_pk_add_f32 v[202:203], v[140:141], v[204:205] neg_lo:[0,1] neg_hi:[0,1]
	v_pk_mul_f32 v[138:139], v[208:209], v[138:139]
	v_pk_add_f32 v[202:203], v[210:211], v[202:203] neg_lo:[0,1] neg_hi:[0,1]
	v_cvt_f32_i32_e32 v211, v187
	v_pk_add_f32 v[138:139], v[202:203], v[138:139]
	v_cvt_f32_i32_e32 v210, v183
	v_pk_add_f32 v[204:205], v[140:141], v[138:139]
	s_nop 0
	v_pk_add_f32 v[140:141], v[204:205], v[140:141] neg_lo:[0,1] neg_hi:[0,1]
	v_pk_mul_f32 v[206:207], v[204:205], v[204:205]
	v_pk_add_f32 v[140:141], v[138:139], v[140:141] neg_lo:[0,1] neg_hi:[0,1]
	v_mov_b64_e32 v[138:139], s[50:51]
	v_pk_fma_f32 v[208:209], v[206:207], s[52:53], v[138:139] op_sel_hi:[1,0,0]
	v_ldexp_f32 v202, v204, 1
	v_pk_fma_f32 v[208:209], v[206:207], v[208:209], s[54:55] op_sel_hi:[1,1,0]
	v_ldexp_f32 v203, v205, 1
	v_pk_mul_f32 v[204:205], v[204:205], v[206:207]
	v_ldexp_f32 v213, v141, 1
	v_pk_mul_f32 v[214:215], v[204:205], v[208:209]
	v_pk_mul_f32 v[206:207], v[210:211], s[64:65] op_sel_hi:[1,0]
	v_pk_add_f32 v[204:205], v[202:203], v[214:215]
	v_ldexp_f32 v140, v140, 1
	v_pk_add_f32 v[202:203], v[204:205], v[202:203] neg_lo:[0,1] neg_hi:[0,1]
	v_pk_fma_f32 v[208:209], v[210:211], s[64:65], v[206:207] op_sel_hi:[1,0,1] neg_lo:[0,0,1] neg_hi:[0,0,1]
	v_pk_add_f32 v[216:217], v[214:215], v[202:203] neg_lo:[0,1] neg_hi:[0,1]
	v_mov_b32_e32 v141, v213
	v_pk_fma_f32 v[208:209], v[210:211], s[66:67], v[208:209] op_sel_hi:[1,0,1]
	v_pk_add_f32 v[214:215], v[140:141], v[216:217]
	v_mov_b32_e32 v202, v206
	v_mov_b32_e32 v203, v217
	v_mov_b32_e32 v212, v208
	v_mov_b32_e32 v141, v215
	v_mov_b32_e32 v217, v205
	v_pk_add_f32 v[210:211], v[206:207], v[208:209]
	v_pk_add_f32 v[202:203], v[202:203], v[212:213]
	v_pk_add_f32 v[212:213], v[140:141], v[216:217]
	v_pk_add_f32 v[216:217], v[204:205], v[214:215]
	v_mov_b32_e32 v224, v204
	v_pk_add_f32 v[140:141], v[210:211], v[216:217]
	v_mov_b32_e32 v222, v216
	v_mov_b32_e32 v223, v141
	v_mov_b32_e32 v225, v211
	v_pk_add_f32 v[222:223], v[222:223], v[224:225] neg_lo:[0,1] neg_hi:[0,1]
	v_mov_b32_e32 v218, v140
	v_mov_b32_e32 v219, v211
	v_mov_b32_e32 v220, v210
	v_mov_b32_e32 v221, v207
	v_mov_b32_e32 v224, v210
	v_mov_b32_e32 v225, v141
	v_mov_b32_e32 v207, v223
	v_pk_add_f32 v[218:219], v[218:219], v[220:221] neg_lo:[0,1] neg_hi:[0,1]
	v_mov_b32_e32 v220, v216
	v_mov_b32_e32 v221, v209
	v_pk_add_f32 v[206:207], v[224:225], v[206:207] neg_lo:[0,1] neg_hi:[0,1]
	v_pk_add_f32 v[220:221], v[220:221], v[218:219] neg_lo:[0,1] neg_hi:[0,1]
	v_mov_b32_e32 v224, v206
	v_mov_b32_e32 v225, v219
	v_mov_b32_e32 v226, v140
	v_mov_b32_e32 v227, v217
	v_mov_b32_e32 v219, v205
	v_pk_add_f32 v[224:225], v[208:209], v[224:225] neg_lo:[0,1] neg_hi:[0,1]
	v_pk_add_f32 v[218:219], v[226:227], v[218:219] neg_lo:[0,1] neg_hi:[0,1]
	v_mov_b32_e32 v209, v211
	v_pk_add_f32 v[202:203], v[202:203], v[218:219] neg_lo:[0,1] neg_hi:[0,1]
	v_pk_add_f32 v[206:207], v[208:209], v[206:207] neg_lo:[0,1] neg_hi:[0,1]
	v_pk_add_f32 v[208:209], v[212:213], v[222:223] neg_lo:[0,1] neg_hi:[0,1]
	v_pk_add_f32 v[212:213], v[220:221], v[202:203]
	v_pk_add_f32 v[210:211], v[208:209], v[206:207]
	v_mov_b32_e32 v207, v221
	v_mov_b32_e32 v209, v203
	v_pk_add_f32 v[202:203], v[206:207], v[208:209]
	v_pk_add_f32 v[204:205], v[216:217], v[204:205] neg_lo:[0,1] neg_hi:[0,1]
	v_pk_add_f32 v[202:203], v[202:203], v[224:225] neg_lo:[0,1] neg_hi:[0,1]
	v_mov_b32_e32 v208, v210
	v_mov_b32_e32 v209, v213
	v_pk_add_f32 v[204:205], v[214:215], v[204:205] neg_lo:[0,1] neg_hi:[0,1]
	v_pk_add_f32 v[208:209], v[208:209], v[202:203] neg_lo:[0,1] neg_hi:[0,1]
	v_pk_add_f32 v[202:203], v[204:205], v[202:203] neg_lo:[0,1] neg_hi:[0,1]
	v_pk_add_f32 v[206:207], v[206:207], v[208:209] neg_lo:[0,1] neg_hi:[0,1]
	v_pk_add_f32 v[204:205], v[212:213], v[210:211]
	v_pk_add_f32 v[202:203], v[202:203], v[206:207]
	v_pk_add_f32 v[206:207], v[140:141], v[204:205]
	s_nop 0
	v_pk_add_f32 v[140:141], v[206:207], v[140:141] neg_lo:[0,1] neg_hi:[0,1]
	s_nop 0
	v_pk_add_f32 v[140:141], v[204:205], v[140:141] neg_lo:[0,1] neg_hi:[0,1]
	s_nop 0
	v_pk_add_f32 v[140:141], v[202:203], v[140:141]
	s_nop 0
	v_pk_add_f32 v[140:141], v[206:207], v[140:141]
	s_nop 0
	v_cndmask_b32_e64 v140, v231, v140, s[12:13]
	v_cmp_neq_f32_e64 s[12:13], s4, v179
	s_nop 1
	v_cndmask_b32_e64 v141, v231, v141, s[12:13]
	v_cmp_ngt_f32_e64 s[12:13], -1.0, v179
	s_nop 1
	v_cndmask_b32_e64 v141, v232, v141, s[12:13]
	v_cmp_ngt_f32_e64 s[12:13], -1.0, v173
	s_nop 1
	v_cndmask_b32_e64 v140, v232, v140, s[12:13]
	v_cmp_neq_f32_e64 s[12:13], -1.0, v173
	s_nop 1
	v_cndmask_b32_e64 v140, v233, v140, s[12:13]
	v_cmp_neq_f32_e64 s[12:13], -1.0, v179
	s_nop 1
	v_cndmask_b32_e64 v141, v233, v141, s[12:13]
	v_cmp_lt_f32_e64 s[12:13], |v173|, s5
	v_cndmask_b32_e64 v141, v141, v179, s[14:15]
	s_nop 0
	v_cndmask_b32_e64 v140, v140, v173, s[12:13]
	v_pk_add_f32 v[130:131], v[130:131], v[140:141] neg_lo:[0,1] neg_hi:[0,1]
	v_min_f32_e32 v140, 0, v132
	v_mul_f32_e64 v132, |v132|, s34
	v_exp_f32_e32 v173, v132
	s_nop 0
	v_add_f32_e32 v132, 1.0, v173
	v_add_f32_e32 v141, -1.0, v132
	v_sub_f32_e32 v179, v141, v132
	v_add_f32_e32 v179, 1.0, v179
; __device__ __forceinline__ float log_sigmoid_f(float x) { return fminf(x, 0.f) - log1pf(__expf(-fabsf(x))); }
;     __device__ __forceinline__ void operator()(const f32x4 (&acc)[2][2][4][2], const Unit& u, int wr, int wc, int fr, int fq) const {
;     ...
;                         for (int n = 0; n < 2; ++n) { const int c = 8 * fq + 4 * n; const f32x4 bv = *(const f32x4*)(b_f + c); const f32x4 x = acc[ai][0][m][n] * s + bv; f32x4 lf;
;                             lf[0] = log_sigmoid_f(x[0]); lf[1] = log_sigmoid_f(x[1]); lf[2] = log_sigmoid_f(x[2]); lf[3] = log_sigmoid_f(x[3]);
	v_sub_f32_e32 v141, v173, v141
	v_add_f32_e32 v141, v141, v179
	v_frexp_mant_f32_e32 v179, v132
	v_cvt_f64_f32_e32 v[202:203], v132
	v_cmp_gt_f32_e64 s[12:13], s35, v179
	v_frexp_exp_i32_f64_e32 v179, v[202:203]
	s_nop 0
	v_subbrev_co_u32_e64 v179, s[12:13], 0, v179, s[12:13]
	v_sub_u32_e32 v183, 0, v179
	v_ldexp_f32 v202, v141, v183
	v_min_f32_e32 v141, 0, v133
	v_mul_f32_e64 v133, |v133|, s34
	v_ldexp_f32 v132, v132, v183
	v_exp_f32_e32 v183, v133
	s_nop 0
	v_add_f32_e32 v133, 1.0, v183
	v_add_f32_e32 v187, -1.0, v133
	v_sub_f32_e32 v191, v187, v133
	v_add_f32_e32 v191, 1.0, v191
	v_sub_f32_e32 v187, v183, v187
	v_add_f32_e32 v187, v187, v191
	v_frexp_mant_f32_e32 v191, v133
	v_cvt_f64_f32_e32 v[204:205], v133
	v_cmp_gt_f32_e64 s[12:13], s35, v191
	v_frexp_exp_i32_f64_e32 v191, v[204:205]
	v_cmp_lt_f32_e64 s[14:15], |v183|, s5
	v_subbrev_co_u32_e64 v191, s[12:13], 0, v191, s[12:13]
	v_sub_u32_e32 v195, 0, v191
	v_ldexp_f32 v133, v133, v195
	v_pk_add_f32 v[204:205], v[132:133], 1.0 op_sel_hi:[1,0]
	v_ldexp_f32 v203, v187, v195
	v_pk_add_f32 v[206:207], v[204:205], -1.0 op_sel_hi:[1,0]
	v_pk_add_f32 v[212:213], v[132:133], -1.0 op_sel_hi:[1,0]
	v_pk_add_f32 v[206:207], v[132:133], v[206:207] neg_lo:[0,1] neg_hi:[0,1]
	v_pk_add_f32 v[214:215], v[212:213], 1.0 op_sel_hi:[1,0]
	v_pk_add_f32 v[206:207], v[202:203], v[206:207]
	v_pk_add_f32 v[132:133], v[132:133], v[214:215] neg_lo:[0,1] neg_hi:[0,1]
	v_pk_add_f32 v[208:209], v[204:205], v[206:207]
	v_pk_add_f32 v[132:133], v[202:203], v[132:133]
	v_rcp_f32_e32 v210, v208
	v_rcp_f32_e32 v211, v209
	v_pk_add_f32 v[202:203], v[212:213], v[132:133]
	v_pk_add_f32 v[204:205], v[208:209], v[204:205] neg_lo:[0,1] neg_hi:[0,1]
	v_pk_add_f32 v[212:213], v[202:203], v[212:213] neg_lo:[0,1] neg_hi:[0,1]
	v_pk_add_f32 v[204:205], v[206:207], v[204:205] neg_lo:[0,1] neg_hi:[0,1]
	v_pk_mul_f32 v[206:207], v[202:203], v[210:211]
	v_pk_add_f32 v[132:133], v[132:133], v[212:213] neg_lo:[0,1] neg_hi:[0,1]
	v_pk_mul_f32 v[212:213], v[208:209], v[206:207]
	v_cmp_neq_f32_e64 s[12:13], s4, v173
	v_pk_fma_f32 v[214:215], v[206:207], v[208:209], v[212:213] neg_lo:[0,0,1] neg_hi:[0,0,1]
	s_nop 0
	v_pk_fma_f32 v[214:215], v[206:207], v[204:205], v[214:215]
	s_nop 0
	v_pk_add_f32 v[216:217], v[212:213], v[214:215]
	s_nop 0
	v_pk_add_f32 v[218:219], v[202:203], v[216:217] neg_lo:[0,1] neg_hi:[0,1]
	v_pk_add_f32 v[212:213], v[216:217], v[212:213] neg_lo:[0,1] neg_hi:[0,1]
	v_pk_add_f32 v[202:203], v[202:203], v[218:219] neg_lo:[0,1] neg_hi:[0,1]
	s_nop 0
	v_pk_add_f32 v[202:203], v[202:203], v[216:217] neg_lo:[0,1] neg_hi:[0,1]
	s_nop 0
	v_pk_add_f32 v[132:133], v[132:133], v[202:203]
	v_pk_add_f32 v[202:203], v[212:213], v[214:215] neg_lo:[0,1] neg_hi:[0,1]
	s_nop 0
	v_pk_add_f32 v[132:133], v[202:203], v[132:133]
	s_nop 0
	v_pk_add_f32 v[202:203], v[218:219], v[132:133]
	s_nop 0
	v_pk_mul_f32 v[212:213], v[210:211], v[202:203]
	s_nop 0
	v_pk_mul_f32 v[214:215], v[208:209], v[212:213]
	s_nop 0
	v_pk_fma_f32 v[208:209], v[212:213], v[208:209], v[214:215] neg_lo:[0,0,1] neg_hi:[0,0,1]
	s_nop 0
	v_pk_fma_f32 v[204:205], v[212:213], v[204:205], v[208:209]
	v_pk_add_f32 v[208:209], v[218:219], v[202:203] neg_lo:[0,1] neg_hi:[0,1]
	s_nop 0
	v_pk_add_f32 v[132:133], v[132:133], v[208:209]
	v_pk_add_f32 v[208:209], v[214:215], v[204:205]
	s_nop 0
	v_pk_add_f32 v[216:217], v[202:203], v[208:209] neg_lo:[0,1] neg_hi:[0,1]
	v_pk_add_f32 v[214:215], v[208:209], v[214:215] neg_lo:[0,1] neg_hi:[0,1]
	v_pk_add_f32 v[202:203], v[202:203], v[216:217] neg_lo:[0,1] neg_hi:[0,1]
	s_nop 0
	v_pk_add_f32 v[202:203], v[202:203], v[208:209] neg_lo:[0,1] neg_hi:[0,1]
	s_nop 0
	v_pk_add_f32 v[132:133], v[132:133], v[202:203]
	v_pk_add_f32 v[202:203], v[214:215], v[204:205] neg_lo:[0,1] neg_hi:[0,1]
	s_nop 0
	v_pk_add_f32 v[132:133], v[202:203], v[132:133]
	v_pk_add_f32 v[202:203], v[206:207], v[212:213]
	v_pk_add_f32 v[132:133], v[216:217], v[132:133]
	v_pk_add_f32 v[204:205], v[202:203], v[206:207] neg_lo:[0,1] neg_hi:[0,1]
	v_pk_mul_f32 v[132:133], v[210:211], v[132:133]
	v_pk_add_f32 v[204:205], v[212:213], v[204:205] neg_lo:[0,1] neg_hi:[0,1]
	s_nop 0
	v_pk_add_f32 v[132:133], v[204:205], v[132:133]
	s_nop 0
	v_pk_add_f32 v[204:205], v[202:203], v[132:133]
	s_nop 0
	v_pk_mul_f32 v[206:207], v[204:205], v[204:205]
	v_pk_add_f32 v[202:203], v[204:205], v[202:203] neg_lo:[0,1] neg_hi:[0,1]
	v_pk_fma_f32 v[138:139], v[206:207], s[52:53], v[138:139] op_sel_hi:[1,0,0]
	v_pk_add_f32 v[132:133], v[132:133], v[202:203] neg_lo:[0,1] neg_hi:[0,1]
; __device__ __forceinline__ float log_sigmoid_f(float x) { return fminf(x, 0.f) - log1pf(__expf(-fabsf(x))); }
;     __device__ __forceinline__ void operator()(const f32x4 (&acc)[2][2][4][2], const Unit& u, int wr, int wc, int fr, int fq) const {
;     ...
;                         for (int n = 0; n < 2; ++n) { const int c = 8 * fq + 4 * n; const f32x4 bv = *(const f32x4*)(b_f + c); const f32x4 x = acc[ai][0][m][n] * s + bv; f32x4 lf;
;                             lf[0] = log_sigmoid_f(x[0]); lf[1] = log_sigmoid_f(x[1]); lf[2] = log_sigmoid_f(x[2]); lf[3] = log_sigmoid_f(x[3]);
;                             *(f32x4*)(LF + (size_t)row * 16 + c) = lf; if (dst) *(f32x4*)(dst + c) = lf; } }
	v_ldexp_f32 v202, v204, 1
	v_pk_fma_f32 v[138:139], v[206:207], v[138:139], s[54:55] op_sel_hi:[1,1,0]
	v_ldexp_f32 v203, v205, 1
	v_pk_mul_f32 v[204:205], v[204:205], v[206:207]
	v_cvt_f32_i32_e32 v207, v191
	v_cvt_f32_i32_e32 v206, v179
	v_pk_mul_f32 v[138:139], v[204:205], v[138:139]
	v_ldexp_f32 v209, v133, 1
	v_pk_add_f32 v[204:205], v[202:203], v[138:139]
	v_pk_mul_f32 v[210:211], v[206:207], s[64:65] op_sel_hi:[1,0]
	v_pk_add_f32 v[202:203], v[204:205], v[202:203] neg_lo:[0,1] neg_hi:[0,1]
	v_pk_fma_f32 v[212:213], v[206:207], s[64:65], v[210:211] op_sel_hi:[1,0,1] neg_lo:[0,0,1] neg_hi:[0,0,1]
	v_pk_add_f32 v[138:139], v[138:139], v[202:203] neg_lo:[0,1] neg_hi:[0,1]
	v_pk_fma_f32 v[206:207], v[206:207], s[66:67], v[212:213] op_sel_hi:[1,0,1]
	v_ldexp_f32 v132, v132, 1
	v_mov_b32_e32 v202, v210
	v_mov_b32_e32 v203, v139
	v_mov_b32_e32 v208, v206
	v_mov_b32_e32 v133, v209
	v_pk_add_f32 v[202:203], v[202:203], v[208:209]
	v_pk_add_f32 v[208:209], v[132:133], v[138:139]
	v_mov_b32_e32 v139, v205
	v_mov_b32_e32 v133, v209
	v_pk_add_f32 v[212:213], v[210:211], v[206:207]
	v_pk_add_f32 v[132:133], v[132:133], v[138:139]
	v_pk_add_f32 v[138:139], v[204:205], v[208:209]
	v_mov_b32_e32 v222, v204
	v_pk_add_f32 v[214:215], v[212:213], v[138:139]
	v_mov_b32_e32 v220, v138
	v_mov_b32_e32 v221, v215
	v_mov_b32_e32 v223, v213
	v_pk_add_f32 v[220:221], v[220:221], v[222:223] neg_lo:[0,1] neg_hi:[0,1]
	v_mov_b32_e32 v216, v214
	v_mov_b32_e32 v217, v213
	v_mov_b32_e32 v218, v212
	v_mov_b32_e32 v219, v211
	v_mov_b32_e32 v222, v212
	v_mov_b32_e32 v223, v215
	v_mov_b32_e32 v211, v221
	v_pk_add_f32 v[216:217], v[216:217], v[218:219] neg_lo:[0,1] neg_hi:[0,1]
	v_mov_b32_e32 v218, v138
	v_mov_b32_e32 v219, v207
	v_pk_add_f32 v[210:211], v[222:223], v[210:211] neg_lo:[0,1] neg_hi:[0,1]
	v_pk_add_f32 v[218:219], v[218:219], v[216:217] neg_lo:[0,1] neg_hi:[0,1]
	v_mov_b32_e32 v222, v210
	v_mov_b32_e32 v223, v217
	v_mov_b32_e32 v224, v214
	v_mov_b32_e32 v225, v139
	v_mov_b32_e32 v217, v205
	v_pk_add_f32 v[222:223], v[206:207], v[222:223] neg_lo:[0,1] neg_hi:[0,1]
	v_pk_add_f32 v[216:217], v[224:225], v[216:217] neg_lo:[0,1] neg_hi:[0,1]
	v_mov_b32_e32 v207, v213
	v_pk_add_f32 v[138:139], v[138:139], v[204:205] neg_lo:[0,1] neg_hi:[0,1]
	v_pk_add_f32 v[202:203], v[202:203], v[216:217] neg_lo:[0,1] neg_hi:[0,1]
	v_pk_add_f32 v[204:205], v[206:207], v[210:211] neg_lo:[0,1] neg_hi:[0,1]
	v_pk_add_f32 v[132:133], v[132:133], v[220:221] neg_lo:[0,1] neg_hi:[0,1]
	v_pk_add_f32 v[138:139], v[208:209], v[138:139] neg_lo:[0,1] neg_hi:[0,1]
	v_pk_add_f32 v[206:207], v[132:133], v[204:205]
	v_mov_b32_e32 v205, v219
	v_mov_b32_e32 v133, v203
	v_pk_add_f32 v[208:209], v[218:219], v[202:203]
	v_pk_add_f32 v[132:133], v[204:205], v[132:133]
	v_mov_b32_e32 v202, v206
	v_pk_add_f32 v[132:133], v[132:133], v[222:223] neg_lo:[0,1] neg_hi:[0,1]
	v_mov_b32_e32 v203, v209
	v_pk_add_f32 v[202:203], v[202:203], v[132:133] neg_lo:[0,1] neg_hi:[0,1]
	v_pk_add_f32 v[132:133], v[138:139], v[132:133] neg_lo:[0,1] neg_hi:[0,1]
	v_pk_add_f32 v[202:203], v[204:205], v[202:203] neg_lo:[0,1] neg_hi:[0,1]
	v_pk_add_f32 v[138:139], v[208:209], v[206:207]
	v_pk_add_f32 v[132:133], v[132:133], v[202:203]
	v_pk_add_f32 v[202:203], v[214:215], v[138:139]
	s_nop 0
	v_pk_add_f32 v[204:205], v[202:203], v[214:215] neg_lo:[0,1] neg_hi:[0,1]
	s_nop 0
	v_pk_add_f32 v[138:139], v[138:139], v[204:205] neg_lo:[0,1] neg_hi:[0,1]
	s_nop 0
	v_pk_add_f32 v[132:133], v[132:133], v[138:139]
	s_nop 0
	v_pk_add_f32 v[132:133], v[202:203], v[132:133]
	s_nop 0
	v_cndmask_b32_e64 v132, v231, v132, s[12:13]
	v_cmp_neq_f32_e64 s[12:13], s4, v183
	s_nop 1
	v_cndmask_b32_e64 v133, v231, v133, s[12:13]
	v_cmp_ngt_f32_e64 s[12:13], -1.0, v183
	s_nop 1
	v_cndmask_b32_e64 v133, v232, v133, s[12:13]
	v_cmp_ngt_f32_e64 s[12:13], -1.0, v173
	s_nop 1
	v_cndmask_b32_e64 v132, v232, v132, s[12:13]
	v_cmp_neq_f32_e64 s[12:13], -1.0, v173
	s_nop 1
	v_cndmask_b32_e64 v132, v233, v132, s[12:13]
	v_cmp_neq_f32_e64 s[12:13], -1.0, v183
	s_nop 1
	v_cndmask_b32_e64 v133, v233, v133, s[12:13]
	v_cmp_lt_f32_e64 s[12:13], |v173|, s5
	v_cndmask_b32_e64 v133, v133, v183, s[14:15]
	s_nop 0
	v_cndmask_b32_e64 v132, v132, v173, s[12:13]
	v_pk_add_f32 v[132:133], v[140:141], v[132:133] neg_lo:[0,1] neg_hi:[0,1]
	global_store_dwordx4 v[136:137], v[130:133], off offset:16 nt
	s_and_saveexec_b64 s[12:13], vcc
	s_cbranch_execz .LBB0_400
	v_lshl_add_u64 v[134:135], v[134:135], 0, v[150:151]
	global_store_dwordx4 v[134:135], v[130:133], off offset:16 nt

; __device__ __forceinline__ float log_sigmoid_f(float x) { return fminf(x, 0.f) - log1pf(__expf(-fabsf(x))); }
;     __device__ __forceinline__ void operator()(const f32x4 (&acc)[2][2][4][2], const Unit& u, int wr, int wc, int fr, int fq) const {
;     ...
;                         if (pm == 0) dst = o_lfs + (size_t)row * 16; else { const int t = row - G_ROWP; if (t < G_TP) dst = o_lfp + (size_t)t * 16; }
; #pragma unroll
;                         for (int n = 0; n < 2; ++n) { const int c = 8 * fq + 4 * n; const f32x4 bv = *(const f32x4*)(b_f + c); const f32x4 x = acc[ai][0][m][n] * s + bv; f32x4 lf;
;                             lf[0] = log_sigmoid_f(x[0]); lf[1] = log_sigmoid_f(x[1]); lf[2] = log_sigmoid_f(x[2]); lf[3] = log_sigmoid_f(x[3]);
.LBB0_403:
	global_load_dwordx4 v[130:133], v[158:159], off
	v_cmp_ne_u64_e32 vcc, 0, v[134:135]
	v_lshl_add_u64 v[136:137], v[162:163], 0, v[136:137]
	s_waitcnt vmcnt(0)
	v_pk_fma_f32 v[138:139], v[62:63], v[186:187], v[130:131] op_sel_hi:[1,0,1]
	s_nop 0
	v_mul_f32_e64 v131, |v138|, s34
	v_exp_f32_e32 v173, v131
	v_min_f32_e32 v130, 0, v138
	v_pk_fma_f32 v[132:133], v[64:65], v[186:187], v[132:133] op_sel_hi:[1,0,1]
	v_add_f32_e32 v131, 1.0, v173
	v_add_f32_e32 v138, -1.0, v131
	v_sub_f32_e32 v140, v138, v131
	v_add_f32_e32 v140, 1.0, v140
	v_sub_f32_e32 v138, v173, v138
	v_add_f32_e32 v179, v138, v140
	v_frexp_mant_f32_e32 v138, v131
	v_cvt_f64_f32_e32 v[140:141], v131
	v_cmp_gt_f32_e64 s[12:13], s35, v138
	v_frexp_exp_i32_f64_e32 v138, v[140:141]
	s_nop 0
	v_subbrev_co_u32_e64 v183, s[12:13], 0, v138, s[12:13]
	v_sub_u32_e32 v140, 0, v183
	v_ldexp_f32 v138, v131, v140
	v_min_f32_e32 v131, 0, v139
	v_mul_f32_e64 v139, |v139|, s34
	v_ldexp_f32 v140, v179, v140
	v_exp_f32_e32 v179, v139
	s_nop 0
	v_add_f32_e32 v139, 1.0, v179
	v_add_f32_e32 v141, -1.0, v139
	v_sub_f32_e32 v187, v141, v139
	v_add_f32_e32 v187, 1.0, v187
	v_sub_f32_e32 v141, v179, v141
	v_add_f32_e32 v141, v141, v187
	v_frexp_mant_f32_e32 v187, v139
	v_cvt_f64_f32_e32 v[202:203], v139
	v_cmp_gt_f32_e64 s[12:13], s35, v187
	v_frexp_exp_i32_f64_e32 v187, v[202:203]
	v_cmp_lt_f32_e64 s[14:15], |v179|, s5
	v_subbrev_co_u32_e64 v187, s[12:13], 0, v187, s[12:13]
	v_sub_u32_e32 v191, 0, v187
	v_ldexp_f32 v139, v139, v191
	v_pk_add_f32 v[202:203], v[138:139], 1.0 op_sel_hi:[1,0]
	v_ldexp_f32 v141, v141, v191
	v_pk_add_f32 v[204:205], v[202:203], -1.0 op_sel_hi:[1,0]
	v_pk_add_f32 v[210:211], v[138:139], -1.0 op_sel_hi:[1,0]
	v_pk_add_f32 v[204:205], v[138:139], v[204:205] neg_lo:[0,1] neg_hi:[0,1]
	v_pk_add_f32 v[212:213], v[210:211], 1.0 op_sel_hi:[1,0]
	v_pk_add_f32 v[204:205], v[140:141], v[204:205]
	v_pk_add_f32 v[138:139], v[138:139], v[212:213] neg_lo:[0,1] neg_hi:[0,1]
	v_pk_add_f32 v[206:207], v[202:203], v[204:205]
	v_pk_add_f32 v[138:139], v[140:141], v[138:139]
	v_rcp_f32_e32 v208, v206
	v_rcp_f32_e32 v209, v207
	v_pk_add_f32 v[140:141], v[210:211], v[138:139]
	v_pk_add_f32 v[202:203], v[206:207], v[202:203] neg_lo:[0,1] neg_hi:[0,1]
	v_pk_add_f32 v[210:211], v[140:141], v[210:211] neg_lo:[0,1] neg_hi:[0,1]
	v_pk_add_f32 v[202:203], v[204:205], v[202:203] neg_lo:[0,1] neg_hi:[0,1]
	v_pk_mul_f32 v[204:205], v[140:141], v[208:209]
	v_pk_add_f32 v[138:139], v[138:139], v[210:211] neg_lo:[0,1] neg_hi:[0,1]
	v_pk_mul_f32 v[210:211], v[206:207], v[204:205]
	v_cmp_neq_f32_e64 s[12:13], s4, v173
	v_pk_fma_f32 v[212:213], v[204:205], v[206:207], v[210:211] neg_lo:[0,0,1] neg_hi:[0,0,1]
	s_nop 0
	v_pk_fma_f32 v[212:213], v[204:205], v[202:203], v[212:213]
	s_nop 0
	v_pk_add_f32 v[214:215], v[210:211], v[212:213]
	s_nop 0
	v_pk_add_f32 v[216:217], v[140:141], v[214:215] neg_lo:[0,1] neg_hi:[0,1]
	v_pk_add_f32 v[210:211], v[214:215], v[210:211] neg_lo:[0,1] neg_hi:[0,1]
	v_pk_add_f32 v[140:141], v[140:141], v[216:217] neg_lo:[0,1] neg_hi:[0,1]
	s_nop 0
	v_pk_add_f32 v[140:141], v[140:141], v[214:215] neg_lo:[0,1] neg_hi:[0,1]
	s_nop 0
	v_pk_add_f32 v[138:139], v[138:139], v[140:141]
	v_pk_add_f32 v[140:141], v[210:211], v[212:213] neg_lo:[0,1] neg_hi:[0,1]
	s_nop 0
	v_pk_add_f32 v[138:139], v[140:141], v[138:139]
	s_nop 0
	v_pk_add_f32 v[140:141], v[216:217], v[138:139]
	s_nop 0
	v_pk_mul_f32 v[210:211], v[208:209], v[140:141]
	s_nop 0
	v_pk_mul_f32 v[212:213], v[206:207], v[210:211]
	s_nop 0
	v_pk_fma_f32 v[206:207], v[210:211], v[206:207], v[212:213] neg_lo:[0,0,1] neg_hi:[0,0,1]
	s_nop 0
	v_pk_fma_f32 v[202:203], v[210:211], v[202:203], v[206:207]
	v_pk_add_f32 v[206:207], v[216:217], v[140:141] neg_lo:[0,1] neg_hi:[0,1]
	s_nop 0
	v_pk_add_f32 v[138:139], v[138:139], v[206:207]
	v_pk_add_f32 v[206:207], v[212:213], v[202:203]
	s_nop 0
	v_pk_add_f32 v[214:215], v[140:141], v[206:207] neg_lo:[0,1] neg_hi:[0,1]
	v_pk_add_f32 v[212:213], v[206:207], v[212:213] neg_lo:[0,1] neg_hi:[0,1]
	v_pk_add_f32 v[140:141], v[140:141], v[214:215] neg_lo:[0,1] neg_hi:[0,1]
	s_nop 0
	v_pk_add_f32 v[140:141], v[140:141], v[206:207] neg_lo:[0,1] neg_hi:[0,1]
	s_nop 0
	v_pk_add_f32 v[138:139], v[138:139], v[140:141]
	v_pk_add_f32 v[140:141], v[212:213], v[202:203] neg_lo:[0,1] neg_hi:[0,1]
	s_nop 0
	v_pk_add_f32 v[138:139], v[140:141], v[138:139]
	v_pk_add_f32 v[140:141], v[204:205], v[210:211]
	v_pk_add_f32 v[138:139], v[214:215], v[138:139]
	v_pk_add_f32 v[202:203], v[140:141], v[204:205] neg_lo:[0,1] neg_hi:[0,1]
	v_pk_mul_f32 v[138:139], v[208:209], v[138:139]
	v_pk_add_f32 v[202:203], v[210:211], v[202:203] neg_lo:[0,1] neg_hi:[0,1]
	s_nop 0
	v_pk_add_f32 v[138:139], v[202:203], v[138:139]
	s_nop 0
	v_pk_add_f32 v[204:205], v[140:141], v[138:139]
	s_nop 0
	v_pk_add_f32 v[140:141], v[204:205], v[140:141] neg_lo:[0,1] neg_hi:[0,1]
	v_pk_mul_f32 v[206:207], v[204:205], v[204:205]
	v_pk_add_f32 v[140:141], v[138:139], v[140:141] neg_lo:[0,1] neg_hi:[0,1]
	v_mov_b64_e32 v[138:139], s[50:51]
	v_pk_fma_f32 v[208:209], v[206:207], s[52:53], v[138:139] op_sel_hi:[1,0,0]
	v_ldexp_f32 v202, v204, 1
	v_pk_fma_f32 v[208:209], v[206:207], v[208:209], s[54:55] op_sel_hi:[1,1,0]
	v_ldexp_f32 v203, v205, 1
	v_pk_mul_f32 v[204:205], v[204:205], v[206:207]
	v_cvt_f32_i32_e32 v207, v187
	v_cvt_f32_i32_e32 v206, v183
	v_pk_mul_f32 v[214:215], v[204:205], v[208:209]
	v_ldexp_f32 v213, v141, 1
	v_pk_add_f32 v[204:205], v[202:203], v[214:215]
	v_pk_mul_f32 v[210:211], v[206:207], s[64:65] op_sel_hi:[1,0]
	v_pk_add_f32 v[202:203], v[204:205], v[202:203] neg_lo:[0,1] neg_hi:[0,1]
	v_ldexp_f32 v140, v140, 1
; __device__ __forceinline__ float log_sigmoid_f(float x) { return fminf(x, 0.f) - log1pf(__expf(-fabsf(x))); }
;     __device__ __forceinline__ void operator()(const f32x4 (&acc)[2][2][4][2], const Unit& u, int wr, int wc, int fr, int fq) const {
;     ...
;                         for (int n = 0; n < 2; ++n) { const int c = 8 * fq + 4 * n; const f32x4 bv = *(const f32x4*)(b_f + c); const f32x4 x = acc[ai][0][m][n] * s + bv; f32x4 lf;
;                             lf[0] = log_sigmoid_f(x[0]); lf[1] = log_sigmoid_f(x[1]); lf[2] = log_sigmoid_f(x[2]); lf[3] = log_sigmoid_f(x[3]);
	v_pk_fma_f32 v[208:209], v[206:207], s[64:65], v[210:211] op_sel_hi:[1,0,1] neg_lo:[0,0,1] neg_hi:[0,0,1]
	v_pk_add_f32 v[216:217], v[214:215], v[202:203] neg_lo:[0,1] neg_hi:[0,1]
	v_mov_b32_e32 v141, v213
	v_pk_fma_f32 v[206:207], v[206:207], s[66:67], v[208:209] op_sel_hi:[1,0,1]
	v_pk_add_f32 v[214:215], v[140:141], v[216:217]
	v_mov_b32_e32 v202, v210
	v_mov_b32_e32 v203, v217
	v_mov_b32_e32 v212, v206
	v_mov_b32_e32 v141, v215
	v_mov_b32_e32 v217, v205
	v_pk_add_f32 v[208:209], v[210:211], v[206:207]
	v_pk_add_f32 v[202:203], v[202:203], v[212:213]
	v_pk_add_f32 v[212:213], v[140:141], v[216:217]
	v_pk_add_f32 v[216:217], v[204:205], v[214:215]
	v_mov_b32_e32 v224, v204
	v_pk_add_f32 v[140:141], v[208:209], v[216:217]
	v_mov_b32_e32 v222, v216
	v_mov_b32_e32 v223, v141
	v_mov_b32_e32 v225, v209
	v_pk_add_f32 v[222:223], v[222:223], v[224:225] neg_lo:[0,1] neg_hi:[0,1]
	v_mov_b32_e32 v218, v140
	v_mov_b32_e32 v219, v209
	v_mov_b32_e32 v220, v208
	v_mov_b32_e32 v221, v211
	v_mov_b32_e32 v224, v208
	v_mov_b32_e32 v225, v141
	v_mov_b32_e32 v211, v223
	v_pk_add_f32 v[218:219], v[218:219], v[220:221] neg_lo:[0,1] neg_hi:[0,1]
	v_mov_b32_e32 v220, v216
	v_mov_b32_e32 v221, v207
	v_pk_add_f32 v[210:211], v[224:225], v[210:211] neg_lo:[0,1] neg_hi:[0,1]
	v_pk_add_f32 v[220:221], v[220:221], v[218:219] neg_lo:[0,1] neg_hi:[0,1]
	v_mov_b32_e32 v224, v210
	v_mov_b32_e32 v225, v219
	v_mov_b32_e32 v226, v140
	v_mov_b32_e32 v227, v217
	v_mov_b32_e32 v219, v205
	v_pk_add_f32 v[224:225], v[206:207], v[224:225] neg_lo:[0,1] neg_hi:[0,1]
	v_pk_add_f32 v[218:219], v[226:227], v[218:219] neg_lo:[0,1] neg_hi:[0,1]
	v_mov_b32_e32 v207, v209
	v_pk_add_f32 v[202:203], v[202:203], v[218:219] neg_lo:[0,1] neg_hi:[0,1]
	v_pk_add_f32 v[206:207], v[206:207], v[210:211] neg_lo:[0,1] neg_hi:[0,1]
	v_pk_add_f32 v[208:209], v[212:213], v[222:223] neg_lo:[0,1] neg_hi:[0,1]
	v_pk_add_f32 v[212:213], v[220:221], v[202:203]
	v_pk_add_f32 v[210:211], v[208:209], v[206:207]
	v_mov_b32_e32 v207, v221
	v_mov_b32_e32 v209, v203
	v_pk_add_f32 v[202:203], v[206:207], v[208:209]
	v_pk_add_f32 v[204:205], v[216:217], v[204:205] neg_lo:[0,1] neg_hi:[0,1]
	v_pk_add_f32 v[202:203], v[202:203], v[224:225] neg_lo:[0,1] neg_hi:[0,1]
	v_mov_b32_e32 v208, v210
	v_mov_b32_e32 v209, v213
	v_pk_add_f32 v[204:205], v[214:215], v[204:205] neg_lo:[0,1] neg_hi:[0,1]
	v_pk_add_f32 v[208:209], v[208:209], v[202:203] neg_lo:[0,1] neg_hi:[0,1]
	v_pk_add_f32 v[202:203], v[204:205], v[202:203] neg_lo:[0,1] neg_hi:[0,1]
	v_pk_add_f32 v[206:207], v[206:207], v[208:209] neg_lo:[0,1] neg_hi:[0,1]
	v_pk_add_f32 v[204:205], v[212:213], v[210:211]
	v_pk_add_f32 v[202:203], v[202:203], v[206:207]
	v_pk_add_f32 v[206:207], v[140:141], v[204:205]
	s_nop 0
	v_pk_add_f32 v[140:141], v[206:207], v[140:141] neg_lo:[0,1] neg_hi:[0,1]
	s_nop 0
	v_pk_add_f32 v[140:141], v[204:205], v[140:141] neg_lo:[0,1] neg_hi:[0,1]
	s_nop 0
	v_pk_add_f32 v[140:141], v[202:203], v[140:141]
	s_nop 0
	v_pk_add_f32 v[140:141], v[206:207], v[140:141]
	s_nop 0
	v_cndmask_b32_e64 v140, v231, v140, s[12:13]
	v_cmp_neq_f32_e64 s[12:13], s4, v179
	s_nop 1
	v_cndmask_b32_e64 v141, v231, v141, s[12:13]
	v_cmp_ngt_f32_e64 s[12:13], -1.0, v179
	s_nop 1
	v_cndmask_b32_e64 v141, v232, v141, s[12:13]
	v_cmp_ngt_f32_e64 s[12:13], -1.0, v173
	s_nop 1
	v_cndmask_b32_e64 v140, v232, v140, s[12:13]
	v_cmp_neq_f32_e64 s[12:13], -1.0, v173
	s_nop 1
	v_cndmask_b32_e64 v140, v233, v140, s[12:13]
	v_cmp_neq_f32_e64 s[12:13], -1.0, v179
	s_nop 1
	v_cndmask_b32_e64 v141, v233, v141, s[12:13]
	v_cmp_lt_f32_e64 s[12:13], |v173|, s5
	v_cndmask_b32_e64 v141, v141, v179, s[14:15]
	s_nop 0
	v_cndmask_b32_e64 v140, v140, v173, s[12:13]
	v_pk_add_f32 v[130:131], v[130:131], v[140:141] neg_lo:[0,1] neg_hi:[0,1]
	v_min_f32_e32 v140, 0, v132
	v_mul_f32_e64 v132, |v132|, s34
	v_exp_f32_e32 v173, v132
	s_nop 0
	v_add_f32_e32 v132, 1.0, v173
	v_add_f32_e32 v141, -1.0, v132
	v_sub_f32_e32 v179, v141, v132
	v_add_f32_e32 v179, 1.0, v179
	v_sub_f32_e32 v141, v173, v141
	v_add_f32_e32 v141, v141, v179
	v_frexp_mant_f32_e32 v179, v132
	v_cvt_f64_f32_e32 v[202:203], v132
	v_cmp_gt_f32_e64 s[12:13], s35, v179
	v_frexp_exp_i32_f64_e32 v179, v[202:203]
	s_nop 0
	v_subbrev_co_u32_e64 v179, s[12:13], 0, v179, s[12:13]
	v_sub_u32_e32 v183, 0, v179
	v_ldexp_f32 v202, v141, v183
	v_min_f32_e32 v141, 0, v133
	v_mul_f32_e64 v133, |v133|, s34
	v_ldexp_f32 v132, v132, v183
	v_exp_f32_e32 v183, v133
	s_nop 0
	v_add_f32_e32 v133, 1.0, v183
	v_add_f32_e32 v187, -1.0, v133
	v_sub_f32_e32 v191, v187, v133
	v_add_f32_e32 v191, 1.0, v191
	v_sub_f32_e32 v187, v183, v187
	v_add_f32_e32 v187, v187, v191
	v_frexp_mant_f32_e32 v191, v133
	v_cvt_f64_f32_e32 v[204:205], v133
	v_cmp_gt_f32_e64 s[12:13], s35, v191
	v_frexp_exp_i32_f64_e32 v191, v[204:205]
	v_cmp_lt_f32_e64 s[14:15], |v183|, s5
	v_subbrev_co_u32_e64 v191, s[12:13], 0, v191, s[12:13]
	v_sub_u32_e32 v195, 0, v191
	v_ldexp_f32 v133, v133, v195
	v_pk_add_f32 v[204:205], v[132:133], 1.0 op_sel_hi:[1,0]
	v_ldexp_f32 v203, v187, v195
	v_pk_add_f32 v[206:207], v[204:205], -1.0 op_sel_hi:[1,0]
	v_pk_add_f32 v[212:213], v[132:133], -1.0 op_sel_hi:[1,0]
	v_pk_add_f32 v[206:207], v[132:133], v[206:207] neg_lo:[0,1] neg_hi:[0,1]
	v_pk_add_f32 v[214:215], v[212:213], 1.0 op_sel_hi:[1,0]
	v_pk_add_f32 v[206:207], v[202:203], v[206:207]
	v_pk_add_f32 v[132:133], v[132:133], v[214:215] neg_lo:[0,1] neg_hi:[0,1]
	v_pk_add_f32 v[208:209], v[204:205], v[206:207]
	v_pk_add_f32 v[132:133], v[202:203], v[132:133]
	v_rcp_f32_e32 v210, v208
	v_rcp_f32_e32 v211, v209
	v_pk_add_f32 v[202:203], v[212:213], v[132:133]
	v_pk_add_f32 v[204:205], v[208:209], v[204:205] neg_lo:[0,1] neg_hi:[0,1]
; __device__ __forceinline__ float log_sigmoid_f(float x) { return fminf(x, 0.f) - log1pf(__expf(-fabsf(x))); }
;     __device__ __forceinline__ void operator()(const f32x4 (&acc)[2][2][4][2], const Unit& u, int wr, int wc, int fr, int fq) const {
;     ...
;                         for (int n = 0; n < 2; ++n) { const int c = 8 * fq + 4 * n; const f32x4 bv = *(const f32x4*)(b_f + c); const f32x4 x = acc[ai][0][m][n] * s + bv; f32x4 lf;
;                             lf[0] = log_sigmoid_f(x[0]); lf[1] = log_sigmoid_f(x[1]); lf[2] = log_sigmoid_f(x[2]); lf[3] = log_sigmoid_f(x[3]);
	v_pk_add_f32 v[212:213], v[202:203], v[212:213] neg_lo:[0,1] neg_hi:[0,1]
	v_pk_add_f32 v[204:205], v[206:207], v[204:205] neg_lo:[0,1] neg_hi:[0,1]
	v_pk_mul_f32 v[206:207], v[202:203], v[210:211]
	v_pk_add_f32 v[132:133], v[132:133], v[212:213] neg_lo:[0,1] neg_hi:[0,1]
	v_pk_mul_f32 v[212:213], v[208:209], v[206:207]
	v_cmp_neq_f32_e64 s[12:13], s4, v173
	v_pk_fma_f32 v[214:215], v[206:207], v[208:209], v[212:213] neg_lo:[0,0,1] neg_hi:[0,0,1]
	s_nop 0
	v_pk_fma_f32 v[214:215], v[206:207], v[204:205], v[214:215]
	s_nop 0
	v_pk_add_f32 v[216:217], v[212:213], v[214:215]
	s_nop 0
	v_pk_add_f32 v[218:219], v[202:203], v[216:217] neg_lo:[0,1] neg_hi:[0,1]
	v_pk_add_f32 v[212:213], v[216:217], v[212:213] neg_lo:[0,1] neg_hi:[0,1]
	v_pk_add_f32 v[202:203], v[202:203], v[218:219] neg_lo:[0,1] neg_hi:[0,1]
	s_nop 0
	v_pk_add_f32 v[202:203], v[202:203], v[216:217] neg_lo:[0,1] neg_hi:[0,1]
	s_nop 0
	v_pk_add_f32 v[132:133], v[132:133], v[202:203]
	v_pk_add_f32 v[202:203], v[212:213], v[214:215] neg_lo:[0,1] neg_hi:[0,1]
	s_nop 0
	v_pk_add_f32 v[132:133], v[202:203], v[132:133]
	s_nop 0
	v_pk_add_f32 v[202:203], v[218:219], v[132:133]
	s_nop 0
	v_pk_mul_f32 v[212:213], v[210:211], v[202:203]
	s_nop 0
	v_pk_mul_f32 v[214:215], v[208:209], v[212:213]
	s_nop 0
	v_pk_fma_f32 v[208:209], v[212:213], v[208:209], v[214:215] neg_lo:[0,0,1] neg_hi:[0,0,1]
	s_nop 0
	v_pk_fma_f32 v[204:205], v[212:213], v[204:205], v[208:209]
	v_pk_add_f32 v[208:209], v[218:219], v[202:203] neg_lo:[0,1] neg_hi:[0,1]
	s_nop 0
	v_pk_add_f32 v[132:133], v[132:133], v[208:209]
	v_pk_add_f32 v[208:209], v[214:215], v[204:205]
	s_nop 0
	v_pk_add_f32 v[216:217], v[202:203], v[208:209] neg_lo:[0,1] neg_hi:[0,1]
	v_pk_add_f32 v[214:215], v[208:209], v[214:215] neg_lo:[0,1] neg_hi:[0,1]
	v_pk_add_f32 v[202:203], v[202:203], v[216:217] neg_lo:[0,1] neg_hi:[0,1]
	s_nop 0
	v_pk_add_f32 v[202:203], v[202:203], v[208:209] neg_lo:[0,1] neg_hi:[0,1]
	s_nop 0
	v_pk_add_f32 v[132:133], v[132:133], v[202:203]
	v_pk_add_f32 v[202:203], v[214:215], v[204:205] neg_lo:[0,1] neg_hi:[0,1]
	s_nop 0
	v_pk_add_f32 v[132:133], v[202:203], v[132:133]
	v_pk_add_f32 v[202:203], v[206:207], v[212:213]
	v_pk_add_f32 v[132:133], v[216:217], v[132:133]
	v_pk_add_f32 v[204:205], v[202:203], v[206:207] neg_lo:[0,1] neg_hi:[0,1]
	v_pk_mul_f32 v[132:133], v[210:211], v[132:133]
	v_pk_add_f32 v[204:205], v[212:213], v[204:205] neg_lo:[0,1] neg_hi:[0,1]
	s_nop 0
	v_pk_add_f32 v[132:133], v[204:205], v[132:133]
	s_nop 0
	v_pk_add_f32 v[204:205], v[202:203], v[132:133]
	s_nop 0
	v_pk_mul_f32 v[206:207], v[204:205], v[204:205]
	v_pk_add_f32 v[202:203], v[204:205], v[202:203] neg_lo:[0,1] neg_hi:[0,1]
	v_pk_fma_f32 v[138:139], v[206:207], s[52:53], v[138:139] op_sel_hi:[1,0,0]
	v_pk_add_f32 v[132:133], v[132:133], v[202:203] neg_lo:[0,1] neg_hi:[0,1]
	v_ldexp_f32 v202, v204, 1
	v_pk_fma_f32 v[138:139], v[206:207], v[138:139], s[54:55] op_sel_hi:[1,1,0]
	v_ldexp_f32 v203, v205, 1
	v_pk_mul_f32 v[204:205], v[204:205], v[206:207]
	v_cvt_f32_i32_e32 v207, v191
	v_cvt_f32_i32_e32 v206, v179
	v_pk_mul_f32 v[138:139], v[204:205], v[138:139]
	v_ldexp_f32 v209, v133, 1
	v_pk_add_f32 v[204:205], v[202:203], v[138:139]
	v_pk_mul_f32 v[210:211], v[206:207], s[64:65] op_sel_hi:[1,0]
	v_pk_add_f32 v[202:203], v[204:205], v[202:203] neg_lo:[0,1] neg_hi:[0,1]
	v_pk_fma_f32 v[212:213], v[206:207], s[64:65], v[210:211] op_sel_hi:[1,0,1] neg_lo:[0,0,1] neg_hi:[0,0,1]
	v_pk_add_f32 v[138:139], v[138:139], v[202:203] neg_lo:[0,1] neg_hi:[0,1]
	v_pk_fma_f32 v[206:207], v[206:207], s[66:67], v[212:213] op_sel_hi:[1,0,1]
	v_ldexp_f32 v132, v132, 1
	v_mov_b32_e32 v202, v210
	v_mov_b32_e32 v203, v139
	v_mov_b32_e32 v208, v206
	v_mov_b32_e32 v133, v209
	v_pk_add_f32 v[202:203], v[202:203], v[208:209]
	v_pk_add_f32 v[208:209], v[132:133], v[138:139]
	v_mov_b32_e32 v139, v205
	v_mov_b32_e32 v133, v209
	v_pk_add_f32 v[212:213], v[210:211], v[206:207]
	v_pk_add_f32 v[132:133], v[132:133], v[138:139]
	v_pk_add_f32 v[138:139], v[204:205], v[208:209]
	v_mov_b32_e32 v222, v204
	v_pk_add_f32 v[214:215], v[212:213], v[138:139]
	v_mov_b32_e32 v220, v138
	v_mov_b32_e32 v221, v215
	v_mov_b32_e32 v223, v213
	v_pk_add_f32 v[220:221], v[220:221], v[222:223] neg_lo:[0,1] neg_hi:[0,1]
	v_mov_b32_e32 v216, v214
	v_mov_b32_e32 v217, v213
	v_mov_b32_e32 v218, v212
	v_mov_b32_e32 v219, v211
	v_mov_b32_e32 v222, v212
	v_mov_b32_e32 v223, v215
	v_mov_b32_e32 v211, v221
	v_pk_add_f32 v[216:217], v[216:217], v[218:219] neg_lo:[0,1] neg_hi:[0,1]
	v_mov_b32_e32 v218, v138
	v_mov_b32_e32 v219, v207
	v_pk_add_f32 v[210:211], v[222:223], v[210:211] neg_lo:[0,1] neg_hi:[0,1]
	v_pk_add_f32 v[218:219], v[218:219], v[216:217] neg_lo:[0,1] neg_hi:[0,1]
	v_mov_b32_e32 v222, v210
	v_mov_b32_e32 v223, v217
	v_mov_b32_e32 v224, v214
	v_mov_b32_e32 v225, v139
	v_mov_b32_e32 v217, v205
	v_pk_add_f32 v[222:223], v[206:207], v[222:223] neg_lo:[0,1] neg_hi:[0,1]
	v_pk_add_f32 v[216:217], v[224:225], v[216:217] neg_lo:[0,1] neg_hi:[0,1]
	v_mov_b32_e32 v207, v213
	v_pk_add_f32 v[138:139], v[138:139], v[204:205] neg_lo:[0,1] neg_hi:[0,1]
	v_pk_add_f32 v[202:203], v[202:203], v[216:217] neg_lo:[0,1] neg_hi:[0,1]
	v_pk_add_f32 v[204:205], v[206:207], v[210:211] neg_lo:[0,1] neg_hi:[0,1]
	v_pk_add_f32 v[132:133], v[132:133], v[220:221] neg_lo:[0,1] neg_hi:[0,1]
	v_pk_add_f32 v[138:139], v[208:209], v[138:139] neg_lo:[0,1] neg_hi:[0,1]
	v_pk_add_f32 v[206:207], v[132:133], v[204:205]
	v_mov_b32_e32 v205, v219
	v_mov_b32_e32 v133, v203
	v_pk_add_f32 v[208:209], v[218:219], v[202:203]
	v_pk_add_f32 v[132:133], v[204:205], v[132:133]
	v_mov_b32_e32 v202, v206
; __device__ __forceinline__ float log_sigmoid_f(float x) { return fminf(x, 0.f) - log1pf(__expf(-fabsf(x))); }
;     __device__ __forceinline__ void operator()(const f32x4 (&acc)[2][2][4][2], const Unit& u, int wr, int wc, int fr, int fq) const {
;     ...
;                         for (int n = 0; n < 2; ++n) { const int c = 8 * fq + 4 * n; const f32x4 bv = *(const f32x4*)(b_f + c); const f32x4 x = acc[ai][0][m][n] * s + bv; f32x4 lf;
;                             lf[0] = log_sigmoid_f(x[0]); lf[1] = log_sigmoid_f(x[1]); lf[2] = log_sigmoid_f(x[2]); lf[3] = log_sigmoid_f(x[3]);
;                             *(f32x4*)(LF + (size_t)row * 16 + c) = lf; if (dst) *(f32x4*)(dst + c) = lf; } }
	v_pk_add_f32 v[132:133], v[132:133], v[222:223] neg_lo:[0,1] neg_hi:[0,1]
	v_mov_b32_e32 v203, v209
	v_pk_add_f32 v[202:203], v[202:203], v[132:133] neg_lo:[0,1] neg_hi:[0,1]
	v_pk_add_f32 v[132:133], v[138:139], v[132:133] neg_lo:[0,1] neg_hi:[0,1]
	v_pk_add_f32 v[202:203], v[204:205], v[202:203] neg_lo:[0,1] neg_hi:[0,1]
	v_pk_add_f32 v[138:139], v[208:209], v[206:207]
	v_pk_add_f32 v[132:133], v[132:133], v[202:203]
	v_pk_add_f32 v[202:203], v[214:215], v[138:139]
	s_nop 0
	v_pk_add_f32 v[204:205], v[202:203], v[214:215] neg_lo:[0,1] neg_hi:[0,1]
	s_nop 0
	v_pk_add_f32 v[138:139], v[138:139], v[204:205] neg_lo:[0,1] neg_hi:[0,1]
	s_nop 0
	v_pk_add_f32 v[132:133], v[132:133], v[138:139]
	s_nop 0
	v_pk_add_f32 v[132:133], v[202:203], v[132:133]
	s_nop 0
	v_cndmask_b32_e64 v132, v231, v132, s[12:13]
	v_cmp_neq_f32_e64 s[12:13], s4, v183
	s_nop 1
	v_cndmask_b32_e64 v133, v231, v133, s[12:13]
	v_cmp_ngt_f32_e64 s[12:13], -1.0, v183
	s_nop 1
	v_cndmask_b32_e64 v133, v232, v133, s[12:13]
	v_cmp_ngt_f32_e64 s[12:13], -1.0, v173
	s_nop 1
	v_cndmask_b32_e64 v132, v232, v132, s[12:13]
	v_cmp_neq_f32_e64 s[12:13], -1.0, v173
	s_nop 1
	v_cndmask_b32_e64 v132, v233, v132, s[12:13]
	v_cmp_neq_f32_e64 s[12:13], -1.0, v183
	s_nop 1
	v_cndmask_b32_e64 v133, v233, v133, s[12:13]
	v_cmp_lt_f32_e64 s[12:13], |v173|, s5
	v_cndmask_b32_e64 v133, v133, v183, s[14:15]
	s_nop 0
	v_cndmask_b32_e64 v132, v132, v173, s[12:13]
	v_pk_add_f32 v[132:133], v[140:141], v[132:133] neg_lo:[0,1] neg_hi:[0,1]
	global_store_dwordx4 v[136:137], v[130:133], off nt
	s_and_saveexec_b64 s[12:13], vcc
	s_cbranch_execz .LBB0_405
	v_lshl_add_u64 v[138:139], v[134:135], 0, v[150:151]
	global_store_dwordx4 v[138:139], v[130:133], off nt
.LBB0_405:
	s_or_b64 exec, exec, s[12:13]
	global_load_dwordx4 v[130:133], v[158:159], off offset:16
	v_mov_b32_e32 v187, v186
	v_mov_b32_e32 v138, v186
	v_mov_b32_e32 v139, v186
	s_waitcnt vmcnt(0)
	v_pk_fma_f32 v[132:133], v[60:61], v[138:139], v[132:133]
	v_pk_fma_f32 v[138:139], v[58:59], v[186:187], v[130:131]
	s_nop 0
	v_mul_f32_e64 v131, |v138|, s34
	v_exp_f32_e32 v173, v131
	v_min_f32_e32 v130, 0, v138
	v_add_f32_e32 v131, 1.0, v173
	v_add_f32_e32 v138, -1.0, v131
	v_sub_f32_e32 v140, v138, v131
	v_add_f32_e32 v140, 1.0, v140
	v_sub_f32_e32 v138, v173, v138
	v_add_f32_e32 v179, v138, v140
	v_frexp_mant_f32_e32 v138, v131
	v_cvt_f64_f32_e32 v[140:141], v131
	v_cmp_gt_f32_e64 s[12:13], s35, v138
	v_frexp_exp_i32_f64_e32 v138, v[140:141]
	s_nop 0
	v_subbrev_co_u32_e64 v183, s[12:13], 0, v138, s[12:13]
	v_sub_u32_e32 v140, 0, v183
	v_ldexp_f32 v138, v131, v140
	v_min_f32_e32 v131, 0, v139
	v_mul_f32_e64 v139, |v139|, s34
	v_ldexp_f32 v140, v179, v140
	v_exp_f32_e32 v179, v139
	s_nop 0
	v_add_f32_e32 v139, 1.0, v179
	v_add_f32_e32 v141, -1.0, v139
	v_sub_f32_e32 v187, v141, v139
	v_add_f32_e32 v187, 1.0, v187
	v_sub_f32_e32 v141, v179, v141
	v_add_f32_e32 v141, v141, v187
	v_frexp_mant_f32_e32 v187, v139
	v_cvt_f64_f32_e32 v[202:203], v139
	v_cmp_gt_f32_e64 s[12:13], s35, v187
	v_frexp_exp_i32_f64_e32 v187, v[202:203]
	v_cmp_lt_f32_e64 s[14:15], |v179|, s5
	v_subbrev_co_u32_e64 v187, s[12:13], 0, v187, s[12:13]
	v_sub_u32_e32 v191, 0, v187
	v_ldexp_f32 v139, v139, v191
	v_pk_add_f32 v[202:203], v[138:139], 1.0 op_sel_hi:[1,0]
	v_ldexp_f32 v141, v141, v191
	v_pk_add_f32 v[204:205], v[202:203], -1.0 op_sel_hi:[1,0]
	v_pk_add_f32 v[210:211], v[138:139], -1.0 op_sel_hi:[1,0]
	v_pk_add_f32 v[204:205], v[138:139], v[204:205] neg_lo:[0,1] neg_hi:[0,1]
	v_pk_add_f32 v[212:213], v[210:211], 1.0 op_sel_hi:[1,0]
	v_pk_add_f32 v[204:205], v[140:141], v[204:205]
	v_pk_add_f32 v[138:139], v[138:139], v[212:213] neg_lo:[0,1] neg_hi:[0,1]
	v_pk_add_f32 v[206:207], v[202:203], v[204:205]
	v_pk_add_f32 v[138:139], v[140:141], v[138:139]
	v_rcp_f32_e32 v208, v206
	v_rcp_f32_e32 v209, v207
	v_pk_add_f32 v[140:141], v[210:211], v[138:139]
	v_pk_add_f32 v[202:203], v[206:207], v[202:203] neg_lo:[0,1] neg_hi:[0,1]
	v_pk_add_f32 v[210:211], v[140:141], v[210:211] neg_lo:[0,1] neg_hi:[0,1]
	v_pk_add_f32 v[202:203], v[204:205], v[202:203] neg_lo:[0,1] neg_hi:[0,1]
	v_pk_mul_f32 v[204:205], v[140:141], v[208:209]
	v_pk_add_f32 v[138:139], v[138:139], v[210:211] neg_lo:[0,1] neg_hi:[0,1]
	v_pk_mul_f32 v[210:211], v[206:207], v[204:205]
	v_cmp_neq_f32_e64 s[12:13], s4, v173
	v_pk_fma_f32 v[212:213], v[204:205], v[206:207], v[210:211] neg_lo:[0,0,1] neg_hi:[0,0,1]
	s_nop 0
	v_pk_fma_f32 v[212:213], v[204:205], v[202:203], v[212:213]
	s_nop 0
	v_pk_add_f32 v[214:215], v[210:211], v[212:213]
	s_nop 0
	v_pk_add_f32 v[216:217], v[140:141], v[214:215] neg_lo:[0,1] neg_hi:[0,1]
	v_pk_add_f32 v[210:211], v[214:215], v[210:211] neg_lo:[0,1] neg_hi:[0,1]
	v_pk_add_f32 v[140:141], v[140:141], v[216:217] neg_lo:[0,1] neg_hi:[0,1]
	s_nop 0
	v_pk_add_f32 v[140:141], v[140:141], v[214:215] neg_lo:[0,1] neg_hi:[0,1]
	s_nop 0
	v_pk_add_f32 v[138:139], v[138:139], v[140:141]
	v_pk_add_f32 v[140:141], v[210:211], v[212:213] neg_lo:[0,1] neg_hi:[0,1]
	s_nop 0
	v_pk_add_f32 v[138:139], v[140:141], v[138:139]
	s_nop 0
	v_pk_add_f32 v[140:141], v[216:217], v[138:139]
	s_nop 0
	v_pk_mul_f32 v[210:211], v[208:209], v[140:141]
	s_nop 0
	v_pk_mul_f32 v[212:213], v[206:207], v[210:211]
	s_nop 0
	v_pk_fma_f32 v[206:207], v[210:211], v[206:207], v[212:213] neg_lo:[0,0,1] neg_hi:[0,0,1]
	s_nop 0
	v_pk_fma_f32 v[202:203], v[210:211], v[202:203], v[206:207]
	v_pk_add_f32 v[206:207], v[216:217], v[140:141] neg_lo:[0,1] neg_hi:[0,1]
	s_nop 0
	v_pk_add_f32 v[138:139], v[138:139], v[206:207]
	v_pk_add_f32 v[206:207], v[212:213], v[202:203]
	s_nop 0
	v_pk_add_f32 v[214:215], v[140:141], v[206:207] neg_lo:[0,1] neg_hi:[0,1]
; __device__ __forceinline__ float log_sigmoid_f(float x) { return fminf(x, 0.f) - log1pf(__expf(-fabsf(x))); }
;     __device__ __forceinline__ void operator()(const f32x4 (&acc)[2][2][4][2], const Unit& u, int wr, int wc, int fr, int fq) const {
;     ...
;                         for (int n = 0; n < 2; ++n) { const int c = 8 * fq + 4 * n; const f32x4 bv = *(const f32x4*)(b_f + c); const f32x4 x = acc[ai][0][m][n] * s + bv; f32x4 lf;
;                             lf[0] = log_sigmoid_f(x[0]); lf[1] = log_sigmoid_f(x[1]); lf[2] = log_sigmoid_f(x[2]); lf[3] = log_sigmoid_f(x[3]);
;                             *(f32x4*)(LF + (size_t)row * 16 + c) = lf; if (dst) *(f32x4*)(dst + c) = lf; } }
	v_pk_add_f32 v[212:213], v[206:207], v[212:213] neg_lo:[0,1] neg_hi:[0,1]
	v_pk_add_f32 v[140:141], v[140:141], v[214:215] neg_lo:[0,1] neg_hi:[0,1]
	s_nop 0
	v_pk_add_f32 v[140:141], v[140:141], v[206:207] neg_lo:[0,1] neg_hi:[0,1]
	s_nop 0
	v_pk_add_f32 v[138:139], v[138:139], v[140:141]
	v_pk_add_f32 v[140:141], v[212:213], v[202:203] neg_lo:[0,1] neg_hi:[0,1]
	s_nop 0
	v_pk_add_f32 v[138:139], v[140:141], v[138:139]
	v_pk_add_f32 v[140:141], v[204:205], v[210:211]
	v_pk_add_f32 v[138:139], v[214:215], v[138:139]
	v_pk_add_f32 v[202:203], v[140:141], v[204:205] neg_lo:[0,1] neg_hi:[0,1]
	v_pk_mul_f32 v[138:139], v[208:209], v[138:139]
	v_pk_add_f32 v[202:203], v[210:211], v[202:203] neg_lo:[0,1] neg_hi:[0,1]
	v_cvt_f32_i32_e32 v211, v187
	v_pk_add_f32 v[138:139], v[202:203], v[138:139]
	v_cvt_f32_i32_e32 v210, v183
	v_pk_add_f32 v[204:205], v[140:141], v[138:139]
	s_nop 0
	v_pk_add_f32 v[140:141], v[204:205], v[140:141] neg_lo:[0,1] neg_hi:[0,1]
	v_pk_mul_f32 v[206:207], v[204:205], v[204:205]
	v_pk_add_f32 v[140:141], v[138:139], v[140:141] neg_lo:[0,1] neg_hi:[0,1]
	v_mov_b64_e32 v[138:139], s[50:51]
	v_pk_fma_f32 v[208:209], v[206:207], s[52:53], v[138:139] op_sel_hi:[1,0,0]
	v_ldexp_f32 v202, v204, 1
	v_pk_fma_f32 v[208:209], v[206:207], v[208:209], s[54:55] op_sel_hi:[1,1,0]
	v_ldexp_f32 v203, v205, 1
	v_pk_mul_f32 v[204:205], v[204:205], v[206:207]
	v_ldexp_f32 v213, v141, 1
	v_pk_mul_f32 v[214:215], v[204:205], v[208:209]
	v_pk_mul_f32 v[206:207], v[210:211], s[64:65] op_sel_hi:[1,0]
	v_pk_add_f32 v[204:205], v[202:203], v[214:215]
	v_ldexp_f32 v140, v140, 1
	v_pk_add_f32 v[202:203], v[204:205], v[202:203] neg_lo:[0,1] neg_hi:[0,1]
	v_pk_fma_f32 v[208:209], v[210:211], s[64:65], v[206:207] op_sel_hi:[1,0,1] neg_lo:[0,0,1] neg_hi:[0,0,1]
	v_pk_add_f32 v[216:217], v[214:215], v[202:203] neg_lo:[0,1] neg_hi:[0,1]
	v_mov_b32_e32 v141, v213
	v_pk_fma_f32 v[208:209], v[210:211], s[66:67], v[208:209] op_sel_hi:[1,0,1]
	v_pk_add_f32 v[214:215], v[140:141], v[216:217]
	v_mov_b32_e32 v202, v206
	v_mov_b32_e32 v203, v217
	v_mov_b32_e32 v212, v208
	v_mov_b32_e32 v141, v215
	v_mov_b32_e32 v217, v205
	v_pk_add_f32 v[210:211], v[206:207], v[208:209]
	v_pk_add_f32 v[202:203], v[202:203], v[212:213]
	v_pk_add_f32 v[212:213], v[140:141], v[216:217]
	v_pk_add_f32 v[216:217], v[204:205], v[214:215]
	v_mov_b32_e32 v224, v204
	v_pk_add_f32 v[140:141], v[210:211], v[216:217]
	v_mov_b32_e32 v222, v216
	v_mov_b32_e32 v223, v141
	v_mov_b32_e32 v225, v211
	v_pk_add_f32 v[222:223], v[222:223], v[224:225] neg_lo:[0,1] neg_hi:[0,1]
	v_mov_b32_e32 v218, v140
	v_mov_b32_e32 v219, v211
	v_mov_b32_e32 v220, v210
	v_mov_b32_e32 v221, v207
	v_mov_b32_e32 v224, v210
	v_mov_b32_e32 v225, v141
	v_mov_b32_e32 v207, v223
	v_pk_add_f32 v[218:219], v[218:219], v[220:221] neg_lo:[0,1] neg_hi:[0,1]
	v_mov_b32_e32 v220, v216
	v_mov_b32_e32 v221, v209
	v_pk_add_f32 v[206:207], v[224:225], v[206:207] neg_lo:[0,1] neg_hi:[0,1]
	v_pk_add_f32 v[220:221], v[220:221], v[218:219] neg_lo:[0,1] neg_hi:[0,1]
	v_mov_b32_e32 v224, v206
	v_mov_b32_e32 v225, v219
	v_mov_b32_e32 v226, v140
	v_mov_b32_e32 v227, v217
	v_mov_b32_e32 v219, v205
	v_pk_add_f32 v[224:225], v[208:209], v[224:225] neg_lo:[0,1] neg_hi:[0,1]
	v_pk_add_f32 v[218:219], v[226:227], v[218:219] neg_lo:[0,1] neg_hi:[0,1]
	v_mov_b32_e32 v209, v211
	v_pk_add_f32 v[202:203], v[202:203], v[218:219] neg_lo:[0,1] neg_hi:[0,1]
	v_pk_add_f32 v[206:207], v[208:209], v[206:207] neg_lo:[0,1] neg_hi:[0,1]
	v_pk_add_f32 v[208:209], v[212:213], v[222:223] neg_lo:[0,1] neg_hi:[0,1]
	v_pk_add_f32 v[212:213], v[220:221], v[202:203]
	v_pk_add_f32 v[210:211], v[208:209], v[206:207]
	v_mov_b32_e32 v207, v221
	v_mov_b32_e32 v209, v203
	v_pk_add_f32 v[202:203], v[206:207], v[208:209]
	v_pk_add_f32 v[204:205], v[216:217], v[204:205] neg_lo:[0,1] neg_hi:[0,1]
	v_pk_add_f32 v[202:203], v[202:203], v[224:225] neg_lo:[0,1] neg_hi:[0,1]
	v_mov_b32_e32 v208, v210
	v_mov_b32_e32 v209, v213
	v_pk_add_f32 v[204:205], v[214:215], v[204:205] neg_lo:[0,1] neg_hi:[0,1]
	v_pk_add_f32 v[208:209], v[208:209], v[202:203] neg_lo:[0,1] neg_hi:[0,1]
	v_pk_add_f32 v[202:203], v[204:205], v[202:203] neg_lo:[0,1] neg_hi:[0,1]
	v_pk_add_f32 v[206:207], v[206:207], v[208:209] neg_lo:[0,1] neg_hi:[0,1]
	v_pk_add_f32 v[204:205], v[212:213], v[210:211]
	v_pk_add_f32 v[202:203], v[202:203], v[206:207]
	v_pk_add_f32 v[206:207], v[140:141], v[204:205]
	s_nop 0
	v_pk_add_f32 v[140:141], v[206:207], v[140:141] neg_lo:[0,1] neg_hi:[0,1]
	s_nop 0
	v_pk_add_f32 v[140:141], v[204:205], v[140:141] neg_lo:[0,1] neg_hi:[0,1]
	s_nop 0
	v_pk_add_f32 v[140:141], v[202:203], v[140:141]
	s_nop 0
	v_pk_add_f32 v[140:141], v[206:207], v[140:141]
	s_nop 0
	v_cndmask_b32_e64 v140, v231, v140, s[12:13]
	v_cmp_neq_f32_e64 s[12:13], s4, v179
	s_nop 1
	v_cndmask_b32_e64 v141, v231, v141, s[12:13]
	v_cmp_ngt_f32_e64 s[12:13], -1.0, v179
	s_nop 1
	v_cndmask_b32_e64 v141, v232, v141, s[12:13]
	v_cmp_ngt_f32_e64 s[12:13], -1.0, v173
	s_nop 1
	v_cndmask_b32_e64 v140, v232, v140, s[12:13]
	v_cmp_neq_f32_e64 s[12:13], -1.0, v173
	s_nop 1
	v_cndmask_b32_e64 v140, v233, v140, s[12:13]
	v_cmp_neq_f32_e64 s[12:13], -1.0, v179
	s_nop 1
	v_cndmask_b32_e64 v141, v233, v141, s[12:13]
	v_cmp_lt_f32_e64 s[12:13], |v173|, s5
	v_cndmask_b32_e64 v141, v141, v179, s[14:15]
	s_nop 0
	v_cndmask_b32_e64 v140, v140, v173, s[12:13]
	v_pk_add_f32 v[130:131], v[130:131], v[140:141] neg_lo:[0,1] neg_hi:[0,1]
	v_min_f32_e32 v140, 0, v132
	v_mul_f32_e64 v132, |v132|, s34
	v_exp_f32_e32 v173, v132
	s_nop 0
	v_add_f32_e32 v132, 1.0, v173
	v_add_f32_e32 v141, -1.0, v132
	v_sub_f32_e32 v179, v141, v132
	v_add_f32_e32 v179, 1.0, v179
; __device__ __forceinline__ float log_sigmoid_f(float x) { return fminf(x, 0.f) - log1pf(__expf(-fabsf(x))); }
	v_sub_f32_e32 v141, v173, v141
	v_add_f32_e32 v141, v141, v179
	v_frexp_mant_f32_e32 v179, v132
	v_cvt_f64_f32_e32 v[202:203], v132
	v_cmp_gt_f32_e64 s[12:13], s35, v179
	v_frexp_exp_i32_f64_e32 v179, v[202:203]
	s_nop 0
	v_subbrev_co_u32_e64 v179, s[12:13], 0, v179, s[12:13]
	v_sub_u32_e32 v183, 0, v179
	v_ldexp_f32 v202, v141, v183
	v_min_f32_e32 v141, 0, v133
	v_mul_f32_e64 v133, |v133|, s34
	v_ldexp_f32 v132, v132, v183
	v_exp_f32_e32 v183, v133
	s_nop 0
	v_add_f32_e32 v133, 1.0, v183
	v_add_f32_e32 v187, -1.0, v133
	v_sub_f32_e32 v191, v187, v133
	v_add_f32_e32 v191, 1.0, v191
	v_sub_f32_e32 v187, v183, v187
	v_add_f32_e32 v187, v187, v191
	v_frexp_mant_f32_e32 v191, v133
	v_cvt_f64_f32_e32 v[204:205], v133
	v_cmp_gt_f32_e64 s[12:13], s35, v191
	v_frexp_exp_i32_f64_e32 v191, v[204:205]
	v_cmp_lt_f32_e64 s[14:15], |v183|, s5
	v_subbrev_co_u32_e64 v191, s[12:13], 0, v191, s[12:13]
	v_sub_u32_e32 v195, 0, v191
	v_ldexp_f32 v133, v133, v195
	v_pk_add_f32 v[204:205], v[132:133], 1.0 op_sel_hi:[1,0]
	v_ldexp_f32 v203, v187, v195
	v_pk_add_f32 v[206:207], v[204:205], -1.0 op_sel_hi:[1,0]
	v_pk_add_f32 v[212:213], v[132:133], -1.0 op_sel_hi:[1,0]
	v_pk_add_f32 v[206:207], v[132:133], v[206:207] neg_lo:[0,1] neg_hi:[0,1]
	v_pk_add_f32 v[214:215], v[212:213], 1.0 op_sel_hi:[1,0]
	v_pk_add_f32 v[206:207], v[202:203], v[206:207]
	v_pk_add_f32 v[132:133], v[132:133], v[214:215] neg_lo:[0,1] neg_hi:[0,1]
	v_pk_add_f32 v[208:209], v[204:205], v[206:207]
	v_pk_add_f32 v[132:133], v[202:203], v[132:133]
	v_rcp_f32_e32 v210, v208
	v_rcp_f32_e32 v211, v209
	v_pk_add_f32 v[202:203], v[212:213], v[132:133]
	v_pk_add_f32 v[204:205], v[208:209], v[204:205] neg_lo:[0,1] neg_hi:[0,1]
	v_pk_add_f32 v[212:213], v[202:203], v[212:213] neg_lo:[0,1] neg_hi:[0,1]
	v_pk_add_f32 v[204:205], v[206:207], v[204:205] neg_lo:[0,1] neg_hi:[0,1]
	v_pk_mul_f32 v[206:207], v[202:203], v[210:211]
	v_pk_add_f32 v[132:133], v[132:133], v[212:213] neg_lo:[0,1] neg_hi:[0,1]
	v_pk_mul_f32 v[212:213], v[208:209], v[206:207]
	v_cmp_neq_f32_e64 s[12:13], s4, v173
	v_pk_fma_f32 v[214:215], v[206:207], v[208:209], v[212:213] neg_lo:[0,0,1] neg_hi:[0,0,1]
	s_nop 0
	v_pk_fma_f32 v[214:215], v[206:207], v[204:205], v[214:215]
	s_nop 0
	v_pk_add_f32 v[216:217], v[212:213], v[214:215]
	s_nop 0
	v_pk_add_f32 v[218:219], v[202:203], v[216:217] neg_lo:[0,1] neg_hi:[0,1]
	v_pk_add_f32 v[212:213], v[216:217], v[212:213] neg_lo:[0,1] neg_hi:[0,1]
	v_pk_add_f32 v[202:203], v[202:203], v[218:219] neg_lo:[0,1] neg_hi:[0,1]
	s_nop 0
	v_pk_add_f32 v[202:203], v[202:203], v[216:217] neg_lo:[0,1] neg_hi:[0,1]
	s_nop 0
	v_pk_add_f32 v[132:133], v[132:133], v[202:203]
	v_pk_add_f32 v[202:203], v[212:213], v[214:215] neg_lo:[0,1] neg_hi:[0,1]
	s_nop 0
	v_pk_add_f32 v[132:133], v[202:203], v[132:133]
	s_nop 0
	v_pk_add_f32 v[202:203], v[218:219], v[132:133]
	s_nop 0
	v_pk_mul_f32 v[212:213], v[210:211], v[202:203]
	s_nop 0
	v_pk_mul_f32 v[214:215], v[208:209], v[212:213]
	s_nop 0
	v_pk_fma_f32 v[208:209], v[212:213], v[208:209], v[214:215] neg_lo:[0,0,1] neg_hi:[0,0,1]
	s_nop 0
	v_pk_fma_f32 v[204:205], v[212:213], v[204:205], v[208:209]
	v_pk_add_f32 v[208:209], v[218:219], v[202:203] neg_lo:[0,1] neg_hi:[0,1]
	s_nop 0
	v_pk_add_f32 v[132:133], v[132:133], v[208:209]
	v_pk_add_f32 v[208:209], v[214:215], v[204:205]
	s_nop 0
	v_pk_add_f32 v[216:217], v[202:203], v[208:209] neg_lo:[0,1] neg_hi:[0,1]
	v_pk_add_f32 v[214:215], v[208:209], v[214:215] neg_lo:[0,1] neg_hi:[0,1]
	v_pk_add_f32 v[202:203], v[202:203], v[216:217] neg_lo:[0,1] neg_hi:[0,1]
	s_nop 0
	v_pk_add_f32 v[202:203], v[202:203], v[208:209] neg_lo:[0,1] neg_hi:[0,1]
	s_nop 0
	v_pk_add_f32 v[132:133], v[132:133], v[202:203]
	v_pk_add_f32 v[202:203], v[214:215], v[204:205] neg_lo:[0,1] neg_hi:[0,1]
	s_nop 0
	v_pk_add_f32 v[132:133], v[202:203], v[132:133]
	v_pk_add_f32 v[202:203], v[206:207], v[212:213]
	v_pk_add_f32 v[132:133], v[216:217], v[132:133]
	v_pk_add_f32 v[204:205], v[202:203], v[206:207] neg_lo:[0,1] neg_hi:[0,1]
	v_pk_mul_f32 v[132:133], v[210:211], v[132:133]
	v_pk_add_f32 v[204:205], v[212:213], v[204:205] neg_lo:[0,1] neg_hi:[0,1]
	s_nop 0
	v_pk_add_f32 v[132:133], v[204:205], v[132:133]
	s_nop 0
	v_pk_add_f32 v[204:205], v[202:203], v[132:133]
	s_nop 0
	v_pk_mul_f32 v[206:207], v[204:205], v[204:205]
	v_pk_add_f32 v[202:203], v[204:205], v[202:203] neg_lo:[0,1] neg_hi:[0,1]
	v_pk_fma_f32 v[138:139], v[206:207], s[52:53], v[138:139] op_sel_hi:[1,0,0]
	v_pk_add_f32 v[132:133], v[132:133], v[202:203] neg_lo:[0,1] neg_hi:[0,1]
; __device__ __forceinline__ float log_sigmoid_f(float x) { return fminf(x, 0.f) - log1pf(__expf(-fabsf(x))); }
;     __device__ __forceinline__ void operator()(const f32x4 (&acc)[2][2][4][2], const Unit& u, int wr, int wc, int fr, int fq) const {
;     ...
;                         for (int n = 0; n < 2; ++n) { const int c = 8 * fq + 4 * n; const f32x4 bv = *(const f32x4*)(b_f + c); const f32x4 x = acc[ai][0][m][n] * s + bv; f32x4 lf;
;                             lf[0] = log_sigmoid_f(x[0]); lf[1] = log_sigmoid_f(x[1]); lf[2] = log_sigmoid_f(x[2]); lf[3] = log_sigmoid_f(x[3]);
;                             *(f32x4*)(LF + (size_t)row * 16 + c) = lf; if (dst) *(f32x4*)(dst + c) = lf; } }
	v_ldexp_f32 v202, v204, 1
	v_pk_fma_f32 v[138:139], v[206:207], v[138:139], s[54:55] op_sel_hi:[1,1,0]
	v_ldexp_f32 v203, v205, 1
	v_pk_mul_f32 v[204:205], v[204:205], v[206:207]
	v_cvt_f32_i32_e32 v207, v191
	v_cvt_f32_i32_e32 v206, v179
	v_pk_mul_f32 v[138:139], v[204:205], v[138:139]
	v_ldexp_f32 v209, v133, 1
	v_pk_add_f32 v[204:205], v[202:203], v[138:139]
	v_pk_mul_f32 v[210:211], v[206:207], s[64:65] op_sel_hi:[1,0]
	v_pk_add_f32 v[202:203], v[204:205], v[202:203] neg_lo:[0,1] neg_hi:[0,1]
	v_pk_fma_f32 v[212:213], v[206:207], s[64:65], v[210:211] op_sel_hi:[1,0,1] neg_lo:[0,0,1] neg_hi:[0,0,1]
	v_pk_add_f32 v[138:139], v[138:139], v[202:203] neg_lo:[0,1] neg_hi:[0,1]
	v_pk_fma_f32 v[206:207], v[206:207], s[66:67], v[212:213] op_sel_hi:[1,0,1]
	v_ldexp_f32 v132, v132, 1
	v_mov_b32_e32 v202, v210
	v_mov_b32_e32 v203, v139
	v_mov_b32_e32 v208, v206
	v_mov_b32_e32 v133, v209
	v_pk_add_f32 v[202:203], v[202:203], v[208:209]
	v_pk_add_f32 v[208:209], v[132:133], v[138:139]
	v_mov_b32_e32 v139, v205
	v_mov_b32_e32 v133, v209
	v_pk_add_f32 v[212:213], v[210:211], v[206:207]
	v_pk_add_f32 v[132:133], v[132:133], v[138:139]
	v_pk_add_f32 v[138:139], v[204:205], v[208:209]
	v_mov_b32_e32 v222, v204
	v_pk_add_f32 v[214:215], v[212:213], v[138:139]
	v_mov_b32_e32 v220, v138
	v_mov_b32_e32 v221, v215
	v_mov_b32_e32 v223, v213
	v_pk_add_f32 v[220:221], v[220:221], v[222:223] neg_lo:[0,1] neg_hi:[0,1]
	v_mov_b32_e32 v216, v214
	v_mov_b32_e32 v217, v213
	v_mov_b32_e32 v218, v212
	v_mov_b32_e32 v219, v211
	v_mov_b32_e32 v222, v212
	v_mov_b32_e32 v223, v215
	v_mov_b32_e32 v211, v221
	v_pk_add_f32 v[216:217], v[216:217], v[218:219] neg_lo:[0,1] neg_hi:[0,1]
	v_mov_b32_e32 v218, v138
	v_mov_b32_e32 v219, v207
	v_pk_add_f32 v[210:211], v[222:223], v[210:211] neg_lo:[0,1] neg_hi:[0,1]
	v_pk_add_f32 v[218:219], v[218:219], v[216:217] neg_lo:[0,1] neg_hi:[0,1]
	v_mov_b32_e32 v222, v210
	v_mov_b32_e32 v223, v217
	v_mov_b32_e32 v224, v214
	v_mov_b32_e32 v225, v139
	v_mov_b32_e32 v217, v205
	v_pk_add_f32 v[222:223], v[206:207], v[222:223] neg_lo:[0,1] neg_hi:[0,1]
	v_pk_add_f32 v[216:217], v[224:225], v[216:217] neg_lo:[0,1] neg_hi:[0,1]
	v_mov_b32_e32 v207, v213
	v_pk_add_f32 v[138:139], v[138:139], v[204:205] neg_lo:[0,1] neg_hi:[0,1]
	v_pk_add_f32 v[202:203], v[202:203], v[216:217] neg_lo:[0,1] neg_hi:[0,1]
	v_pk_add_f32 v[204:205], v[206:207], v[210:211] neg_lo:[0,1] neg_hi:[0,1]
	v_pk_add_f32 v[132:133], v[132:133], v[220:221] neg_lo:[0,1] neg_hi:[0,1]
	v_pk_add_f32 v[138:139], v[208:209], v[138:139] neg_lo:[0,1] neg_hi:[0,1]
	v_pk_add_f32 v[206:207], v[132:133], v[204:205]
	v_mov_b32_e32 v205, v219
	v_mov_b32_e32 v133, v203
	v_pk_add_f32 v[208:209], v[218:219], v[202:203]
	v_pk_add_f32 v[132:133], v[204:205], v[132:133]
	v_mov_b32_e32 v202, v206
	v_pk_add_f32 v[132:133], v[132:133], v[222:223] neg_lo:[0,1] neg_hi:[0,1]
	v_mov_b32_e32 v203, v209
	v_pk_add_f32 v[202:203], v[202:203], v[132:133] neg_lo:[0,1] neg_hi:[0,1]
	v_pk_add_f32 v[132:133], v[138:139], v[132:133] neg_lo:[0,1] neg_hi:[0,1]
	v_pk_add_f32 v[202:203], v[204:205], v[202:203] neg_lo:[0,1] neg_hi:[0,1]
	v_pk_add_f32 v[138:139], v[208:209], v[206:207]
	v_pk_add_f32 v[132:133], v[132:133], v[202:203]
	v_pk_add_f32 v[202:203], v[214:215], v[138:139]
	s_nop 0
	v_pk_add_f32 v[204:205], v[202:203], v[214:215] neg_lo:[0,1] neg_hi:[0,1]
	s_nop 0
	v_pk_add_f32 v[138:139], v[138:139], v[204:205] neg_lo:[0,1] neg_hi:[0,1]
	s_nop 0
	v_pk_add_f32 v[132:133], v[132:133], v[138:139]
	s_nop 0
	v_pk_add_f32 v[132:133], v[202:203], v[132:133]
	s_nop 0
	v_cndmask_b32_e64 v132, v231, v132, s[12:13]
	v_cmp_neq_f32_e64 s[12:13], s4, v183
	s_nop 1
	v_cndmask_b32_e64 v133, v231, v133, s[12:13]
	v_cmp_ngt_f32_e64 s[12:13], -1.0, v183
	s_nop 1
	v_cndmask_b32_e64 v133, v232, v133, s[12:13]
	v_cmp_ngt_f32_e64 s[12:13], -1.0, v173
	s_nop 1
	v_cndmask_b32_e64 v132, v232, v132, s[12:13]
	v_cmp_neq_f32_e64 s[12:13], -1.0, v173
	s_nop 1
	v_cndmask_b32_e64 v132, v233, v132, s[12:13]
	v_cmp_neq_f32_e64 s[12:13], -1.0, v183
	s_nop 1
	v_cndmask_b32_e64 v133, v233, v133, s[12:13]
	v_cmp_lt_f32_e64 s[12:13], |v173|, s5
	v_cndmask_b32_e64 v133, v133, v183, s[14:15]
	s_nop 0
	v_cndmask_b32_e64 v132, v132, v173, s[12:13]
	v_pk_add_f32 v[132:133], v[140:141], v[132:133] neg_lo:[0,1] neg_hi:[0,1]
	global_store_dwordx4 v[136:137], v[130:133], off offset:16 nt
	s_and_saveexec_b64 s[12:13], vcc
	s_cbranch_execz .LBB0_407
	v_lshl_add_u64 v[134:135], v[134:135], 0, v[150:151]
	global_store_dwordx4 v[134:135], v[130:133], off offset:16 nt

; __device__ __forceinline__ float log_sigmoid_f(float x) { return fminf(x, 0.f) - log1pf(__expf(-fabsf(x))); }
;     __device__ __forceinline__ void operator()(const f32x4 (&acc)[2][2][4][2], const Unit& u, int wr, int wc, int fr, int fq) const {
;     ...
;                     for (int m = 0; m < 4; ++m) { const int row = row0 + ai * HALF + m * 16; const float s = sc8[ai][m];
;                         float* dst = nullptr;
;                         if (pm == 0) dst = o_lfs + (size_t)row * 16; else { const int t = row - G_ROWP; if (t < G_TP) dst = o_lfp + (size_t)t * 16; }
; #pragma unroll
;                         for (int n = 0; n < 2; ++n) { const int c = 8 * fq + 4 * n; const f32x4 bv = *(const f32x4*)(b_f + c); const f32x4 x = acc[ai][0][m][n] * s + bv; f32x4 lf;
;                             lf[0] = log_sigmoid_f(x[0]); lf[1] = log_sigmoid_f(x[1]); lf[2] = log_sigmoid_f(x[2]); lf[3] = log_sigmoid_f(x[3]);
.LBB0_410:
	global_load_dwordx4 v[130:133], v[158:159], off
	v_cmp_ne_u64_e32 vcc, 0, v[134:135]
	v_lshl_add_u64 v[136:137], v[162:163], 0, v[136:137]
	s_waitcnt vmcnt(0)
	v_pk_fma_f32 v[138:139], v[46:47], v[182:183], v[130:131] op_sel_hi:[1,0,1]
	s_nop 0
	v_mul_f32_e64 v131, |v138|, s34
	v_exp_f32_e32 v173, v131
	v_min_f32_e32 v130, 0, v138
	v_pk_fma_f32 v[132:133], v[48:49], v[182:183], v[132:133] op_sel_hi:[1,0,1]
	v_add_f32_e32 v131, 1.0, v173
	v_add_f32_e32 v138, -1.0, v131
	v_sub_f32_e32 v140, v138, v131
	v_add_f32_e32 v140, 1.0, v140
	v_sub_f32_e32 v138, v173, v138
	v_add_f32_e32 v179, v138, v140
	v_frexp_mant_f32_e32 v138, v131
	v_cvt_f64_f32_e32 v[140:141], v131
	v_cmp_gt_f32_e64 s[12:13], s35, v138
	v_frexp_exp_i32_f64_e32 v138, v[140:141]
	s_nop 0
	v_subbrev_co_u32_e64 v183, s[12:13], 0, v138, s[12:13]
	v_sub_u32_e32 v140, 0, v183
	v_ldexp_f32 v138, v131, v140
	v_min_f32_e32 v131, 0, v139
	v_mul_f32_e64 v139, |v139|, s34
	v_ldexp_f32 v140, v179, v140
	v_exp_f32_e32 v179, v139
	s_nop 0
	v_add_f32_e32 v139, 1.0, v179
	v_add_f32_e32 v141, -1.0, v139
	v_sub_f32_e32 v187, v141, v139
	v_add_f32_e32 v187, 1.0, v187
	v_sub_f32_e32 v141, v179, v141
	v_add_f32_e32 v141, v141, v187
	v_frexp_mant_f32_e32 v187, v139
	v_cvt_f64_f32_e32 v[202:203], v139
	v_cmp_gt_f32_e64 s[12:13], s35, v187
	v_frexp_exp_i32_f64_e32 v187, v[202:203]
	v_cmp_lt_f32_e64 s[14:15], |v179|, s5
	v_subbrev_co_u32_e64 v187, s[12:13], 0, v187, s[12:13]
	v_sub_u32_e32 v191, 0, v187
	v_ldexp_f32 v139, v139, v191
	v_pk_add_f32 v[202:203], v[138:139], 1.0 op_sel_hi:[1,0]
	v_ldexp_f32 v141, v141, v191
	v_pk_add_f32 v[204:205], v[202:203], -1.0 op_sel_hi:[1,0]
	v_pk_add_f32 v[210:211], v[138:139], -1.0 op_sel_hi:[1,0]
	v_pk_add_f32 v[204:205], v[138:139], v[204:205] neg_lo:[0,1] neg_hi:[0,1]
	v_pk_add_f32 v[212:213], v[210:211], 1.0 op_sel_hi:[1,0]
	v_pk_add_f32 v[204:205], v[140:141], v[204:205]
	v_pk_add_f32 v[138:139], v[138:139], v[212:213] neg_lo:[0,1] neg_hi:[0,1]
	v_pk_add_f32 v[206:207], v[202:203], v[204:205]
	v_pk_add_f32 v[138:139], v[140:141], v[138:139]
	v_rcp_f32_e32 v208, v206
	v_rcp_f32_e32 v209, v207
	v_pk_add_f32 v[140:141], v[210:211], v[138:139]
	v_pk_add_f32 v[202:203], v[206:207], v[202:203] neg_lo:[0,1] neg_hi:[0,1]
	v_pk_add_f32 v[210:211], v[140:141], v[210:211] neg_lo:[0,1] neg_hi:[0,1]
	v_pk_add_f32 v[202:203], v[204:205], v[202:203] neg_lo:[0,1] neg_hi:[0,1]
	v_pk_mul_f32 v[204:205], v[140:141], v[208:209]
	v_pk_add_f32 v[138:139], v[138:139], v[210:211] neg_lo:[0,1] neg_hi:[0,1]
	v_pk_mul_f32 v[210:211], v[206:207], v[204:205]
	v_cmp_neq_f32_e64 s[12:13], s4, v173
	v_pk_fma_f32 v[212:213], v[204:205], v[206:207], v[210:211] neg_lo:[0,0,1] neg_hi:[0,0,1]
	s_nop 0
	v_pk_fma_f32 v[212:213], v[204:205], v[202:203], v[212:213]
	s_nop 0
	v_pk_add_f32 v[214:215], v[210:211], v[212:213]
	s_nop 0
	v_pk_add_f32 v[216:217], v[140:141], v[214:215] neg_lo:[0,1] neg_hi:[0,1]
	v_pk_add_f32 v[210:211], v[214:215], v[210:211] neg_lo:[0,1] neg_hi:[0,1]
	v_pk_add_f32 v[140:141], v[140:141], v[216:217] neg_lo:[0,1] neg_hi:[0,1]
	s_nop 0
	v_pk_add_f32 v[140:141], v[140:141], v[214:215] neg_lo:[0,1] neg_hi:[0,1]
	s_nop 0
	v_pk_add_f32 v[138:139], v[138:139], v[140:141]
	v_pk_add_f32 v[140:141], v[210:211], v[212:213] neg_lo:[0,1] neg_hi:[0,1]
	s_nop 0
	v_pk_add_f32 v[138:139], v[140:141], v[138:139]
	s_nop 0
	v_pk_add_f32 v[140:141], v[216:217], v[138:139]
	s_nop 0
	v_pk_mul_f32 v[210:211], v[208:209], v[140:141]
	s_nop 0
	v_pk_mul_f32 v[212:213], v[206:207], v[210:211]
	s_nop 0
	v_pk_fma_f32 v[206:207], v[210:211], v[206:207], v[212:213] neg_lo:[0,0,1] neg_hi:[0,0,1]
	s_nop 0
	v_pk_fma_f32 v[202:203], v[210:211], v[202:203], v[206:207]
	v_pk_add_f32 v[206:207], v[216:217], v[140:141] neg_lo:[0,1] neg_hi:[0,1]
	s_nop 0
	v_pk_add_f32 v[138:139], v[138:139], v[206:207]
	v_pk_add_f32 v[206:207], v[212:213], v[202:203]
	s_nop 0
	v_pk_add_f32 v[214:215], v[140:141], v[206:207] neg_lo:[0,1] neg_hi:[0,1]
	v_pk_add_f32 v[212:213], v[206:207], v[212:213] neg_lo:[0,1] neg_hi:[0,1]
	v_pk_add_f32 v[140:141], v[140:141], v[214:215] neg_lo:[0,1] neg_hi:[0,1]
	s_nop 0
	v_pk_add_f32 v[140:141], v[140:141], v[206:207] neg_lo:[0,1] neg_hi:[0,1]
	s_nop 0
	v_pk_add_f32 v[138:139], v[138:139], v[140:141]
	v_pk_add_f32 v[140:141], v[212:213], v[202:203] neg_lo:[0,1] neg_hi:[0,1]
	s_nop 0
	v_pk_add_f32 v[138:139], v[140:141], v[138:139]
	v_pk_add_f32 v[140:141], v[204:205], v[210:211]
	v_pk_add_f32 v[138:139], v[214:215], v[138:139]
	v_pk_add_f32 v[202:203], v[140:141], v[204:205] neg_lo:[0,1] neg_hi:[0,1]
	v_pk_mul_f32 v[138:139], v[208:209], v[138:139]
	v_pk_add_f32 v[202:203], v[210:211], v[202:203] neg_lo:[0,1] neg_hi:[0,1]
	s_nop 0
	v_pk_add_f32 v[138:139], v[202:203], v[138:139]
	s_nop 0
	v_pk_add_f32 v[204:205], v[140:141], v[138:139]
	s_nop 0
	v_pk_add_f32 v[140:141], v[204:205], v[140:141] neg_lo:[0,1] neg_hi:[0,1]
	v_pk_mul_f32 v[206:207], v[204:205], v[204:205]
	v_pk_add_f32 v[140:141], v[138:139], v[140:141] neg_lo:[0,1] neg_hi:[0,1]
	v_mov_b64_e32 v[138:139], s[50:51]
	v_pk_fma_f32 v[208:209], v[206:207], s[52:53], v[138:139] op_sel_hi:[1,0,0]
	v_ldexp_f32 v202, v204, 1
	v_pk_fma_f32 v[208:209], v[206:207], v[208:209], s[54:55] op_sel_hi:[1,1,0]
	v_ldexp_f32 v203, v205, 1
	v_pk_mul_f32 v[204:205], v[204:205], v[206:207]
	v_cvt_f32_i32_e32 v207, v187
	v_cvt_f32_i32_e32 v206, v183
	v_pk_mul_f32 v[214:215], v[204:205], v[208:209]
	v_ldexp_f32 v213, v141, 1
	v_pk_add_f32 v[204:205], v[202:203], v[214:215]
	v_pk_mul_f32 v[210:211], v[206:207], s[64:65] op_sel_hi:[1,0]
	v_pk_add_f32 v[202:203], v[204:205], v[202:203] neg_lo:[0,1] neg_hi:[0,1]
	v_ldexp_f32 v140, v140, 1
; __device__ __forceinline__ float log_sigmoid_f(float x) { return fminf(x, 0.f) - log1pf(__expf(-fabsf(x))); }
;     __device__ __forceinline__ void operator()(const f32x4 (&acc)[2][2][4][2], const Unit& u, int wr, int wc, int fr, int fq) const {
;     ...
;                         for (int n = 0; n < 2; ++n) { const int c = 8 * fq + 4 * n; const f32x4 bv = *(const f32x4*)(b_f + c); const f32x4 x = acc[ai][0][m][n] * s + bv; f32x4 lf;
;                             lf[0] = log_sigmoid_f(x[0]); lf[1] = log_sigmoid_f(x[1]); lf[2] = log_sigmoid_f(x[2]); lf[3] = log_sigmoid_f(x[3]);
	v_pk_fma_f32 v[208:209], v[206:207], s[64:65], v[210:211] op_sel_hi:[1,0,1] neg_lo:[0,0,1] neg_hi:[0,0,1]
	v_pk_add_f32 v[216:217], v[214:215], v[202:203] neg_lo:[0,1] neg_hi:[0,1]
	v_mov_b32_e32 v141, v213
	v_pk_fma_f32 v[206:207], v[206:207], s[66:67], v[208:209] op_sel_hi:[1,0,1]
	v_pk_add_f32 v[214:215], v[140:141], v[216:217]
	v_mov_b32_e32 v202, v210
	v_mov_b32_e32 v203, v217
	v_mov_b32_e32 v212, v206
	v_mov_b32_e32 v141, v215
	v_mov_b32_e32 v217, v205
	v_pk_add_f32 v[208:209], v[210:211], v[206:207]
	v_pk_add_f32 v[202:203], v[202:203], v[212:213]
	v_pk_add_f32 v[212:213], v[140:141], v[216:217]
	v_pk_add_f32 v[216:217], v[204:205], v[214:215]
	v_mov_b32_e32 v224, v204
	v_pk_add_f32 v[140:141], v[208:209], v[216:217]
	v_mov_b32_e32 v222, v216
	v_mov_b32_e32 v223, v141
	v_mov_b32_e32 v225, v209
	v_pk_add_f32 v[222:223], v[222:223], v[224:225] neg_lo:[0,1] neg_hi:[0,1]
	v_mov_b32_e32 v218, v140
	v_mov_b32_e32 v219, v209
	v_mov_b32_e32 v220, v208
	v_mov_b32_e32 v221, v211
	v_mov_b32_e32 v224, v208
	v_mov_b32_e32 v225, v141
	v_mov_b32_e32 v211, v223
	v_pk_add_f32 v[218:219], v[218:219], v[220:221] neg_lo:[0,1] neg_hi:[0,1]
	v_mov_b32_e32 v220, v216
	v_mov_b32_e32 v221, v207
	v_pk_add_f32 v[210:211], v[224:225], v[210:211] neg_lo:[0,1] neg_hi:[0,1]
	v_pk_add_f32 v[220:221], v[220:221], v[218:219] neg_lo:[0,1] neg_hi:[0,1]
	v_mov_b32_e32 v224, v210
	v_mov_b32_e32 v225, v219
	v_mov_b32_e32 v226, v140
	v_mov_b32_e32 v227, v217
	v_mov_b32_e32 v219, v205
	v_pk_add_f32 v[224:225], v[206:207], v[224:225] neg_lo:[0,1] neg_hi:[0,1]
	v_pk_add_f32 v[218:219], v[226:227], v[218:219] neg_lo:[0,1] neg_hi:[0,1]
	v_mov_b32_e32 v207, v209
	v_pk_add_f32 v[202:203], v[202:203], v[218:219] neg_lo:[0,1] neg_hi:[0,1]
	v_pk_add_f32 v[206:207], v[206:207], v[210:211] neg_lo:[0,1] neg_hi:[0,1]
	v_pk_add_f32 v[208:209], v[212:213], v[222:223] neg_lo:[0,1] neg_hi:[0,1]
	v_pk_add_f32 v[212:213], v[220:221], v[202:203]
	v_pk_add_f32 v[210:211], v[208:209], v[206:207]
	v_mov_b32_e32 v207, v221
	v_mov_b32_e32 v209, v203
	v_pk_add_f32 v[202:203], v[206:207], v[208:209]
	v_pk_add_f32 v[204:205], v[216:217], v[204:205] neg_lo:[0,1] neg_hi:[0,1]
	v_pk_add_f32 v[202:203], v[202:203], v[224:225] neg_lo:[0,1] neg_hi:[0,1]
	v_mov_b32_e32 v208, v210
	v_mov_b32_e32 v209, v213
	v_pk_add_f32 v[204:205], v[214:215], v[204:205] neg_lo:[0,1] neg_hi:[0,1]
	v_pk_add_f32 v[208:209], v[208:209], v[202:203] neg_lo:[0,1] neg_hi:[0,1]
	v_pk_add_f32 v[202:203], v[204:205], v[202:203] neg_lo:[0,1] neg_hi:[0,1]
	v_pk_add_f32 v[206:207], v[206:207], v[208:209] neg_lo:[0,1] neg_hi:[0,1]
	v_pk_add_f32 v[204:205], v[212:213], v[210:211]
	v_pk_add_f32 v[202:203], v[202:203], v[206:207]
	v_pk_add_f32 v[206:207], v[140:141], v[204:205]
	s_nop 0
	v_pk_add_f32 v[140:141], v[206:207], v[140:141] neg_lo:[0,1] neg_hi:[0,1]
	s_nop 0
	v_pk_add_f32 v[140:141], v[204:205], v[140:141] neg_lo:[0,1] neg_hi:[0,1]
	s_nop 0
	v_pk_add_f32 v[140:141], v[202:203], v[140:141]
	s_nop 0
	v_pk_add_f32 v[140:141], v[206:207], v[140:141]
	s_nop 0
	v_cndmask_b32_e64 v140, v231, v140, s[12:13]
	v_cmp_neq_f32_e64 s[12:13], s4, v179
	s_nop 1
	v_cndmask_b32_e64 v141, v231, v141, s[12:13]
	v_cmp_ngt_f32_e64 s[12:13], -1.0, v179
	s_nop 1
	v_cndmask_b32_e64 v141, v232, v141, s[12:13]
	v_cmp_ngt_f32_e64 s[12:13], -1.0, v173
	s_nop 1
	v_cndmask_b32_e64 v140, v232, v140, s[12:13]
	v_cmp_neq_f32_e64 s[12:13], -1.0, v173
	s_nop 1
	v_cndmask_b32_e64 v140, v233, v140, s[12:13]
	v_cmp_neq_f32_e64 s[12:13], -1.0, v179
	s_nop 1
	v_cndmask_b32_e64 v141, v233, v141, s[12:13]
	v_cmp_lt_f32_e64 s[12:13], |v173|, s5
	v_cndmask_b32_e64 v141, v141, v179, s[14:15]
	s_nop 0
	v_cndmask_b32_e64 v140, v140, v173, s[12:13]
	v_pk_add_f32 v[130:131], v[130:131], v[140:141] neg_lo:[0,1] neg_hi:[0,1]
	v_min_f32_e32 v140, 0, v132
	v_mul_f32_e64 v132, |v132|, s34
	v_exp_f32_e32 v173, v132
	s_nop 0
	v_add_f32_e32 v132, 1.0, v173
	v_add_f32_e32 v141, -1.0, v132
	v_sub_f32_e32 v179, v141, v132
	v_add_f32_e32 v179, 1.0, v179
	v_sub_f32_e32 v141, v173, v141
	v_add_f32_e32 v141, v141, v179
	v_frexp_mant_f32_e32 v179, v132
	v_cvt_f64_f32_e32 v[202:203], v132
	v_cmp_gt_f32_e64 s[12:13], s35, v179
	v_frexp_exp_i32_f64_e32 v179, v[202:203]
	s_nop 0
	v_subbrev_co_u32_e64 v179, s[12:13], 0, v179, s[12:13]
	v_sub_u32_e32 v183, 0, v179
	v_ldexp_f32 v202, v141, v183
	v_min_f32_e32 v141, 0, v133
	v_mul_f32_e64 v133, |v133|, s34
	v_ldexp_f32 v132, v132, v183
	v_exp_f32_e32 v183, v133
	s_nop 0
	v_add_f32_e32 v133, 1.0, v183
	v_add_f32_e32 v187, -1.0, v133
	v_sub_f32_e32 v191, v187, v133
	v_add_f32_e32 v191, 1.0, v191
	v_sub_f32_e32 v187, v183, v187
	v_add_f32_e32 v187, v187, v191
	v_frexp_mant_f32_e32 v191, v133
	v_cvt_f64_f32_e32 v[204:205], v133
	v_cmp_gt_f32_e64 s[12:13], s35, v191
	v_frexp_exp_i32_f64_e32 v191, v[204:205]
	v_cmp_lt_f32_e64 s[14:15], |v183|, s5
	v_subbrev_co_u32_e64 v191, s[12:13], 0, v191, s[12:13]
	v_sub_u32_e32 v195, 0, v191
	v_ldexp_f32 v133, v133, v195
	v_pk_add_f32 v[204:205], v[132:133], 1.0 op_sel_hi:[1,0]
	v_ldexp_f32 v203, v187, v195
	v_pk_add_f32 v[206:207], v[204:205], -1.0 op_sel_hi:[1,0]
	v_pk_add_f32 v[212:213], v[132:133], -1.0 op_sel_hi:[1,0]
	v_pk_add_f32 v[206:207], v[132:133], v[206:207] neg_lo:[0,1] neg_hi:[0,1]
	v_pk_add_f32 v[214:215], v[212:213], 1.0 op_sel_hi:[1,0]
	v_pk_add_f32 v[206:207], v[202:203], v[206:207]
	v_pk_add_f32 v[132:133], v[132:133], v[214:215] neg_lo:[0,1] neg_hi:[0,1]
	v_pk_add_f32 v[208:209], v[204:205], v[206:207]
	v_pk_add_f32 v[132:133], v[202:203], v[132:133]
	v_rcp_f32_e32 v210, v208
	v_rcp_f32_e32 v211, v209
	v_pk_add_f32 v[202:203], v[212:213], v[132:133]
	v_pk_add_f32 v[204:205], v[208:209], v[204:205] neg_lo:[0,1] neg_hi:[0,1]
; __device__ __forceinline__ float log_sigmoid_f(float x) { return fminf(x, 0.f) - log1pf(__expf(-fabsf(x))); }
	v_pk_add_f32 v[212:213], v[202:203], v[212:213] neg_lo:[0,1] neg_hi:[0,1]
	v_pk_add_f32 v[204:205], v[206:207], v[204:205] neg_lo:[0,1] neg_hi:[0,1]
	v_pk_mul_f32 v[206:207], v[202:203], v[210:211]
	v_pk_add_f32 v[132:133], v[132:133], v[212:213] neg_lo:[0,1] neg_hi:[0,1]
	v_pk_mul_f32 v[212:213], v[208:209], v[206:207]
	v_cmp_neq_f32_e64 s[12:13], s4, v173
	v_pk_fma_f32 v[214:215], v[206:207], v[208:209], v[212:213] neg_lo:[0,0,1] neg_hi:[0,0,1]
	s_nop 0
	v_pk_fma_f32 v[214:215], v[206:207], v[204:205], v[214:215]
	s_nop 0
	v_pk_add_f32 v[216:217], v[212:213], v[214:215]
	s_nop 0
	v_pk_add_f32 v[218:219], v[202:203], v[216:217] neg_lo:[0,1] neg_hi:[0,1]
	v_pk_add_f32 v[212:213], v[216:217], v[212:213] neg_lo:[0,1] neg_hi:[0,1]
	v_pk_add_f32 v[202:203], v[202:203], v[218:219] neg_lo:[0,1] neg_hi:[0,1]
	s_nop 0
	v_pk_add_f32 v[202:203], v[202:203], v[216:217] neg_lo:[0,1] neg_hi:[0,1]
	s_nop 0
	v_pk_add_f32 v[132:133], v[132:133], v[202:203]
	v_pk_add_f32 v[202:203], v[212:213], v[214:215] neg_lo:[0,1] neg_hi:[0,1]
	s_nop 0
	v_pk_add_f32 v[132:133], v[202:203], v[132:133]
	s_nop 0
	v_pk_add_f32 v[202:203], v[218:219], v[132:133]
	s_nop 0
	v_pk_mul_f32 v[212:213], v[210:211], v[202:203]
	s_nop 0
	v_pk_mul_f32 v[214:215], v[208:209], v[212:213]
	s_nop 0
	v_pk_fma_f32 v[208:209], v[212:213], v[208:209], v[214:215] neg_lo:[0,0,1] neg_hi:[0,0,1]
	s_nop 0
	v_pk_fma_f32 v[204:205], v[212:213], v[204:205], v[208:209]
	v_pk_add_f32 v[208:209], v[218:219], v[202:203] neg_lo:[0,1] neg_hi:[0,1]
	s_nop 0
	v_pk_add_f32 v[132:133], v[132:133], v[208:209]
	v_pk_add_f32 v[208:209], v[214:215], v[204:205]
	s_nop 0
	v_pk_add_f32 v[216:217], v[202:203], v[208:209] neg_lo:[0,1] neg_hi:[0,1]
	v_pk_add_f32 v[214:215], v[208:209], v[214:215] neg_lo:[0,1] neg_hi:[0,1]
	v_pk_add_f32 v[202:203], v[202:203], v[216:217] neg_lo:[0,1] neg_hi:[0,1]
	s_nop 0
	v_pk_add_f32 v[202:203], v[202:203], v[208:209] neg_lo:[0,1] neg_hi:[0,1]
	s_nop 0
	v_pk_add_f32 v[132:133], v[132:133], v[202:203]
	v_pk_add_f32 v[202:203], v[214:215], v[204:205] neg_lo:[0,1] neg_hi:[0,1]
	s_nop 0
	v_pk_add_f32 v[132:133], v[202:203], v[132:133]
	v_pk_add_f32 v[202:203], v[206:207], v[212:213]
	v_pk_add_f32 v[132:133], v[216:217], v[132:133]
	v_pk_add_f32 v[204:205], v[202:203], v[206:207] neg_lo:[0,1] neg_hi:[0,1]
	v_pk_mul_f32 v[132:133], v[210:211], v[132:133]
	v_pk_add_f32 v[204:205], v[212:213], v[204:205] neg_lo:[0,1] neg_hi:[0,1]
	s_nop 0
	v_pk_add_f32 v[132:133], v[204:205], v[132:133]
	s_nop 0
	v_pk_add_f32 v[204:205], v[202:203], v[132:133]
	s_nop 0
	v_pk_mul_f32 v[206:207], v[204:205], v[204:205]
	v_pk_add_f32 v[202:203], v[204:205], v[202:203] neg_lo:[0,1] neg_hi:[0,1]
	v_pk_fma_f32 v[138:139], v[206:207], s[52:53], v[138:139] op_sel_hi:[1,0,0]
	v_pk_add_f32 v[132:133], v[132:133], v[202:203] neg_lo:[0,1] neg_hi:[0,1]
	v_ldexp_f32 v202, v204, 1
	v_pk_fma_f32 v[138:139], v[206:207], v[138:139], s[54:55] op_sel_hi:[1,1,0]
	v_ldexp_f32 v203, v205, 1
	v_pk_mul_f32 v[204:205], v[204:205], v[206:207]
	v_cvt_f32_i32_e32 v207, v191
	v_cvt_f32_i32_e32 v206, v179
	v_pk_mul_f32 v[138:139], v[204:205], v[138:139]
	v_ldexp_f32 v209, v133, 1
	v_pk_add_f32 v[204:205], v[202:203], v[138:139]
	v_pk_mul_f32 v[210:211], v[206:207], s[64:65] op_sel_hi:[1,0]
	v_pk_add_f32 v[202:203], v[204:205], v[202:203] neg_lo:[0,1] neg_hi:[0,1]
	v_pk_fma_f32 v[212:213], v[206:207], s[64:65], v[210:211] op_sel_hi:[1,0,1] neg_lo:[0,0,1] neg_hi:[0,0,1]
	v_pk_add_f32 v[138:139], v[138:139], v[202:203] neg_lo:[0,1] neg_hi:[0,1]
	v_pk_fma_f32 v[206:207], v[206:207], s[66:67], v[212:213] op_sel_hi:[1,0,1]
	v_ldexp_f32 v132, v132, 1
	v_mov_b32_e32 v202, v210
	v_mov_b32_e32 v203, v139
	v_mov_b32_e32 v208, v206
	v_mov_b32_e32 v133, v209
	v_pk_add_f32 v[202:203], v[202:203], v[208:209]
	v_pk_add_f32 v[208:209], v[132:133], v[138:139]
	v_mov_b32_e32 v139, v205
	v_mov_b32_e32 v133, v209
	v_pk_add_f32 v[212:213], v[210:211], v[206:207]
	v_pk_add_f32 v[132:133], v[132:133], v[138:139]
	v_pk_add_f32 v[138:139], v[204:205], v[208:209]
	v_mov_b32_e32 v222, v204
	v_pk_add_f32 v[214:215], v[212:213], v[138:139]
	v_mov_b32_e32 v220, v138
	v_mov_b32_e32 v221, v215
	v_mov_b32_e32 v223, v213
	v_pk_add_f32 v[220:221], v[220:221], v[222:223] neg_lo:[0,1] neg_hi:[0,1]
	v_mov_b32_e32 v216, v214
	v_mov_b32_e32 v217, v213
	v_mov_b32_e32 v218, v212
	v_mov_b32_e32 v219, v211
	v_mov_b32_e32 v222, v212
	v_mov_b32_e32 v223, v215
	v_mov_b32_e32 v211, v221
	v_pk_add_f32 v[216:217], v[216:217], v[218:219] neg_lo:[0,1] neg_hi:[0,1]
	v_mov_b32_e32 v218, v138
	v_mov_b32_e32 v219, v207
	v_pk_add_f32 v[210:211], v[222:223], v[210:211] neg_lo:[0,1] neg_hi:[0,1]
	v_pk_add_f32 v[218:219], v[218:219], v[216:217] neg_lo:[0,1] neg_hi:[0,1]
	v_mov_b32_e32 v222, v210
	v_mov_b32_e32 v223, v217
	v_mov_b32_e32 v224, v214
	v_mov_b32_e32 v225, v139
	v_mov_b32_e32 v217, v205
	v_pk_add_f32 v[222:223], v[206:207], v[222:223] neg_lo:[0,1] neg_hi:[0,1]
	v_pk_add_f32 v[216:217], v[224:225], v[216:217] neg_lo:[0,1] neg_hi:[0,1]
	v_mov_b32_e32 v207, v213
	v_pk_add_f32 v[138:139], v[138:139], v[204:205] neg_lo:[0,1] neg_hi:[0,1]
	v_pk_add_f32 v[202:203], v[202:203], v[216:217] neg_lo:[0,1] neg_hi:[0,1]
	v_pk_add_f32 v[204:205], v[206:207], v[210:211] neg_lo:[0,1] neg_hi:[0,1]
	v_pk_add_f32 v[132:133], v[132:133], v[220:221] neg_lo:[0,1] neg_hi:[0,1]
	v_pk_add_f32 v[138:139], v[208:209], v[138:139] neg_lo:[0,1] neg_hi:[0,1]
	v_pk_add_f32 v[206:207], v[132:133], v[204:205]
	v_mov_b32_e32 v205, v219
	v_mov_b32_e32 v133, v203
	v_pk_add_f32 v[208:209], v[218:219], v[202:203]
	v_pk_add_f32 v[132:133], v[204:205], v[132:133]
	v_mov_b32_e32 v202, v206
; __device__ __forceinline__ float log_sigmoid_f(float x) { return fminf(x, 0.f) - log1pf(__expf(-fabsf(x))); }
;     __device__ __forceinline__ void operator()(const f32x4 (&acc)[2][2][4][2], const Unit& u, int wr, int wc, int fr, int fq) const {
;     ...
;                     for (int m = 0; m < 4; ++m) { const int row = row0 + ai * HALF + m * 16; const float s = sc8[ai][m];
;                         float* dst = nullptr;
;                         if (pm == 0) dst = o_lfs + (size_t)row * 16; else { const int t = row - G_ROWP; if (t < G_TP) dst = o_lfp + (size_t)t * 16; }
; #pragma unroll
;                         for (int n = 0; n < 2; ++n) { const int c = 8 * fq + 4 * n; const f32x4 bv = *(const f32x4*)(b_f + c); const f32x4 x = acc[ai][0][m][n] * s + bv; f32x4 lf;
;                             lf[0] = log_sigmoid_f(x[0]); lf[1] = log_sigmoid_f(x[1]); lf[2] = log_sigmoid_f(x[2]); lf[3] = log_sigmoid_f(x[3]);
;                             *(f32x4*)(LF + (size_t)row * 16 + c) = lf; if (dst) *(f32x4*)(dst + c) = lf; } }
	v_pk_add_f32 v[132:133], v[132:133], v[222:223] neg_lo:[0,1] neg_hi:[0,1]
	v_mov_b32_e32 v203, v209
	v_pk_add_f32 v[202:203], v[202:203], v[132:133] neg_lo:[0,1] neg_hi:[0,1]
	v_pk_add_f32 v[132:133], v[138:139], v[132:133] neg_lo:[0,1] neg_hi:[0,1]
	v_pk_add_f32 v[202:203], v[204:205], v[202:203] neg_lo:[0,1] neg_hi:[0,1]
	v_pk_add_f32 v[138:139], v[208:209], v[206:207]
	v_pk_add_f32 v[132:133], v[132:133], v[202:203]
	v_pk_add_f32 v[202:203], v[214:215], v[138:139]
	s_nop 0
	v_pk_add_f32 v[204:205], v[202:203], v[214:215] neg_lo:[0,1] neg_hi:[0,1]
	s_nop 0
	v_pk_add_f32 v[138:139], v[138:139], v[204:205] neg_lo:[0,1] neg_hi:[0,1]
	s_nop 0
	v_pk_add_f32 v[132:133], v[132:133], v[138:139]
	s_nop 0
	v_pk_add_f32 v[132:133], v[202:203], v[132:133]
	s_nop 0
	v_cndmask_b32_e64 v132, v231, v132, s[12:13]
	v_cmp_neq_f32_e64 s[12:13], s4, v183
	s_nop 1
	v_cndmask_b32_e64 v133, v231, v133, s[12:13]
	v_cmp_ngt_f32_e64 s[12:13], -1.0, v183
	s_nop 1
	v_cndmask_b32_e64 v133, v232, v133, s[12:13]
	v_cmp_ngt_f32_e64 s[12:13], -1.0, v173
	s_nop 1
	v_cndmask_b32_e64 v132, v232, v132, s[12:13]
	v_cmp_neq_f32_e64 s[12:13], -1.0, v173
	s_nop 1
	v_cndmask_b32_e64 v132, v233, v132, s[12:13]
	v_cmp_neq_f32_e64 s[12:13], -1.0, v183
	s_nop 1
	v_cndmask_b32_e64 v133, v233, v133, s[12:13]
	v_cmp_lt_f32_e64 s[12:13], |v173|, s5
	v_cndmask_b32_e64 v133, v133, v183, s[14:15]
	s_nop 0
	v_cndmask_b32_e64 v132, v132, v173, s[12:13]
	v_pk_add_f32 v[132:133], v[140:141], v[132:133] neg_lo:[0,1] neg_hi:[0,1]
	global_store_dwordx4 v[136:137], v[130:133], off nt
	s_and_saveexec_b64 s[12:13], vcc
	s_cbranch_execz .LBB0_412
	v_lshl_add_u64 v[138:139], v[134:135], 0, v[150:151]
	global_store_dwordx4 v[138:139], v[130:133], off nt
.LBB0_412:
	s_or_b64 exec, exec, s[12:13]
	global_load_dwordx4 v[130:133], v[158:159], off offset:16
	v_mov_b32_e32 v183, v182
	v_mov_b32_e32 v138, v182
	v_mov_b32_e32 v139, v182
	s_waitcnt vmcnt(0)
	v_pk_fma_f32 v[132:133], v[44:45], v[138:139], v[132:133]
	v_pk_fma_f32 v[138:139], v[42:43], v[182:183], v[130:131]
	s_nop 0
	v_mul_f32_e64 v131, |v138|, s34
	v_exp_f32_e32 v173, v131
	v_min_f32_e32 v130, 0, v138
	v_add_f32_e32 v131, 1.0, v173
	v_add_f32_e32 v138, -1.0, v131
	v_sub_f32_e32 v140, v138, v131
	v_add_f32_e32 v140, 1.0, v140
	v_sub_f32_e32 v138, v173, v138
	v_add_f32_e32 v179, v138, v140
	v_frexp_mant_f32_e32 v138, v131
	v_cvt_f64_f32_e32 v[140:141], v131
	v_cmp_gt_f32_e64 s[12:13], s35, v138
	v_frexp_exp_i32_f64_e32 v138, v[140:141]
	s_nop 0
	v_subbrev_co_u32_e64 v183, s[12:13], 0, v138, s[12:13]
	v_sub_u32_e32 v140, 0, v183
	v_ldexp_f32 v138, v131, v140
	v_min_f32_e32 v131, 0, v139
	v_mul_f32_e64 v139, |v139|, s34
	v_ldexp_f32 v140, v179, v140
	v_exp_f32_e32 v179, v139
	s_nop 0
	v_add_f32_e32 v139, 1.0, v179
	v_add_f32_e32 v141, -1.0, v139
	v_sub_f32_e32 v187, v141, v139
	v_add_f32_e32 v187, 1.0, v187
	v_sub_f32_e32 v141, v179, v141
	v_add_f32_e32 v141, v141, v187
	v_frexp_mant_f32_e32 v187, v139
	v_cvt_f64_f32_e32 v[202:203], v139
	v_cmp_gt_f32_e64 s[12:13], s35, v187
	v_frexp_exp_i32_f64_e32 v187, v[202:203]
	v_cmp_lt_f32_e64 s[14:15], |v179|, s5
	v_subbrev_co_u32_e64 v187, s[12:13], 0, v187, s[12:13]
	v_sub_u32_e32 v191, 0, v187
	v_ldexp_f32 v139, v139, v191
	v_pk_add_f32 v[202:203], v[138:139], 1.0 op_sel_hi:[1,0]
	v_ldexp_f32 v141, v141, v191
	v_pk_add_f32 v[204:205], v[202:203], -1.0 op_sel_hi:[1,0]
	v_pk_add_f32 v[210:211], v[138:139], -1.0 op_sel_hi:[1,0]
	v_pk_add_f32 v[204:205], v[138:139], v[204:205] neg_lo:[0,1] neg_hi:[0,1]
	v_pk_add_f32 v[212:213], v[210:211], 1.0 op_sel_hi:[1,0]
	v_pk_add_f32 v[204:205], v[140:141], v[204:205]
	v_pk_add_f32 v[138:139], v[138:139], v[212:213] neg_lo:[0,1] neg_hi:[0,1]
	v_pk_add_f32 v[206:207], v[202:203], v[204:205]
	v_pk_add_f32 v[138:139], v[140:141], v[138:139]
	v_rcp_f32_e32 v208, v206
	v_rcp_f32_e32 v209, v207
	v_pk_add_f32 v[140:141], v[210:211], v[138:139]
	v_pk_add_f32 v[202:203], v[206:207], v[202:203] neg_lo:[0,1] neg_hi:[0,1]
	v_pk_add_f32 v[210:211], v[140:141], v[210:211] neg_lo:[0,1] neg_hi:[0,1]
	v_pk_add_f32 v[202:203], v[204:205], v[202:203] neg_lo:[0,1] neg_hi:[0,1]
	v_pk_mul_f32 v[204:205], v[140:141], v[208:209]
	v_pk_add_f32 v[138:139], v[138:139], v[210:211] neg_lo:[0,1] neg_hi:[0,1]
	v_pk_mul_f32 v[210:211], v[206:207], v[204:205]
	v_cmp_neq_f32_e64 s[12:13], s4, v173
	v_pk_fma_f32 v[212:213], v[204:205], v[206:207], v[210:211] neg_lo:[0,0,1] neg_hi:[0,0,1]
	s_nop 0
	v_pk_fma_f32 v[212:213], v[204:205], v[202:203], v[212:213]
	s_nop 0
	v_pk_add_f32 v[214:215], v[210:211], v[212:213]
	s_nop 0
	v_pk_add_f32 v[216:217], v[140:141], v[214:215] neg_lo:[0,1] neg_hi:[0,1]
	v_pk_add_f32 v[210:211], v[214:215], v[210:211] neg_lo:[0,1] neg_hi:[0,1]
	v_pk_add_f32 v[140:141], v[140:141], v[216:217] neg_lo:[0,1] neg_hi:[0,1]
	s_nop 0
	v_pk_add_f32 v[140:141], v[140:141], v[214:215] neg_lo:[0,1] neg_hi:[0,1]
	s_nop 0
	v_pk_add_f32 v[138:139], v[138:139], v[140:141]
	v_pk_add_f32 v[140:141], v[210:211], v[212:213] neg_lo:[0,1] neg_hi:[0,1]
	s_nop 0
	v_pk_add_f32 v[138:139], v[140:141], v[138:139]
	s_nop 0
	v_pk_add_f32 v[140:141], v[216:217], v[138:139]
	s_nop 0
	v_pk_mul_f32 v[210:211], v[208:209], v[140:141]
	s_nop 0
	v_pk_mul_f32 v[212:213], v[206:207], v[210:211]
	s_nop 0
	v_pk_fma_f32 v[206:207], v[210:211], v[206:207], v[212:213] neg_lo:[0,0,1] neg_hi:[0,0,1]
	s_nop 0
	v_pk_fma_f32 v[202:203], v[210:211], v[202:203], v[206:207]
	v_pk_add_f32 v[206:207], v[216:217], v[140:141] neg_lo:[0,1] neg_hi:[0,1]
	s_nop 0
	v_pk_add_f32 v[138:139], v[138:139], v[206:207]
	v_pk_add_f32 v[206:207], v[212:213], v[202:203]
	s_nop 0
	v_pk_add_f32 v[214:215], v[140:141], v[206:207] neg_lo:[0,1] neg_hi:[0,1]
; __device__ __forceinline__ float log_sigmoid_f(float x) { return fminf(x, 0.f) - log1pf(__expf(-fabsf(x))); }
;     __device__ __forceinline__ void operator()(const f32x4 (&acc)[2][2][4][2], const Unit& u, int wr, int wc, int fr, int fq) const {
;     ...
;                         for (int n = 0; n < 2; ++n) { const int c = 8 * fq + 4 * n; const f32x4 bv = *(const f32x4*)(b_f + c); const f32x4 x = acc[ai][0][m][n] * s + bv; f32x4 lf;
;                             lf[0] = log_sigmoid_f(x[0]); lf[1] = log_sigmoid_f(x[1]); lf[2] = log_sigmoid_f(x[2]); lf[3] = log_sigmoid_f(x[3]);
	v_pk_add_f32 v[212:213], v[206:207], v[212:213] neg_lo:[0,1] neg_hi:[0,1]
	v_pk_add_f32 v[140:141], v[140:141], v[214:215] neg_lo:[0,1] neg_hi:[0,1]
	s_nop 0
	v_pk_add_f32 v[140:141], v[140:141], v[206:207] neg_lo:[0,1] neg_hi:[0,1]
	s_nop 0
	v_pk_add_f32 v[138:139], v[138:139], v[140:141]
	v_pk_add_f32 v[140:141], v[212:213], v[202:203] neg_lo:[0,1] neg_hi:[0,1]
	s_nop 0
	v_pk_add_f32 v[138:139], v[140:141], v[138:139]
	v_pk_add_f32 v[140:141], v[204:205], v[210:211]
	v_pk_add_f32 v[138:139], v[214:215], v[138:139]
	v_pk_add_f32 v[202:203], v[140:141], v[204:205] neg_lo:[0,1] neg_hi:[0,1]
	v_pk_mul_f32 v[138:139], v[208:209], v[138:139]
	v_pk_add_f32 v[202:203], v[210:211], v[202:203] neg_lo:[0,1] neg_hi:[0,1]
	v_cvt_f32_i32_e32 v211, v187
	v_pk_add_f32 v[138:139], v[202:203], v[138:139]
	v_cvt_f32_i32_e32 v210, v183
	v_pk_add_f32 v[204:205], v[140:141], v[138:139]
	s_nop 0
	v_pk_add_f32 v[140:141], v[204:205], v[140:141] neg_lo:[0,1] neg_hi:[0,1]
	v_pk_mul_f32 v[206:207], v[204:205], v[204:205]
	v_pk_add_f32 v[140:141], v[138:139], v[140:141] neg_lo:[0,1] neg_hi:[0,1]
	v_mov_b64_e32 v[138:139], s[50:51]
	v_pk_fma_f32 v[208:209], v[206:207], s[52:53], v[138:139] op_sel_hi:[1,0,0]
	v_ldexp_f32 v202, v204, 1
	v_pk_fma_f32 v[208:209], v[206:207], v[208:209], s[54:55] op_sel_hi:[1,1,0]
	v_ldexp_f32 v203, v205, 1
	v_pk_mul_f32 v[204:205], v[204:205], v[206:207]
	v_ldexp_f32 v213, v141, 1
	v_pk_mul_f32 v[214:215], v[204:205], v[208:209]
	v_pk_mul_f32 v[206:207], v[210:211], s[64:65] op_sel_hi:[1,0]
	v_pk_add_f32 v[204:205], v[202:203], v[214:215]
	v_ldexp_f32 v140, v140, 1
	v_pk_add_f32 v[202:203], v[204:205], v[202:203] neg_lo:[0,1] neg_hi:[0,1]
	v_pk_fma_f32 v[208:209], v[210:211], s[64:65], v[206:207] op_sel_hi:[1,0,1] neg_lo:[0,0,1] neg_hi:[0,0,1]
	v_pk_add_f32 v[216:217], v[214:215], v[202:203] neg_lo:[0,1] neg_hi:[0,1]
	v_mov_b32_e32 v141, v213
	v_pk_fma_f32 v[208:209], v[210:211], s[66:67], v[208:209] op_sel_hi:[1,0,1]
	v_pk_add_f32 v[214:215], v[140:141], v[216:217]
	v_mov_b32_e32 v202, v206
	v_mov_b32_e32 v203, v217
	v_mov_b32_e32 v212, v208
	v_mov_b32_e32 v141, v215
	v_mov_b32_e32 v217, v205
	v_pk_add_f32 v[210:211], v[206:207], v[208:209]
	v_pk_add_f32 v[202:203], v[202:203], v[212:213]
	v_pk_add_f32 v[212:213], v[140:141], v[216:217]
	v_pk_add_f32 v[216:217], v[204:205], v[214:215]
	v_mov_b32_e32 v224, v204
	v_pk_add_f32 v[140:141], v[210:211], v[216:217]
	v_mov_b32_e32 v222, v216
	v_mov_b32_e32 v223, v141
	v_mov_b32_e32 v225, v211
	v_pk_add_f32 v[222:223], v[222:223], v[224:225] neg_lo:[0,1] neg_hi:[0,1]
	v_mov_b32_e32 v218, v140
	v_mov_b32_e32 v219, v211
	v_mov_b32_e32 v220, v210
	v_mov_b32_e32 v221, v207
	v_mov_b32_e32 v224, v210
	v_mov_b32_e32 v225, v141
	v_mov_b32_e32 v207, v223
	v_pk_add_f32 v[218:219], v[218:219], v[220:221] neg_lo:[0,1] neg_hi:[0,1]
	v_mov_b32_e32 v220, v216
	v_mov_b32_e32 v221, v209
	v_pk_add_f32 v[206:207], v[224:225], v[206:207] neg_lo:[0,1] neg_hi:[0,1]
	v_pk_add_f32 v[220:221], v[220:221], v[218:219] neg_lo:[0,1] neg_hi:[0,1]
	v_mov_b32_e32 v224, v206
	v_mov_b32_e32 v225, v219
	v_mov_b32_e32 v226, v140
	v_mov_b32_e32 v227, v217
	v_mov_b32_e32 v219, v205
	v_pk_add_f32 v[224:225], v[208:209], v[224:225] neg_lo:[0,1] neg_hi:[0,1]
	v_pk_add_f32 v[218:219], v[226:227], v[218:219] neg_lo:[0,1] neg_hi:[0,1]
	v_mov_b32_e32 v209, v211
	v_pk_add_f32 v[202:203], v[202:203], v[218:219] neg_lo:[0,1] neg_hi:[0,1]
	v_pk_add_f32 v[206:207], v[208:209], v[206:207] neg_lo:[0,1] neg_hi:[0,1]
	v_pk_add_f32 v[208:209], v[212:213], v[222:223] neg_lo:[0,1] neg_hi:[0,1]
	v_pk_add_f32 v[212:213], v[220:221], v[202:203]
	v_pk_add_f32 v[210:211], v[208:209], v[206:207]
	v_mov_b32_e32 v207, v221
	v_mov_b32_e32 v209, v203
	v_pk_add_f32 v[202:203], v[206:207], v[208:209]
	v_pk_add_f32 v[204:205], v[216:217], v[204:205] neg_lo:[0,1] neg_hi:[0,1]
	v_pk_add_f32 v[202:203], v[202:203], v[224:225] neg_lo:[0,1] neg_hi:[0,1]
	v_mov_b32_e32 v208, v210
	v_mov_b32_e32 v209, v213
	v_pk_add_f32 v[204:205], v[214:215], v[204:205] neg_lo:[0,1] neg_hi:[0,1]
	v_pk_add_f32 v[208:209], v[208:209], v[202:203] neg_lo:[0,1] neg_hi:[0,1]
	v_pk_add_f32 v[202:203], v[204:205], v[202:203] neg_lo:[0,1] neg_hi:[0,1]
	v_pk_add_f32 v[206:207], v[206:207], v[208:209] neg_lo:[0,1] neg_hi:[0,1]
	v_pk_add_f32 v[204:205], v[212:213], v[210:211]
	v_pk_add_f32 v[202:203], v[202:203], v[206:207]
	v_pk_add_f32 v[206:207], v[140:141], v[204:205]
	s_nop 0
	v_pk_add_f32 v[140:141], v[206:207], v[140:141] neg_lo:[0,1] neg_hi:[0,1]
	s_nop 0
	v_pk_add_f32 v[140:141], v[204:205], v[140:141] neg_lo:[0,1] neg_hi:[0,1]
	s_nop 0
	v_pk_add_f32 v[140:141], v[202:203], v[140:141]
	s_nop 0
	v_pk_add_f32 v[140:141], v[206:207], v[140:141]
	s_nop 0
	v_cndmask_b32_e64 v140, v231, v140, s[12:13]
	v_cmp_neq_f32_e64 s[12:13], s4, v179
	s_nop 1
	v_cndmask_b32_e64 v141, v231, v141, s[12:13]
	v_cmp_ngt_f32_e64 s[12:13], -1.0, v179
	s_nop 1
	v_cndmask_b32_e64 v141, v232, v141, s[12:13]
	v_cmp_ngt_f32_e64 s[12:13], -1.0, v173
	s_nop 1
	v_cndmask_b32_e64 v140, v232, v140, s[12:13]
	v_cmp_neq_f32_e64 s[12:13], -1.0, v173
	s_nop 1
	v_cndmask_b32_e64 v140, v233, v140, s[12:13]
	v_cmp_neq_f32_e64 s[12:13], -1.0, v179
	s_nop 1
	v_cndmask_b32_e64 v141, v233, v141, s[12:13]
	v_cmp_lt_f32_e64 s[12:13], |v173|, s5
	v_cndmask_b32_e64 v141, v141, v179, s[14:15]
	s_nop 0
	v_cndmask_b32_e64 v140, v140, v173, s[12:13]
	v_pk_add_f32 v[130:131], v[130:131], v[140:141] neg_lo:[0,1] neg_hi:[0,1]
	v_min_f32_e32 v140, 0, v132
	v_mul_f32_e64 v132, |v132|, s34
	v_exp_f32_e32 v173, v132
	s_nop 0
	v_add_f32_e32 v132, 1.0, v173
	v_add_f32_e32 v141, -1.0, v132
	v_sub_f32_e32 v179, v141, v132
	v_add_f32_e32 v179, 1.0, v179
; __device__ __forceinline__ float log_sigmoid_f(float x) { return fminf(x, 0.f) - log1pf(__expf(-fabsf(x))); }
	v_sub_f32_e32 v141, v173, v141
	v_add_f32_e32 v141, v141, v179
	v_frexp_mant_f32_e32 v179, v132
	v_cvt_f64_f32_e32 v[202:203], v132
	v_cmp_gt_f32_e64 s[12:13], s35, v179
	v_frexp_exp_i32_f64_e32 v179, v[202:203]
	s_nop 0
	v_subbrev_co_u32_e64 v179, s[12:13], 0, v179, s[12:13]
	v_sub_u32_e32 v183, 0, v179
	v_ldexp_f32 v202, v141, v183
	v_min_f32_e32 v141, 0, v133
	v_mul_f32_e64 v133, |v133|, s34
	v_ldexp_f32 v132, v132, v183
	v_exp_f32_e32 v183, v133
	s_nop 0
	v_add_f32_e32 v133, 1.0, v183
	v_add_f32_e32 v187, -1.0, v133
	v_sub_f32_e32 v191, v187, v133
	v_add_f32_e32 v191, 1.0, v191
	v_sub_f32_e32 v187, v183, v187
	v_add_f32_e32 v187, v187, v191
	v_frexp_mant_f32_e32 v191, v133
	v_cvt_f64_f32_e32 v[204:205], v133
	v_cmp_gt_f32_e64 s[12:13], s35, v191
	v_frexp_exp_i32_f64_e32 v191, v[204:205]
	v_cmp_lt_f32_e64 s[14:15], |v183|, s5
	v_subbrev_co_u32_e64 v191, s[12:13], 0, v191, s[12:13]
	v_sub_u32_e32 v195, 0, v191
	v_ldexp_f32 v133, v133, v195
	v_pk_add_f32 v[204:205], v[132:133], 1.0 op_sel_hi:[1,0]
	v_ldexp_f32 v203, v187, v195
	v_pk_add_f32 v[206:207], v[204:205], -1.0 op_sel_hi:[1,0]
	v_pk_add_f32 v[212:213], v[132:133], -1.0 op_sel_hi:[1,0]
	v_pk_add_f32 v[206:207], v[132:133], v[206:207] neg_lo:[0,1] neg_hi:[0,1]
	v_pk_add_f32 v[214:215], v[212:213], 1.0 op_sel_hi:[1,0]
	v_pk_add_f32 v[206:207], v[202:203], v[206:207]
	v_pk_add_f32 v[132:133], v[132:133], v[214:215] neg_lo:[0,1] neg_hi:[0,1]
	v_pk_add_f32 v[208:209], v[204:205], v[206:207]
	v_pk_add_f32 v[132:133], v[202:203], v[132:133]
	v_rcp_f32_e32 v210, v208
	v_rcp_f32_e32 v211, v209
	v_pk_add_f32 v[202:203], v[212:213], v[132:133]
	v_pk_add_f32 v[204:205], v[208:209], v[204:205] neg_lo:[0,1] neg_hi:[0,1]
	v_pk_add_f32 v[212:213], v[202:203], v[212:213] neg_lo:[0,1] neg_hi:[0,1]
	v_pk_add_f32 v[204:205], v[206:207], v[204:205] neg_lo:[0,1] neg_hi:[0,1]
	v_pk_mul_f32 v[206:207], v[202:203], v[210:211]
	v_pk_add_f32 v[132:133], v[132:133], v[212:213] neg_lo:[0,1] neg_hi:[0,1]
	v_pk_mul_f32 v[212:213], v[208:209], v[206:207]
	v_cmp_neq_f32_e64 s[12:13], s4, v173
	v_pk_fma_f32 v[214:215], v[206:207], v[208:209], v[212:213] neg_lo:[0,0,1] neg_hi:[0,0,1]
	s_nop 0
	v_pk_fma_f32 v[214:215], v[206:207], v[204:205], v[214:215]
	s_nop 0
	v_pk_add_f32 v[216:217], v[212:213], v[214:215]
	s_nop 0
	v_pk_add_f32 v[218:219], v[202:203], v[216:217] neg_lo:[0,1] neg_hi:[0,1]
	v_pk_add_f32 v[212:213], v[216:217], v[212:213] neg_lo:[0,1] neg_hi:[0,1]
	v_pk_add_f32 v[202:203], v[202:203], v[218:219] neg_lo:[0,1] neg_hi:[0,1]
	s_nop 0
	v_pk_add_f32 v[202:203], v[202:203], v[216:217] neg_lo:[0,1] neg_hi:[0,1]
	s_nop 0
	v_pk_add_f32 v[132:133], v[132:133], v[202:203]
	v_pk_add_f32 v[202:203], v[212:213], v[214:215] neg_lo:[0,1] neg_hi:[0,1]
	s_nop 0
	v_pk_add_f32 v[132:133], v[202:203], v[132:133]
	s_nop 0
	v_pk_add_f32 v[202:203], v[218:219], v[132:133]
	s_nop 0
	v_pk_mul_f32 v[212:213], v[210:211], v[202:203]
	s_nop 0
	v_pk_mul_f32 v[214:215], v[208:209], v[212:213]
	s_nop 0
	v_pk_fma_f32 v[208:209], v[212:213], v[208:209], v[214:215] neg_lo:[0,0,1] neg_hi:[0,0,1]
	s_nop 0
	v_pk_fma_f32 v[204:205], v[212:213], v[204:205], v[208:209]
	v_pk_add_f32 v[208:209], v[218:219], v[202:203] neg_lo:[0,1] neg_hi:[0,1]
	s_nop 0
	v_pk_add_f32 v[132:133], v[132:133], v[208:209]
	v_pk_add_f32 v[208:209], v[214:215], v[204:205]
	s_nop 0
	v_pk_add_f32 v[216:217], v[202:203], v[208:209] neg_lo:[0,1] neg_hi:[0,1]
	v_pk_add_f32 v[214:215], v[208:209], v[214:215] neg_lo:[0,1] neg_hi:[0,1]
	v_pk_add_f32 v[202:203], v[202:203], v[216:217] neg_lo:[0,1] neg_hi:[0,1]
	s_nop 0
	v_pk_add_f32 v[202:203], v[202:203], v[208:209] neg_lo:[0,1] neg_hi:[0,1]
	s_nop 0
	v_pk_add_f32 v[132:133], v[132:133], v[202:203]
	v_pk_add_f32 v[202:203], v[214:215], v[204:205] neg_lo:[0,1] neg_hi:[0,1]
	s_nop 0
	v_pk_add_f32 v[132:133], v[202:203], v[132:133]
	v_pk_add_f32 v[202:203], v[206:207], v[212:213]
	v_pk_add_f32 v[132:133], v[216:217], v[132:133]
	v_pk_add_f32 v[204:205], v[202:203], v[206:207] neg_lo:[0,1] neg_hi:[0,1]
	v_pk_mul_f32 v[132:133], v[210:211], v[132:133]
	v_pk_add_f32 v[204:205], v[212:213], v[204:205] neg_lo:[0,1] neg_hi:[0,1]
	s_nop 0
	v_pk_add_f32 v[132:133], v[204:205], v[132:133]
	s_nop 0
	v_pk_add_f32 v[204:205], v[202:203], v[132:133]
	s_nop 0
	v_pk_mul_f32 v[206:207], v[204:205], v[204:205]
	v_pk_add_f32 v[202:203], v[204:205], v[202:203] neg_lo:[0,1] neg_hi:[0,1]
	v_pk_fma_f32 v[138:139], v[206:207], s[52:53], v[138:139] op_sel_hi:[1,0,0]
	v_pk_add_f32 v[132:133], v[132:133], v[202:203] neg_lo:[0,1] neg_hi:[0,1]
; __device__ __forceinline__ float log_sigmoid_f(float x) { return fminf(x, 0.f) - log1pf(__expf(-fabsf(x))); }
;     __device__ __forceinline__ void operator()(const f32x4 (&acc)[2][2][4][2], const Unit& u, int wr, int wc, int fr, int fq) const {
;     ...
;                         for (int n = 0; n < 2; ++n) { const int c = 8 * fq + 4 * n; const f32x4 bv = *(const f32x4*)(b_f + c); const f32x4 x = acc[ai][0][m][n] * s + bv; f32x4 lf;
;                             lf[0] = log_sigmoid_f(x[0]); lf[1] = log_sigmoid_f(x[1]); lf[2] = log_sigmoid_f(x[2]); lf[3] = log_sigmoid_f(x[3]);
;                             *(f32x4*)(LF + (size_t)row * 16 + c) = lf; if (dst) *(f32x4*)(dst + c) = lf; } }
	v_ldexp_f32 v202, v204, 1
	v_pk_fma_f32 v[138:139], v[206:207], v[138:139], s[54:55] op_sel_hi:[1,1,0]
	v_ldexp_f32 v203, v205, 1
	v_pk_mul_f32 v[204:205], v[204:205], v[206:207]
	v_cvt_f32_i32_e32 v207, v191
	v_cvt_f32_i32_e32 v206, v179
	v_pk_mul_f32 v[138:139], v[204:205], v[138:139]
	v_ldexp_f32 v209, v133, 1
	v_pk_add_f32 v[204:205], v[202:203], v[138:139]
	v_pk_mul_f32 v[210:211], v[206:207], s[64:65] op_sel_hi:[1,0]
	v_pk_add_f32 v[202:203], v[204:205], v[202:203] neg_lo:[0,1] neg_hi:[0,1]
	v_pk_fma_f32 v[212:213], v[206:207], s[64:65], v[210:211] op_sel_hi:[1,0,1] neg_lo:[0,0,1] neg_hi:[0,0,1]
	v_pk_add_f32 v[138:139], v[138:139], v[202:203] neg_lo:[0,1] neg_hi:[0,1]
	v_pk_fma_f32 v[206:207], v[206:207], s[66:67], v[212:213] op_sel_hi:[1,0,1]
	v_ldexp_f32 v132, v132, 1
	v_mov_b32_e32 v202, v210
	v_mov_b32_e32 v203, v139
	v_mov_b32_e32 v208, v206
	v_mov_b32_e32 v133, v209
	v_pk_add_f32 v[202:203], v[202:203], v[208:209]
	v_pk_add_f32 v[208:209], v[132:133], v[138:139]
	v_mov_b32_e32 v139, v205
	v_mov_b32_e32 v133, v209
	v_pk_add_f32 v[212:213], v[210:211], v[206:207]
	v_pk_add_f32 v[132:133], v[132:133], v[138:139]
	v_pk_add_f32 v[138:139], v[204:205], v[208:209]
	v_mov_b32_e32 v222, v204
	v_pk_add_f32 v[214:215], v[212:213], v[138:139]
	v_mov_b32_e32 v220, v138
	v_mov_b32_e32 v221, v215
	v_mov_b32_e32 v223, v213
	v_pk_add_f32 v[220:221], v[220:221], v[222:223] neg_lo:[0,1] neg_hi:[0,1]
	v_mov_b32_e32 v216, v214
	v_mov_b32_e32 v217, v213
	v_mov_b32_e32 v218, v212
	v_mov_b32_e32 v219, v211
	v_mov_b32_e32 v222, v212
	v_mov_b32_e32 v223, v215
	v_mov_b32_e32 v211, v221
	v_pk_add_f32 v[216:217], v[216:217], v[218:219] neg_lo:[0,1] neg_hi:[0,1]
	v_mov_b32_e32 v218, v138
	v_mov_b32_e32 v219, v207
	v_pk_add_f32 v[210:211], v[222:223], v[210:211] neg_lo:[0,1] neg_hi:[0,1]
	v_pk_add_f32 v[218:219], v[218:219], v[216:217] neg_lo:[0,1] neg_hi:[0,1]
	v_mov_b32_e32 v222, v210
	v_mov_b32_e32 v223, v217
	v_mov_b32_e32 v224, v214
	v_mov_b32_e32 v225, v139
	v_mov_b32_e32 v217, v205
	v_pk_add_f32 v[222:223], v[206:207], v[222:223] neg_lo:[0,1] neg_hi:[0,1]
	v_pk_add_f32 v[216:217], v[224:225], v[216:217] neg_lo:[0,1] neg_hi:[0,1]
	v_mov_b32_e32 v207, v213
	v_pk_add_f32 v[138:139], v[138:139], v[204:205] neg_lo:[0,1] neg_hi:[0,1]
	v_pk_add_f32 v[202:203], v[202:203], v[216:217] neg_lo:[0,1] neg_hi:[0,1]
	v_pk_add_f32 v[204:205], v[206:207], v[210:211] neg_lo:[0,1] neg_hi:[0,1]
	v_pk_add_f32 v[132:133], v[132:133], v[220:221] neg_lo:[0,1] neg_hi:[0,1]
	v_pk_add_f32 v[138:139], v[208:209], v[138:139] neg_lo:[0,1] neg_hi:[0,1]
	v_pk_add_f32 v[206:207], v[132:133], v[204:205]
	v_mov_b32_e32 v205, v219
	v_mov_b32_e32 v133, v203
	v_pk_add_f32 v[208:209], v[218:219], v[202:203]
	v_pk_add_f32 v[132:133], v[204:205], v[132:133]
	v_mov_b32_e32 v202, v206
	v_pk_add_f32 v[132:133], v[132:133], v[222:223] neg_lo:[0,1] neg_hi:[0,1]
	v_mov_b32_e32 v203, v209
	v_pk_add_f32 v[202:203], v[202:203], v[132:133] neg_lo:[0,1] neg_hi:[0,1]
	v_pk_add_f32 v[132:133], v[138:139], v[132:133] neg_lo:[0,1] neg_hi:[0,1]
	v_pk_add_f32 v[202:203], v[204:205], v[202:203] neg_lo:[0,1] neg_hi:[0,1]
	v_pk_add_f32 v[138:139], v[208:209], v[206:207]
	v_pk_add_f32 v[132:133], v[132:133], v[202:203]
	v_pk_add_f32 v[202:203], v[214:215], v[138:139]
	s_nop 0
	v_pk_add_f32 v[204:205], v[202:203], v[214:215] neg_lo:[0,1] neg_hi:[0,1]
	s_nop 0
	v_pk_add_f32 v[138:139], v[138:139], v[204:205] neg_lo:[0,1] neg_hi:[0,1]
	s_nop 0
	v_pk_add_f32 v[132:133], v[132:133], v[138:139]
	s_nop 0
	v_pk_add_f32 v[132:133], v[202:203], v[132:133]
	s_nop 0
	v_cndmask_b32_e64 v132, v231, v132, s[12:13]
	v_cmp_neq_f32_e64 s[12:13], s4, v183
	s_nop 1
	v_cndmask_b32_e64 v133, v231, v133, s[12:13]
	v_cmp_ngt_f32_e64 s[12:13], -1.0, v183
	s_nop 1
	v_cndmask_b32_e64 v133, v232, v133, s[12:13]
	v_cmp_ngt_f32_e64 s[12:13], -1.0, v173
	s_nop 1
	v_cndmask_b32_e64 v132, v232, v132, s[12:13]
	v_cmp_neq_f32_e64 s[12:13], -1.0, v173
	s_nop 1
	v_cndmask_b32_e64 v132, v233, v132, s[12:13]
	v_cmp_neq_f32_e64 s[12:13], -1.0, v183
	s_nop 1
	v_cndmask_b32_e64 v133, v233, v133, s[12:13]
	v_cmp_lt_f32_e64 s[12:13], |v173|, s5
	v_cndmask_b32_e64 v133, v133, v183, s[14:15]
	s_nop 0
	v_cndmask_b32_e64 v132, v132, v173, s[12:13]
	v_pk_add_f32 v[132:133], v[140:141], v[132:133] neg_lo:[0,1] neg_hi:[0,1]
	global_store_dwordx4 v[136:137], v[130:133], off offset:16 nt
	s_and_saveexec_b64 s[12:13], vcc
	s_cbranch_execz .LBB0_414
	v_lshl_add_u64 v[134:135], v[134:135], 0, v[150:151]
	global_store_dwordx4 v[134:135], v[130:133], off offset:16 nt

; __device__ __forceinline__ float log_sigmoid_f(float x) { return fminf(x, 0.f) - log1pf(__expf(-fabsf(x))); }
;     __device__ __forceinline__ void operator()(const f32x4 (&acc)[2][2][4][2], const Unit& u, int wr, int wc, int fr, int fq) const {
;     ...
;                     for (int m = 0; m < 4; ++m) { const int row = row0 + ai * HALF + m * 16; const float s = sc8[ai][m];
;                         float* dst = nullptr;
;                         if (pm == 0) dst = o_lfs + (size_t)row * 16; else { const int t = row - G_ROWP; if (t < G_TP) dst = o_lfp + (size_t)t * 16; }
; #pragma unroll
;                         for (int n = 0; n < 2; ++n) { const int c = 8 * fq + 4 * n; const f32x4 bv = *(const f32x4*)(b_f + c); const f32x4 x = acc[ai][0][m][n] * s + bv; f32x4 lf;
;                             lf[0] = log_sigmoid_f(x[0]); lf[1] = log_sigmoid_f(x[1]); lf[2] = log_sigmoid_f(x[2]); lf[3] = log_sigmoid_f(x[3]);
.LBB0_417:
	global_load_dwordx4 v[130:133], v[158:159], off
	v_cmp_ne_u64_e32 vcc, 0, v[134:135]
	v_lshl_add_u64 v[136:137], v[162:163], 0, v[136:137]
	s_waitcnt vmcnt(0)
	v_pk_fma_f32 v[138:139], v[30:31], v[178:179], v[130:131] op_sel_hi:[1,0,1]
	s_nop 0
	v_mul_f32_e64 v131, |v138|, s34
	v_exp_f32_e32 v173, v131
	v_min_f32_e32 v130, 0, v138
	v_pk_fma_f32 v[132:133], v[32:33], v[178:179], v[132:133] op_sel_hi:[1,0,1]
	v_add_f32_e32 v131, 1.0, v173
	v_add_f32_e32 v138, -1.0, v131
	v_sub_f32_e32 v140, v138, v131
	v_add_f32_e32 v140, 1.0, v140
	v_sub_f32_e32 v138, v173, v138
	v_add_f32_e32 v179, v138, v140
	v_frexp_mant_f32_e32 v138, v131
	v_cvt_f64_f32_e32 v[140:141], v131
	v_cmp_gt_f32_e64 s[12:13], s35, v138
	v_frexp_exp_i32_f64_e32 v138, v[140:141]
	s_nop 0
	v_subbrev_co_u32_e64 v183, s[12:13], 0, v138, s[12:13]
	v_sub_u32_e32 v140, 0, v183
	v_ldexp_f32 v138, v131, v140
	v_min_f32_e32 v131, 0, v139
	v_mul_f32_e64 v139, |v139|, s34
	v_ldexp_f32 v140, v179, v140
	v_exp_f32_e32 v179, v139
	s_nop 0
	v_add_f32_e32 v139, 1.0, v179
	v_add_f32_e32 v141, -1.0, v139
	v_sub_f32_e32 v187, v141, v139
	v_add_f32_e32 v187, 1.0, v187
	v_sub_f32_e32 v141, v179, v141
	v_add_f32_e32 v141, v141, v187
	v_frexp_mant_f32_e32 v187, v139
	v_cvt_f64_f32_e32 v[202:203], v139
	v_cmp_gt_f32_e64 s[12:13], s35, v187
	v_frexp_exp_i32_f64_e32 v187, v[202:203]
	v_cmp_lt_f32_e64 s[14:15], |v179|, s5
	v_subbrev_co_u32_e64 v187, s[12:13], 0, v187, s[12:13]
	v_sub_u32_e32 v191, 0, v187
	v_ldexp_f32 v139, v139, v191
	v_pk_add_f32 v[202:203], v[138:139], 1.0 op_sel_hi:[1,0]
	v_ldexp_f32 v141, v141, v191
	v_pk_add_f32 v[204:205], v[202:203], -1.0 op_sel_hi:[1,0]
	v_pk_add_f32 v[210:211], v[138:139], -1.0 op_sel_hi:[1,0]
	v_pk_add_f32 v[204:205], v[138:139], v[204:205] neg_lo:[0,1] neg_hi:[0,1]
	v_pk_add_f32 v[212:213], v[210:211], 1.0 op_sel_hi:[1,0]
	v_pk_add_f32 v[204:205], v[140:141], v[204:205]
	v_pk_add_f32 v[138:139], v[138:139], v[212:213] neg_lo:[0,1] neg_hi:[0,1]
	v_pk_add_f32 v[206:207], v[202:203], v[204:205]
	v_pk_add_f32 v[138:139], v[140:141], v[138:139]
	v_rcp_f32_e32 v208, v206
	v_rcp_f32_e32 v209, v207
	v_pk_add_f32 v[140:141], v[210:211], v[138:139]
	v_pk_add_f32 v[202:203], v[206:207], v[202:203] neg_lo:[0,1] neg_hi:[0,1]
	v_pk_add_f32 v[210:211], v[140:141], v[210:211] neg_lo:[0,1] neg_hi:[0,1]
	v_pk_add_f32 v[202:203], v[204:205], v[202:203] neg_lo:[0,1] neg_hi:[0,1]
	v_pk_mul_f32 v[204:205], v[140:141], v[208:209]
	v_pk_add_f32 v[138:139], v[138:139], v[210:211] neg_lo:[0,1] neg_hi:[0,1]
	v_pk_mul_f32 v[210:211], v[206:207], v[204:205]
	v_cmp_neq_f32_e64 s[12:13], s4, v173
	v_pk_fma_f32 v[212:213], v[204:205], v[206:207], v[210:211] neg_lo:[0,0,1] neg_hi:[0,0,1]
	s_nop 0
	v_pk_fma_f32 v[212:213], v[204:205], v[202:203], v[212:213]
	s_nop 0
	v_pk_add_f32 v[214:215], v[210:211], v[212:213]
	s_nop 0
	v_pk_add_f32 v[216:217], v[140:141], v[214:215] neg_lo:[0,1] neg_hi:[0,1]
	v_pk_add_f32 v[210:211], v[214:215], v[210:211] neg_lo:[0,1] neg_hi:[0,1]
	v_pk_add_f32 v[140:141], v[140:141], v[216:217] neg_lo:[0,1] neg_hi:[0,1]
	s_nop 0
	v_pk_add_f32 v[140:141], v[140:141], v[214:215] neg_lo:[0,1] neg_hi:[0,1]
	s_nop 0
	v_pk_add_f32 v[138:139], v[138:139], v[140:141]
	v_pk_add_f32 v[140:141], v[210:211], v[212:213] neg_lo:[0,1] neg_hi:[0,1]
	s_nop 0
	v_pk_add_f32 v[138:139], v[140:141], v[138:139]
	s_nop 0
	v_pk_add_f32 v[140:141], v[216:217], v[138:139]
	s_nop 0
	v_pk_mul_f32 v[210:211], v[208:209], v[140:141]
	s_nop 0
	v_pk_mul_f32 v[212:213], v[206:207], v[210:211]
	s_nop 0
	v_pk_fma_f32 v[206:207], v[210:211], v[206:207], v[212:213] neg_lo:[0,0,1] neg_hi:[0,0,1]
	s_nop 0
	v_pk_fma_f32 v[202:203], v[210:211], v[202:203], v[206:207]
	v_pk_add_f32 v[206:207], v[216:217], v[140:141] neg_lo:[0,1] neg_hi:[0,1]
	s_nop 0
	v_pk_add_f32 v[138:139], v[138:139], v[206:207]
	v_pk_add_f32 v[206:207], v[212:213], v[202:203]
	s_nop 0
	v_pk_add_f32 v[214:215], v[140:141], v[206:207] neg_lo:[0,1] neg_hi:[0,1]
	v_pk_add_f32 v[212:213], v[206:207], v[212:213] neg_lo:[0,1] neg_hi:[0,1]
	v_pk_add_f32 v[140:141], v[140:141], v[214:215] neg_lo:[0,1] neg_hi:[0,1]
	s_nop 0
	v_pk_add_f32 v[140:141], v[140:141], v[206:207] neg_lo:[0,1] neg_hi:[0,1]
	s_nop 0
	v_pk_add_f32 v[138:139], v[138:139], v[140:141]
	v_pk_add_f32 v[140:141], v[212:213], v[202:203] neg_lo:[0,1] neg_hi:[0,1]
	s_nop 0
	v_pk_add_f32 v[138:139], v[140:141], v[138:139]
	v_pk_add_f32 v[140:141], v[204:205], v[210:211]
	v_pk_add_f32 v[138:139], v[214:215], v[138:139]
	v_pk_add_f32 v[202:203], v[140:141], v[204:205] neg_lo:[0,1] neg_hi:[0,1]
	v_pk_mul_f32 v[138:139], v[208:209], v[138:139]
	v_pk_add_f32 v[202:203], v[210:211], v[202:203] neg_lo:[0,1] neg_hi:[0,1]
	s_nop 0
	v_pk_add_f32 v[138:139], v[202:203], v[138:139]
	s_nop 0
	v_pk_add_f32 v[204:205], v[140:141], v[138:139]
	s_nop 0
	v_pk_add_f32 v[140:141], v[204:205], v[140:141] neg_lo:[0,1] neg_hi:[0,1]
	v_pk_mul_f32 v[206:207], v[204:205], v[204:205]
	v_pk_add_f32 v[140:141], v[138:139], v[140:141] neg_lo:[0,1] neg_hi:[0,1]
	v_mov_b64_e32 v[138:139], s[50:51]
	v_pk_fma_f32 v[208:209], v[206:207], s[52:53], v[138:139] op_sel_hi:[1,0,0]
	v_ldexp_f32 v202, v204, 1
	v_pk_fma_f32 v[208:209], v[206:207], v[208:209], s[54:55] op_sel_hi:[1,1,0]
	v_ldexp_f32 v203, v205, 1
	v_pk_mul_f32 v[204:205], v[204:205], v[206:207]
	v_cvt_f32_i32_e32 v207, v187
	v_cvt_f32_i32_e32 v206, v183
	v_pk_mul_f32 v[214:215], v[204:205], v[208:209]
	v_ldexp_f32 v213, v141, 1
	v_pk_add_f32 v[204:205], v[202:203], v[214:215]
	v_pk_mul_f32 v[210:211], v[206:207], s[64:65] op_sel_hi:[1,0]
	v_pk_add_f32 v[202:203], v[204:205], v[202:203] neg_lo:[0,1] neg_hi:[0,1]
	v_ldexp_f32 v140, v140, 1
; __device__ __forceinline__ float log_sigmoid_f(float x) { return fminf(x, 0.f) - log1pf(__expf(-fabsf(x))); }
;     __device__ __forceinline__ void operator()(const f32x4 (&acc)[2][2][4][2], const Unit& u, int wr, int wc, int fr, int fq) const {
;     ...
;                         for (int n = 0; n < 2; ++n) { const int c = 8 * fq + 4 * n; const f32x4 bv = *(const f32x4*)(b_f + c); const f32x4 x = acc[ai][0][m][n] * s + bv; f32x4 lf;
;                             lf[0] = log_sigmoid_f(x[0]); lf[1] = log_sigmoid_f(x[1]); lf[2] = log_sigmoid_f(x[2]); lf[3] = log_sigmoid_f(x[3]);
	v_pk_fma_f32 v[208:209], v[206:207], s[64:65], v[210:211] op_sel_hi:[1,0,1] neg_lo:[0,0,1] neg_hi:[0,0,1]
	v_pk_add_f32 v[216:217], v[214:215], v[202:203] neg_lo:[0,1] neg_hi:[0,1]
	v_mov_b32_e32 v141, v213
	v_pk_fma_f32 v[206:207], v[206:207], s[66:67], v[208:209] op_sel_hi:[1,0,1]
	v_pk_add_f32 v[214:215], v[140:141], v[216:217]
	v_mov_b32_e32 v202, v210
	v_mov_b32_e32 v203, v217
	v_mov_b32_e32 v212, v206
	v_mov_b32_e32 v141, v215
	v_mov_b32_e32 v217, v205
	v_pk_add_f32 v[208:209], v[210:211], v[206:207]
	v_pk_add_f32 v[202:203], v[202:203], v[212:213]
	v_pk_add_f32 v[212:213], v[140:141], v[216:217]
	v_pk_add_f32 v[216:217], v[204:205], v[214:215]
	v_mov_b32_e32 v224, v204
	v_pk_add_f32 v[140:141], v[208:209], v[216:217]
	v_mov_b32_e32 v222, v216
	v_mov_b32_e32 v223, v141
	v_mov_b32_e32 v225, v209
	v_pk_add_f32 v[222:223], v[222:223], v[224:225] neg_lo:[0,1] neg_hi:[0,1]
	v_mov_b32_e32 v218, v140
	v_mov_b32_e32 v219, v209
	v_mov_b32_e32 v220, v208
	v_mov_b32_e32 v221, v211
	v_mov_b32_e32 v224, v208
	v_mov_b32_e32 v225, v141
	v_mov_b32_e32 v211, v223
	v_pk_add_f32 v[218:219], v[218:219], v[220:221] neg_lo:[0,1] neg_hi:[0,1]
	v_mov_b32_e32 v220, v216
	v_mov_b32_e32 v221, v207
	v_pk_add_f32 v[210:211], v[224:225], v[210:211] neg_lo:[0,1] neg_hi:[0,1]
	v_pk_add_f32 v[220:221], v[220:221], v[218:219] neg_lo:[0,1] neg_hi:[0,1]
	v_mov_b32_e32 v224, v210
	v_mov_b32_e32 v225, v219
	v_mov_b32_e32 v226, v140
	v_mov_b32_e32 v227, v217
	v_mov_b32_e32 v219, v205
	v_pk_add_f32 v[224:225], v[206:207], v[224:225] neg_lo:[0,1] neg_hi:[0,1]
	v_pk_add_f32 v[218:219], v[226:227], v[218:219] neg_lo:[0,1] neg_hi:[0,1]
	v_mov_b32_e32 v207, v209
	v_pk_add_f32 v[202:203], v[202:203], v[218:219] neg_lo:[0,1] neg_hi:[0,1]
	v_pk_add_f32 v[206:207], v[206:207], v[210:211] neg_lo:[0,1] neg_hi:[0,1]
	v_pk_add_f32 v[208:209], v[212:213], v[222:223] neg_lo:[0,1] neg_hi:[0,1]
	v_pk_add_f32 v[212:213], v[220:221], v[202:203]
	v_pk_add_f32 v[210:211], v[208:209], v[206:207]
	v_mov_b32_e32 v207, v221
	v_mov_b32_e32 v209, v203
	v_pk_add_f32 v[202:203], v[206:207], v[208:209]
	v_pk_add_f32 v[204:205], v[216:217], v[204:205] neg_lo:[0,1] neg_hi:[0,1]
	v_pk_add_f32 v[202:203], v[202:203], v[224:225] neg_lo:[0,1] neg_hi:[0,1]
	v_mov_b32_e32 v208, v210
	v_mov_b32_e32 v209, v213
	v_pk_add_f32 v[204:205], v[214:215], v[204:205] neg_lo:[0,1] neg_hi:[0,1]
	v_pk_add_f32 v[208:209], v[208:209], v[202:203] neg_lo:[0,1] neg_hi:[0,1]
	v_pk_add_f32 v[202:203], v[204:205], v[202:203] neg_lo:[0,1] neg_hi:[0,1]
	v_pk_add_f32 v[206:207], v[206:207], v[208:209] neg_lo:[0,1] neg_hi:[0,1]
	v_pk_add_f32 v[204:205], v[212:213], v[210:211]
	v_pk_add_f32 v[202:203], v[202:203], v[206:207]
	v_pk_add_f32 v[206:207], v[140:141], v[204:205]
	s_nop 0
	v_pk_add_f32 v[140:141], v[206:207], v[140:141] neg_lo:[0,1] neg_hi:[0,1]
	s_nop 0
	v_pk_add_f32 v[140:141], v[204:205], v[140:141] neg_lo:[0,1] neg_hi:[0,1]
	s_nop 0
	v_pk_add_f32 v[140:141], v[202:203], v[140:141]
	s_nop 0
	v_pk_add_f32 v[140:141], v[206:207], v[140:141]
	s_nop 0
	v_cndmask_b32_e64 v140, v231, v140, s[12:13]
	v_cmp_neq_f32_e64 s[12:13], s4, v179
	s_nop 1
	v_cndmask_b32_e64 v141, v231, v141, s[12:13]
	v_cmp_ngt_f32_e64 s[12:13], -1.0, v179
	s_nop 1
	v_cndmask_b32_e64 v141, v232, v141, s[12:13]
	v_cmp_ngt_f32_e64 s[12:13], -1.0, v173
	s_nop 1
	v_cndmask_b32_e64 v140, v232, v140, s[12:13]
	v_cmp_neq_f32_e64 s[12:13], -1.0, v173
	s_nop 1
	v_cndmask_b32_e64 v140, v233, v140, s[12:13]
	v_cmp_neq_f32_e64 s[12:13], -1.0, v179
	s_nop 1
	v_cndmask_b32_e64 v141, v233, v141, s[12:13]
	v_cmp_lt_f32_e64 s[12:13], |v173|, s5
	v_cndmask_b32_e64 v141, v141, v179, s[14:15]
	s_nop 0
	v_cndmask_b32_e64 v140, v140, v173, s[12:13]
	v_pk_add_f32 v[130:131], v[130:131], v[140:141] neg_lo:[0,1] neg_hi:[0,1]
	v_min_f32_e32 v140, 0, v132
	v_mul_f32_e64 v132, |v132|, s34
	v_exp_f32_e32 v173, v132
	s_nop 0
	v_add_f32_e32 v132, 1.0, v173
	v_add_f32_e32 v141, -1.0, v132
	v_sub_f32_e32 v179, v141, v132
	v_add_f32_e32 v179, 1.0, v179
	v_sub_f32_e32 v141, v173, v141
	v_add_f32_e32 v141, v141, v179
	v_frexp_mant_f32_e32 v179, v132
	v_cvt_f64_f32_e32 v[202:203], v132
	v_cmp_gt_f32_e64 s[12:13], s35, v179
	v_frexp_exp_i32_f64_e32 v179, v[202:203]
	s_nop 0
	v_subbrev_co_u32_e64 v179, s[12:13], 0, v179, s[12:13]
	v_sub_u32_e32 v183, 0, v179
	v_ldexp_f32 v202, v141, v183
	v_min_f32_e32 v141, 0, v133
	v_mul_f32_e64 v133, |v133|, s34
	v_ldexp_f32 v132, v132, v183
	v_exp_f32_e32 v183, v133
	s_nop 0
	v_add_f32_e32 v133, 1.0, v183
	v_add_f32_e32 v187, -1.0, v133
	v_sub_f32_e32 v191, v187, v133
	v_add_f32_e32 v191, 1.0, v191
	v_sub_f32_e32 v187, v183, v187
	v_add_f32_e32 v187, v187, v191
	v_frexp_mant_f32_e32 v191, v133
	v_cvt_f64_f32_e32 v[204:205], v133
	v_cmp_gt_f32_e64 s[12:13], s35, v191
	v_frexp_exp_i32_f64_e32 v191, v[204:205]
	v_cmp_lt_f32_e64 s[14:15], |v183|, s5
	v_subbrev_co_u32_e64 v191, s[12:13], 0, v191, s[12:13]
	v_sub_u32_e32 v195, 0, v191
	v_ldexp_f32 v133, v133, v195
	v_pk_add_f32 v[204:205], v[132:133], 1.0 op_sel_hi:[1,0]
	v_ldexp_f32 v203, v187, v195
	v_pk_add_f32 v[206:207], v[204:205], -1.0 op_sel_hi:[1,0]
	v_pk_add_f32 v[212:213], v[132:133], -1.0 op_sel_hi:[1,0]
	v_pk_add_f32 v[206:207], v[132:133], v[206:207] neg_lo:[0,1] neg_hi:[0,1]
	v_pk_add_f32 v[214:215], v[212:213], 1.0 op_sel_hi:[1,0]
	v_pk_add_f32 v[206:207], v[202:203], v[206:207]
	v_pk_add_f32 v[132:133], v[132:133], v[214:215] neg_lo:[0,1] neg_hi:[0,1]
	v_pk_add_f32 v[208:209], v[204:205], v[206:207]
	v_pk_add_f32 v[132:133], v[202:203], v[132:133]
	v_rcp_f32_e32 v210, v208
	v_rcp_f32_e32 v211, v209
	v_pk_add_f32 v[202:203], v[212:213], v[132:133]
	v_pk_add_f32 v[204:205], v[208:209], v[204:205] neg_lo:[0,1] neg_hi:[0,1]
; __device__ __forceinline__ float log_sigmoid_f(float x) { return fminf(x, 0.f) - log1pf(__expf(-fabsf(x))); }
	v_pk_add_f32 v[212:213], v[202:203], v[212:213] neg_lo:[0,1] neg_hi:[0,1]
	v_pk_add_f32 v[204:205], v[206:207], v[204:205] neg_lo:[0,1] neg_hi:[0,1]
	v_pk_mul_f32 v[206:207], v[202:203], v[210:211]
	v_pk_add_f32 v[132:133], v[132:133], v[212:213] neg_lo:[0,1] neg_hi:[0,1]
	v_pk_mul_f32 v[212:213], v[208:209], v[206:207]
	v_cmp_neq_f32_e64 s[12:13], s4, v173
	v_pk_fma_f32 v[214:215], v[206:207], v[208:209], v[212:213] neg_lo:[0,0,1] neg_hi:[0,0,1]
	s_nop 0
	v_pk_fma_f32 v[214:215], v[206:207], v[204:205], v[214:215]
	s_nop 0
	v_pk_add_f32 v[216:217], v[212:213], v[214:215]
	s_nop 0
	v_pk_add_f32 v[218:219], v[202:203], v[216:217] neg_lo:[0,1] neg_hi:[0,1]
	v_pk_add_f32 v[212:213], v[216:217], v[212:213] neg_lo:[0,1] neg_hi:[0,1]
	v_pk_add_f32 v[202:203], v[202:203], v[218:219] neg_lo:[0,1] neg_hi:[0,1]
	s_nop 0
	v_pk_add_f32 v[202:203], v[202:203], v[216:217] neg_lo:[0,1] neg_hi:[0,1]
	s_nop 0
	v_pk_add_f32 v[132:133], v[132:133], v[202:203]
	v_pk_add_f32 v[202:203], v[212:213], v[214:215] neg_lo:[0,1] neg_hi:[0,1]
	s_nop 0
	v_pk_add_f32 v[132:133], v[202:203], v[132:133]
	s_nop 0
	v_pk_add_f32 v[202:203], v[218:219], v[132:133]
	s_nop 0
	v_pk_mul_f32 v[212:213], v[210:211], v[202:203]
	s_nop 0
	v_pk_mul_f32 v[214:215], v[208:209], v[212:213]
	s_nop 0
	v_pk_fma_f32 v[208:209], v[212:213], v[208:209], v[214:215] neg_lo:[0,0,1] neg_hi:[0,0,1]
	s_nop 0
	v_pk_fma_f32 v[204:205], v[212:213], v[204:205], v[208:209]
	v_pk_add_f32 v[208:209], v[218:219], v[202:203] neg_lo:[0,1] neg_hi:[0,1]
	s_nop 0
	v_pk_add_f32 v[132:133], v[132:133], v[208:209]
	v_pk_add_f32 v[208:209], v[214:215], v[204:205]
	s_nop 0
	v_pk_add_f32 v[216:217], v[202:203], v[208:209] neg_lo:[0,1] neg_hi:[0,1]
	v_pk_add_f32 v[214:215], v[208:209], v[214:215] neg_lo:[0,1] neg_hi:[0,1]
	v_pk_add_f32 v[202:203], v[202:203], v[216:217] neg_lo:[0,1] neg_hi:[0,1]
	s_nop 0
	v_pk_add_f32 v[202:203], v[202:203], v[208:209] neg_lo:[0,1] neg_hi:[0,1]
	s_nop 0
	v_pk_add_f32 v[132:133], v[132:133], v[202:203]
	v_pk_add_f32 v[202:203], v[214:215], v[204:205] neg_lo:[0,1] neg_hi:[0,1]
	s_nop 0
	v_pk_add_f32 v[132:133], v[202:203], v[132:133]
	v_pk_add_f32 v[202:203], v[206:207], v[212:213]
	v_pk_add_f32 v[132:133], v[216:217], v[132:133]
	v_pk_add_f32 v[204:205], v[202:203], v[206:207] neg_lo:[0,1] neg_hi:[0,1]
	v_pk_mul_f32 v[132:133], v[210:211], v[132:133]
	v_pk_add_f32 v[204:205], v[212:213], v[204:205] neg_lo:[0,1] neg_hi:[0,1]
	s_nop 0
	v_pk_add_f32 v[132:133], v[204:205], v[132:133]
	s_nop 0
	v_pk_add_f32 v[204:205], v[202:203], v[132:133]
	s_nop 0
	v_pk_mul_f32 v[206:207], v[204:205], v[204:205]
	v_pk_add_f32 v[202:203], v[204:205], v[202:203] neg_lo:[0,1] neg_hi:[0,1]
	v_pk_fma_f32 v[138:139], v[206:207], s[52:53], v[138:139] op_sel_hi:[1,0,0]
	v_pk_add_f32 v[132:133], v[132:133], v[202:203] neg_lo:[0,1] neg_hi:[0,1]
	v_ldexp_f32 v202, v204, 1
	v_pk_fma_f32 v[138:139], v[206:207], v[138:139], s[54:55] op_sel_hi:[1,1,0]
	v_ldexp_f32 v203, v205, 1
	v_pk_mul_f32 v[204:205], v[204:205], v[206:207]
	v_cvt_f32_i32_e32 v207, v191
	v_cvt_f32_i32_e32 v206, v179
	v_pk_mul_f32 v[138:139], v[204:205], v[138:139]
	v_ldexp_f32 v209, v133, 1
	v_pk_add_f32 v[204:205], v[202:203], v[138:139]
	v_pk_mul_f32 v[210:211], v[206:207], s[64:65] op_sel_hi:[1,0]
	v_pk_add_f32 v[202:203], v[204:205], v[202:203] neg_lo:[0,1] neg_hi:[0,1]
	v_pk_fma_f32 v[212:213], v[206:207], s[64:65], v[210:211] op_sel_hi:[1,0,1] neg_lo:[0,0,1] neg_hi:[0,0,1]
	v_pk_add_f32 v[138:139], v[138:139], v[202:203] neg_lo:[0,1] neg_hi:[0,1]
	v_pk_fma_f32 v[206:207], v[206:207], s[66:67], v[212:213] op_sel_hi:[1,0,1]
	v_ldexp_f32 v132, v132, 1
	v_mov_b32_e32 v202, v210
	v_mov_b32_e32 v203, v139
	v_mov_b32_e32 v208, v206
	v_mov_b32_e32 v133, v209
	v_pk_add_f32 v[202:203], v[202:203], v[208:209]
	v_pk_add_f32 v[208:209], v[132:133], v[138:139]
	v_mov_b32_e32 v139, v205
	v_mov_b32_e32 v133, v209
	v_pk_add_f32 v[212:213], v[210:211], v[206:207]
	v_pk_add_f32 v[132:133], v[132:133], v[138:139]
	v_pk_add_f32 v[138:139], v[204:205], v[208:209]
	v_mov_b32_e32 v222, v204
	v_pk_add_f32 v[214:215], v[212:213], v[138:139]
	v_mov_b32_e32 v220, v138
	v_mov_b32_e32 v221, v215
	v_mov_b32_e32 v223, v213
	v_pk_add_f32 v[220:221], v[220:221], v[222:223] neg_lo:[0,1] neg_hi:[0,1]
	v_mov_b32_e32 v216, v214
	v_mov_b32_e32 v217, v213
	v_mov_b32_e32 v218, v212
	v_mov_b32_e32 v219, v211
	v_mov_b32_e32 v222, v212
	v_mov_b32_e32 v223, v215
	v_mov_b32_e32 v211, v221
	v_pk_add_f32 v[216:217], v[216:217], v[218:219] neg_lo:[0,1] neg_hi:[0,1]
	v_mov_b32_e32 v218, v138
	v_mov_b32_e32 v219, v207
	v_pk_add_f32 v[210:211], v[222:223], v[210:211] neg_lo:[0,1] neg_hi:[0,1]
	v_pk_add_f32 v[218:219], v[218:219], v[216:217] neg_lo:[0,1] neg_hi:[0,1]
	v_mov_b32_e32 v222, v210
	v_mov_b32_e32 v223, v217
	v_mov_b32_e32 v224, v214
	v_mov_b32_e32 v225, v139
	v_mov_b32_e32 v217, v205
	v_pk_add_f32 v[222:223], v[206:207], v[222:223] neg_lo:[0,1] neg_hi:[0,1]
	v_pk_add_f32 v[216:217], v[224:225], v[216:217] neg_lo:[0,1] neg_hi:[0,1]
	v_mov_b32_e32 v207, v213
	v_pk_add_f32 v[138:139], v[138:139], v[204:205] neg_lo:[0,1] neg_hi:[0,1]
	v_pk_add_f32 v[202:203], v[202:203], v[216:217] neg_lo:[0,1] neg_hi:[0,1]
	v_pk_add_f32 v[204:205], v[206:207], v[210:211] neg_lo:[0,1] neg_hi:[0,1]
	v_pk_add_f32 v[132:133], v[132:133], v[220:221] neg_lo:[0,1] neg_hi:[0,1]
	v_pk_add_f32 v[138:139], v[208:209], v[138:139] neg_lo:[0,1] neg_hi:[0,1]
	v_pk_add_f32 v[206:207], v[132:133], v[204:205]
	v_mov_b32_e32 v205, v219
	v_mov_b32_e32 v133, v203
	v_pk_add_f32 v[208:209], v[218:219], v[202:203]
	v_pk_add_f32 v[132:133], v[204:205], v[132:133]
	v_mov_b32_e32 v202, v206
; __device__ __forceinline__ float log_sigmoid_f(float x) { return fminf(x, 0.f) - log1pf(__expf(-fabsf(x))); }
;     __device__ __forceinline__ void operator()(const f32x4 (&acc)[2][2][4][2], const Unit& u, int wr, int wc, int fr, int fq) const {
;     ...
;                     for (int m = 0; m < 4; ++m) { const int row = row0 + ai * HALF + m * 16; const float s = sc8[ai][m];
;                         float* dst = nullptr;
;                         if (pm == 0) dst = o_lfs + (size_t)row * 16; else { const int t = row - G_ROWP; if (t < G_TP) dst = o_lfp + (size_t)t * 16; }
; #pragma unroll
;                         for (int n = 0; n < 2; ++n) { const int c = 8 * fq + 4 * n; const f32x4 bv = *(const f32x4*)(b_f + c); const f32x4 x = acc[ai][0][m][n] * s + bv; f32x4 lf;
;                             lf[0] = log_sigmoid_f(x[0]); lf[1] = log_sigmoid_f(x[1]); lf[2] = log_sigmoid_f(x[2]); lf[3] = log_sigmoid_f(x[3]);
;                             *(f32x4*)(LF + (size_t)row * 16 + c) = lf; if (dst) *(f32x4*)(dst + c) = lf; } }
	v_pk_add_f32 v[132:133], v[132:133], v[222:223] neg_lo:[0,1] neg_hi:[0,1]
	v_mov_b32_e32 v203, v209
	v_pk_add_f32 v[202:203], v[202:203], v[132:133] neg_lo:[0,1] neg_hi:[0,1]
	v_pk_add_f32 v[132:133], v[138:139], v[132:133] neg_lo:[0,1] neg_hi:[0,1]
	v_pk_add_f32 v[202:203], v[204:205], v[202:203] neg_lo:[0,1] neg_hi:[0,1]
	v_pk_add_f32 v[138:139], v[208:209], v[206:207]
	v_pk_add_f32 v[132:133], v[132:133], v[202:203]
	v_pk_add_f32 v[202:203], v[214:215], v[138:139]
	s_nop 0
	v_pk_add_f32 v[204:205], v[202:203], v[214:215] neg_lo:[0,1] neg_hi:[0,1]
	s_nop 0
	v_pk_add_f32 v[138:139], v[138:139], v[204:205] neg_lo:[0,1] neg_hi:[0,1]
	s_nop 0
	v_pk_add_f32 v[132:133], v[132:133], v[138:139]
	s_nop 0
	v_pk_add_f32 v[132:133], v[202:203], v[132:133]
	s_nop 0
	v_cndmask_b32_e64 v132, v231, v132, s[12:13]
	v_cmp_neq_f32_e64 s[12:13], s4, v183
	s_nop 1
	v_cndmask_b32_e64 v133, v231, v133, s[12:13]
	v_cmp_ngt_f32_e64 s[12:13], -1.0, v183
	s_nop 1
	v_cndmask_b32_e64 v133, v232, v133, s[12:13]
	v_cmp_ngt_f32_e64 s[12:13], -1.0, v173
	s_nop 1
	v_cndmask_b32_e64 v132, v232, v132, s[12:13]
	v_cmp_neq_f32_e64 s[12:13], -1.0, v173
	s_nop 1
	v_cndmask_b32_e64 v132, v233, v132, s[12:13]
	v_cmp_neq_f32_e64 s[12:13], -1.0, v183
	s_nop 1
	v_cndmask_b32_e64 v133, v233, v133, s[12:13]
	v_cmp_lt_f32_e64 s[12:13], |v173|, s5
	v_cndmask_b32_e64 v133, v133, v183, s[14:15]
	s_nop 0
	v_cndmask_b32_e64 v132, v132, v173, s[12:13]
	v_pk_add_f32 v[132:133], v[140:141], v[132:133] neg_lo:[0,1] neg_hi:[0,1]
	global_store_dwordx4 v[136:137], v[130:133], off nt
	s_and_saveexec_b64 s[12:13], vcc
	s_cbranch_execz .LBB0_419
	v_lshl_add_u64 v[138:139], v[134:135], 0, v[150:151]
	global_store_dwordx4 v[138:139], v[130:133], off nt
.LBB0_419:
	s_or_b64 exec, exec, s[12:13]
	global_load_dwordx4 v[130:133], v[158:159], off offset:16
	v_mov_b32_e32 v179, v178
	v_mov_b32_e32 v138, v178
	v_mov_b32_e32 v139, v178
	s_waitcnt vmcnt(0)
	v_pk_fma_f32 v[132:133], v[28:29], v[138:139], v[132:133]
	v_pk_fma_f32 v[138:139], v[26:27], v[178:179], v[130:131]
	s_nop 0
	v_mul_f32_e64 v131, |v138|, s34
	v_exp_f32_e32 v173, v131
	v_min_f32_e32 v130, 0, v138
	v_add_f32_e32 v131, 1.0, v173
	v_add_f32_e32 v138, -1.0, v131
	v_sub_f32_e32 v140, v138, v131
	v_add_f32_e32 v140, 1.0, v140
	v_sub_f32_e32 v138, v173, v138
	v_add_f32_e32 v179, v138, v140
	v_frexp_mant_f32_e32 v138, v131
	v_cvt_f64_f32_e32 v[140:141], v131
	v_cmp_gt_f32_e64 s[12:13], s35, v138
	v_frexp_exp_i32_f64_e32 v138, v[140:141]
	s_nop 0
	v_subbrev_co_u32_e64 v183, s[12:13], 0, v138, s[12:13]
	v_sub_u32_e32 v140, 0, v183
	v_ldexp_f32 v138, v131, v140
	v_min_f32_e32 v131, 0, v139
	v_mul_f32_e64 v139, |v139|, s34
	v_ldexp_f32 v140, v179, v140
	v_exp_f32_e32 v179, v139
	s_nop 0
	v_add_f32_e32 v139, 1.0, v179
	v_add_f32_e32 v141, -1.0, v139
	v_sub_f32_e32 v187, v141, v139
	v_add_f32_e32 v187, 1.0, v187
	v_sub_f32_e32 v141, v179, v141
	v_add_f32_e32 v141, v141, v187
	v_frexp_mant_f32_e32 v187, v139
	v_cvt_f64_f32_e32 v[202:203], v139
	v_cmp_gt_f32_e64 s[12:13], s35, v187
	v_frexp_exp_i32_f64_e32 v187, v[202:203]
	v_cmp_lt_f32_e64 s[14:15], |v179|, s5
	v_subbrev_co_u32_e64 v187, s[12:13], 0, v187, s[12:13]
	v_sub_u32_e32 v191, 0, v187
	v_ldexp_f32 v139, v139, v191
	v_pk_add_f32 v[202:203], v[138:139], 1.0 op_sel_hi:[1,0]
	v_ldexp_f32 v141, v141, v191
	v_pk_add_f32 v[204:205], v[202:203], -1.0 op_sel_hi:[1,0]
	v_pk_add_f32 v[210:211], v[138:139], -1.0 op_sel_hi:[1,0]
	v_pk_add_f32 v[204:205], v[138:139], v[204:205] neg_lo:[0,1] neg_hi:[0,1]
	v_pk_add_f32 v[212:213], v[210:211], 1.0 op_sel_hi:[1,0]
	v_pk_add_f32 v[204:205], v[140:141], v[204:205]
	v_pk_add_f32 v[138:139], v[138:139], v[212:213] neg_lo:[0,1] neg_hi:[0,1]
	v_pk_add_f32 v[206:207], v[202:203], v[204:205]
	v_pk_add_f32 v[138:139], v[140:141], v[138:139]
	v_rcp_f32_e32 v208, v206
	v_rcp_f32_e32 v209, v207
	v_pk_add_f32 v[140:141], v[210:211], v[138:139]
	v_pk_add_f32 v[202:203], v[206:207], v[202:203] neg_lo:[0,1] neg_hi:[0,1]
	v_pk_add_f32 v[210:211], v[140:141], v[210:211] neg_lo:[0,1] neg_hi:[0,1]
	v_pk_add_f32 v[202:203], v[204:205], v[202:203] neg_lo:[0,1] neg_hi:[0,1]
	v_pk_mul_f32 v[204:205], v[140:141], v[208:209]
	v_pk_add_f32 v[138:139], v[138:139], v[210:211] neg_lo:[0,1] neg_hi:[0,1]
	v_pk_mul_f32 v[210:211], v[206:207], v[204:205]
	v_cmp_neq_f32_e64 s[12:13], s4, v173
	v_pk_fma_f32 v[212:213], v[204:205], v[206:207], v[210:211] neg_lo:[0,0,1] neg_hi:[0,0,1]
	s_nop 0
	v_pk_fma_f32 v[212:213], v[204:205], v[202:203], v[212:213]
	s_nop 0
	v_pk_add_f32 v[214:215], v[210:211], v[212:213]
	s_nop 0
	v_pk_add_f32 v[216:217], v[140:141], v[214:215] neg_lo:[0,1] neg_hi:[0,1]
	v_pk_add_f32 v[210:211], v[214:215], v[210:211] neg_lo:[0,1] neg_hi:[0,1]
	v_pk_add_f32 v[140:141], v[140:141], v[216:217] neg_lo:[0,1] neg_hi:[0,1]
	s_nop 0
	v_pk_add_f32 v[140:141], v[140:141], v[214:215] neg_lo:[0,1] neg_hi:[0,1]
	s_nop 0
	v_pk_add_f32 v[138:139], v[138:139], v[140:141]
	v_pk_add_f32 v[140:141], v[210:211], v[212:213] neg_lo:[0,1] neg_hi:[0,1]
	s_nop 0
	v_pk_add_f32 v[138:139], v[140:141], v[138:139]
	s_nop 0
	v_pk_add_f32 v[140:141], v[216:217], v[138:139]
	s_nop 0
	v_pk_mul_f32 v[210:211], v[208:209], v[140:141]
	s_nop 0
	v_pk_mul_f32 v[212:213], v[206:207], v[210:211]
	s_nop 0
	v_pk_fma_f32 v[206:207], v[210:211], v[206:207], v[212:213] neg_lo:[0,0,1] neg_hi:[0,0,1]
	s_nop 0
	v_pk_fma_f32 v[202:203], v[210:211], v[202:203], v[206:207]
	v_pk_add_f32 v[206:207], v[216:217], v[140:141] neg_lo:[0,1] neg_hi:[0,1]
	s_nop 0
	v_pk_add_f32 v[138:139], v[138:139], v[206:207]
	v_pk_add_f32 v[206:207], v[212:213], v[202:203]
	s_nop 0
	v_pk_add_f32 v[214:215], v[140:141], v[206:207] neg_lo:[0,1] neg_hi:[0,1]
; __device__ __forceinline__ float log_sigmoid_f(float x) { return fminf(x, 0.f) - log1pf(__expf(-fabsf(x))); }
;     __device__ __forceinline__ void operator()(const f32x4 (&acc)[2][2][4][2], const Unit& u, int wr, int wc, int fr, int fq) const {
;     ...
;                         for (int n = 0; n < 2; ++n) { const int c = 8 * fq + 4 * n; const f32x4 bv = *(const f32x4*)(b_f + c); const f32x4 x = acc[ai][0][m][n] * s + bv; f32x4 lf;
;                             lf[0] = log_sigmoid_f(x[0]); lf[1] = log_sigmoid_f(x[1]); lf[2] = log_sigmoid_f(x[2]); lf[3] = log_sigmoid_f(x[3]);
	v_pk_add_f32 v[212:213], v[206:207], v[212:213] neg_lo:[0,1] neg_hi:[0,1]
	v_pk_add_f32 v[140:141], v[140:141], v[214:215] neg_lo:[0,1] neg_hi:[0,1]
	s_nop 0
	v_pk_add_f32 v[140:141], v[140:141], v[206:207] neg_lo:[0,1] neg_hi:[0,1]
	s_nop 0
	v_pk_add_f32 v[138:139], v[138:139], v[140:141]
	v_pk_add_f32 v[140:141], v[212:213], v[202:203] neg_lo:[0,1] neg_hi:[0,1]
	s_nop 0
	v_pk_add_f32 v[138:139], v[140:141], v[138:139]
	v_pk_add_f32 v[140:141], v[204:205], v[210:211]
	v_pk_add_f32 v[138:139], v[214:215], v[138:139]
	v_pk_add_f32 v[202:203], v[140:141], v[204:205] neg_lo:[0,1] neg_hi:[0,1]
	v_pk_mul_f32 v[138:139], v[208:209], v[138:139]
	v_pk_add_f32 v[202:203], v[210:211], v[202:203] neg_lo:[0,1] neg_hi:[0,1]
	v_cvt_f32_i32_e32 v211, v187
	v_pk_add_f32 v[138:139], v[202:203], v[138:139]
	v_cvt_f32_i32_e32 v210, v183
	v_pk_add_f32 v[204:205], v[140:141], v[138:139]
	s_nop 0
	v_pk_add_f32 v[140:141], v[204:205], v[140:141] neg_lo:[0,1] neg_hi:[0,1]
	v_pk_mul_f32 v[206:207], v[204:205], v[204:205]
	v_pk_add_f32 v[140:141], v[138:139], v[140:141] neg_lo:[0,1] neg_hi:[0,1]
	v_mov_b64_e32 v[138:139], s[50:51]
	v_pk_fma_f32 v[208:209], v[206:207], s[52:53], v[138:139] op_sel_hi:[1,0,0]
	v_ldexp_f32 v202, v204, 1
	v_pk_fma_f32 v[208:209], v[206:207], v[208:209], s[54:55] op_sel_hi:[1,1,0]
	v_ldexp_f32 v203, v205, 1
	v_pk_mul_f32 v[204:205], v[204:205], v[206:207]
	v_ldexp_f32 v213, v141, 1
	v_pk_mul_f32 v[214:215], v[204:205], v[208:209]
	v_pk_mul_f32 v[206:207], v[210:211], s[64:65] op_sel_hi:[1,0]
	v_pk_add_f32 v[204:205], v[202:203], v[214:215]
	v_ldexp_f32 v140, v140, 1
	v_pk_add_f32 v[202:203], v[204:205], v[202:203] neg_lo:[0,1] neg_hi:[0,1]
	v_pk_fma_f32 v[208:209], v[210:211], s[64:65], v[206:207] op_sel_hi:[1,0,1] neg_lo:[0,0,1] neg_hi:[0,0,1]
	v_pk_add_f32 v[216:217], v[214:215], v[202:203] neg_lo:[0,1] neg_hi:[0,1]
	v_mov_b32_e32 v141, v213
	v_pk_fma_f32 v[208:209], v[210:211], s[66:67], v[208:209] op_sel_hi:[1,0,1]
	v_pk_add_f32 v[214:215], v[140:141], v[216:217]
	v_mov_b32_e32 v202, v206
	v_mov_b32_e32 v203, v217
	v_mov_b32_e32 v212, v208
	v_mov_b32_e32 v141, v215
	v_mov_b32_e32 v217, v205
	v_pk_add_f32 v[210:211], v[206:207], v[208:209]
	v_pk_add_f32 v[202:203], v[202:203], v[212:213]
	v_pk_add_f32 v[212:213], v[140:141], v[216:217]
	v_pk_add_f32 v[216:217], v[204:205], v[214:215]
	v_mov_b32_e32 v224, v204
	v_pk_add_f32 v[140:141], v[210:211], v[216:217]
	v_mov_b32_e32 v222, v216
	v_mov_b32_e32 v223, v141
	v_mov_b32_e32 v225, v211
	v_pk_add_f32 v[222:223], v[222:223], v[224:225] neg_lo:[0,1] neg_hi:[0,1]
	v_mov_b32_e32 v218, v140
	v_mov_b32_e32 v219, v211
	v_mov_b32_e32 v220, v210
	v_mov_b32_e32 v221, v207
	v_mov_b32_e32 v224, v210
	v_mov_b32_e32 v225, v141
	v_mov_b32_e32 v207, v223
	v_pk_add_f32 v[218:219], v[218:219], v[220:221] neg_lo:[0,1] neg_hi:[0,1]
	v_mov_b32_e32 v220, v216
	v_mov_b32_e32 v221, v209
	v_pk_add_f32 v[206:207], v[224:225], v[206:207] neg_lo:[0,1] neg_hi:[0,1]
	v_pk_add_f32 v[220:221], v[220:221], v[218:219] neg_lo:[0,1] neg_hi:[0,1]
	v_mov_b32_e32 v224, v206
	v_mov_b32_e32 v225, v219
	v_mov_b32_e32 v226, v140
	v_mov_b32_e32 v227, v217
	v_mov_b32_e32 v219, v205
	v_pk_add_f32 v[224:225], v[208:209], v[224:225] neg_lo:[0,1] neg_hi:[0,1]
	v_pk_add_f32 v[218:219], v[226:227], v[218:219] neg_lo:[0,1] neg_hi:[0,1]
	v_mov_b32_e32 v209, v211
	v_pk_add_f32 v[202:203], v[202:203], v[218:219] neg_lo:[0,1] neg_hi:[0,1]
	v_pk_add_f32 v[206:207], v[208:209], v[206:207] neg_lo:[0,1] neg_hi:[0,1]
	v_pk_add_f32 v[208:209], v[212:213], v[222:223] neg_lo:[0,1] neg_hi:[0,1]
	v_pk_add_f32 v[212:213], v[220:221], v[202:203]
	v_pk_add_f32 v[210:211], v[208:209], v[206:207]
	v_mov_b32_e32 v207, v221
	v_mov_b32_e32 v209, v203
	v_pk_add_f32 v[202:203], v[206:207], v[208:209]
	v_pk_add_f32 v[204:205], v[216:217], v[204:205] neg_lo:[0,1] neg_hi:[0,1]
	v_pk_add_f32 v[202:203], v[202:203], v[224:225] neg_lo:[0,1] neg_hi:[0,1]
	v_mov_b32_e32 v208, v210
	v_mov_b32_e32 v209, v213
	v_pk_add_f32 v[204:205], v[214:215], v[204:205] neg_lo:[0,1] neg_hi:[0,1]
	v_pk_add_f32 v[208:209], v[208:209], v[202:203] neg_lo:[0,1] neg_hi:[0,1]
	v_pk_add_f32 v[202:203], v[204:205], v[202:203] neg_lo:[0,1] neg_hi:[0,1]
	v_pk_add_f32 v[206:207], v[206:207], v[208:209] neg_lo:[0,1] neg_hi:[0,1]
	v_pk_add_f32 v[204:205], v[212:213], v[210:211]
	v_pk_add_f32 v[202:203], v[202:203], v[206:207]
	v_pk_add_f32 v[206:207], v[140:141], v[204:205]
	s_nop 0
	v_pk_add_f32 v[140:141], v[206:207], v[140:141] neg_lo:[0,1] neg_hi:[0,1]
	s_nop 0
	v_pk_add_f32 v[140:141], v[204:205], v[140:141] neg_lo:[0,1] neg_hi:[0,1]
	s_nop 0
	v_pk_add_f32 v[140:141], v[202:203], v[140:141]
	s_nop 0
	v_pk_add_f32 v[140:141], v[206:207], v[140:141]
	s_nop 0
	v_cndmask_b32_e64 v140, v231, v140, s[12:13]
	v_cmp_neq_f32_e64 s[12:13], s4, v179
	s_nop 1
	v_cndmask_b32_e64 v141, v231, v141, s[12:13]
	v_cmp_ngt_f32_e64 s[12:13], -1.0, v179
	s_nop 1
	v_cndmask_b32_e64 v141, v232, v141, s[12:13]
	v_cmp_ngt_f32_e64 s[12:13], -1.0, v173
	s_nop 1
	v_cndmask_b32_e64 v140, v232, v140, s[12:13]
	v_cmp_neq_f32_e64 s[12:13], -1.0, v173
	s_nop 1
	v_cndmask_b32_e64 v140, v233, v140, s[12:13]
	v_cmp_neq_f32_e64 s[12:13], -1.0, v179
	s_nop 1
	v_cndmask_b32_e64 v141, v233, v141, s[12:13]
	v_cmp_lt_f32_e64 s[12:13], |v173|, s5
	v_cndmask_b32_e64 v141, v141, v179, s[14:15]
	s_nop 0
	v_cndmask_b32_e64 v140, v140, v173, s[12:13]
	v_pk_add_f32 v[130:131], v[130:131], v[140:141] neg_lo:[0,1] neg_hi:[0,1]
	v_min_f32_e32 v140, 0, v132
	v_mul_f32_e64 v132, |v132|, s34
	v_exp_f32_e32 v173, v132
	s_nop 0
	v_add_f32_e32 v132, 1.0, v173
	v_add_f32_e32 v141, -1.0, v132
	v_sub_f32_e32 v179, v141, v132
	v_add_f32_e32 v179, 1.0, v179
; __device__ __forceinline__ float log_sigmoid_f(float x) { return fminf(x, 0.f) - log1pf(__expf(-fabsf(x))); }
	v_sub_f32_e32 v141, v173, v141
	v_add_f32_e32 v141, v141, v179
	v_frexp_mant_f32_e32 v179, v132
	v_cvt_f64_f32_e32 v[202:203], v132
	v_cmp_gt_f32_e64 s[12:13], s35, v179
	v_frexp_exp_i32_f64_e32 v179, v[202:203]
	s_nop 0
	v_subbrev_co_u32_e64 v179, s[12:13], 0, v179, s[12:13]
	v_sub_u32_e32 v183, 0, v179
	v_ldexp_f32 v202, v141, v183
	v_min_f32_e32 v141, 0, v133
	v_mul_f32_e64 v133, |v133|, s34
	v_ldexp_f32 v132, v132, v183
	v_exp_f32_e32 v183, v133
	s_nop 0
	v_add_f32_e32 v133, 1.0, v183
	v_add_f32_e32 v187, -1.0, v133
	v_sub_f32_e32 v191, v187, v133
	v_add_f32_e32 v191, 1.0, v191
	v_sub_f32_e32 v187, v183, v187
	v_add_f32_e32 v187, v187, v191
	v_frexp_mant_f32_e32 v191, v133
	v_cvt_f64_f32_e32 v[204:205], v133
	v_cmp_gt_f32_e64 s[12:13], s35, v191
	v_frexp_exp_i32_f64_e32 v191, v[204:205]
	v_cmp_lt_f32_e64 s[14:15], |v183|, s5
	v_subbrev_co_u32_e64 v191, s[12:13], 0, v191, s[12:13]
	v_sub_u32_e32 v195, 0, v191
	v_ldexp_f32 v133, v133, v195
	v_pk_add_f32 v[204:205], v[132:133], 1.0 op_sel_hi:[1,0]
	v_ldexp_f32 v203, v187, v195
	v_pk_add_f32 v[206:207], v[204:205], -1.0 op_sel_hi:[1,0]
	v_pk_add_f32 v[212:213], v[132:133], -1.0 op_sel_hi:[1,0]
	v_pk_add_f32 v[206:207], v[132:133], v[206:207] neg_lo:[0,1] neg_hi:[0,1]
	v_pk_add_f32 v[214:215], v[212:213], 1.0 op_sel_hi:[1,0]
	v_pk_add_f32 v[206:207], v[202:203], v[206:207]
	v_pk_add_f32 v[132:133], v[132:133], v[214:215] neg_lo:[0,1] neg_hi:[0,1]
	v_pk_add_f32 v[208:209], v[204:205], v[206:207]
	v_pk_add_f32 v[132:133], v[202:203], v[132:133]
	v_rcp_f32_e32 v210, v208
	v_rcp_f32_e32 v211, v209
	v_pk_add_f32 v[202:203], v[212:213], v[132:133]
	v_pk_add_f32 v[204:205], v[208:209], v[204:205] neg_lo:[0,1] neg_hi:[0,1]
	v_pk_add_f32 v[212:213], v[202:203], v[212:213] neg_lo:[0,1] neg_hi:[0,1]
	v_pk_add_f32 v[204:205], v[206:207], v[204:205] neg_lo:[0,1] neg_hi:[0,1]
	v_pk_mul_f32 v[206:207], v[202:203], v[210:211]
	v_pk_add_f32 v[132:133], v[132:133], v[212:213] neg_lo:[0,1] neg_hi:[0,1]
	v_pk_mul_f32 v[212:213], v[208:209], v[206:207]
	v_cmp_neq_f32_e64 s[12:13], s4, v173
	v_pk_fma_f32 v[214:215], v[206:207], v[208:209], v[212:213] neg_lo:[0,0,1] neg_hi:[0,0,1]
	s_nop 0
	v_pk_fma_f32 v[214:215], v[206:207], v[204:205], v[214:215]
	s_nop 0
	v_pk_add_f32 v[216:217], v[212:213], v[214:215]
	s_nop 0
	v_pk_add_f32 v[218:219], v[202:203], v[216:217] neg_lo:[0,1] neg_hi:[0,1]
	v_pk_add_f32 v[212:213], v[216:217], v[212:213] neg_lo:[0,1] neg_hi:[0,1]
	v_pk_add_f32 v[202:203], v[202:203], v[218:219] neg_lo:[0,1] neg_hi:[0,1]
	s_nop 0
	v_pk_add_f32 v[202:203], v[202:203], v[216:217] neg_lo:[0,1] neg_hi:[0,1]
	s_nop 0
	v_pk_add_f32 v[132:133], v[132:133], v[202:203]
	v_pk_add_f32 v[202:203], v[212:213], v[214:215] neg_lo:[0,1] neg_hi:[0,1]
	s_nop 0
	v_pk_add_f32 v[132:133], v[202:203], v[132:133]
	s_nop 0
	v_pk_add_f32 v[202:203], v[218:219], v[132:133]
	s_nop 0
	v_pk_mul_f32 v[212:213], v[210:211], v[202:203]
	s_nop 0
	v_pk_mul_f32 v[214:215], v[208:209], v[212:213]
	s_nop 0
	v_pk_fma_f32 v[208:209], v[212:213], v[208:209], v[214:215] neg_lo:[0,0,1] neg_hi:[0,0,1]
	s_nop 0
	v_pk_fma_f32 v[204:205], v[212:213], v[204:205], v[208:209]
	v_pk_add_f32 v[208:209], v[218:219], v[202:203] neg_lo:[0,1] neg_hi:[0,1]
	s_nop 0
	v_pk_add_f32 v[132:133], v[132:133], v[208:209]
	v_pk_add_f32 v[208:209], v[214:215], v[204:205]
	s_nop 0
	v_pk_add_f32 v[216:217], v[202:203], v[208:209] neg_lo:[0,1] neg_hi:[0,1]
	v_pk_add_f32 v[214:215], v[208:209], v[214:215] neg_lo:[0,1] neg_hi:[0,1]
	v_pk_add_f32 v[202:203], v[202:203], v[216:217] neg_lo:[0,1] neg_hi:[0,1]
	s_nop 0
	v_pk_add_f32 v[202:203], v[202:203], v[208:209] neg_lo:[0,1] neg_hi:[0,1]
	s_nop 0
	v_pk_add_f32 v[132:133], v[132:133], v[202:203]
	v_pk_add_f32 v[202:203], v[214:215], v[204:205] neg_lo:[0,1] neg_hi:[0,1]
	s_nop 0
	v_pk_add_f32 v[132:133], v[202:203], v[132:133]
	v_pk_add_f32 v[202:203], v[206:207], v[212:213]
	v_pk_add_f32 v[132:133], v[216:217], v[132:133]
	v_pk_add_f32 v[204:205], v[202:203], v[206:207] neg_lo:[0,1] neg_hi:[0,1]
	v_pk_mul_f32 v[132:133], v[210:211], v[132:133]
	v_pk_add_f32 v[204:205], v[212:213], v[204:205] neg_lo:[0,1] neg_hi:[0,1]
	s_nop 0
	v_pk_add_f32 v[132:133], v[204:205], v[132:133]
	s_nop 0
	v_pk_add_f32 v[204:205], v[202:203], v[132:133]
	s_nop 0
	v_pk_mul_f32 v[206:207], v[204:205], v[204:205]
	v_pk_add_f32 v[202:203], v[204:205], v[202:203] neg_lo:[0,1] neg_hi:[0,1]
	v_pk_fma_f32 v[138:139], v[206:207], s[52:53], v[138:139] op_sel_hi:[1,0,0]
	v_pk_add_f32 v[132:133], v[132:133], v[202:203] neg_lo:[0,1] neg_hi:[0,1]
; __device__ __forceinline__ float log_sigmoid_f(float x) { return fminf(x, 0.f) - log1pf(__expf(-fabsf(x))); }
;     __device__ __forceinline__ void operator()(const f32x4 (&acc)[2][2][4][2], const Unit& u, int wr, int wc, int fr, int fq) const {
;     ...
;                         for (int n = 0; n < 2; ++n) { const int c = 8 * fq + 4 * n; const f32x4 bv = *(const f32x4*)(b_f + c); const f32x4 x = acc[ai][0][m][n] * s + bv; f32x4 lf;
;                             lf[0] = log_sigmoid_f(x[0]); lf[1] = log_sigmoid_f(x[1]); lf[2] = log_sigmoid_f(x[2]); lf[3] = log_sigmoid_f(x[3]);
;                             *(f32x4*)(LF + (size_t)row * 16 + c) = lf; if (dst) *(f32x4*)(dst + c) = lf; } }
	v_ldexp_f32 v202, v204, 1
	v_pk_fma_f32 v[138:139], v[206:207], v[138:139], s[54:55] op_sel_hi:[1,1,0]
	v_ldexp_f32 v203, v205, 1
	v_pk_mul_f32 v[204:205], v[204:205], v[206:207]
	v_cvt_f32_i32_e32 v207, v191
	v_cvt_f32_i32_e32 v206, v179
	v_pk_mul_f32 v[138:139], v[204:205], v[138:139]
	v_ldexp_f32 v209, v133, 1
	v_pk_add_f32 v[204:205], v[202:203], v[138:139]
	v_pk_mul_f32 v[210:211], v[206:207], s[64:65] op_sel_hi:[1,0]
	v_pk_add_f32 v[202:203], v[204:205], v[202:203] neg_lo:[0,1] neg_hi:[0,1]
	v_pk_fma_f32 v[212:213], v[206:207], s[64:65], v[210:211] op_sel_hi:[1,0,1] neg_lo:[0,0,1] neg_hi:[0,0,1]
	v_pk_add_f32 v[138:139], v[138:139], v[202:203] neg_lo:[0,1] neg_hi:[0,1]
	v_pk_fma_f32 v[206:207], v[206:207], s[66:67], v[212:213] op_sel_hi:[1,0,1]
	v_ldexp_f32 v132, v132, 1
	v_mov_b32_e32 v202, v210
	v_mov_b32_e32 v203, v139
	v_mov_b32_e32 v208, v206
	v_mov_b32_e32 v133, v209
	v_pk_add_f32 v[202:203], v[202:203], v[208:209]
	v_pk_add_f32 v[208:209], v[132:133], v[138:139]
	v_mov_b32_e32 v139, v205
	v_mov_b32_e32 v133, v209
	v_pk_add_f32 v[212:213], v[210:211], v[206:207]
	v_pk_add_f32 v[132:133], v[132:133], v[138:139]
	v_pk_add_f32 v[138:139], v[204:205], v[208:209]
	v_mov_b32_e32 v222, v204
	v_pk_add_f32 v[214:215], v[212:213], v[138:139]
	v_mov_b32_e32 v220, v138
	v_mov_b32_e32 v221, v215
	v_mov_b32_e32 v223, v213
	v_pk_add_f32 v[220:221], v[220:221], v[222:223] neg_lo:[0,1] neg_hi:[0,1]
	v_mov_b32_e32 v216, v214
	v_mov_b32_e32 v217, v213
	v_mov_b32_e32 v218, v212
	v_mov_b32_e32 v219, v211
	v_mov_b32_e32 v222, v212
	v_mov_b32_e32 v223, v215
	v_mov_b32_e32 v211, v221
	v_pk_add_f32 v[216:217], v[216:217], v[218:219] neg_lo:[0,1] neg_hi:[0,1]
	v_mov_b32_e32 v218, v138
	v_mov_b32_e32 v219, v207
	v_pk_add_f32 v[210:211], v[222:223], v[210:211] neg_lo:[0,1] neg_hi:[0,1]
	v_pk_add_f32 v[218:219], v[218:219], v[216:217] neg_lo:[0,1] neg_hi:[0,1]
	v_mov_b32_e32 v222, v210
	v_mov_b32_e32 v223, v217
	v_mov_b32_e32 v224, v214
	v_mov_b32_e32 v225, v139
	v_mov_b32_e32 v217, v205
	v_pk_add_f32 v[222:223], v[206:207], v[222:223] neg_lo:[0,1] neg_hi:[0,1]
	v_pk_add_f32 v[216:217], v[224:225], v[216:217] neg_lo:[0,1] neg_hi:[0,1]
	v_mov_b32_e32 v207, v213
	v_pk_add_f32 v[138:139], v[138:139], v[204:205] neg_lo:[0,1] neg_hi:[0,1]
	v_pk_add_f32 v[202:203], v[202:203], v[216:217] neg_lo:[0,1] neg_hi:[0,1]
	v_pk_add_f32 v[204:205], v[206:207], v[210:211] neg_lo:[0,1] neg_hi:[0,1]
	v_pk_add_f32 v[132:133], v[132:133], v[220:221] neg_lo:[0,1] neg_hi:[0,1]
	v_pk_add_f32 v[138:139], v[208:209], v[138:139] neg_lo:[0,1] neg_hi:[0,1]
	v_pk_add_f32 v[206:207], v[132:133], v[204:205]
	v_mov_b32_e32 v205, v219
	v_mov_b32_e32 v133, v203
	v_pk_add_f32 v[208:209], v[218:219], v[202:203]
	v_pk_add_f32 v[132:133], v[204:205], v[132:133]
	v_mov_b32_e32 v202, v206
	v_pk_add_f32 v[132:133], v[132:133], v[222:223] neg_lo:[0,1] neg_hi:[0,1]
	v_mov_b32_e32 v203, v209
	v_pk_add_f32 v[202:203], v[202:203], v[132:133] neg_lo:[0,1] neg_hi:[0,1]
	v_pk_add_f32 v[132:133], v[138:139], v[132:133] neg_lo:[0,1] neg_hi:[0,1]
	v_pk_add_f32 v[202:203], v[204:205], v[202:203] neg_lo:[0,1] neg_hi:[0,1]
	v_pk_add_f32 v[138:139], v[208:209], v[206:207]
	v_pk_add_f32 v[132:133], v[132:133], v[202:203]
	v_pk_add_f32 v[202:203], v[214:215], v[138:139]
	s_nop 0
	v_pk_add_f32 v[204:205], v[202:203], v[214:215] neg_lo:[0,1] neg_hi:[0,1]
	s_nop 0
	v_pk_add_f32 v[138:139], v[138:139], v[204:205] neg_lo:[0,1] neg_hi:[0,1]
	s_nop 0
	v_pk_add_f32 v[132:133], v[132:133], v[138:139]
	s_nop 0
	v_pk_add_f32 v[132:133], v[202:203], v[132:133]
	s_nop 0
	v_cndmask_b32_e64 v132, v231, v132, s[12:13]
	v_cmp_neq_f32_e64 s[12:13], s4, v183
	s_nop 1
	v_cndmask_b32_e64 v133, v231, v133, s[12:13]
	v_cmp_ngt_f32_e64 s[12:13], -1.0, v183
	s_nop 1
	v_cndmask_b32_e64 v133, v232, v133, s[12:13]
	v_cmp_ngt_f32_e64 s[12:13], -1.0, v173
	s_nop 1
	v_cndmask_b32_e64 v132, v232, v132, s[12:13]
	v_cmp_neq_f32_e64 s[12:13], -1.0, v173
	s_nop 1
	v_cndmask_b32_e64 v132, v233, v132, s[12:13]
	v_cmp_neq_f32_e64 s[12:13], -1.0, v183
	s_nop 1
	v_cndmask_b32_e64 v133, v233, v133, s[12:13]
	v_cmp_lt_f32_e64 s[12:13], |v173|, s5
	v_cndmask_b32_e64 v133, v133, v183, s[14:15]
	s_nop 0
	v_cndmask_b32_e64 v132, v132, v173, s[12:13]
	v_pk_add_f32 v[132:133], v[140:141], v[132:133] neg_lo:[0,1] neg_hi:[0,1]
	global_store_dwordx4 v[136:137], v[130:133], off offset:16 nt
	s_and_saveexec_b64 s[12:13], vcc
	s_cbranch_execz .LBB0_421
	v_lshl_add_u64 v[134:135], v[134:135], 0, v[150:151]
	global_store_dwordx4 v[134:135], v[130:133], off offset:16 nt

; __device__ __forceinline__ float log_sigmoid_f(float x) { return fminf(x, 0.f) - log1pf(__expf(-fabsf(x))); }
;     __device__ __forceinline__ void operator()(const f32x4 (&acc)[2][2][4][2], const Unit& u, int wr, int wc, int fr, int fq) const {
;     ...
;                     for (int m = 0; m < 4; ++m) { const int row = row0 + ai * HALF + m * 16; const float s = sc8[ai][m];
;                         float* dst = nullptr;
;                         if (pm == 0) dst = o_lfs + (size_t)row * 16; else { const int t = row - G_ROWP; if (t < G_TP) dst = o_lfp + (size_t)t * 16; }
; #pragma unroll
;                         for (int n = 0; n < 2; ++n) { const int c = 8 * fq + 4 * n; const f32x4 bv = *(const f32x4*)(b_f + c); const f32x4 x = acc[ai][0][m][n] * s + bv; f32x4 lf;
;                             lf[0] = log_sigmoid_f(x[0]); lf[1] = log_sigmoid_f(x[1]); lf[2] = log_sigmoid_f(x[2]); lf[3] = log_sigmoid_f(x[3]);
.LBB0_424:
	global_load_dwordx4 v[130:133], v[158:159], off
	v_cmp_ne_u64_e32 vcc, 0, v[134:135]
	v_lshl_add_u64 v[136:137], v[162:163], 0, v[136:137]
	s_waitcnt vmcnt(0)
	v_pk_fma_f32 v[138:139], v[14:15], v[172:173], v[130:131] op_sel_hi:[1,0,1]
	s_nop 0
	v_mul_f32_e64 v131, |v138|, s34
	v_pk_fma_f32 v[132:133], v[16:17], v[172:173], v[132:133] op_sel_hi:[1,0,1]
	v_exp_f32_e32 v173, v131
	v_min_f32_e32 v130, 0, v138
	v_add_f32_e32 v131, 1.0, v173
	v_add_f32_e32 v138, -1.0, v131
	v_sub_f32_e32 v140, v138, v131
	v_add_f32_e32 v140, 1.0, v140
	v_sub_f32_e32 v138, v173, v138
	v_add_f32_e32 v179, v138, v140
	v_frexp_mant_f32_e32 v138, v131
	v_cvt_f64_f32_e32 v[140:141], v131
	v_cmp_gt_f32_e64 s[10:11], s35, v138
	v_frexp_exp_i32_f64_e32 v138, v[140:141]
	s_nop 0
	v_subbrev_co_u32_e64 v183, s[10:11], 0, v138, s[10:11]
	v_sub_u32_e32 v140, 0, v183
	v_ldexp_f32 v138, v131, v140
	v_min_f32_e32 v131, 0, v139
	v_mul_f32_e64 v139, |v139|, s34
	v_ldexp_f32 v140, v179, v140
	v_exp_f32_e32 v179, v139
	s_nop 0
	v_add_f32_e32 v139, 1.0, v179
	v_add_f32_e32 v141, -1.0, v139
	v_sub_f32_e32 v187, v141, v139
	v_add_f32_e32 v187, 1.0, v187
	v_sub_f32_e32 v141, v179, v141
	v_add_f32_e32 v141, v141, v187
	v_frexp_mant_f32_e32 v187, v139
	v_cvt_f64_f32_e32 v[202:203], v139
	v_cmp_gt_f32_e64 s[10:11], s35, v187
	v_frexp_exp_i32_f64_e32 v187, v[202:203]
	v_cmp_lt_f32_e64 s[12:13], |v179|, s5
	v_subbrev_co_u32_e64 v187, s[10:11], 0, v187, s[10:11]
	v_sub_u32_e32 v191, 0, v187
	v_ldexp_f32 v139, v139, v191
	v_pk_add_f32 v[202:203], v[138:139], 1.0 op_sel_hi:[1,0]
	v_ldexp_f32 v141, v141, v191
	v_pk_add_f32 v[204:205], v[202:203], -1.0 op_sel_hi:[1,0]
	v_pk_add_f32 v[210:211], v[138:139], -1.0 op_sel_hi:[1,0]
	v_pk_add_f32 v[204:205], v[138:139], v[204:205] neg_lo:[0,1] neg_hi:[0,1]
	v_pk_add_f32 v[212:213], v[210:211], 1.0 op_sel_hi:[1,0]
	v_pk_add_f32 v[204:205], v[140:141], v[204:205]
	v_pk_add_f32 v[138:139], v[138:139], v[212:213] neg_lo:[0,1] neg_hi:[0,1]
	v_pk_add_f32 v[206:207], v[202:203], v[204:205]
	v_pk_add_f32 v[138:139], v[140:141], v[138:139]
	v_rcp_f32_e32 v208, v206
	v_rcp_f32_e32 v209, v207
	v_pk_add_f32 v[140:141], v[210:211], v[138:139]
	v_pk_add_f32 v[202:203], v[206:207], v[202:203] neg_lo:[0,1] neg_hi:[0,1]
	v_pk_add_f32 v[210:211], v[140:141], v[210:211] neg_lo:[0,1] neg_hi:[0,1]
	v_pk_add_f32 v[202:203], v[204:205], v[202:203] neg_lo:[0,1] neg_hi:[0,1]
	v_pk_mul_f32 v[204:205], v[140:141], v[208:209]
	v_pk_add_f32 v[138:139], v[138:139], v[210:211] neg_lo:[0,1] neg_hi:[0,1]
	v_pk_mul_f32 v[210:211], v[206:207], v[204:205]
	v_cmp_neq_f32_e64 s[10:11], s4, v173
	v_pk_fma_f32 v[212:213], v[204:205], v[206:207], v[210:211] neg_lo:[0,0,1] neg_hi:[0,0,1]
	s_nop 0
	v_pk_fma_f32 v[212:213], v[204:205], v[202:203], v[212:213]
	s_nop 0
	v_pk_add_f32 v[214:215], v[210:211], v[212:213]
	s_nop 0
	v_pk_add_f32 v[216:217], v[140:141], v[214:215] neg_lo:[0,1] neg_hi:[0,1]
	v_pk_add_f32 v[210:211], v[214:215], v[210:211] neg_lo:[0,1] neg_hi:[0,1]
	v_pk_add_f32 v[140:141], v[140:141], v[216:217] neg_lo:[0,1] neg_hi:[0,1]
	s_nop 0
	v_pk_add_f32 v[140:141], v[140:141], v[214:215] neg_lo:[0,1] neg_hi:[0,1]
	s_nop 0
	v_pk_add_f32 v[138:139], v[138:139], v[140:141]
	v_pk_add_f32 v[140:141], v[210:211], v[212:213] neg_lo:[0,1] neg_hi:[0,1]
	s_nop 0
	v_pk_add_f32 v[138:139], v[140:141], v[138:139]
	s_nop 0
	v_pk_add_f32 v[140:141], v[216:217], v[138:139]
	s_nop 0
	v_pk_mul_f32 v[210:211], v[208:209], v[140:141]
	s_nop 0
	v_pk_mul_f32 v[212:213], v[206:207], v[210:211]
	s_nop 0
	v_pk_fma_f32 v[206:207], v[210:211], v[206:207], v[212:213] neg_lo:[0,0,1] neg_hi:[0,0,1]
	s_nop 0
	v_pk_fma_f32 v[202:203], v[210:211], v[202:203], v[206:207]
	v_pk_add_f32 v[206:207], v[216:217], v[140:141] neg_lo:[0,1] neg_hi:[0,1]
	s_nop 0
	v_pk_add_f32 v[138:139], v[138:139], v[206:207]
	v_pk_add_f32 v[206:207], v[212:213], v[202:203]
	s_nop 0
	v_pk_add_f32 v[214:215], v[140:141], v[206:207] neg_lo:[0,1] neg_hi:[0,1]
	v_pk_add_f32 v[212:213], v[206:207], v[212:213] neg_lo:[0,1] neg_hi:[0,1]
	v_pk_add_f32 v[140:141], v[140:141], v[214:215] neg_lo:[0,1] neg_hi:[0,1]
	s_nop 0
	v_pk_add_f32 v[140:141], v[140:141], v[206:207] neg_lo:[0,1] neg_hi:[0,1]
	s_nop 0
	v_pk_add_f32 v[138:139], v[138:139], v[140:141]
	v_pk_add_f32 v[140:141], v[212:213], v[202:203] neg_lo:[0,1] neg_hi:[0,1]
	s_nop 0
	v_pk_add_f32 v[138:139], v[140:141], v[138:139]
	v_pk_add_f32 v[140:141], v[204:205], v[210:211]
	v_pk_add_f32 v[138:139], v[214:215], v[138:139]
	v_pk_add_f32 v[202:203], v[140:141], v[204:205] neg_lo:[0,1] neg_hi:[0,1]
	v_pk_mul_f32 v[138:139], v[208:209], v[138:139]
	v_pk_add_f32 v[202:203], v[210:211], v[202:203] neg_lo:[0,1] neg_hi:[0,1]
	s_nop 0
	v_pk_add_f32 v[138:139], v[202:203], v[138:139]
	s_nop 0
	v_pk_add_f32 v[204:205], v[140:141], v[138:139]
	s_nop 0
	v_pk_add_f32 v[140:141], v[204:205], v[140:141] neg_lo:[0,1] neg_hi:[0,1]
	v_pk_mul_f32 v[206:207], v[204:205], v[204:205]
	v_pk_add_f32 v[140:141], v[138:139], v[140:141] neg_lo:[0,1] neg_hi:[0,1]
	v_mov_b64_e32 v[138:139], s[50:51]
	v_pk_fma_f32 v[208:209], v[206:207], s[52:53], v[138:139] op_sel_hi:[1,0,0]
	v_ldexp_f32 v202, v204, 1
	v_pk_fma_f32 v[208:209], v[206:207], v[208:209], s[54:55] op_sel_hi:[1,1,0]
	v_ldexp_f32 v203, v205, 1
	v_pk_mul_f32 v[204:205], v[204:205], v[206:207]
	v_cvt_f32_i32_e32 v207, v187
	v_cvt_f32_i32_e32 v206, v183
	v_pk_mul_f32 v[214:215], v[204:205], v[208:209]
	v_ldexp_f32 v213, v141, 1
	v_pk_add_f32 v[204:205], v[202:203], v[214:215]
	v_pk_mul_f32 v[210:211], v[206:207], s[64:65] op_sel_hi:[1,0]
	v_pk_add_f32 v[202:203], v[204:205], v[202:203] neg_lo:[0,1] neg_hi:[0,1]
	v_ldexp_f32 v140, v140, 1
; __device__ __forceinline__ float log_sigmoid_f(float x) { return fminf(x, 0.f) - log1pf(__expf(-fabsf(x))); }
;     __device__ __forceinline__ void operator()(const f32x4 (&acc)[2][2][4][2], const Unit& u, int wr, int wc, int fr, int fq) const {
;     ...
;                         for (int n = 0; n < 2; ++n) { const int c = 8 * fq + 4 * n; const f32x4 bv = *(const f32x4*)(b_f + c); const f32x4 x = acc[ai][0][m][n] * s + bv; f32x4 lf;
;                             lf[0] = log_sigmoid_f(x[0]); lf[1] = log_sigmoid_f(x[1]); lf[2] = log_sigmoid_f(x[2]); lf[3] = log_sigmoid_f(x[3]);
	v_pk_fma_f32 v[208:209], v[206:207], s[64:65], v[210:211] op_sel_hi:[1,0,1] neg_lo:[0,0,1] neg_hi:[0,0,1]
	v_pk_add_f32 v[216:217], v[214:215], v[202:203] neg_lo:[0,1] neg_hi:[0,1]
	v_mov_b32_e32 v141, v213
	v_pk_fma_f32 v[206:207], v[206:207], s[66:67], v[208:209] op_sel_hi:[1,0,1]
	v_pk_add_f32 v[214:215], v[140:141], v[216:217]
	v_mov_b32_e32 v202, v210
	v_mov_b32_e32 v203, v217
	v_mov_b32_e32 v212, v206
	v_mov_b32_e32 v141, v215
	v_mov_b32_e32 v217, v205
	v_pk_add_f32 v[208:209], v[210:211], v[206:207]
	v_pk_add_f32 v[202:203], v[202:203], v[212:213]
	v_pk_add_f32 v[212:213], v[140:141], v[216:217]
	v_pk_add_f32 v[216:217], v[204:205], v[214:215]
	v_mov_b32_e32 v224, v204
	v_pk_add_f32 v[140:141], v[208:209], v[216:217]
	v_mov_b32_e32 v222, v216
	v_mov_b32_e32 v223, v141
	v_mov_b32_e32 v225, v209
	v_pk_add_f32 v[222:223], v[222:223], v[224:225] neg_lo:[0,1] neg_hi:[0,1]
	v_mov_b32_e32 v218, v140
	v_mov_b32_e32 v219, v209
	v_mov_b32_e32 v220, v208
	v_mov_b32_e32 v221, v211
	v_mov_b32_e32 v224, v208
	v_mov_b32_e32 v225, v141
	v_mov_b32_e32 v211, v223
	v_pk_add_f32 v[218:219], v[218:219], v[220:221] neg_lo:[0,1] neg_hi:[0,1]
	v_mov_b32_e32 v220, v216
	v_mov_b32_e32 v221, v207
	v_pk_add_f32 v[210:211], v[224:225], v[210:211] neg_lo:[0,1] neg_hi:[0,1]
	v_pk_add_f32 v[220:221], v[220:221], v[218:219] neg_lo:[0,1] neg_hi:[0,1]
	v_mov_b32_e32 v224, v210
	v_mov_b32_e32 v225, v219
	v_mov_b32_e32 v226, v140
	v_mov_b32_e32 v227, v217
	v_mov_b32_e32 v219, v205
	v_pk_add_f32 v[224:225], v[206:207], v[224:225] neg_lo:[0,1] neg_hi:[0,1]
	v_pk_add_f32 v[218:219], v[226:227], v[218:219] neg_lo:[0,1] neg_hi:[0,1]
	v_mov_b32_e32 v207, v209
	v_pk_add_f32 v[202:203], v[202:203], v[218:219] neg_lo:[0,1] neg_hi:[0,1]
	v_pk_add_f32 v[206:207], v[206:207], v[210:211] neg_lo:[0,1] neg_hi:[0,1]
	v_pk_add_f32 v[208:209], v[212:213], v[222:223] neg_lo:[0,1] neg_hi:[0,1]
	v_pk_add_f32 v[212:213], v[220:221], v[202:203]
	v_pk_add_f32 v[210:211], v[208:209], v[206:207]
	v_mov_b32_e32 v207, v221
	v_mov_b32_e32 v209, v203
	v_pk_add_f32 v[202:203], v[206:207], v[208:209]
	v_pk_add_f32 v[204:205], v[216:217], v[204:205] neg_lo:[0,1] neg_hi:[0,1]
	v_pk_add_f32 v[202:203], v[202:203], v[224:225] neg_lo:[0,1] neg_hi:[0,1]
	v_mov_b32_e32 v208, v210
	v_mov_b32_e32 v209, v213
	v_pk_add_f32 v[204:205], v[214:215], v[204:205] neg_lo:[0,1] neg_hi:[0,1]
	v_pk_add_f32 v[208:209], v[208:209], v[202:203] neg_lo:[0,1] neg_hi:[0,1]
	v_pk_add_f32 v[202:203], v[204:205], v[202:203] neg_lo:[0,1] neg_hi:[0,1]
	v_pk_add_f32 v[206:207], v[206:207], v[208:209] neg_lo:[0,1] neg_hi:[0,1]
	v_pk_add_f32 v[204:205], v[212:213], v[210:211]
	v_pk_add_f32 v[202:203], v[202:203], v[206:207]
	v_pk_add_f32 v[206:207], v[140:141], v[204:205]
	s_nop 0
	v_pk_add_f32 v[140:141], v[206:207], v[140:141] neg_lo:[0,1] neg_hi:[0,1]
	s_nop 0
	v_pk_add_f32 v[140:141], v[204:205], v[140:141] neg_lo:[0,1] neg_hi:[0,1]
	s_nop 0
	v_pk_add_f32 v[140:141], v[202:203], v[140:141]
	s_nop 0
	v_pk_add_f32 v[140:141], v[206:207], v[140:141]
	s_nop 0
	v_cndmask_b32_e64 v140, v231, v140, s[10:11]
	v_cmp_neq_f32_e64 s[10:11], s4, v179
	s_nop 1
	v_cndmask_b32_e64 v141, v231, v141, s[10:11]
	v_cmp_ngt_f32_e64 s[10:11], -1.0, v179
	s_nop 1
	v_cndmask_b32_e64 v141, v232, v141, s[10:11]
	v_cmp_ngt_f32_e64 s[10:11], -1.0, v173
	s_nop 1
	v_cndmask_b32_e64 v140, v232, v140, s[10:11]
	v_cmp_neq_f32_e64 s[10:11], -1.0, v173
	s_nop 1
	v_cndmask_b32_e64 v140, v233, v140, s[10:11]
	v_cmp_neq_f32_e64 s[10:11], -1.0, v179
	s_nop 1
	v_cndmask_b32_e64 v141, v233, v141, s[10:11]
	v_cmp_lt_f32_e64 s[10:11], |v173|, s5
	v_cndmask_b32_e64 v141, v141, v179, s[12:13]
	s_nop 0
	v_cndmask_b32_e64 v140, v140, v173, s[10:11]
	v_pk_add_f32 v[130:131], v[130:131], v[140:141] neg_lo:[0,1] neg_hi:[0,1]
	v_min_f32_e32 v140, 0, v132
	v_mul_f32_e64 v132, |v132|, s34
	v_exp_f32_e32 v173, v132
	s_nop 0
	v_add_f32_e32 v132, 1.0, v173
	v_add_f32_e32 v141, -1.0, v132
	v_sub_f32_e32 v179, v141, v132
	v_add_f32_e32 v179, 1.0, v179
	v_sub_f32_e32 v141, v173, v141
	v_add_f32_e32 v141, v141, v179
	v_frexp_mant_f32_e32 v179, v132
	v_cvt_f64_f32_e32 v[202:203], v132
	v_cmp_gt_f32_e64 s[10:11], s35, v179
	v_frexp_exp_i32_f64_e32 v179, v[202:203]
	s_nop 0
	v_subbrev_co_u32_e64 v179, s[10:11], 0, v179, s[10:11]
	v_sub_u32_e32 v183, 0, v179
	v_ldexp_f32 v202, v141, v183
	v_min_f32_e32 v141, 0, v133
	v_mul_f32_e64 v133, |v133|, s34
	v_ldexp_f32 v132, v132, v183
	v_exp_f32_e32 v183, v133
	s_nop 0
	v_add_f32_e32 v133, 1.0, v183
	v_add_f32_e32 v187, -1.0, v133
	v_sub_f32_e32 v191, v187, v133
	v_add_f32_e32 v191, 1.0, v191
	v_sub_f32_e32 v187, v183, v187
	v_add_f32_e32 v187, v187, v191
	v_frexp_mant_f32_e32 v191, v133
	v_cvt_f64_f32_e32 v[204:205], v133
	v_cmp_gt_f32_e64 s[10:11], s35, v191
	v_frexp_exp_i32_f64_e32 v191, v[204:205]
	v_cmp_lt_f32_e64 s[12:13], |v183|, s5
	v_subbrev_co_u32_e64 v191, s[10:11], 0, v191, s[10:11]
	v_sub_u32_e32 v195, 0, v191
	v_ldexp_f32 v133, v133, v195
	v_pk_add_f32 v[204:205], v[132:133], 1.0 op_sel_hi:[1,0]
	v_ldexp_f32 v203, v187, v195
	v_pk_add_f32 v[206:207], v[204:205], -1.0 op_sel_hi:[1,0]
	v_pk_add_f32 v[212:213], v[132:133], -1.0 op_sel_hi:[1,0]
	v_pk_add_f32 v[206:207], v[132:133], v[206:207] neg_lo:[0,1] neg_hi:[0,1]
	v_pk_add_f32 v[214:215], v[212:213], 1.0 op_sel_hi:[1,0]
	v_pk_add_f32 v[206:207], v[202:203], v[206:207]
	v_pk_add_f32 v[132:133], v[132:133], v[214:215] neg_lo:[0,1] neg_hi:[0,1]
	v_pk_add_f32 v[208:209], v[204:205], v[206:207]
	v_pk_add_f32 v[132:133], v[202:203], v[132:133]
	v_rcp_f32_e32 v210, v208
	v_rcp_f32_e32 v211, v209
	v_pk_add_f32 v[202:203], v[212:213], v[132:133]
	v_pk_add_f32 v[204:205], v[208:209], v[204:205] neg_lo:[0,1] neg_hi:[0,1]
; __device__ __forceinline__ float log_sigmoid_f(float x) { return fminf(x, 0.f) - log1pf(__expf(-fabsf(x))); }
	v_pk_add_f32 v[212:213], v[202:203], v[212:213] neg_lo:[0,1] neg_hi:[0,1]
	v_pk_add_f32 v[204:205], v[206:207], v[204:205] neg_lo:[0,1] neg_hi:[0,1]
	v_pk_mul_f32 v[206:207], v[202:203], v[210:211]
	v_pk_add_f32 v[132:133], v[132:133], v[212:213] neg_lo:[0,1] neg_hi:[0,1]
	v_pk_mul_f32 v[212:213], v[208:209], v[206:207]
	v_cmp_neq_f32_e64 s[10:11], s4, v173
	v_pk_fma_f32 v[214:215], v[206:207], v[208:209], v[212:213] neg_lo:[0,0,1] neg_hi:[0,0,1]
	s_nop 0
	v_pk_fma_f32 v[214:215], v[206:207], v[204:205], v[214:215]
	s_nop 0
	v_pk_add_f32 v[216:217], v[212:213], v[214:215]
	s_nop 0
	v_pk_add_f32 v[218:219], v[202:203], v[216:217] neg_lo:[0,1] neg_hi:[0,1]
	v_pk_add_f32 v[212:213], v[216:217], v[212:213] neg_lo:[0,1] neg_hi:[0,1]
	v_pk_add_f32 v[202:203], v[202:203], v[218:219] neg_lo:[0,1] neg_hi:[0,1]
	s_nop 0
	v_pk_add_f32 v[202:203], v[202:203], v[216:217] neg_lo:[0,1] neg_hi:[0,1]
	s_nop 0
	v_pk_add_f32 v[132:133], v[132:133], v[202:203]
	v_pk_add_f32 v[202:203], v[212:213], v[214:215] neg_lo:[0,1] neg_hi:[0,1]
	s_nop 0
	v_pk_add_f32 v[132:133], v[202:203], v[132:133]
	s_nop 0
	v_pk_add_f32 v[202:203], v[218:219], v[132:133]
	s_nop 0
	v_pk_mul_f32 v[212:213], v[210:211], v[202:203]
	s_nop 0
	v_pk_mul_f32 v[214:215], v[208:209], v[212:213]
	s_nop 0
	v_pk_fma_f32 v[208:209], v[212:213], v[208:209], v[214:215] neg_lo:[0,0,1] neg_hi:[0,0,1]
	s_nop 0
	v_pk_fma_f32 v[204:205], v[212:213], v[204:205], v[208:209]
	v_pk_add_f32 v[208:209], v[218:219], v[202:203] neg_lo:[0,1] neg_hi:[0,1]
	s_nop 0
	v_pk_add_f32 v[132:133], v[132:133], v[208:209]
	v_pk_add_f32 v[208:209], v[214:215], v[204:205]
	s_nop 0
	v_pk_add_f32 v[216:217], v[202:203], v[208:209] neg_lo:[0,1] neg_hi:[0,1]
	v_pk_add_f32 v[214:215], v[208:209], v[214:215] neg_lo:[0,1] neg_hi:[0,1]
	v_pk_add_f32 v[202:203], v[202:203], v[216:217] neg_lo:[0,1] neg_hi:[0,1]
	s_nop 0
	v_pk_add_f32 v[202:203], v[202:203], v[208:209] neg_lo:[0,1] neg_hi:[0,1]
	s_nop 0
	v_pk_add_f32 v[132:133], v[132:133], v[202:203]
	v_pk_add_f32 v[202:203], v[214:215], v[204:205] neg_lo:[0,1] neg_hi:[0,1]
	s_nop 0
	v_pk_add_f32 v[132:133], v[202:203], v[132:133]
	v_pk_add_f32 v[202:203], v[206:207], v[212:213]
	v_pk_add_f32 v[132:133], v[216:217], v[132:133]
	v_pk_add_f32 v[204:205], v[202:203], v[206:207] neg_lo:[0,1] neg_hi:[0,1]
	v_pk_mul_f32 v[132:133], v[210:211], v[132:133]
	v_pk_add_f32 v[204:205], v[212:213], v[204:205] neg_lo:[0,1] neg_hi:[0,1]
	s_nop 0
	v_pk_add_f32 v[132:133], v[204:205], v[132:133]
	s_nop 0
	v_pk_add_f32 v[204:205], v[202:203], v[132:133]
	s_nop 0
	v_pk_mul_f32 v[206:207], v[204:205], v[204:205]
	v_pk_add_f32 v[202:203], v[204:205], v[202:203] neg_lo:[0,1] neg_hi:[0,1]
	v_pk_fma_f32 v[138:139], v[206:207], s[52:53], v[138:139] op_sel_hi:[1,0,0]
	v_pk_add_f32 v[132:133], v[132:133], v[202:203] neg_lo:[0,1] neg_hi:[0,1]
	v_ldexp_f32 v202, v204, 1
	v_pk_fma_f32 v[138:139], v[206:207], v[138:139], s[54:55] op_sel_hi:[1,1,0]
	v_ldexp_f32 v203, v205, 1
	v_pk_mul_f32 v[204:205], v[204:205], v[206:207]
	v_cvt_f32_i32_e32 v207, v191
	v_cvt_f32_i32_e32 v206, v179
	v_pk_mul_f32 v[138:139], v[204:205], v[138:139]
	v_ldexp_f32 v209, v133, 1
	v_pk_add_f32 v[204:205], v[202:203], v[138:139]
	v_pk_mul_f32 v[210:211], v[206:207], s[64:65] op_sel_hi:[1,0]
	v_pk_add_f32 v[202:203], v[204:205], v[202:203] neg_lo:[0,1] neg_hi:[0,1]
	v_pk_fma_f32 v[212:213], v[206:207], s[64:65], v[210:211] op_sel_hi:[1,0,1] neg_lo:[0,0,1] neg_hi:[0,0,1]
	v_pk_add_f32 v[138:139], v[138:139], v[202:203] neg_lo:[0,1] neg_hi:[0,1]
	v_pk_fma_f32 v[206:207], v[206:207], s[66:67], v[212:213] op_sel_hi:[1,0,1]
	v_ldexp_f32 v132, v132, 1
	v_mov_b32_e32 v202, v210
	v_mov_b32_e32 v203, v139
	v_mov_b32_e32 v208, v206
	v_mov_b32_e32 v133, v209
	v_pk_add_f32 v[202:203], v[202:203], v[208:209]
	v_pk_add_f32 v[208:209], v[132:133], v[138:139]
	v_mov_b32_e32 v139, v205
	v_mov_b32_e32 v133, v209
	v_pk_add_f32 v[212:213], v[210:211], v[206:207]
	v_pk_add_f32 v[132:133], v[132:133], v[138:139]
	v_pk_add_f32 v[138:139], v[204:205], v[208:209]
	v_mov_b32_e32 v222, v204
	v_pk_add_f32 v[214:215], v[212:213], v[138:139]
	v_mov_b32_e32 v220, v138
	v_mov_b32_e32 v221, v215
	v_mov_b32_e32 v223, v213
	v_pk_add_f32 v[220:221], v[220:221], v[222:223] neg_lo:[0,1] neg_hi:[0,1]
	v_mov_b32_e32 v216, v214
	v_mov_b32_e32 v217, v213
	v_mov_b32_e32 v218, v212
	v_mov_b32_e32 v219, v211
	v_mov_b32_e32 v222, v212
	v_mov_b32_e32 v223, v215
	v_mov_b32_e32 v211, v221
	v_pk_add_f32 v[216:217], v[216:217], v[218:219] neg_lo:[0,1] neg_hi:[0,1]
	v_mov_b32_e32 v218, v138
	v_mov_b32_e32 v219, v207
	v_pk_add_f32 v[210:211], v[222:223], v[210:211] neg_lo:[0,1] neg_hi:[0,1]
	v_pk_add_f32 v[218:219], v[218:219], v[216:217] neg_lo:[0,1] neg_hi:[0,1]
	v_mov_b32_e32 v222, v210
	v_mov_b32_e32 v223, v217
	v_mov_b32_e32 v224, v214
	v_mov_b32_e32 v225, v139
	v_mov_b32_e32 v217, v205
	v_pk_add_f32 v[222:223], v[206:207], v[222:223] neg_lo:[0,1] neg_hi:[0,1]
	v_pk_add_f32 v[216:217], v[224:225], v[216:217] neg_lo:[0,1] neg_hi:[0,1]
	v_mov_b32_e32 v207, v213
	v_pk_add_f32 v[138:139], v[138:139], v[204:205] neg_lo:[0,1] neg_hi:[0,1]
	v_pk_add_f32 v[202:203], v[202:203], v[216:217] neg_lo:[0,1] neg_hi:[0,1]
	v_pk_add_f32 v[204:205], v[206:207], v[210:211] neg_lo:[0,1] neg_hi:[0,1]
	v_pk_add_f32 v[132:133], v[132:133], v[220:221] neg_lo:[0,1] neg_hi:[0,1]
	v_pk_add_f32 v[138:139], v[208:209], v[138:139] neg_lo:[0,1] neg_hi:[0,1]
	v_pk_add_f32 v[206:207], v[132:133], v[204:205]
	v_mov_b32_e32 v205, v219
	v_mov_b32_e32 v133, v203
	v_pk_add_f32 v[208:209], v[218:219], v[202:203]
	v_pk_add_f32 v[132:133], v[204:205], v[132:133]
	v_mov_b32_e32 v202, v206
; __device__ __forceinline__ float log_sigmoid_f(float x) { return fminf(x, 0.f) - log1pf(__expf(-fabsf(x))); }
;     __device__ __forceinline__ void operator()(const f32x4 (&acc)[2][2][4][2], const Unit& u, int wr, int wc, int fr, int fq) const {
;     ...
;                     for (int m = 0; m < 4; ++m) { const int row = row0 + ai * HALF + m * 16; const float s = sc8[ai][m];
;                         float* dst = nullptr;
;                         if (pm == 0) dst = o_lfs + (size_t)row * 16; else { const int t = row - G_ROWP; if (t < G_TP) dst = o_lfp + (size_t)t * 16; }
; #pragma unroll
;                         for (int n = 0; n < 2; ++n) { const int c = 8 * fq + 4 * n; const f32x4 bv = *(const f32x4*)(b_f + c); const f32x4 x = acc[ai][0][m][n] * s + bv; f32x4 lf;
;                             lf[0] = log_sigmoid_f(x[0]); lf[1] = log_sigmoid_f(x[1]); lf[2] = log_sigmoid_f(x[2]); lf[3] = log_sigmoid_f(x[3]);
;                             *(f32x4*)(LF + (size_t)row * 16 + c) = lf; if (dst) *(f32x4*)(dst + c) = lf; } }
	v_pk_add_f32 v[132:133], v[132:133], v[222:223] neg_lo:[0,1] neg_hi:[0,1]
	v_mov_b32_e32 v203, v209
	v_pk_add_f32 v[202:203], v[202:203], v[132:133] neg_lo:[0,1] neg_hi:[0,1]
	v_pk_add_f32 v[132:133], v[138:139], v[132:133] neg_lo:[0,1] neg_hi:[0,1]
	v_pk_add_f32 v[202:203], v[204:205], v[202:203] neg_lo:[0,1] neg_hi:[0,1]
	v_pk_add_f32 v[138:139], v[208:209], v[206:207]
	v_pk_add_f32 v[132:133], v[132:133], v[202:203]
	v_pk_add_f32 v[202:203], v[214:215], v[138:139]
	s_nop 0
	v_pk_add_f32 v[204:205], v[202:203], v[214:215] neg_lo:[0,1] neg_hi:[0,1]
	s_nop 0
	v_pk_add_f32 v[138:139], v[138:139], v[204:205] neg_lo:[0,1] neg_hi:[0,1]
	s_nop 0
	v_pk_add_f32 v[132:133], v[132:133], v[138:139]
	s_nop 0
	v_pk_add_f32 v[132:133], v[202:203], v[132:133]
	s_nop 0
	v_cndmask_b32_e64 v132, v231, v132, s[10:11]
	v_cmp_neq_f32_e64 s[10:11], s4, v183
	s_nop 1
	v_cndmask_b32_e64 v133, v231, v133, s[10:11]
	v_cmp_ngt_f32_e64 s[10:11], -1.0, v183
	s_nop 1
	v_cndmask_b32_e64 v133, v232, v133, s[10:11]
	v_cmp_ngt_f32_e64 s[10:11], -1.0, v173
	s_nop 1
	v_cndmask_b32_e64 v132, v232, v132, s[10:11]
	v_cmp_neq_f32_e64 s[10:11], -1.0, v173
	s_nop 1
	v_cndmask_b32_e64 v132, v233, v132, s[10:11]
	v_cmp_neq_f32_e64 s[10:11], -1.0, v183
	s_nop 1
	v_cndmask_b32_e64 v133, v233, v133, s[10:11]
	v_cmp_lt_f32_e64 s[10:11], |v173|, s5
	v_cndmask_b32_e64 v133, v133, v183, s[12:13]
	s_nop 0
	v_cndmask_b32_e64 v132, v132, v173, s[10:11]
	v_pk_add_f32 v[132:133], v[140:141], v[132:133] neg_lo:[0,1] neg_hi:[0,1]
	global_store_dwordx4 v[136:137], v[130:133], off nt
	s_and_saveexec_b64 s[10:11], vcc
	s_cbranch_execz .LBB0_426
	v_lshl_add_u64 v[138:139], v[134:135], 0, v[150:151]
	global_store_dwordx4 v[138:139], v[130:133], off nt
.LBB0_426:
	s_or_b64 exec, exec, s[10:11]
	global_load_dwordx4 v[130:133], v[158:159], off offset:16
	v_mov_b32_e32 v173, v172
	v_mov_b32_e32 v138, v172
	v_mov_b32_e32 v139, v172
	s_waitcnt vmcnt(0)
	v_pk_fma_f32 v[132:133], v[12:13], v[138:139], v[132:133]
	v_pk_fma_f32 v[138:139], v[10:11], v[172:173], v[130:131]
	s_nop 0
	v_mul_f32_e64 v131, |v138|, s34
	v_exp_f32_e32 v173, v131
	v_min_f32_e32 v130, 0, v138
	v_add_f32_e32 v131, 1.0, v173
	v_add_f32_e32 v138, -1.0, v131
	v_sub_f32_e32 v140, v138, v131
	v_add_f32_e32 v140, 1.0, v140
	v_sub_f32_e32 v138, v173, v138
	v_add_f32_e32 v179, v138, v140
	v_frexp_mant_f32_e32 v138, v131
	v_cvt_f64_f32_e32 v[140:141], v131
	v_cmp_gt_f32_e64 s[10:11], s35, v138
	v_frexp_exp_i32_f64_e32 v138, v[140:141]
	s_nop 0
	v_subbrev_co_u32_e64 v183, s[10:11], 0, v138, s[10:11]
	v_sub_u32_e32 v140, 0, v183
	v_ldexp_f32 v138, v131, v140
	v_min_f32_e32 v131, 0, v139
	v_mul_f32_e64 v139, |v139|, s34
	v_ldexp_f32 v140, v179, v140
	v_exp_f32_e32 v179, v139
	s_nop 0
	v_add_f32_e32 v139, 1.0, v179
	v_add_f32_e32 v141, -1.0, v139
	v_sub_f32_e32 v187, v141, v139
	v_add_f32_e32 v187, 1.0, v187
	v_sub_f32_e32 v141, v179, v141
	v_add_f32_e32 v141, v141, v187
	v_frexp_mant_f32_e32 v187, v139
	v_cvt_f64_f32_e32 v[202:203], v139
	v_cmp_gt_f32_e64 s[10:11], s35, v187
	v_frexp_exp_i32_f64_e32 v187, v[202:203]
	v_cmp_lt_f32_e64 s[12:13], |v179|, s5
	v_subbrev_co_u32_e64 v187, s[10:11], 0, v187, s[10:11]
	v_sub_u32_e32 v191, 0, v187
	v_ldexp_f32 v139, v139, v191
	v_pk_add_f32 v[202:203], v[138:139], 1.0 op_sel_hi:[1,0]
	v_ldexp_f32 v141, v141, v191
	v_pk_add_f32 v[204:205], v[202:203], -1.0 op_sel_hi:[1,0]
	v_pk_add_f32 v[210:211], v[138:139], -1.0 op_sel_hi:[1,0]
	v_pk_add_f32 v[204:205], v[138:139], v[204:205] neg_lo:[0,1] neg_hi:[0,1]
	v_pk_add_f32 v[212:213], v[210:211], 1.0 op_sel_hi:[1,0]
	v_pk_add_f32 v[204:205], v[140:141], v[204:205]
	v_pk_add_f32 v[138:139], v[138:139], v[212:213] neg_lo:[0,1] neg_hi:[0,1]
	v_pk_add_f32 v[206:207], v[202:203], v[204:205]
	v_pk_add_f32 v[138:139], v[140:141], v[138:139]
	v_rcp_f32_e32 v208, v206
	v_rcp_f32_e32 v209, v207
	v_pk_add_f32 v[140:141], v[210:211], v[138:139]
	v_pk_add_f32 v[202:203], v[206:207], v[202:203] neg_lo:[0,1] neg_hi:[0,1]
	v_pk_add_f32 v[210:211], v[140:141], v[210:211] neg_lo:[0,1] neg_hi:[0,1]
	v_pk_add_f32 v[202:203], v[204:205], v[202:203] neg_lo:[0,1] neg_hi:[0,1]
	v_pk_mul_f32 v[204:205], v[140:141], v[208:209]
	v_pk_add_f32 v[138:139], v[138:139], v[210:211] neg_lo:[0,1] neg_hi:[0,1]
	v_pk_mul_f32 v[210:211], v[206:207], v[204:205]
	v_cmp_neq_f32_e64 s[10:11], s4, v173
	v_pk_fma_f32 v[212:213], v[204:205], v[206:207], v[210:211] neg_lo:[0,0,1] neg_hi:[0,0,1]
	s_nop 0
	v_pk_fma_f32 v[212:213], v[204:205], v[202:203], v[212:213]
	s_nop 0
	v_pk_add_f32 v[214:215], v[210:211], v[212:213]
	s_nop 0
	v_pk_add_f32 v[216:217], v[140:141], v[214:215] neg_lo:[0,1] neg_hi:[0,1]
	v_pk_add_f32 v[210:211], v[214:215], v[210:211] neg_lo:[0,1] neg_hi:[0,1]
	v_pk_add_f32 v[140:141], v[140:141], v[216:217] neg_lo:[0,1] neg_hi:[0,1]
	s_nop 0
	v_pk_add_f32 v[140:141], v[140:141], v[214:215] neg_lo:[0,1] neg_hi:[0,1]
	s_nop 0
	v_pk_add_f32 v[138:139], v[138:139], v[140:141]
	v_pk_add_f32 v[140:141], v[210:211], v[212:213] neg_lo:[0,1] neg_hi:[0,1]
	s_nop 0
	v_pk_add_f32 v[138:139], v[140:141], v[138:139]
	s_nop 0
	v_pk_add_f32 v[140:141], v[216:217], v[138:139]
	s_nop 0
	v_pk_mul_f32 v[210:211], v[208:209], v[140:141]
	s_nop 0
	v_pk_mul_f32 v[212:213], v[206:207], v[210:211]
	s_nop 0
	v_pk_fma_f32 v[206:207], v[210:211], v[206:207], v[212:213] neg_lo:[0,0,1] neg_hi:[0,0,1]
	s_nop 0
	v_pk_fma_f32 v[202:203], v[210:211], v[202:203], v[206:207]
	v_pk_add_f32 v[206:207], v[216:217], v[140:141] neg_lo:[0,1] neg_hi:[0,1]
	s_nop 0
	v_pk_add_f32 v[138:139], v[138:139], v[206:207]
	v_pk_add_f32 v[206:207], v[212:213], v[202:203]
	s_nop 0
	v_pk_add_f32 v[214:215], v[140:141], v[206:207] neg_lo:[0,1] neg_hi:[0,1]
; __device__ __forceinline__ float log_sigmoid_f(float x) { return fminf(x, 0.f) - log1pf(__expf(-fabsf(x))); }
;     __device__ __forceinline__ void operator()(const f32x4 (&acc)[2][2][4][2], const Unit& u, int wr, int wc, int fr, int fq) const {
;     ...
;                         for (int n = 0; n < 2; ++n) { const int c = 8 * fq + 4 * n; const f32x4 bv = *(const f32x4*)(b_f + c); const f32x4 x = acc[ai][0][m][n] * s + bv; f32x4 lf;
;                             lf[0] = log_sigmoid_f(x[0]); lf[1] = log_sigmoid_f(x[1]); lf[2] = log_sigmoid_f(x[2]); lf[3] = log_sigmoid_f(x[3]);
	v_pk_add_f32 v[212:213], v[206:207], v[212:213] neg_lo:[0,1] neg_hi:[0,1]
	v_pk_add_f32 v[140:141], v[140:141], v[214:215] neg_lo:[0,1] neg_hi:[0,1]
	s_nop 0
	v_pk_add_f32 v[140:141], v[140:141], v[206:207] neg_lo:[0,1] neg_hi:[0,1]
	s_nop 0
	v_pk_add_f32 v[138:139], v[138:139], v[140:141]
	v_pk_add_f32 v[140:141], v[212:213], v[202:203] neg_lo:[0,1] neg_hi:[0,1]
	s_nop 0
	v_pk_add_f32 v[138:139], v[140:141], v[138:139]
	v_pk_add_f32 v[140:141], v[204:205], v[210:211]
	v_pk_add_f32 v[138:139], v[214:215], v[138:139]
	v_pk_add_f32 v[202:203], v[140:141], v[204:205] neg_lo:[0,1] neg_hi:[0,1]
	v_pk_mul_f32 v[138:139], v[208:209], v[138:139]
	v_pk_add_f32 v[202:203], v[210:211], v[202:203] neg_lo:[0,1] neg_hi:[0,1]
	v_cvt_f32_i32_e32 v211, v187
	v_pk_add_f32 v[138:139], v[202:203], v[138:139]
	v_cvt_f32_i32_e32 v210, v183
	v_pk_add_f32 v[204:205], v[140:141], v[138:139]
	s_nop 0
	v_pk_add_f32 v[140:141], v[204:205], v[140:141] neg_lo:[0,1] neg_hi:[0,1]
	v_pk_mul_f32 v[206:207], v[204:205], v[204:205]
	v_pk_add_f32 v[140:141], v[138:139], v[140:141] neg_lo:[0,1] neg_hi:[0,1]
	v_mov_b64_e32 v[138:139], s[50:51]
	v_pk_fma_f32 v[208:209], v[206:207], s[52:53], v[138:139] op_sel_hi:[1,0,0]
	v_ldexp_f32 v202, v204, 1
	v_pk_fma_f32 v[208:209], v[206:207], v[208:209], s[54:55] op_sel_hi:[1,1,0]
	v_ldexp_f32 v203, v205, 1
	v_pk_mul_f32 v[204:205], v[204:205], v[206:207]
	v_ldexp_f32 v213, v141, 1
	v_pk_mul_f32 v[214:215], v[204:205], v[208:209]
	v_pk_mul_f32 v[206:207], v[210:211], s[64:65] op_sel_hi:[1,0]
	v_pk_add_f32 v[204:205], v[202:203], v[214:215]
	v_ldexp_f32 v140, v140, 1
	v_pk_add_f32 v[202:203], v[204:205], v[202:203] neg_lo:[0,1] neg_hi:[0,1]
	v_pk_fma_f32 v[208:209], v[210:211], s[64:65], v[206:207] op_sel_hi:[1,0,1] neg_lo:[0,0,1] neg_hi:[0,0,1]
	v_pk_add_f32 v[216:217], v[214:215], v[202:203] neg_lo:[0,1] neg_hi:[0,1]
	v_mov_b32_e32 v141, v213
	v_pk_fma_f32 v[208:209], v[210:211], s[66:67], v[208:209] op_sel_hi:[1,0,1]
	v_pk_add_f32 v[214:215], v[140:141], v[216:217]
	v_mov_b32_e32 v202, v206
	v_mov_b32_e32 v203, v217
	v_mov_b32_e32 v212, v208
	v_mov_b32_e32 v141, v215
	v_mov_b32_e32 v217, v205
	v_pk_add_f32 v[210:211], v[206:207], v[208:209]
	v_pk_add_f32 v[202:203], v[202:203], v[212:213]
	v_pk_add_f32 v[212:213], v[140:141], v[216:217]
	v_pk_add_f32 v[216:217], v[204:205], v[214:215]
	v_mov_b32_e32 v224, v204
	v_pk_add_f32 v[140:141], v[210:211], v[216:217]
	v_mov_b32_e32 v222, v216
	v_mov_b32_e32 v223, v141
	v_mov_b32_e32 v225, v211
	v_pk_add_f32 v[222:223], v[222:223], v[224:225] neg_lo:[0,1] neg_hi:[0,1]
	v_mov_b32_e32 v218, v140
	v_mov_b32_e32 v219, v211
	v_mov_b32_e32 v220, v210
	v_mov_b32_e32 v221, v207
	v_mov_b32_e32 v224, v210
	v_mov_b32_e32 v225, v141
	v_mov_b32_e32 v207, v223
	v_pk_add_f32 v[218:219], v[218:219], v[220:221] neg_lo:[0,1] neg_hi:[0,1]
	v_mov_b32_e32 v220, v216
	v_mov_b32_e32 v221, v209
	v_pk_add_f32 v[206:207], v[224:225], v[206:207] neg_lo:[0,1] neg_hi:[0,1]
	v_pk_add_f32 v[220:221], v[220:221], v[218:219] neg_lo:[0,1] neg_hi:[0,1]
	v_mov_b32_e32 v224, v206
	v_mov_b32_e32 v225, v219
	v_mov_b32_e32 v226, v140
	v_mov_b32_e32 v227, v217
	v_mov_b32_e32 v219, v205
	v_pk_add_f32 v[224:225], v[208:209], v[224:225] neg_lo:[0,1] neg_hi:[0,1]
	v_pk_add_f32 v[218:219], v[226:227], v[218:219] neg_lo:[0,1] neg_hi:[0,1]
	v_mov_b32_e32 v209, v211
	v_pk_add_f32 v[202:203], v[202:203], v[218:219] neg_lo:[0,1] neg_hi:[0,1]
	v_pk_add_f32 v[206:207], v[208:209], v[206:207] neg_lo:[0,1] neg_hi:[0,1]
	v_pk_add_f32 v[208:209], v[212:213], v[222:223] neg_lo:[0,1] neg_hi:[0,1]
	v_pk_add_f32 v[212:213], v[220:221], v[202:203]
	v_pk_add_f32 v[210:211], v[208:209], v[206:207]
	v_mov_b32_e32 v207, v221
	v_mov_b32_e32 v209, v203
	v_pk_add_f32 v[202:203], v[206:207], v[208:209]
	v_pk_add_f32 v[204:205], v[216:217], v[204:205] neg_lo:[0,1] neg_hi:[0,1]
	v_pk_add_f32 v[202:203], v[202:203], v[224:225] neg_lo:[0,1] neg_hi:[0,1]
	v_mov_b32_e32 v208, v210
	v_mov_b32_e32 v209, v213
	v_pk_add_f32 v[204:205], v[214:215], v[204:205] neg_lo:[0,1] neg_hi:[0,1]
	v_pk_add_f32 v[208:209], v[208:209], v[202:203] neg_lo:[0,1] neg_hi:[0,1]
	v_pk_add_f32 v[202:203], v[204:205], v[202:203] neg_lo:[0,1] neg_hi:[0,1]
	v_pk_add_f32 v[206:207], v[206:207], v[208:209] neg_lo:[0,1] neg_hi:[0,1]
	v_pk_add_f32 v[204:205], v[212:213], v[210:211]
	v_pk_add_f32 v[202:203], v[202:203], v[206:207]
	v_pk_add_f32 v[206:207], v[140:141], v[204:205]
	s_nop 0
	v_pk_add_f32 v[140:141], v[206:207], v[140:141] neg_lo:[0,1] neg_hi:[0,1]
	s_nop 0
	v_pk_add_f32 v[140:141], v[204:205], v[140:141] neg_lo:[0,1] neg_hi:[0,1]
	s_nop 0
	v_pk_add_f32 v[140:141], v[202:203], v[140:141]
	s_nop 0
	v_pk_add_f32 v[140:141], v[206:207], v[140:141]
	s_nop 0
	v_cndmask_b32_e64 v140, v231, v140, s[10:11]
	v_cmp_neq_f32_e64 s[10:11], s4, v179
	s_nop 1
	v_cndmask_b32_e64 v141, v231, v141, s[10:11]
	v_cmp_ngt_f32_e64 s[10:11], -1.0, v179
	s_nop 1
	v_cndmask_b32_e64 v141, v232, v141, s[10:11]
	v_cmp_ngt_f32_e64 s[10:11], -1.0, v173
	s_nop 1
	v_cndmask_b32_e64 v140, v232, v140, s[10:11]
	v_cmp_neq_f32_e64 s[10:11], -1.0, v173
	s_nop 1
	v_cndmask_b32_e64 v140, v233, v140, s[10:11]
	v_cmp_neq_f32_e64 s[10:11], -1.0, v179
	s_nop 1
	v_cndmask_b32_e64 v141, v233, v141, s[10:11]
	v_cmp_lt_f32_e64 s[10:11], |v173|, s5
	v_cndmask_b32_e64 v141, v141, v179, s[12:13]
	s_nop 0
	v_cndmask_b32_e64 v140, v140, v173, s[10:11]
	v_pk_add_f32 v[130:131], v[130:131], v[140:141] neg_lo:[0,1] neg_hi:[0,1]
	v_min_f32_e32 v140, 0, v132
	v_mul_f32_e64 v132, |v132|, s34
	v_exp_f32_e32 v173, v132
	s_nop 0
	v_add_f32_e32 v132, 1.0, v173
	v_add_f32_e32 v141, -1.0, v132
	v_sub_f32_e32 v179, v141, v132
	v_add_f32_e32 v179, 1.0, v179
; __device__ __forceinline__ float log_sigmoid_f(float x) { return fminf(x, 0.f) - log1pf(__expf(-fabsf(x))); }
	v_sub_f32_e32 v141, v173, v141
	v_add_f32_e32 v141, v141, v179
	v_frexp_mant_f32_e32 v179, v132
	v_cvt_f64_f32_e32 v[202:203], v132
	v_cmp_gt_f32_e64 s[10:11], s35, v179
	v_frexp_exp_i32_f64_e32 v179, v[202:203]
	s_nop 0
	v_subbrev_co_u32_e64 v179, s[10:11], 0, v179, s[10:11]
	v_sub_u32_e32 v183, 0, v179
	v_ldexp_f32 v202, v141, v183
	v_min_f32_e32 v141, 0, v133
	v_mul_f32_e64 v133, |v133|, s34
	v_ldexp_f32 v132, v132, v183
	v_exp_f32_e32 v183, v133
	s_nop 0
	v_add_f32_e32 v133, 1.0, v183
	v_add_f32_e32 v187, -1.0, v133
	v_sub_f32_e32 v191, v187, v133
	v_add_f32_e32 v191, 1.0, v191
	v_sub_f32_e32 v187, v183, v187
	v_add_f32_e32 v187, v187, v191
	v_frexp_mant_f32_e32 v191, v133
	v_cvt_f64_f32_e32 v[204:205], v133
	v_cmp_gt_f32_e64 s[10:11], s35, v191
	v_frexp_exp_i32_f64_e32 v191, v[204:205]
	v_cmp_lt_f32_e64 s[12:13], |v183|, s5
	v_subbrev_co_u32_e64 v191, s[10:11], 0, v191, s[10:11]
	v_sub_u32_e32 v195, 0, v191
	v_ldexp_f32 v133, v133, v195
	v_pk_add_f32 v[204:205], v[132:133], 1.0 op_sel_hi:[1,0]
	v_ldexp_f32 v203, v187, v195
	v_pk_add_f32 v[206:207], v[204:205], -1.0 op_sel_hi:[1,0]
	v_pk_add_f32 v[212:213], v[132:133], -1.0 op_sel_hi:[1,0]
	v_pk_add_f32 v[206:207], v[132:133], v[206:207] neg_lo:[0,1] neg_hi:[0,1]
	v_pk_add_f32 v[214:215], v[212:213], 1.0 op_sel_hi:[1,0]
	v_pk_add_f32 v[206:207], v[202:203], v[206:207]
	v_pk_add_f32 v[132:133], v[132:133], v[214:215] neg_lo:[0,1] neg_hi:[0,1]
	v_pk_add_f32 v[208:209], v[204:205], v[206:207]
	v_pk_add_f32 v[132:133], v[202:203], v[132:133]
	v_rcp_f32_e32 v210, v208
	v_rcp_f32_e32 v211, v209
	v_pk_add_f32 v[202:203], v[212:213], v[132:133]
	v_pk_add_f32 v[204:205], v[208:209], v[204:205] neg_lo:[0,1] neg_hi:[0,1]
	v_pk_add_f32 v[212:213], v[202:203], v[212:213] neg_lo:[0,1] neg_hi:[0,1]
	v_pk_add_f32 v[204:205], v[206:207], v[204:205] neg_lo:[0,1] neg_hi:[0,1]
	v_pk_mul_f32 v[206:207], v[202:203], v[210:211]
	v_pk_add_f32 v[132:133], v[132:133], v[212:213] neg_lo:[0,1] neg_hi:[0,1]
	v_pk_mul_f32 v[212:213], v[208:209], v[206:207]
	v_cmp_neq_f32_e64 s[10:11], s4, v173
	v_pk_fma_f32 v[214:215], v[206:207], v[208:209], v[212:213] neg_lo:[0,0,1] neg_hi:[0,0,1]
	s_nop 0
	v_pk_fma_f32 v[214:215], v[206:207], v[204:205], v[214:215]
	s_nop 0
	v_pk_add_f32 v[216:217], v[212:213], v[214:215]
	s_nop 0
	v_pk_add_f32 v[218:219], v[202:203], v[216:217] neg_lo:[0,1] neg_hi:[0,1]
	v_pk_add_f32 v[212:213], v[216:217], v[212:213] neg_lo:[0,1] neg_hi:[0,1]
	v_pk_add_f32 v[202:203], v[202:203], v[218:219] neg_lo:[0,1] neg_hi:[0,1]
	s_nop 0
	v_pk_add_f32 v[202:203], v[202:203], v[216:217] neg_lo:[0,1] neg_hi:[0,1]
	s_nop 0
	v_pk_add_f32 v[132:133], v[132:133], v[202:203]
	v_pk_add_f32 v[202:203], v[212:213], v[214:215] neg_lo:[0,1] neg_hi:[0,1]
	s_nop 0
	v_pk_add_f32 v[132:133], v[202:203], v[132:133]
	s_nop 0
	v_pk_add_f32 v[202:203], v[218:219], v[132:133]
	s_nop 0
	v_pk_mul_f32 v[212:213], v[210:211], v[202:203]
	s_nop 0
	v_pk_mul_f32 v[214:215], v[208:209], v[212:213]
	s_nop 0
	v_pk_fma_f32 v[208:209], v[212:213], v[208:209], v[214:215] neg_lo:[0,0,1] neg_hi:[0,0,1]
	s_nop 0
	v_pk_fma_f32 v[204:205], v[212:213], v[204:205], v[208:209]
	v_pk_add_f32 v[208:209], v[218:219], v[202:203] neg_lo:[0,1] neg_hi:[0,1]
	s_nop 0
	v_pk_add_f32 v[132:133], v[132:133], v[208:209]
	v_pk_add_f32 v[208:209], v[214:215], v[204:205]
	s_nop 0
	v_pk_add_f32 v[216:217], v[202:203], v[208:209] neg_lo:[0,1] neg_hi:[0,1]
	v_pk_add_f32 v[214:215], v[208:209], v[214:215] neg_lo:[0,1] neg_hi:[0,1]
	v_pk_add_f32 v[202:203], v[202:203], v[216:217] neg_lo:[0,1] neg_hi:[0,1]
	s_nop 0
	v_pk_add_f32 v[202:203], v[202:203], v[208:209] neg_lo:[0,1] neg_hi:[0,1]
	s_nop 0
	v_pk_add_f32 v[132:133], v[132:133], v[202:203]
	v_pk_add_f32 v[202:203], v[214:215], v[204:205] neg_lo:[0,1] neg_hi:[0,1]
	s_nop 0
	v_pk_add_f32 v[132:133], v[202:203], v[132:133]
	v_pk_add_f32 v[202:203], v[206:207], v[212:213]
	v_pk_add_f32 v[132:133], v[216:217], v[132:133]
	v_pk_add_f32 v[204:205], v[202:203], v[206:207] neg_lo:[0,1] neg_hi:[0,1]
	v_pk_mul_f32 v[132:133], v[210:211], v[132:133]
	v_pk_add_f32 v[204:205], v[212:213], v[204:205] neg_lo:[0,1] neg_hi:[0,1]
	s_nop 0
	v_pk_add_f32 v[132:133], v[204:205], v[132:133]
	s_nop 0
	v_pk_add_f32 v[204:205], v[202:203], v[132:133]
	s_nop 0
	v_pk_mul_f32 v[206:207], v[204:205], v[204:205]
	v_pk_add_f32 v[202:203], v[204:205], v[202:203] neg_lo:[0,1] neg_hi:[0,1]
	v_pk_fma_f32 v[138:139], v[206:207], s[52:53], v[138:139] op_sel_hi:[1,0,0]
	v_pk_add_f32 v[132:133], v[132:133], v[202:203] neg_lo:[0,1] neg_hi:[0,1]
; __device__ __forceinline__ float log_sigmoid_f(float x) { return fminf(x, 0.f) - log1pf(__expf(-fabsf(x))); }
;     __device__ __forceinline__ void operator()(const f32x4 (&acc)[2][2][4][2], const Unit& u, int wr, int wc, int fr, int fq) const {
;     ...
;                         if (pm == 0) dst = o_lfs + (size_t)row * 16; else { const int t = row - G_ROWP; if (t < G_TP) dst = o_lfp + (size_t)t * 16; }
; #pragma unroll
;                         for (int n = 0; n < 2; ++n) { const int c = 8 * fq + 4 * n; const f32x4 bv = *(const f32x4*)(b_f + c); const f32x4 x = acc[ai][0][m][n] * s + bv; f32x4 lf;
;                             lf[0] = log_sigmoid_f(x[0]); lf[1] = log_sigmoid_f(x[1]); lf[2] = log_sigmoid_f(x[2]); lf[3] = log_sigmoid_f(x[3]);
;                             *(f32x4*)(LF + (size_t)row * 16 + c) = lf; if (dst) *(f32x4*)(dst + c) = lf; } }
	v_ldexp_f32 v202, v204, 1
	v_pk_fma_f32 v[138:139], v[206:207], v[138:139], s[54:55] op_sel_hi:[1,1,0]
	v_ldexp_f32 v203, v205, 1
	v_pk_mul_f32 v[204:205], v[204:205], v[206:207]
	v_cvt_f32_i32_e32 v207, v191
	v_cvt_f32_i32_e32 v206, v179
	v_pk_mul_f32 v[138:139], v[204:205], v[138:139]
	v_ldexp_f32 v209, v133, 1
	v_pk_add_f32 v[204:205], v[202:203], v[138:139]
	v_pk_mul_f32 v[210:211], v[206:207], s[64:65] op_sel_hi:[1,0]
	v_pk_add_f32 v[202:203], v[204:205], v[202:203] neg_lo:[0,1] neg_hi:[0,1]
	v_pk_fma_f32 v[212:213], v[206:207], s[64:65], v[210:211] op_sel_hi:[1,0,1] neg_lo:[0,0,1] neg_hi:[0,0,1]
	v_pk_add_f32 v[138:139], v[138:139], v[202:203] neg_lo:[0,1] neg_hi:[0,1]
	v_pk_fma_f32 v[206:207], v[206:207], s[66:67], v[212:213] op_sel_hi:[1,0,1]
	v_ldexp_f32 v132, v132, 1
	v_mov_b32_e32 v202, v210
	v_mov_b32_e32 v203, v139
	v_mov_b32_e32 v208, v206
	v_mov_b32_e32 v133, v209
	v_pk_add_f32 v[202:203], v[202:203], v[208:209]
	v_pk_add_f32 v[208:209], v[132:133], v[138:139]
	v_mov_b32_e32 v139, v205
	v_mov_b32_e32 v133, v209
	v_pk_add_f32 v[212:213], v[210:211], v[206:207]
	v_pk_add_f32 v[132:133], v[132:133], v[138:139]
	v_pk_add_f32 v[138:139], v[204:205], v[208:209]
	v_mov_b32_e32 v222, v204
	v_pk_add_f32 v[214:215], v[212:213], v[138:139]
	v_mov_b32_e32 v220, v138
	v_mov_b32_e32 v221, v215
	v_mov_b32_e32 v223, v213
	v_pk_add_f32 v[220:221], v[220:221], v[222:223] neg_lo:[0,1] neg_hi:[0,1]
	v_mov_b32_e32 v216, v214
	v_mov_b32_e32 v217, v213
	v_mov_b32_e32 v218, v212
	v_mov_b32_e32 v219, v211
	v_mov_b32_e32 v222, v212
	v_mov_b32_e32 v223, v215
	v_mov_b32_e32 v211, v221
	v_pk_add_f32 v[216:217], v[216:217], v[218:219] neg_lo:[0,1] neg_hi:[0,1]
	v_mov_b32_e32 v218, v138
	v_mov_b32_e32 v219, v207
	v_pk_add_f32 v[210:211], v[222:223], v[210:211] neg_lo:[0,1] neg_hi:[0,1]
	v_pk_add_f32 v[218:219], v[218:219], v[216:217] neg_lo:[0,1] neg_hi:[0,1]
	v_mov_b32_e32 v222, v210
	v_mov_b32_e32 v223, v217
	v_mov_b32_e32 v224, v214
	v_mov_b32_e32 v225, v139
	v_mov_b32_e32 v217, v205
	v_pk_add_f32 v[222:223], v[206:207], v[222:223] neg_lo:[0,1] neg_hi:[0,1]
	v_pk_add_f32 v[216:217], v[224:225], v[216:217] neg_lo:[0,1] neg_hi:[0,1]
	v_mov_b32_e32 v207, v213
	v_pk_add_f32 v[138:139], v[138:139], v[204:205] neg_lo:[0,1] neg_hi:[0,1]
	v_pk_add_f32 v[202:203], v[202:203], v[216:217] neg_lo:[0,1] neg_hi:[0,1]
	v_pk_add_f32 v[204:205], v[206:207], v[210:211] neg_lo:[0,1] neg_hi:[0,1]
	v_pk_add_f32 v[132:133], v[132:133], v[220:221] neg_lo:[0,1] neg_hi:[0,1]
	v_pk_add_f32 v[138:139], v[208:209], v[138:139] neg_lo:[0,1] neg_hi:[0,1]
	v_pk_add_f32 v[206:207], v[132:133], v[204:205]
	v_mov_b32_e32 v205, v219
	v_mov_b32_e32 v133, v203
	v_pk_add_f32 v[208:209], v[218:219], v[202:203]
	v_pk_add_f32 v[132:133], v[204:205], v[132:133]
	v_mov_b32_e32 v202, v206
	v_pk_add_f32 v[132:133], v[132:133], v[222:223] neg_lo:[0,1] neg_hi:[0,1]
	v_mov_b32_e32 v203, v209
	v_pk_add_f32 v[202:203], v[202:203], v[132:133] neg_lo:[0,1] neg_hi:[0,1]
	v_pk_add_f32 v[132:133], v[138:139], v[132:133] neg_lo:[0,1] neg_hi:[0,1]
	v_pk_add_f32 v[202:203], v[204:205], v[202:203] neg_lo:[0,1] neg_hi:[0,1]
	v_pk_add_f32 v[138:139], v[208:209], v[206:207]
	v_pk_add_f32 v[132:133], v[132:133], v[202:203]
	v_pk_add_f32 v[202:203], v[214:215], v[138:139]
	s_nop 0
	v_pk_add_f32 v[204:205], v[202:203], v[214:215] neg_lo:[0,1] neg_hi:[0,1]
	s_nop 0
	v_pk_add_f32 v[138:139], v[138:139], v[204:205] neg_lo:[0,1] neg_hi:[0,1]
	s_nop 0
	v_pk_add_f32 v[132:133], v[132:133], v[138:139]
	s_nop 0
	v_pk_add_f32 v[132:133], v[202:203], v[132:133]
	s_nop 0
	v_cndmask_b32_e64 v132, v231, v132, s[10:11]
	v_cmp_neq_f32_e64 s[10:11], s4, v183
	s_nop 1
	v_cndmask_b32_e64 v133, v231, v133, s[10:11]
	v_cmp_ngt_f32_e64 s[10:11], -1.0, v183
	s_nop 1
	v_cndmask_b32_e64 v133, v232, v133, s[10:11]
	v_cmp_ngt_f32_e64 s[10:11], -1.0, v173
	s_nop 1
	v_cndmask_b32_e64 v132, v232, v132, s[10:11]
	v_cmp_neq_f32_e64 s[10:11], -1.0, v173
	s_nop 1
	v_cndmask_b32_e64 v132, v233, v132, s[10:11]
	v_cmp_neq_f32_e64 s[10:11], -1.0, v183
	s_nop 1
	v_cndmask_b32_e64 v133, v233, v133, s[10:11]
	v_cmp_lt_f32_e64 s[10:11], |v173|, s5
	v_cndmask_b32_e64 v133, v133, v183, s[12:13]
	s_nop 0
	v_cndmask_b32_e64 v132, v132, v173, s[10:11]
	v_pk_add_f32 v[132:133], v[140:141], v[132:133] neg_lo:[0,1] neg_hi:[0,1]
	global_store_dwordx4 v[136:137], v[130:133], off offset:16 nt
	s_and_b64 exec, exec, vcc
	s_cbranch_execz .LBB0_428
	v_lshl_add_u64 v[134:135], v[134:135], 0, v[150:151]
	global_store_dwordx4 v[134:135], v[130:133], off offset:16 nt

; __device__ __forceinline__ u32x4 pack8(f32x4 a, f32x4 b) { u32x4 w; w.x = cvt_pk_bf16(a[0], a[1]); w.y = cvt_pk_bf16(a[2], a[3]); w.z = cvt_pk_bf16(b[0], b[1]); w.w = cvt_pk_bf16(b[2], b[3]); return w; }
;     __device__ __forceinline__ void operator()(const f32x4 (&acc)[2][2][4][2], const Unit& u, int wr, int wc, int fr, int fq) const {
;     ...
;             const bool isv = pn >= 26; bf16_t* base = (bf16_t*)(ws + (isv ? WS_VB : WS_KB)); float* op = out + (isv ? O_VP : O_KP); float* os = out + (isv ? O_VS : O_KS); bf16_t* stg = (bf16_t*)(ws + (isv ? WS_VS : WS_KS));
;             const int col0 = (pn & 1) * BM + wc * 32 + 8 * fq;
; #pragma unroll
;             for (int ai = 0; ai < 2; ++ai)
; #pragma unroll
;                 for (int m = 0; m < 4; ++m) { const int row = row0 + ai * HALF + m * 16; bf16_t* rowp = base + (size_t)row * 512 + col0; const float s = sc8[ai][m];
;                     float* dst = nullptr;
;                     if (pm == 0) dst = os + (size_t)row * 512; else { const int t = row - G_ROWP; if (t < G_TP) dst = op + (size_t)t * 512; }
; #pragma unroll
;                     for (int bj = 0; bj < 2; ++bj) { const f32x4 v0 = acc[ai][bj][m][0] * s, v1 = acc[ai][bj][m][1] * s; const u32x4 w = pack8(v0, v1); *(u32x4*)(rowp + bj * HALF) = w;
;                         if (dst) { *(f32x4*)(dst + col0 + bj * HALF) = v0; *(f32x4*)(dst + col0 + bj * HALF + 4) = v1; }
;                         if (pm == 0) { const int b = row >> 4, s16 = row & 15;
;                             *(u32x4*)(stg + ((size_t)b * 2112 + 2048 + s16) * 512 + col0 + bj * HALF) = w; } } }
.LBB0_434:
	s_and_b64 s[0:1], s[10:11], exec
	s_mov_b32 s0, 0x3b400000
	s_cselect_b32 s0, s0, 0x39300000
	s_add_u32 s0, s26, s0
	s_addc_u32 s1, s27, 0
	s_lshl_b32 s12, s76, 8
	s_and_b32 s12, s12, 0x100
	v_or_b32_e32 v134, s12, v157
	v_lshlrev_b32_e32 v150, 1, v134
	v_lshl_add_u64 v[204:205], s[0:1], 0, v[150:151]
	v_lshlrev_b32_e32 v202, 2, v134
	v_mov_b32_e32 v203, v151
	v_lshl_add_u64 v[212:213], v[132:133], 1, v[204:205]
	v_cmp_ne_u64_e64 s[12:13], 0, v[130:131]
	v_lshl_add_u64 v[210:211], v[130:131], 0, v[202:203]
	s_waitcnt vmcnt(0)
	v_pk_mul_f32 v[136:137], v[128:129], v[200:201] op_sel_hi:[1,0]
	v_pk_mul_f32 v[134:135], v[126:127], v[200:201] op_sel_hi:[1,0]
	v_pk_mul_f32 v[140:141], v[124:125], v[200:201] op_sel_hi:[1,0]
	v_pk_mul_f32 v[138:139], v[122:123], v[200:201] op_sel_hi:[1,0]
	v_cvt_pk_bf16_f32 v130, v134, v135
	v_cvt_pk_bf16_f32 v131, v136, v137
	s_nop 0
	v_cvt_pk_bf16_f32 v132, v138, v139
	v_cvt_pk_bf16_f32 v133, v140, v141
	global_store_dwordx4 v[212:213], v[130:133], off nt
	s_and_saveexec_b64 s[86:87], s[12:13]
	s_cbranch_execz .LBB0_436
	global_store_dwordx4 v[210:211], v[134:137], off nt
	global_store_dwordx4 v[210:211], v[138:141], off offset:16 nt
.LBB0_436:
	s_or_b64 exec, exec, s[86:87]
	s_and_b64 s[0:1], s[10:11], exec
	s_mov_b32 s0, 0x4d400000
	s_cselect_b32 s0, s0, 0x4b300000
	s_add_u32 s0, s26, s0
	s_addc_u32 s1, s27, 0
	v_lshl_add_u64 v[206:207], s[0:1], 0, v[150:151]
	s_ashr_i32 s0, s61, 4
	v_mad_i64_i32 v[134:135], s[0:1], s0, v234, v[154:155]
	v_lshlrev_b64 v[134:135], 10, v[134:135]
	v_cndmask_b32_e64 v136, 0, 1, s[84:85]
	v_cmp_ne_u32_e64 s[10:11], 1, v136
	s_andn2_b64 vcc, exec, s[84:85]
	v_lshl_add_u64 v[214:215], v[206:207], 0, v[134:135]
	s_cbranch_vccnz .LBB0_438
	global_store_dwordx4 v[214:215], v[130:133], off nt
.LBB0_438:
	v_mov_b32_e32 v201, v200
	v_mov_b32_e32 v134, v200
	v_mov_b32_e32 v135, v200
	v_pk_mul_f32 v[132:133], v[120:121], v[134:135]
	v_pk_mul_f32 v[130:131], v[118:119], v[200:201]
	v_pk_mul_f32 v[140:141], v[116:117], v[134:135]
	v_pk_mul_f32 v[138:139], v[114:115], v[200:201]
	v_cvt_pk_bf16_f32 v134, v130, v131
	v_cvt_pk_bf16_f32 v135, v132, v133
	s_nop 0
	v_cvt_pk_bf16_f32 v136, v138, v139
	v_cvt_pk_bf16_f32 v137, v140, v141
	global_store_dwordx4 v[212:213], v[134:137], off offset:256 nt
	s_and_saveexec_b64 s[84:85], s[12:13]
	s_cbranch_execz .LBB0_440
	global_store_dwordx4 v[210:211], v[130:133], off offset:512 nt
	global_store_dwordx4 v[210:211], v[138:141], off offset:528 nt
.LBB0_440:
	s_or_b64 exec, exec, s[84:85]
	s_and_b64 vcc, exec, s[10:11]
	s_cbranch_vccnz .LBB0_442
	global_store_dwordx4 v[214:215], v[134:137], off offset:256 nt

; __device__ __forceinline__ u32x4 pack8(f32x4 a, f32x4 b) { u32x4 w; w.x = cvt_pk_bf16(a[0], a[1]); w.y = cvt_pk_bf16(a[2], a[3]); w.z = cvt_pk_bf16(b[0], b[1]); w.w = cvt_pk_bf16(b[2], b[3]); return w; }
;     __device__ __forceinline__ void operator()(const f32x4 (&acc)[2][2][4][2], const Unit& u, int wr, int wc, int fr, int fq) const {
;     ...
;                 for (int m = 0; m < 4; ++m) { const int row = row0 + ai * HALF + m * 16; bf16_t* rowp = base + (size_t)row * 512 + col0; const float s = sc8[ai][m];
;                     float* dst = nullptr;
;                     if (pm == 0) dst = os + (size_t)row * 512; else { const int t = row - G_ROWP; if (t < G_TP) dst = op + (size_t)t * 512; }
; #pragma unroll
;                     for (int bj = 0; bj < 2; ++bj) { const f32x4 v0 = acc[ai][bj][m][0] * s, v1 = acc[ai][bj][m][1] * s; const u32x4 w = pack8(v0, v1); *(u32x4*)(rowp + bj * HALF) = w;
;                         if (dst) { *(f32x4*)(dst + col0 + bj * HALF) = v0; *(f32x4*)(dst + col0 + bj * HALF + 4) = v1; }
;                         if (pm == 0) { const int b = row >> 4, s16 = row & 15;
;                             *(u32x4*)(stg + ((size_t)b * 2112 + 2048 + s16) * 512 + col0 + bj * HALF) = w; } } }
.LBB0_446:
	v_mov_b32_e32 v203, v151
	v_lshl_add_u64 v[212:213], v[132:133], 1, v[204:205]
	v_cmp_ne_u64_e64 s[14:15], 0, v[130:131]
	v_lshl_add_u64 v[210:211], v[130:131], 0, v[202:203]
	v_pk_mul_f32 v[132:133], v[112:113], v[198:199] op_sel_hi:[1,0]
	v_pk_mul_f32 v[130:131], v[110:111], v[198:199] op_sel_hi:[1,0]
	v_pk_mul_f32 v[140:141], v[108:109], v[198:199] op_sel_hi:[1,0]
	v_pk_mul_f32 v[138:139], v[106:107], v[198:199] op_sel_hi:[1,0]
	v_cvt_pk_bf16_f32 v134, v130, v131
	v_cvt_pk_bf16_f32 v135, v132, v133
	s_nop 0
	v_cvt_pk_bf16_f32 v136, v138, v139
	v_cvt_pk_bf16_f32 v137, v140, v141
	global_store_dwordx4 v[212:213], v[134:137], off nt
	s_and_saveexec_b64 s[82:83], s[14:15]
	s_cbranch_execz .LBB0_448
	global_store_dwordx4 v[210:211], v[130:133], off nt
	global_store_dwordx4 v[210:211], v[138:141], off offset:16 nt
.LBB0_448:
	s_or_b64 exec, exec, s[82:83]
	v_ashrrev_i32_e32 v130, 4, v196
	v_mad_i64_i32 v[130:131], s[0:1], v130, s60, v[154:155]
	v_lshlrev_b64 v[130:131], 10, v[130:131]
	s_and_b64 vcc, exec, s[10:11]
	v_lshl_add_u64 v[214:215], v[206:207], 0, v[130:131]
	s_cbranch_vccnz .LBB0_450
	global_store_dwordx4 v[214:215], v[134:137], off nt
.LBB0_450:
	v_mov_b32_e32 v199, v198
	s_nop 0
	v_mov_b32_e32 v134, v198
	v_mov_b32_e32 v135, v198
	v_pk_mul_f32 v[132:133], v[104:105], v[134:135]
	v_pk_mul_f32 v[130:131], v[102:103], v[198:199]
	v_pk_mul_f32 v[140:141], v[100:101], v[134:135]
	v_pk_mul_f32 v[138:139], v[98:99], v[198:199]
	v_cvt_pk_bf16_f32 v134, v130, v131
	v_cvt_pk_bf16_f32 v135, v132, v133
	s_nop 0
	v_cvt_pk_bf16_f32 v136, v138, v139
	v_cvt_pk_bf16_f32 v137, v140, v141
	global_store_dwordx4 v[212:213], v[134:137], off offset:256 nt
	s_and_saveexec_b64 s[82:83], s[14:15]
	s_cbranch_execz .LBB0_571
	global_store_dwordx4 v[210:211], v[130:133], off offset:512 nt
	global_store_dwordx4 v[210:211], v[138:141], off offset:528 nt
	s_or_b64 exec, exec, s[82:83]
	s_and_b64 vcc, exec, s[10:11]
	s_cbranch_vccnz .LBB0_572
.LBB0_452:
	global_store_dwordx4 v[214:215], v[134:137], off offset:256 nt
	s_and_b64 vcc, exec, s[12:13]
	s_mov_b64 s[14:15], -1
	s_cbranch_vccz .LBB0_573

; __device__ __forceinline__ u32x4 pack8(f32x4 a, f32x4 b) { u32x4 w; w.x = cvt_pk_bf16(a[0], a[1]); w.y = cvt_pk_bf16(a[2], a[3]); w.z = cvt_pk_bf16(b[0], b[1]); w.w = cvt_pk_bf16(b[2], b[3]); return w; }
;     __device__ __forceinline__ void operator()(const f32x4 (&acc)[2][2][4][2], const Unit& u, int wr, int wc, int fr, int fq) const {
;     ...
;                 for (int m = 0; m < 4; ++m) { const int row = row0 + ai * HALF + m * 16; bf16_t* rowp = base + (size_t)row * 512 + col0; const float s = sc8[ai][m];
;                     float* dst = nullptr;
;                     if (pm == 0) dst = os + (size_t)row * 512; else { const int t = row - G_ROWP; if (t < G_TP) dst = op + (size_t)t * 512; }
; #pragma unroll
;                     for (int bj = 0; bj < 2; ++bj) { const f32x4 v0 = acc[ai][bj][m][0] * s, v1 = acc[ai][bj][m][1] * s; const u32x4 w = pack8(v0, v1); *(u32x4*)(rowp + bj * HALF) = w;
;                         if (dst) { *(f32x4*)(dst + col0 + bj * HALF) = v0; *(f32x4*)(dst + col0 + bj * HALF + 4) = v1; }
;                         if (pm == 0) { const int b = row >> 4, s16 = row & 15;
;                             *(u32x4*)(stg + ((size_t)b * 2112 + 2048 + s16) * 512 + col0 + bj * HALF) = w; } } }
.LBB0_455:
	v_mov_b32_e32 v203, v151
	v_lshl_add_u64 v[212:213], v[132:133], 1, v[204:205]
	v_cmp_ne_u64_e64 s[14:15], 0, v[130:131]
	v_lshl_add_u64 v[210:211], v[130:131], 0, v[202:203]
	v_pk_mul_f32 v[132:133], v[96:97], v[194:195] op_sel_hi:[1,0]
	v_pk_mul_f32 v[130:131], v[94:95], v[194:195] op_sel_hi:[1,0]
	v_pk_mul_f32 v[140:141], v[92:93], v[194:195] op_sel_hi:[1,0]
	v_pk_mul_f32 v[138:139], v[90:91], v[194:195] op_sel_hi:[1,0]
	v_cvt_pk_bf16_f32 v134, v130, v131
	v_cvt_pk_bf16_f32 v135, v132, v133
	s_nop 0
	v_cvt_pk_bf16_f32 v136, v138, v139
	v_cvt_pk_bf16_f32 v137, v140, v141
	global_store_dwordx4 v[212:213], v[134:137], off nt
	s_and_saveexec_b64 s[82:83], s[14:15]
	s_cbranch_execz .LBB0_457
	global_store_dwordx4 v[210:211], v[130:133], off nt
	global_store_dwordx4 v[210:211], v[138:141], off offset:16 nt
.LBB0_457:
	s_or_b64 exec, exec, s[82:83]
	v_ashrrev_i32_e32 v130, 4, v192
	v_mad_i64_i32 v[130:131], s[0:1], v130, s60, v[154:155]
	v_lshlrev_b64 v[130:131], 10, v[130:131]
	s_and_b64 vcc, exec, s[10:11]
	v_lshl_add_u64 v[214:215], v[206:207], 0, v[130:131]
	s_cbranch_vccnz .LBB0_459
	global_store_dwordx4 v[214:215], v[134:137], off nt
.LBB0_459:
	v_mov_b32_e32 v195, v194
	s_nop 0
	v_mov_b32_e32 v134, v194
	v_mov_b32_e32 v135, v194
	v_pk_mul_f32 v[132:133], v[88:89], v[134:135]
	v_pk_mul_f32 v[130:131], v[86:87], v[194:195]
	v_pk_mul_f32 v[140:141], v[84:85], v[134:135]
	v_pk_mul_f32 v[138:139], v[82:83], v[194:195]
	v_cvt_pk_bf16_f32 v134, v130, v131
	v_cvt_pk_bf16_f32 v135, v132, v133
	s_nop 0
	v_cvt_pk_bf16_f32 v136, v138, v139
	v_cvt_pk_bf16_f32 v137, v140, v141
	global_store_dwordx4 v[212:213], v[134:137], off offset:256 nt
	s_and_saveexec_b64 s[82:83], s[14:15]
	s_cbranch_execz .LBB0_574
	global_store_dwordx4 v[210:211], v[130:133], off offset:512 nt
	global_store_dwordx4 v[210:211], v[138:141], off offset:528 nt
	s_or_b64 exec, exec, s[82:83]
	s_and_b64 vcc, exec, s[10:11]
	s_cbranch_vccnz .LBB0_575

; __device__ __forceinline__ u32x4 pack8(f32x4 a, f32x4 b) { u32x4 w; w.x = cvt_pk_bf16(a[0], a[1]); w.y = cvt_pk_bf16(a[2], a[3]); w.z = cvt_pk_bf16(b[0], b[1]); w.w = cvt_pk_bf16(b[2], b[3]); return w; }
;     __device__ __forceinline__ void operator()(const f32x4 (&acc)[2][2][4][2], const Unit& u, int wr, int wc, int fr, int fq) const {
;     ...
;                 for (int m = 0; m < 4; ++m) { const int row = row0 + ai * HALF + m * 16; bf16_t* rowp = base + (size_t)row * 512 + col0; const float s = sc8[ai][m];
;                     float* dst = nullptr;
;                     if (pm == 0) dst = os + (size_t)row * 512; else { const int t = row - G_ROWP; if (t < G_TP) dst = op + (size_t)t * 512; }
; #pragma unroll
;                     for (int bj = 0; bj < 2; ++bj) { const f32x4 v0 = acc[ai][bj][m][0] * s, v1 = acc[ai][bj][m][1] * s; const u32x4 w = pack8(v0, v1); *(u32x4*)(rowp + bj * HALF) = w;
;                         if (dst) { *(f32x4*)(dst + col0 + bj * HALF) = v0; *(f32x4*)(dst + col0 + bj * HALF + 4) = v1; }
;                         if (pm == 0) { const int b = row >> 4, s16 = row & 15;
;                             *(u32x4*)(stg + ((size_t)b * 2112 + 2048 + s16) * 512 + col0 + bj * HALF) = w; } } }
.LBB0_464:
	v_mov_b32_e32 v203, v151
	v_lshl_add_u64 v[212:213], v[132:133], 1, v[204:205]
	v_cmp_ne_u64_e64 s[14:15], 0, v[130:131]
	v_lshl_add_u64 v[210:211], v[130:131], 0, v[202:203]
	v_pk_mul_f32 v[132:133], v[80:81], v[190:191] op_sel_hi:[1,0]
	v_pk_mul_f32 v[130:131], v[78:79], v[190:191] op_sel_hi:[1,0]
	v_pk_mul_f32 v[140:141], v[76:77], v[190:191] op_sel_hi:[1,0]
	v_pk_mul_f32 v[138:139], v[74:75], v[190:191] op_sel_hi:[1,0]
	v_cvt_pk_bf16_f32 v134, v130, v131
	v_cvt_pk_bf16_f32 v135, v132, v133
	s_nop 0
	v_cvt_pk_bf16_f32 v136, v138, v139
	v_cvt_pk_bf16_f32 v137, v140, v141
	global_store_dwordx4 v[212:213], v[134:137], off nt
	s_and_saveexec_b64 s[82:83], s[14:15]
	s_cbranch_execz .LBB0_466
	global_store_dwordx4 v[210:211], v[130:133], off nt
	global_store_dwordx4 v[210:211], v[138:141], off offset:16 nt
.LBB0_466:
	s_or_b64 exec, exec, s[82:83]
	v_ashrrev_i32_e32 v130, 4, v188
	v_mad_i64_i32 v[130:131], s[0:1], v130, s60, v[154:155]
	v_lshlrev_b64 v[130:131], 10, v[130:131]
	s_and_b64 vcc, exec, s[10:11]
	v_lshl_add_u64 v[214:215], v[206:207], 0, v[130:131]
	s_cbranch_vccnz .LBB0_468
	global_store_dwordx4 v[214:215], v[134:137], off nt
.LBB0_468:
	v_mov_b32_e32 v191, v190
	s_nop 0
	v_mov_b32_e32 v134, v190
	v_mov_b32_e32 v135, v190
	v_pk_mul_f32 v[132:133], v[72:73], v[134:135]
	v_pk_mul_f32 v[130:131], v[70:71], v[190:191]
	v_pk_mul_f32 v[140:141], v[68:69], v[134:135]
	v_pk_mul_f32 v[138:139], v[66:67], v[190:191]
	v_cvt_pk_bf16_f32 v134, v130, v131
	v_cvt_pk_bf16_f32 v135, v132, v133
	s_nop 0
	v_cvt_pk_bf16_f32 v136, v138, v139
	v_cvt_pk_bf16_f32 v137, v140, v141
	global_store_dwordx4 v[212:213], v[134:137], off offset:256 nt
	s_and_saveexec_b64 s[82:83], s[14:15]
	s_cbranch_execz .LBB0_577
	global_store_dwordx4 v[210:211], v[130:133], off offset:512 nt
	global_store_dwordx4 v[210:211], v[138:141], off offset:528 nt
	s_or_b64 exec, exec, s[82:83]
	s_and_b64 vcc, exec, s[10:11]
	s_cbranch_vccnz .LBB0_578

; __device__ __forceinline__ u32x4 pack8(f32x4 a, f32x4 b) { u32x4 w; w.x = cvt_pk_bf16(a[0], a[1]); w.y = cvt_pk_bf16(a[2], a[3]); w.z = cvt_pk_bf16(b[0], b[1]); w.w = cvt_pk_bf16(b[2], b[3]); return w; }
;     __device__ __forceinline__ void operator()(const f32x4 (&acc)[2][2][4][2], const Unit& u, int wr, int wc, int fr, int fq) const {
;     ...
;                 for (int m = 0; m < 4; ++m) { const int row = row0 + ai * HALF + m * 16; bf16_t* rowp = base + (size_t)row * 512 + col0; const float s = sc8[ai][m];
;                     float* dst = nullptr;
;                     if (pm == 0) dst = os + (size_t)row * 512; else { const int t = row - G_ROWP; if (t < G_TP) dst = op + (size_t)t * 512; }
; #pragma unroll
;                     for (int bj = 0; bj < 2; ++bj) { const f32x4 v0 = acc[ai][bj][m][0] * s, v1 = acc[ai][bj][m][1] * s; const u32x4 w = pack8(v0, v1); *(u32x4*)(rowp + bj * HALF) = w;
;                         if (dst) { *(f32x4*)(dst + col0 + bj * HALF) = v0; *(f32x4*)(dst + col0 + bj * HALF + 4) = v1; }
;                         if (pm == 0) { const int b = row >> 4, s16 = row & 15;
;                             *(u32x4*)(stg + ((size_t)b * 2112 + 2048 + s16) * 512 + col0 + bj * HALF) = w; } } }
.LBB0_473:
	v_mov_b32_e32 v203, v151
	v_lshl_add_u64 v[212:213], v[132:133], 1, v[204:205]
	v_cmp_ne_u64_e64 s[14:15], 0, v[130:131]
	v_lshl_add_u64 v[210:211], v[130:131], 0, v[202:203]
	v_pk_mul_f32 v[132:133], v[64:65], v[186:187] op_sel_hi:[1,0]
	v_pk_mul_f32 v[130:131], v[62:63], v[186:187] op_sel_hi:[1,0]
	v_pk_mul_f32 v[140:141], v[60:61], v[186:187] op_sel_hi:[1,0]
	v_pk_mul_f32 v[138:139], v[58:59], v[186:187] op_sel_hi:[1,0]
	v_cvt_pk_bf16_f32 v134, v130, v131
	v_cvt_pk_bf16_f32 v135, v132, v133
	s_nop 0
	v_cvt_pk_bf16_f32 v136, v138, v139
	v_cvt_pk_bf16_f32 v137, v140, v141
	global_store_dwordx4 v[212:213], v[134:137], off nt
	s_and_saveexec_b64 s[82:83], s[14:15]
	s_cbranch_execz .LBB0_475
	global_store_dwordx4 v[210:211], v[130:133], off nt
	global_store_dwordx4 v[210:211], v[138:141], off offset:16 nt
.LBB0_475:
	s_or_b64 exec, exec, s[82:83]
	v_ashrrev_i32_e32 v130, 4, v184
	v_mad_i64_i32 v[130:131], s[0:1], v130, s60, v[154:155]
	v_lshlrev_b64 v[130:131], 10, v[130:131]
	s_and_b64 vcc, exec, s[10:11]
	v_lshl_add_u64 v[214:215], v[206:207], 0, v[130:131]
	s_cbranch_vccnz .LBB0_477
	global_store_dwordx4 v[214:215], v[134:137], off nt
.LBB0_477:
	v_mov_b32_e32 v187, v186
	s_nop 0
	v_mov_b32_e32 v134, v186
	v_mov_b32_e32 v135, v186
	v_pk_mul_f32 v[132:133], v[56:57], v[134:135]
	v_pk_mul_f32 v[130:131], v[54:55], v[186:187]
	v_pk_mul_f32 v[140:141], v[52:53], v[134:135]
	v_pk_mul_f32 v[138:139], v[50:51], v[186:187]
	v_cvt_pk_bf16_f32 v134, v130, v131
	v_cvt_pk_bf16_f32 v135, v132, v133
	s_nop 0
	v_cvt_pk_bf16_f32 v136, v138, v139
	v_cvt_pk_bf16_f32 v137, v140, v141
	global_store_dwordx4 v[212:213], v[134:137], off offset:256 nt
	s_and_saveexec_b64 s[82:83], s[14:15]
	s_cbranch_execz .LBB0_580
	global_store_dwordx4 v[210:211], v[130:133], off offset:512 nt
	global_store_dwordx4 v[210:211], v[138:141], off offset:528 nt
	s_or_b64 exec, exec, s[82:83]
	s_and_b64 vcc, exec, s[10:11]
	s_cbranch_vccnz .LBB0_581

; __device__ __forceinline__ u32x4 pack8(f32x4 a, f32x4 b) { u32x4 w; w.x = cvt_pk_bf16(a[0], a[1]); w.y = cvt_pk_bf16(a[2], a[3]); w.z = cvt_pk_bf16(b[0], b[1]); w.w = cvt_pk_bf16(b[2], b[3]); return w; }
;     __device__ __forceinline__ void operator()(const f32x4 (&acc)[2][2][4][2], const Unit& u, int wr, int wc, int fr, int fq) const {
;     ...
;                 for (int m = 0; m < 4; ++m) { const int row = row0 + ai * HALF + m * 16; bf16_t* rowp = base + (size_t)row * 512 + col0; const float s = sc8[ai][m];
;                     float* dst = nullptr;
;                     if (pm == 0) dst = os + (size_t)row * 512; else { const int t = row - G_ROWP; if (t < G_TP) dst = op + (size_t)t * 512; }
; #pragma unroll
;                     for (int bj = 0; bj < 2; ++bj) { const f32x4 v0 = acc[ai][bj][m][0] * s, v1 = acc[ai][bj][m][1] * s; const u32x4 w = pack8(v0, v1); *(u32x4*)(rowp + bj * HALF) = w;
;                         if (dst) { *(f32x4*)(dst + col0 + bj * HALF) = v0; *(f32x4*)(dst + col0 + bj * HALF + 4) = v1; }
;                         if (pm == 0) { const int b = row >> 4, s16 = row & 15;
;                             *(u32x4*)(stg + ((size_t)b * 2112 + 2048 + s16) * 512 + col0 + bj * HALF) = w; } } }
.LBB0_482:
	v_mov_b32_e32 v203, v151
	v_lshl_add_u64 v[212:213], v[132:133], 1, v[204:205]
	v_cmp_ne_u64_e64 s[14:15], 0, v[130:131]
	v_lshl_add_u64 v[210:211], v[130:131], 0, v[202:203]
	v_pk_mul_f32 v[132:133], v[48:49], v[182:183] op_sel_hi:[1,0]
	v_pk_mul_f32 v[130:131], v[46:47], v[182:183] op_sel_hi:[1,0]
	v_pk_mul_f32 v[140:141], v[44:45], v[182:183] op_sel_hi:[1,0]
	v_pk_mul_f32 v[138:139], v[42:43], v[182:183] op_sel_hi:[1,0]
	v_cvt_pk_bf16_f32 v134, v130, v131
	v_cvt_pk_bf16_f32 v135, v132, v133
	s_nop 0
	v_cvt_pk_bf16_f32 v136, v138, v139
	v_cvt_pk_bf16_f32 v137, v140, v141
	global_store_dwordx4 v[212:213], v[134:137], off nt
	s_and_saveexec_b64 s[82:83], s[14:15]
	s_cbranch_execz .LBB0_484
	global_store_dwordx4 v[210:211], v[130:133], off nt
	global_store_dwordx4 v[210:211], v[138:141], off offset:16 nt
.LBB0_484:
	s_or_b64 exec, exec, s[82:83]
	v_ashrrev_i32_e32 v130, 4, v180
	v_mad_i64_i32 v[130:131], s[0:1], v130, s60, v[154:155]
	v_lshlrev_b64 v[130:131], 10, v[130:131]
	s_and_b64 vcc, exec, s[10:11]
	v_lshl_add_u64 v[214:215], v[206:207], 0, v[130:131]
	s_cbranch_vccnz .LBB0_486
	global_store_dwordx4 v[214:215], v[134:137], off nt
.LBB0_486:
	v_mov_b32_e32 v183, v182
	s_nop 0
	v_mov_b32_e32 v134, v182
	v_mov_b32_e32 v135, v182
	v_pk_mul_f32 v[132:133], v[40:41], v[134:135]
	v_pk_mul_f32 v[130:131], v[38:39], v[182:183]
	v_pk_mul_f32 v[140:141], v[36:37], v[134:135]
	v_pk_mul_f32 v[138:139], v[34:35], v[182:183]
	v_cvt_pk_bf16_f32 v134, v130, v131
	v_cvt_pk_bf16_f32 v135, v132, v133
	s_nop 0
	v_cvt_pk_bf16_f32 v136, v138, v139
	v_cvt_pk_bf16_f32 v137, v140, v141
	global_store_dwordx4 v[212:213], v[134:137], off offset:256 nt
	s_and_saveexec_b64 s[82:83], s[14:15]
	s_cbranch_execz .LBB0_583
	global_store_dwordx4 v[210:211], v[130:133], off offset:512 nt
	global_store_dwordx4 v[210:211], v[138:141], off offset:528 nt
	s_or_b64 exec, exec, s[82:83]
	s_and_b64 vcc, exec, s[10:11]
	s_cbranch_vccnz .LBB0_584

; __device__ __forceinline__ u32x4 pack8(f32x4 a, f32x4 b) { u32x4 w; w.x = cvt_pk_bf16(a[0], a[1]); w.y = cvt_pk_bf16(a[2], a[3]); w.z = cvt_pk_bf16(b[0], b[1]); w.w = cvt_pk_bf16(b[2], b[3]); return w; }
;     __device__ __forceinline__ void operator()(const f32x4 (&acc)[2][2][4][2], const Unit& u, int wr, int wc, int fr, int fq) const {
;     ...
;                 for (int m = 0; m < 4; ++m) { const int row = row0 + ai * HALF + m * 16; bf16_t* rowp = base + (size_t)row * 512 + col0; const float s = sc8[ai][m];
;                     float* dst = nullptr;
;                     if (pm == 0) dst = os + (size_t)row * 512; else { const int t = row - G_ROWP; if (t < G_TP) dst = op + (size_t)t * 512; }
; #pragma unroll
;                     for (int bj = 0; bj < 2; ++bj) { const f32x4 v0 = acc[ai][bj][m][0] * s, v1 = acc[ai][bj][m][1] * s; const u32x4 w = pack8(v0, v1); *(u32x4*)(rowp + bj * HALF) = w;
;                         if (dst) { *(f32x4*)(dst + col0 + bj * HALF) = v0; *(f32x4*)(dst + col0 + bj * HALF + 4) = v1; }
;                         if (pm == 0) { const int b = row >> 4, s16 = row & 15;
;                             *(u32x4*)(stg + ((size_t)b * 2112 + 2048 + s16) * 512 + col0 + bj * HALF) = w; } } }
.LBB0_491:
	v_mov_b32_e32 v203, v151
	v_lshl_add_u64 v[212:213], v[132:133], 1, v[204:205]
	v_cmp_ne_u64_e64 s[14:15], 0, v[130:131]
	v_lshl_add_u64 v[210:211], v[130:131], 0, v[202:203]
	v_pk_mul_f32 v[132:133], v[32:33], v[178:179] op_sel_hi:[1,0]
	v_pk_mul_f32 v[130:131], v[30:31], v[178:179] op_sel_hi:[1,0]
	v_pk_mul_f32 v[140:141], v[28:29], v[178:179] op_sel_hi:[1,0]
	v_pk_mul_f32 v[138:139], v[26:27], v[178:179] op_sel_hi:[1,0]
	v_cvt_pk_bf16_f32 v134, v130, v131
	v_cvt_pk_bf16_f32 v135, v132, v133
	s_nop 0
	v_cvt_pk_bf16_f32 v136, v138, v139
	v_cvt_pk_bf16_f32 v137, v140, v141
	global_store_dwordx4 v[212:213], v[134:137], off nt
	s_and_saveexec_b64 s[82:83], s[14:15]
	s_cbranch_execz .LBB0_493
	global_store_dwordx4 v[210:211], v[130:133], off nt
	global_store_dwordx4 v[210:211], v[138:141], off offset:16 nt
.LBB0_493:
	s_or_b64 exec, exec, s[82:83]
	v_ashrrev_i32_e32 v130, 4, v176
	v_mad_i64_i32 v[130:131], s[0:1], v130, s60, v[154:155]
	v_lshlrev_b64 v[130:131], 10, v[130:131]
	s_and_b64 vcc, exec, s[10:11]
	v_lshl_add_u64 v[214:215], v[206:207], 0, v[130:131]
	s_cbranch_vccnz .LBB0_495
	global_store_dwordx4 v[214:215], v[134:137], off nt
.LBB0_495:
	v_mov_b32_e32 v179, v178
	s_nop 0
	v_mov_b32_e32 v134, v178
	v_mov_b32_e32 v135, v178
	v_pk_mul_f32 v[132:133], v[24:25], v[134:135]
	v_pk_mul_f32 v[130:131], v[22:23], v[178:179]
	v_pk_mul_f32 v[140:141], v[20:21], v[134:135]
	v_pk_mul_f32 v[138:139], v[18:19], v[178:179]
	v_cvt_pk_bf16_f32 v134, v130, v131
	v_cvt_pk_bf16_f32 v135, v132, v133
	s_nop 0
	v_cvt_pk_bf16_f32 v136, v138, v139
	v_cvt_pk_bf16_f32 v137, v140, v141
	global_store_dwordx4 v[212:213], v[134:137], off offset:256 nt
	s_and_saveexec_b64 s[82:83], s[14:15]
	s_cbranch_execz .LBB0_586
	global_store_dwordx4 v[210:211], v[130:133], off offset:512 nt
	global_store_dwordx4 v[210:211], v[138:141], off offset:528 nt
	s_or_b64 exec, exec, s[82:83]
	s_and_b64 vcc, exec, s[10:11]
	s_cbranch_vccnz .LBB0_587
.LBB0_497:
	global_store_dwordx4 v[214:215], v[134:137], off offset:256 nt
	s_and_b64 vcc, exec, s[12:13]
	s_mov_b64 s[12:13], -1
	s_cbranch_vccz .LBB0_588

; __device__ __forceinline__ u32x4 pack8(f32x4 a, f32x4 b) { u32x4 w; w.x = cvt_pk_bf16(a[0], a[1]); w.y = cvt_pk_bf16(a[2], a[3]); w.z = cvt_pk_bf16(b[0], b[1]); w.w = cvt_pk_bf16(b[2], b[3]); return w; }
;     __device__ __forceinline__ void operator()(const f32x4 (&acc)[2][2][4][2], const Unit& u, int wr, int wc, int fr, int fq) const {
;     ...
;                 for (int m = 0; m < 4; ++m) { const int row = row0 + ai * HALF + m * 16; bf16_t* rowp = base + (size_t)row * 512 + col0; const float s = sc8[ai][m];
;                     float* dst = nullptr;
;                     if (pm == 0) dst = os + (size_t)row * 512; else { const int t = row - G_ROWP; if (t < G_TP) dst = op + (size_t)t * 512; }
; #pragma unroll
;                     for (int bj = 0; bj < 2; ++bj) { const f32x4 v0 = acc[ai][bj][m][0] * s, v1 = acc[ai][bj][m][1] * s; const u32x4 w = pack8(v0, v1); *(u32x4*)(rowp + bj * HALF) = w;
;                         if (dst) { *(f32x4*)(dst + col0 + bj * HALF) = v0; *(f32x4*)(dst + col0 + bj * HALF + 4) = v1; }
;                         if (pm == 0) { const int b = row >> 4, s16 = row & 15;
;                             *(u32x4*)(stg + ((size_t)b * 2112 + 2048 + s16) * 512 + col0 + bj * HALF) = w; } } }
.LBB0_500:
	v_mov_b32_e32 v203, v151
	v_lshl_add_u64 v[204:205], v[132:133], 1, v[204:205]
	v_cmp_ne_u64_e64 s[12:13], 0, v[130:131]
	v_lshl_add_u64 v[202:203], v[130:131], 0, v[202:203]
	v_pk_mul_f32 v[132:133], v[16:17], v[172:173] op_sel_hi:[1,0]
	v_pk_mul_f32 v[130:131], v[14:15], v[172:173] op_sel_hi:[1,0]
	v_pk_mul_f32 v[140:141], v[12:13], v[172:173] op_sel_hi:[1,0]
	v_pk_mul_f32 v[138:139], v[10:11], v[172:173] op_sel_hi:[1,0]
	v_cvt_pk_bf16_f32 v134, v130, v131
	v_cvt_pk_bf16_f32 v135, v132, v133
	s_nop 0
	v_cvt_pk_bf16_f32 v136, v138, v139
	v_cvt_pk_bf16_f32 v137, v140, v141
	global_store_dwordx4 v[204:205], v[134:137], off nt
	s_and_saveexec_b64 s[14:15], s[12:13]
	s_cbranch_execz .LBB0_502
	global_store_dwordx4 v[202:203], v[130:133], off nt
	global_store_dwordx4 v[202:203], v[138:141], off offset:16 nt
.LBB0_502:
	s_or_b64 exec, exec, s[14:15]
	v_ashrrev_i32_e32 v130, 4, v170
	v_mad_i64_i32 v[130:131], s[0:1], v130, s60, v[154:155]
	v_lshlrev_b64 v[130:131], 10, v[130:131]
	s_and_b64 vcc, exec, s[10:11]
	v_lshl_add_u64 v[206:207], v[206:207], 0, v[130:131]
	s_cbranch_vccnz .LBB0_504
	global_store_dwordx4 v[206:207], v[134:137], off nt
.LBB0_504:
	v_mov_b32_e32 v173, v172
	s_nop 0
	v_mov_b32_e32 v134, v172
	v_mov_b32_e32 v135, v172
	v_pk_mul_f32 v[132:133], v[8:9], v[134:135]
	v_pk_mul_f32 v[130:131], v[6:7], v[172:173]
	v_pk_mul_f32 v[140:141], v[4:5], v[134:135]
	v_pk_mul_f32 v[138:139], v[2:3], v[172:173]
	v_cvt_pk_bf16_f32 v134, v130, v131
	v_cvt_pk_bf16_f32 v135, v132, v133
	s_nop 0
	v_cvt_pk_bf16_f32 v136, v138, v139
	v_cvt_pk_bf16_f32 v137, v140, v141
	global_store_dwordx4 v[204:205], v[134:137], off offset:256 nt
	s_and_saveexec_b64 s[14:15], s[12:13]
	s_cbranch_execz .LBB0_506
	global_store_dwordx4 v[202:203], v[130:133], off offset:512 nt
	global_store_dwordx4 v[202:203], v[138:141], off offset:528 nt
.LBB0_506:
	s_or_b64 exec, exec, s[14:15]
	s_and_b64 vcc, exec, s[10:11]
	s_cbranch_vccnz .LBB0_508
	global_store_dwordx4 v[206:207], v[134:137], off offset:256 nt

; __device__ __forceinline__ u32x4 pack8(f32x4 a, f32x4 b) { u32x4 w; w.x = cvt_pk_bf16(a[0], a[1]); w.y = cvt_pk_bf16(a[2], a[3]); w.z = cvt_pk_bf16(b[0], b[1]); w.w = cvt_pk_bf16(b[2], b[3]); return w; }
;     __device__ __forceinline__ void operator()(const f32x4 (&acc)[2][2][4][2], const Unit& u, int wr, int wc, int fr, int fq) const {
;     ...
;             bf16_t* base = (bf16_t*)(ws + (pn < 8 ? WS_XR : (pn < 16 ? WS_YG : WS_Q)));
;             const int col0 = (pn & 7) * BM + wc * 32 + 8 * fq;
; #pragma unroll
;             for (int ai = 0; ai < 2; ++ai)
; #pragma unroll
;                 for (int m = 0; m < 4; ++m) { const int row = row0 + ai * HALF + m * 16; bf16_t* rowp = base + (size_t)row * 2048 + col0; const float s = sc8[ai][m];
; #pragma unroll
;                     for (int bj = 0; bj < 2; ++bj) { const f32x4 v0 = acc[ai][bj][m][0] * s, v1 = acc[ai][bj][m][1] * s; *(u32x4*)(rowp + bj * HALF) = pack8(v0, v1); }
;                     if (pn < 8) {
;                         float* dst = nullptr;
;                         if (pm == 0) { const int s16 = row & 15; if (s16 >= 13) dst = o_rcs + (size_t)((row >> 4) * 3 + (s16 - 13)) * 2048; }
;                         else { const int t = row - G_ROWP; if (t >= G_TP - 3 && t < G_TP) dst = o_rcp + (size_t)(t - (G_TP - 3)) * 2048; }
;                         if (dst) {
; #pragma unroll
;                             for (int bj = 0; bj < 2; ++bj) { *(f32x4*)(dst + col0 + bj * HALF) = acc[ai][bj][m][0] * s; *(f32x4*)(dst + col0 + bj * HALF + 4) = acc[ai][bj][m][1] * s; } }
;                     } }
.LBB0_509:
	s_andn2_b64 vcc, exec, s[10:11]
	s_cbranch_vccnz .LBB0_568
	s_cmp_lt_i32 s76, 16
	s_mov_b32 s0, 0x30f00000
	s_cselect_b32 s10, s0, 0x35100000
	s_cmp_lt_i32 s76, 8
	s_cselect_b64 s[80:81], -1, 0
	s_and_b64 s[0:1], s[80:81], exec
	s_cselect_b32 s0, 0x2cd00000, s10
	s_add_u32 s0, s26, s0
	s_addc_u32 s1, s27, 0
	s_lshl_b32 s10, s76, 8
	s_and_b32 s10, s10, 0x700
	v_or_b32_e32 v134, s10, v157
	s_cmp_lg_u32 s78, 0
	v_lshlrev_b32_e32 v150, 1, v134
	s_cselect_b64 s[12:13], -1, 0
	s_cmp_eq_u32 s78, 0
	v_lshl_add_u64 v[130:131], s[0:1], 0, v[150:151]
	v_lshlrev_b64 v[132:133], 12, v[174:175]
	s_cselect_b64 s[14:15], -1, 0
	s_cmp_gt_i32 s76, 7
	v_lshl_add_u64 v[132:133], v[130:131], 0, v[132:133]
	s_waitcnt vmcnt(0)
	v_pk_mul_f32 v[128:129], v[128:129], v[200:201] op_sel_hi:[1,0]
	v_pk_mul_f32 v[126:127], v[126:127], v[200:201] op_sel_hi:[1,0]
	v_pk_mul_f32 v[124:125], v[124:125], v[200:201] op_sel_hi:[1,0]
	v_pk_mul_f32 v[122:123], v[122:123], v[200:201] op_sel_hi:[1,0]
	v_cvt_pk_bf16_f32 v136, v126, v127
	v_cvt_pk_bf16_f32 v137, v128, v129
	v_pk_mul_f32 v[120:121], v[120:121], v[200:201] op_sel_hi:[1,0]
	v_cvt_pk_bf16_f32 v138, v122, v123
	v_cvt_pk_bf16_f32 v139, v124, v125
	v_pk_mul_f32 v[118:119], v[118:119], v[200:201] op_sel_hi:[1,0]
	v_pk_mul_f32 v[116:117], v[116:117], v[200:201] op_sel_hi:[1,0]
	v_pk_mul_f32 v[114:115], v[114:115], v[200:201] op_sel_hi:[1,0]
	global_store_dwordx4 v[132:133], v[136:139], off nt
	s_nop 1
	v_cvt_pk_bf16_f32 v136, v118, v119
	v_cvt_pk_bf16_f32 v137, v120, v121
	v_cvt_pk_bf16_f32 v138, v114, v115
	v_cvt_pk_bf16_f32 v139, v116, v117
	global_store_dwordx4 v[132:133], v[136:139], off offset:256 nt
	s_cbranch_scc1 .LBB0_516
	s_andn2_b64 vcc, exec, s[12:13]
	v_mov_b64_e32 v[132:133], v[160:161]
	s_cbranch_vccnz .LBB0_513
	v_add_u32_e32 v150, 0xffffbef3, v174
	v_lshlrev_b64 v[132:133], 13, v[150:151]
	v_cmp_gt_u32_e32 vcc, 3, v150
	v_lshl_add_u64 v[132:133], s[46:47], 0, v[132:133]
	s_nop 0
	v_cndmask_b32_e32 v133, 0, v133, vcc
	v_cndmask_b32_e32 v132, 0, v132, vcc
.LBB0_513:
	v_cmp_ne_u64_e32 vcc, 0, v[132:133]
	s_and_saveexec_b64 s[10:11], vcc
	s_cbranch_execz .LBB0_515
	v_lshlrev_b32_e32 v150, 2, v134
	v_lshl_add_u64 v[132:133], v[132:133], 0, v[150:151]
	global_store_dwordx4 v[132:133], v[126:129], off nt
	global_store_dwordx4 v[132:133], v[122:125], off offset:16 nt
	global_store_dwordx4 v[132:133], v[118:121], off offset:512 nt
	global_store_dwordx4 v[132:133], v[114:117], off offset:528 nt

; __device__ __forceinline__ u32x4 pack8(f32x4 a, f32x4 b) { u32x4 w; w.x = cvt_pk_bf16(a[0], a[1]); w.y = cvt_pk_bf16(a[2], a[3]); w.z = cvt_pk_bf16(b[0], b[1]); w.w = cvt_pk_bf16(b[2], b[3]); return w; }
;     __device__ __forceinline__ void operator()(const f32x4 (&acc)[2][2][4][2], const Unit& u, int wr, int wc, int fr, int fq) const {
;     ...
;                 for (int m = 0; m < 4; ++m) { const int row = row0 + ai * HALF + m * 16; bf16_t* rowp = base + (size_t)row * 2048 + col0; const float s = sc8[ai][m];
; #pragma unroll
;                     for (int bj = 0; bj < 2; ++bj) { const f32x4 v0 = acc[ai][bj][m][0] * s, v1 = acc[ai][bj][m][1] * s; *(u32x4*)(rowp + bj * HALF) = pack8(v0, v1); }
;                     if (pn < 8) {
;                         float* dst = nullptr;
;                         if (pm == 0) { const int s16 = row & 15; if (s16 >= 13) dst = o_rcs + (size_t)((row >> 4) * 3 + (s16 - 13)) * 2048; }
;                         else { const int t = row - G_ROWP; if (t >= G_TP - 3 && t < G_TP) dst = o_rcp + (size_t)(t - (G_TP - 3)) * 2048; }
;                         if (dst) {
; #pragma unroll
;                             for (int bj = 0; bj < 2; ++bj) { *(f32x4*)(dst + col0 + bj * HALF) = acc[ai][bj][m][0] * s; *(f32x4*)(dst + col0 + bj * HALF + 4) = acc[ai][bj][m][1] * s; } }
.LBB0_516:
	s_nop 0
	v_lshlrev_b64 v[114:115], 12, v[196:197]
	v_cndmask_b32_e64 v120, 0, 1, s[80:81]
	v_lshl_add_u64 v[118:119], v[130:131], 0, v[114:115]
	v_pk_mul_f32 v[112:113], v[112:113], v[198:199] op_sel_hi:[1,0]
	v_pk_mul_f32 v[110:111], v[110:111], v[198:199] op_sel_hi:[1,0]
	v_pk_mul_f32 v[108:109], v[108:109], v[198:199] op_sel_hi:[1,0]
	v_pk_mul_f32 v[106:107], v[106:107], v[198:199] op_sel_hi:[1,0]
	v_cvt_pk_bf16_f32 v114, v110, v111
	v_cvt_pk_bf16_f32 v115, v112, v113
	v_pk_mul_f32 v[104:105], v[104:105], v[198:199] op_sel_hi:[1,0]
	v_cvt_pk_bf16_f32 v116, v106, v107
	v_cvt_pk_bf16_f32 v117, v108, v109
	v_pk_mul_f32 v[102:103], v[102:103], v[198:199] op_sel_hi:[1,0]
	v_pk_mul_f32 v[100:101], v[100:101], v[198:199] op_sel_hi:[1,0]
	v_pk_mul_f32 v[98:99], v[98:99], v[198:199] op_sel_hi:[1,0]
	v_cmp_ne_u32_e64 s[10:11], 1, v120
	s_andn2_b64 vcc, exec, s[80:81]
	global_store_dwordx4 v[118:119], v[114:117], off nt
	s_nop 1
	v_cvt_pk_bf16_f32 v114, v102, v103
	v_cvt_pk_bf16_f32 v115, v104, v105
	v_cvt_pk_bf16_f32 v116, v98, v99
	v_cvt_pk_bf16_f32 v117, v100, v101
	global_store_dwordx4 v[118:119], v[114:117], off offset:256 nt
	s_cbranch_vccnz .LBB0_524
	s_mov_b64 s[76:77], -1
	s_and_b64 vcc, exec, s[14:15]
	s_cbranch_vccz .LBB0_589
	v_mov_b64_e32 v[114:115], 0
	s_and_saveexec_b64 s[76:77], s[38:39]
	v_ashrrev_i32_e32 v114, 4, v196
	v_mad_u64_u32 v[114:115], s[0:1], v114, 3, v[156:157]
	v_ashrrev_i32_e32 v115, 31, v114
	v_lshlrev_b64 v[114:115], 13, v[114:115]
	v_lshl_add_u64 v[114:115], s[48:49], 0, v[114:115]
	s_or_b64 exec, exec, s[76:77]
	s_cbranch_execz .LBB0_590

; __device__ __forceinline__ u32x4 pack8(f32x4 a, f32x4 b) { u32x4 w; w.x = cvt_pk_bf16(a[0], a[1]); w.y = cvt_pk_bf16(a[2], a[3]); w.z = cvt_pk_bf16(b[0], b[1]); w.w = cvt_pk_bf16(b[2], b[3]); return w; }
;     __device__ __forceinline__ void operator()(const f32x4 (&acc)[2][2][4][2], const Unit& u, int wr, int wc, int fr, int fq) const {
;     ...
;                 for (int m = 0; m < 4; ++m) { const int row = row0 + ai * HALF + m * 16; bf16_t* rowp = base + (size_t)row * 2048 + col0; const float s = sc8[ai][m];
; #pragma unroll
;                     for (int bj = 0; bj < 2; ++bj) { const f32x4 v0 = acc[ai][bj][m][0] * s, v1 = acc[ai][bj][m][1] * s; *(u32x4*)(rowp + bj * HALF) = pack8(v0, v1); }
;                     if (pn < 8) {
;                         float* dst = nullptr;
;                         if (pm == 0) { const int s16 = row & 15; if (s16 >= 13) dst = o_rcs + (size_t)((row >> 4) * 3 + (s16 - 13)) * 2048; }
;                         else { const int t = row - G_ROWP; if (t >= G_TP - 3 && t < G_TP) dst = o_rcp + (size_t)(t - (G_TP - 3)) * 2048; }
;                         if (dst) {
; #pragma unroll
;                             for (int bj = 0; bj < 2; ++bj) { *(f32x4*)(dst + col0 + bj * HALF) = acc[ai][bj][m][0] * s; *(f32x4*)(dst + col0 + bj * HALF + 4) = acc[ai][bj][m][1] * s; } }
.LBB0_522:
	v_lshlrev_b32_e32 v150, 2, v134
	v_lshl_add_u64 v[114:115], v[114:115], 0, v[150:151]
	global_store_dwordx4 v[114:115], v[110:113], off nt
	global_store_dwordx4 v[114:115], v[106:109], off offset:16 nt
	global_store_dwordx4 v[114:115], v[102:105], off offset:512 nt
	global_store_dwordx4 v[114:115], v[98:101], off offset:528 nt

; __device__ __forceinline__ u32x4 pack8(f32x4 a, f32x4 b) { u32x4 w; w.x = cvt_pk_bf16(a[0], a[1]); w.y = cvt_pk_bf16(a[2], a[3]); w.z = cvt_pk_bf16(b[0], b[1]); w.w = cvt_pk_bf16(b[2], b[3]); return w; }
;     __device__ __forceinline__ void operator()(const f32x4 (&acc)[2][2][4][2], const Unit& u, int wr, int wc, int fr, int fq) const {
;     ...
;                 for (int m = 0; m < 4; ++m) { const int row = row0 + ai * HALF + m * 16; bf16_t* rowp = base + (size_t)row * 2048 + col0; const float s = sc8[ai][m];
; #pragma unroll
;                     for (int bj = 0; bj < 2; ++bj) { const f32x4 v0 = acc[ai][bj][m][0] * s, v1 = acc[ai][bj][m][1] * s; *(u32x4*)(rowp + bj * HALF) = pack8(v0, v1); }
;                     if (pn < 8) {
;                         float* dst = nullptr;
;                         if (pm == 0) { const int s16 = row & 15; if (s16 >= 13) dst = o_rcs + (size_t)((row >> 4) * 3 + (s16 - 13)) * 2048; }
;                         else { const int t = row - G_ROWP; if (t >= G_TP - 3 && t < G_TP) dst = o_rcp + (size_t)(t - (G_TP - 3)) * 2048; }
;                         if (dst) {
; #pragma unroll
;                             for (int bj = 0; bj < 2; ++bj) { *(f32x4*)(dst + col0 + bj * HALF) = acc[ai][bj][m][0] * s; *(f32x4*)(dst + col0 + bj * HALF + 4) = acc[ai][bj][m][1] * s; } }
.LBB0_524:
	s_nop 0
	v_lshlrev_b64 v[98:99], 12, v[192:193]
	v_lshl_add_u64 v[102:103], v[130:131], 0, v[98:99]
	v_pk_mul_f32 v[96:97], v[96:97], v[194:195] op_sel_hi:[1,0]
	v_pk_mul_f32 v[94:95], v[94:95], v[194:195] op_sel_hi:[1,0]
	v_pk_mul_f32 v[92:93], v[92:93], v[194:195] op_sel_hi:[1,0]
	v_pk_mul_f32 v[90:91], v[90:91], v[194:195] op_sel_hi:[1,0]
	v_cvt_pk_bf16_f32 v98, v94, v95
	v_cvt_pk_bf16_f32 v99, v96, v97
	v_pk_mul_f32 v[88:89], v[88:89], v[194:195] op_sel_hi:[1,0]
	v_cvt_pk_bf16_f32 v100, v90, v91
	v_cvt_pk_bf16_f32 v101, v92, v93
	v_pk_mul_f32 v[86:87], v[86:87], v[194:195] op_sel_hi:[1,0]
	v_pk_mul_f32 v[84:85], v[84:85], v[194:195] op_sel_hi:[1,0]
	v_pk_mul_f32 v[82:83], v[82:83], v[194:195] op_sel_hi:[1,0]
	s_and_b64 vcc, exec, s[10:11]
	global_store_dwordx4 v[102:103], v[98:101], off nt
	s_nop 1
	v_cvt_pk_bf16_f32 v98, v86, v87
	v_cvt_pk_bf16_f32 v99, v88, v89
	v_cvt_pk_bf16_f32 v100, v82, v83
	v_cvt_pk_bf16_f32 v101, v84, v85
	global_store_dwordx4 v[102:103], v[98:101], off offset:256 nt
	s_cbranch_vccnz .LBB0_532
	s_mov_b64 s[76:77], -1
	s_and_b64 vcc, exec, s[14:15]
	s_cbranch_vccz .LBB0_591
	v_mov_b64_e32 v[98:99], 0
	s_and_saveexec_b64 s[76:77], s[38:39]
	v_ashrrev_i32_e32 v98, 4, v192
	v_mad_u64_u32 v[98:99], s[0:1], v98, 3, v[156:157]
	v_ashrrev_i32_e32 v99, 31, v98
	v_lshlrev_b64 v[98:99], 13, v[98:99]
	v_lshl_add_u64 v[98:99], s[48:49], 0, v[98:99]
	s_or_b64 exec, exec, s[76:77]
	s_cbranch_execz .LBB0_592

; __device__ __forceinline__ u32x4 pack8(f32x4 a, f32x4 b) { u32x4 w; w.x = cvt_pk_bf16(a[0], a[1]); w.y = cvt_pk_bf16(a[2], a[3]); w.z = cvt_pk_bf16(b[0], b[1]); w.w = cvt_pk_bf16(b[2], b[3]); return w; }
;     __device__ __forceinline__ void operator()(const f32x4 (&acc)[2][2][4][2], const Unit& u, int wr, int wc, int fr, int fq) const {
;     ...
;                 for (int m = 0; m < 4; ++m) { const int row = row0 + ai * HALF + m * 16; bf16_t* rowp = base + (size_t)row * 2048 + col0; const float s = sc8[ai][m];
; #pragma unroll
;                     for (int bj = 0; bj < 2; ++bj) { const f32x4 v0 = acc[ai][bj][m][0] * s, v1 = acc[ai][bj][m][1] * s; *(u32x4*)(rowp + bj * HALF) = pack8(v0, v1); }
;                     if (pn < 8) {
;                         float* dst = nullptr;
;                         if (pm == 0) { const int s16 = row & 15; if (s16 >= 13) dst = o_rcs + (size_t)((row >> 4) * 3 + (s16 - 13)) * 2048; }
;                         else { const int t = row - G_ROWP; if (t >= G_TP - 3 && t < G_TP) dst = o_rcp + (size_t)(t - (G_TP - 3)) * 2048; }
;                         if (dst) {
; #pragma unroll
;                             for (int bj = 0; bj < 2; ++bj) { *(f32x4*)(dst + col0 + bj * HALF) = acc[ai][bj][m][0] * s; *(f32x4*)(dst + col0 + bj * HALF + 4) = acc[ai][bj][m][1] * s; } }
.LBB0_530:
	v_lshlrev_b32_e32 v150, 2, v134
	v_lshl_add_u64 v[98:99], v[98:99], 0, v[150:151]
	global_store_dwordx4 v[98:99], v[94:97], off nt
	global_store_dwordx4 v[98:99], v[90:93], off offset:16 nt
	global_store_dwordx4 v[98:99], v[86:89], off offset:512 nt
	global_store_dwordx4 v[98:99], v[82:85], off offset:528 nt

; __device__ __forceinline__ u32x4 pack8(f32x4 a, f32x4 b) { u32x4 w; w.x = cvt_pk_bf16(a[0], a[1]); w.y = cvt_pk_bf16(a[2], a[3]); w.z = cvt_pk_bf16(b[0], b[1]); w.w = cvt_pk_bf16(b[2], b[3]); return w; }
;     __device__ __forceinline__ void operator()(const f32x4 (&acc)[2][2][4][2], const Unit& u, int wr, int wc, int fr, int fq) const {
;     ...
;                 for (int m = 0; m < 4; ++m) { const int row = row0 + ai * HALF + m * 16; bf16_t* rowp = base + (size_t)row * 2048 + col0; const float s = sc8[ai][m];
; #pragma unroll
;                     for (int bj = 0; bj < 2; ++bj) { const f32x4 v0 = acc[ai][bj][m][0] * s, v1 = acc[ai][bj][m][1] * s; *(u32x4*)(rowp + bj * HALF) = pack8(v0, v1); }
;                     if (pn < 8) {
;                         float* dst = nullptr;
;                         if (pm == 0) { const int s16 = row & 15; if (s16 >= 13) dst = o_rcs + (size_t)((row >> 4) * 3 + (s16 - 13)) * 2048; }
;                         else { const int t = row - G_ROWP; if (t >= G_TP - 3 && t < G_TP) dst = o_rcp + (size_t)(t - (G_TP - 3)) * 2048; }
;                         if (dst) {
; #pragma unroll
;                             for (int bj = 0; bj < 2; ++bj) { *(f32x4*)(dst + col0 + bj * HALF) = acc[ai][bj][m][0] * s; *(f32x4*)(dst + col0 + bj * HALF + 4) = acc[ai][bj][m][1] * s; } }
.LBB0_532:
	s_nop 0
	v_lshlrev_b64 v[82:83], 12, v[188:189]
	v_lshl_add_u64 v[86:87], v[130:131], 0, v[82:83]
	v_pk_mul_f32 v[80:81], v[80:81], v[190:191] op_sel_hi:[1,0]
	v_pk_mul_f32 v[78:79], v[78:79], v[190:191] op_sel_hi:[1,0]
	v_pk_mul_f32 v[76:77], v[76:77], v[190:191] op_sel_hi:[1,0]
	v_pk_mul_f32 v[74:75], v[74:75], v[190:191] op_sel_hi:[1,0]
	v_cvt_pk_bf16_f32 v82, v78, v79
	v_cvt_pk_bf16_f32 v83, v80, v81
	v_pk_mul_f32 v[72:73], v[72:73], v[190:191] op_sel_hi:[1,0]
	v_cvt_pk_bf16_f32 v84, v74, v75
	v_cvt_pk_bf16_f32 v85, v76, v77
	v_pk_mul_f32 v[70:71], v[70:71], v[190:191] op_sel_hi:[1,0]
	v_pk_mul_f32 v[68:69], v[68:69], v[190:191] op_sel_hi:[1,0]
	v_pk_mul_f32 v[66:67], v[66:67], v[190:191] op_sel_hi:[1,0]
	s_and_b64 vcc, exec, s[10:11]
	global_store_dwordx4 v[86:87], v[82:85], off nt
	s_nop 1
	v_cvt_pk_bf16_f32 v82, v70, v71
	v_cvt_pk_bf16_f32 v83, v72, v73
	v_cvt_pk_bf16_f32 v84, v66, v67
	v_cvt_pk_bf16_f32 v85, v68, v69
	global_store_dwordx4 v[86:87], v[82:85], off offset:256 nt
	s_cbranch_vccnz .LBB0_538
	s_nor_b64 s[0:1], s[12:13], s[6:7]
	v_mov_b64_e32 v[82:83], 0
	s_and_saveexec_b64 s[76:77], s[0:1]
	v_ashrrev_i32_e32 v82, 4, v188
	v_mad_u64_u32 v[82:83], s[0:1], v82, 3, v[156:157]
	v_ashrrev_i32_e32 v83, 31, v82
	v_lshlrev_b64 v[82:83], 13, v[82:83]
	v_lshl_add_u64 v[82:83], s[48:49], 0, v[82:83]
	s_or_b64 exec, exec, s[76:77]
	v_cmp_ne_u64_e32 vcc, 0, v[82:83]
	s_and_saveexec_b64 s[76:77], vcc
	s_cbranch_execz .LBB0_537
	v_lshlrev_b32_e32 v150, 2, v134
	v_lshl_add_u64 v[82:83], v[82:83], 0, v[150:151]
	global_store_dwordx4 v[82:83], v[78:81], off nt
	global_store_dwordx4 v[82:83], v[74:77], off offset:16 nt
	global_store_dwordx4 v[82:83], v[70:73], off offset:512 nt
	global_store_dwordx4 v[82:83], v[66:69], off offset:528 nt

; __device__ __forceinline__ u32x4 pack8(f32x4 a, f32x4 b) { u32x4 w; w.x = cvt_pk_bf16(a[0], a[1]); w.y = cvt_pk_bf16(a[2], a[3]); w.z = cvt_pk_bf16(b[0], b[1]); w.w = cvt_pk_bf16(b[2], b[3]); return w; }
;     __device__ __forceinline__ void operator()(const f32x4 (&acc)[2][2][4][2], const Unit& u, int wr, int wc, int fr, int fq) const {
;     ...
;                 for (int m = 0; m < 4; ++m) { const int row = row0 + ai * HALF + m * 16; bf16_t* rowp = base + (size_t)row * 2048 + col0; const float s = sc8[ai][m];
; #pragma unroll
;                     for (int bj = 0; bj < 2; ++bj) { const f32x4 v0 = acc[ai][bj][m][0] * s, v1 = acc[ai][bj][m][1] * s; *(u32x4*)(rowp + bj * HALF) = pack8(v0, v1); }
;                     if (pn < 8) {
;                         float* dst = nullptr;
;                         if (pm == 0) { const int s16 = row & 15; if (s16 >= 13) dst = o_rcs + (size_t)((row >> 4) * 3 + (s16 - 13)) * 2048; }
;                         else { const int t = row - G_ROWP; if (t >= G_TP - 3 && t < G_TP) dst = o_rcp + (size_t)(t - (G_TP - 3)) * 2048; }
;                         if (dst) {
; #pragma unroll
;                             for (int bj = 0; bj < 2; ++bj) { *(f32x4*)(dst + col0 + bj * HALF) = acc[ai][bj][m][0] * s; *(f32x4*)(dst + col0 + bj * HALF + 4) = acc[ai][bj][m][1] * s; } }
.LBB0_538:
	s_nop 0
	v_lshlrev_b64 v[66:67], 12, v[184:185]
	v_lshl_add_u64 v[70:71], v[130:131], 0, v[66:67]
	v_pk_mul_f32 v[64:65], v[64:65], v[186:187] op_sel_hi:[1,0]
	v_pk_mul_f32 v[62:63], v[62:63], v[186:187] op_sel_hi:[1,0]
	v_pk_mul_f32 v[60:61], v[60:61], v[186:187] op_sel_hi:[1,0]
	v_pk_mul_f32 v[58:59], v[58:59], v[186:187] op_sel_hi:[1,0]
	v_cvt_pk_bf16_f32 v66, v62, v63
	v_cvt_pk_bf16_f32 v67, v64, v65
	v_pk_mul_f32 v[56:57], v[56:57], v[186:187] op_sel_hi:[1,0]
	v_cvt_pk_bf16_f32 v68, v58, v59
	v_cvt_pk_bf16_f32 v69, v60, v61
	v_pk_mul_f32 v[54:55], v[54:55], v[186:187] op_sel_hi:[1,0]
	v_pk_mul_f32 v[52:53], v[52:53], v[186:187] op_sel_hi:[1,0]
	v_pk_mul_f32 v[50:51], v[50:51], v[186:187] op_sel_hi:[1,0]
	s_and_b64 vcc, exec, s[10:11]
	global_store_dwordx4 v[70:71], v[66:69], off nt
	s_nop 1
	v_cvt_pk_bf16_f32 v66, v54, v55
	v_cvt_pk_bf16_f32 v67, v56, v57
	v_cvt_pk_bf16_f32 v68, v50, v51
	v_cvt_pk_bf16_f32 v69, v52, v53
	global_store_dwordx4 v[70:71], v[66:69], off offset:256 nt
	s_cbranch_vccnz .LBB0_546
	s_mov_b64 s[76:77], -1
	s_and_b64 vcc, exec, s[14:15]
	s_cbranch_vccz .LBB0_593
	v_mov_b64_e32 v[66:67], 0
	s_and_saveexec_b64 s[76:77], s[38:39]
	v_ashrrev_i32_e32 v66, 4, v184
	v_mad_u64_u32 v[66:67], s[0:1], v66, 3, v[156:157]
	v_ashrrev_i32_e32 v67, 31, v66
	v_lshlrev_b64 v[66:67], 13, v[66:67]
	v_lshl_add_u64 v[66:67], s[48:49], 0, v[66:67]
	s_or_b64 exec, exec, s[76:77]
	s_cbranch_execz .LBB0_594

; __device__ __forceinline__ u32x4 pack8(f32x4 a, f32x4 b) { u32x4 w; w.x = cvt_pk_bf16(a[0], a[1]); w.y = cvt_pk_bf16(a[2], a[3]); w.z = cvt_pk_bf16(b[0], b[1]); w.w = cvt_pk_bf16(b[2], b[3]); return w; }
;     __device__ __forceinline__ void operator()(const f32x4 (&acc)[2][2][4][2], const Unit& u, int wr, int wc, int fr, int fq) const {
;     ...
;                 for (int m = 0; m < 4; ++m) { const int row = row0 + ai * HALF + m * 16; bf16_t* rowp = base + (size_t)row * 2048 + col0; const float s = sc8[ai][m];
; #pragma unroll
;                     for (int bj = 0; bj < 2; ++bj) { const f32x4 v0 = acc[ai][bj][m][0] * s, v1 = acc[ai][bj][m][1] * s; *(u32x4*)(rowp + bj * HALF) = pack8(v0, v1); }
;                     if (pn < 8) {
;                         float* dst = nullptr;
;                         if (pm == 0) { const int s16 = row & 15; if (s16 >= 13) dst = o_rcs + (size_t)((row >> 4) * 3 + (s16 - 13)) * 2048; }
;                         else { const int t = row - G_ROWP; if (t >= G_TP - 3 && t < G_TP) dst = o_rcp + (size_t)(t - (G_TP - 3)) * 2048; }
;                         if (dst) {
; #pragma unroll
;                             for (int bj = 0; bj < 2; ++bj) { *(f32x4*)(dst + col0 + bj * HALF) = acc[ai][bj][m][0] * s; *(f32x4*)(dst + col0 + bj * HALF + 4) = acc[ai][bj][m][1] * s; } }
.LBB0_544:
	v_lshlrev_b32_e32 v150, 2, v134
	v_lshl_add_u64 v[66:67], v[66:67], 0, v[150:151]
	global_store_dwordx4 v[66:67], v[62:65], off nt
	global_store_dwordx4 v[66:67], v[58:61], off offset:16 nt
	global_store_dwordx4 v[66:67], v[54:57], off offset:512 nt
	global_store_dwordx4 v[66:67], v[50:53], off offset:528 nt

; __device__ __forceinline__ u32x4 pack8(f32x4 a, f32x4 b) { u32x4 w; w.x = cvt_pk_bf16(a[0], a[1]); w.y = cvt_pk_bf16(a[2], a[3]); w.z = cvt_pk_bf16(b[0], b[1]); w.w = cvt_pk_bf16(b[2], b[3]); return w; }
;     __device__ __forceinline__ void operator()(const f32x4 (&acc)[2][2][4][2], const Unit& u, int wr, int wc, int fr, int fq) const {
;     ...
;                 for (int m = 0; m < 4; ++m) { const int row = row0 + ai * HALF + m * 16; bf16_t* rowp = base + (size_t)row * 2048 + col0; const float s = sc8[ai][m];
; #pragma unroll
;                     for (int bj = 0; bj < 2; ++bj) { const f32x4 v0 = acc[ai][bj][m][0] * s, v1 = acc[ai][bj][m][1] * s; *(u32x4*)(rowp + bj * HALF) = pack8(v0, v1); }
;                     if (pn < 8) {
;                         float* dst = nullptr;
;                         if (pm == 0) { const int s16 = row & 15; if (s16 >= 13) dst = o_rcs + (size_t)((row >> 4) * 3 + (s16 - 13)) * 2048; }
;                         else { const int t = row - G_ROWP; if (t >= G_TP - 3 && t < G_TP) dst = o_rcp + (size_t)(t - (G_TP - 3)) * 2048; }
;                         if (dst) {
; #pragma unroll
;                             for (int bj = 0; bj < 2; ++bj) { *(f32x4*)(dst + col0 + bj * HALF) = acc[ai][bj][m][0] * s; *(f32x4*)(dst + col0 + bj * HALF + 4) = acc[ai][bj][m][1] * s; } }
.LBB0_546:
	s_nop 0
	v_lshlrev_b64 v[50:51], 12, v[180:181]
	v_lshl_add_u64 v[54:55], v[130:131], 0, v[50:51]
	v_pk_mul_f32 v[48:49], v[48:49], v[182:183] op_sel_hi:[1,0]
	v_pk_mul_f32 v[46:47], v[46:47], v[182:183] op_sel_hi:[1,0]
	v_pk_mul_f32 v[44:45], v[44:45], v[182:183] op_sel_hi:[1,0]
	v_pk_mul_f32 v[42:43], v[42:43], v[182:183] op_sel_hi:[1,0]
	v_cvt_pk_bf16_f32 v50, v46, v47
	v_cvt_pk_bf16_f32 v51, v48, v49
	v_pk_mul_f32 v[40:41], v[40:41], v[182:183] op_sel_hi:[1,0]
	v_cvt_pk_bf16_f32 v52, v42, v43
	v_cvt_pk_bf16_f32 v53, v44, v45
	v_pk_mul_f32 v[38:39], v[38:39], v[182:183] op_sel_hi:[1,0]
	v_pk_mul_f32 v[36:37], v[36:37], v[182:183] op_sel_hi:[1,0]
	v_pk_mul_f32 v[34:35], v[34:35], v[182:183] op_sel_hi:[1,0]
	s_and_b64 vcc, exec, s[10:11]
	global_store_dwordx4 v[54:55], v[50:53], off nt
	s_nop 1
	v_cvt_pk_bf16_f32 v50, v38, v39
	v_cvt_pk_bf16_f32 v51, v40, v41
	v_cvt_pk_bf16_f32 v52, v34, v35
	v_cvt_pk_bf16_f32 v53, v36, v37
	global_store_dwordx4 v[54:55], v[50:53], off offset:256 nt
	s_cbranch_vccnz .LBB0_554
	s_mov_b64 s[76:77], -1
	s_and_b64 vcc, exec, s[14:15]
	s_cbranch_vccz .LBB0_595
	v_mov_b64_e32 v[50:51], 0
	s_and_saveexec_b64 s[76:77], s[38:39]
	v_ashrrev_i32_e32 v50, 4, v180
	v_mad_u64_u32 v[50:51], s[0:1], v50, 3, v[156:157]
	v_ashrrev_i32_e32 v51, 31, v50
	v_lshlrev_b64 v[50:51], 13, v[50:51]
	v_lshl_add_u64 v[50:51], s[48:49], 0, v[50:51]
	s_or_b64 exec, exec, s[76:77]
	s_cbranch_execz .LBB0_596

; __device__ __forceinline__ u32x4 pack8(f32x4 a, f32x4 b) { u32x4 w; w.x = cvt_pk_bf16(a[0], a[1]); w.y = cvt_pk_bf16(a[2], a[3]); w.z = cvt_pk_bf16(b[0], b[1]); w.w = cvt_pk_bf16(b[2], b[3]); return w; }
;     __device__ __forceinline__ void operator()(const f32x4 (&acc)[2][2][4][2], const Unit& u, int wr, int wc, int fr, int fq) const {
;     ...
;                 for (int m = 0; m < 4; ++m) { const int row = row0 + ai * HALF + m * 16; bf16_t* rowp = base + (size_t)row * 2048 + col0; const float s = sc8[ai][m];
; #pragma unroll
;                     for (int bj = 0; bj < 2; ++bj) { const f32x4 v0 = acc[ai][bj][m][0] * s, v1 = acc[ai][bj][m][1] * s; *(u32x4*)(rowp + bj * HALF) = pack8(v0, v1); }
;                     if (pn < 8) {
;                         float* dst = nullptr;
;                         if (pm == 0) { const int s16 = row & 15; if (s16 >= 13) dst = o_rcs + (size_t)((row >> 4) * 3 + (s16 - 13)) * 2048; }
;                         else { const int t = row - G_ROWP; if (t >= G_TP - 3 && t < G_TP) dst = o_rcp + (size_t)(t - (G_TP - 3)) * 2048; }
;                         if (dst) {
; #pragma unroll
;                             for (int bj = 0; bj < 2; ++bj) { *(f32x4*)(dst + col0 + bj * HALF) = acc[ai][bj][m][0] * s; *(f32x4*)(dst + col0 + bj * HALF + 4) = acc[ai][bj][m][1] * s; } }
.LBB0_552:
	v_lshlrev_b32_e32 v150, 2, v134
	v_lshl_add_u64 v[50:51], v[50:51], 0, v[150:151]
	global_store_dwordx4 v[50:51], v[46:49], off nt
	global_store_dwordx4 v[50:51], v[42:45], off offset:16 nt
	global_store_dwordx4 v[50:51], v[38:41], off offset:512 nt
	global_store_dwordx4 v[50:51], v[34:37], off offset:528 nt

; __device__ __forceinline__ u32x4 pack8(f32x4 a, f32x4 b) { u32x4 w; w.x = cvt_pk_bf16(a[0], a[1]); w.y = cvt_pk_bf16(a[2], a[3]); w.z = cvt_pk_bf16(b[0], b[1]); w.w = cvt_pk_bf16(b[2], b[3]); return w; }
;     __device__ __forceinline__ void operator()(const f32x4 (&acc)[2][2][4][2], const Unit& u, int wr, int wc, int fr, int fq) const {
;     ...
;                 for (int m = 0; m < 4; ++m) { const int row = row0 + ai * HALF + m * 16; bf16_t* rowp = base + (size_t)row * 2048 + col0; const float s = sc8[ai][m];
; #pragma unroll
;                     for (int bj = 0; bj < 2; ++bj) { const f32x4 v0 = acc[ai][bj][m][0] * s, v1 = acc[ai][bj][m][1] * s; *(u32x4*)(rowp + bj * HALF) = pack8(v0, v1); }
;                     if (pn < 8) {
;                         float* dst = nullptr;
;                         if (pm == 0) { const int s16 = row & 15; if (s16 >= 13) dst = o_rcs + (size_t)((row >> 4) * 3 + (s16 - 13)) * 2048; }
;                         else { const int t = row - G_ROWP; if (t >= G_TP - 3 && t < G_TP) dst = o_rcp + (size_t)(t - (G_TP - 3)) * 2048; }
;                         if (dst) {
; #pragma unroll
;                             for (int bj = 0; bj < 2; ++bj) { *(f32x4*)(dst + col0 + bj * HALF) = acc[ai][bj][m][0] * s; *(f32x4*)(dst + col0 + bj * HALF + 4) = acc[ai][bj][m][1] * s; } }
.LBB0_554:
	s_nop 0
	v_lshlrev_b64 v[34:35], 12, v[176:177]
	v_lshl_add_u64 v[38:39], v[130:131], 0, v[34:35]
	v_pk_mul_f32 v[32:33], v[32:33], v[178:179] op_sel_hi:[1,0]
	v_pk_mul_f32 v[30:31], v[30:31], v[178:179] op_sel_hi:[1,0]
	v_pk_mul_f32 v[28:29], v[28:29], v[178:179] op_sel_hi:[1,0]
	v_pk_mul_f32 v[26:27], v[26:27], v[178:179] op_sel_hi:[1,0]
	v_cvt_pk_bf16_f32 v34, v30, v31
	v_cvt_pk_bf16_f32 v35, v32, v33
	v_pk_mul_f32 v[24:25], v[24:25], v[178:179] op_sel_hi:[1,0]
	v_cvt_pk_bf16_f32 v36, v26, v27
	v_cvt_pk_bf16_f32 v37, v28, v29
	v_pk_mul_f32 v[22:23], v[22:23], v[178:179] op_sel_hi:[1,0]
	v_pk_mul_f32 v[20:21], v[20:21], v[178:179] op_sel_hi:[1,0]
	v_pk_mul_f32 v[18:19], v[18:19], v[178:179] op_sel_hi:[1,0]
	s_and_b64 vcc, exec, s[10:11]
	global_store_dwordx4 v[38:39], v[34:37], off nt
	s_nop 1
	v_cvt_pk_bf16_f32 v34, v22, v23
	v_cvt_pk_bf16_f32 v35, v24, v25
	v_cvt_pk_bf16_f32 v36, v18, v19
	v_cvt_pk_bf16_f32 v37, v20, v21
	global_store_dwordx4 v[38:39], v[34:37], off offset:256 nt
	s_cbranch_vccnz .LBB0_562
	s_mov_b64 s[76:77], -1
	s_and_b64 vcc, exec, s[14:15]
	s_cbranch_vccz .LBB0_597
	v_mov_b64_e32 v[34:35], 0
	s_and_saveexec_b64 s[14:15], s[38:39]
	v_ashrrev_i32_e32 v34, 4, v176
	v_mad_u64_u32 v[34:35], s[0:1], v34, 3, v[156:157]
	v_ashrrev_i32_e32 v35, 31, v34
	v_lshlrev_b64 v[34:35], 13, v[34:35]
	v_lshl_add_u64 v[34:35], s[48:49], 0, v[34:35]
	s_or_b64 exec, exec, s[14:15]
	s_cbranch_execz .LBB0_598

; __device__ __forceinline__ u32x4 pack8(f32x4 a, f32x4 b) { u32x4 w; w.x = cvt_pk_bf16(a[0], a[1]); w.y = cvt_pk_bf16(a[2], a[3]); w.z = cvt_pk_bf16(b[0], b[1]); w.w = cvt_pk_bf16(b[2], b[3]); return w; }
;     __device__ __forceinline__ void operator()(const f32x4 (&acc)[2][2][4][2], const Unit& u, int wr, int wc, int fr, int fq) const {
;     ...
;                 for (int m = 0; m < 4; ++m) { const int row = row0 + ai * HALF + m * 16; bf16_t* rowp = base + (size_t)row * 2048 + col0; const float s = sc8[ai][m];
; #pragma unroll
;                     for (int bj = 0; bj < 2; ++bj) { const f32x4 v0 = acc[ai][bj][m][0] * s, v1 = acc[ai][bj][m][1] * s; *(u32x4*)(rowp + bj * HALF) = pack8(v0, v1); }
;                     if (pn < 8) {
;                         float* dst = nullptr;
;                         if (pm == 0) { const int s16 = row & 15; if (s16 >= 13) dst = o_rcs + (size_t)((row >> 4) * 3 + (s16 - 13)) * 2048; }
;                         else { const int t = row - G_ROWP; if (t >= G_TP - 3 && t < G_TP) dst = o_rcp + (size_t)(t - (G_TP - 3)) * 2048; }
;                         if (dst) {
; #pragma unroll
;                             for (int bj = 0; bj < 2; ++bj) { *(f32x4*)(dst + col0 + bj * HALF) = acc[ai][bj][m][0] * s; *(f32x4*)(dst + col0 + bj * HALF + 4) = acc[ai][bj][m][1] * s; } }
.LBB0_560:
	v_lshlrev_b32_e32 v150, 2, v134
	v_lshl_add_u64 v[34:35], v[34:35], 0, v[150:151]
	global_store_dwordx4 v[34:35], v[30:33], off nt
	global_store_dwordx4 v[34:35], v[26:29], off offset:16 nt
	global_store_dwordx4 v[34:35], v[22:25], off offset:512 nt
	global_store_dwordx4 v[34:35], v[18:21], off offset:528 nt

; __device__ __forceinline__ u32x4 pack8(f32x4 a, f32x4 b) { u32x4 w; w.x = cvt_pk_bf16(a[0], a[1]); w.y = cvt_pk_bf16(a[2], a[3]); w.z = cvt_pk_bf16(b[0], b[1]); w.w = cvt_pk_bf16(b[2], b[3]); return w; }
;     __device__ __forceinline__ void operator()(const f32x4 (&acc)[2][2][4][2], const Unit& u, int wr, int wc, int fr, int fq) const {
;     ...
;                 for (int m = 0; m < 4; ++m) { const int row = row0 + ai * HALF + m * 16; bf16_t* rowp = base + (size_t)row * 2048 + col0; const float s = sc8[ai][m];
; #pragma unroll
;                     for (int bj = 0; bj < 2; ++bj) { const f32x4 v0 = acc[ai][bj][m][0] * s, v1 = acc[ai][bj][m][1] * s; *(u32x4*)(rowp + bj * HALF) = pack8(v0, v1); }
;                     if (pn < 8) {
;                         float* dst = nullptr;
;                         if (pm == 0) { const int s16 = row & 15; if (s16 >= 13) dst = o_rcs + (size_t)((row >> 4) * 3 + (s16 - 13)) * 2048; }
;                         else { const int t = row - G_ROWP; if (t >= G_TP - 3 && t < G_TP) dst = o_rcp + (size_t)(t - (G_TP - 3)) * 2048; }
;                         if (dst) {
; #pragma unroll
;                             for (int bj = 0; bj < 2; ++bj) { *(f32x4*)(dst + col0 + bj * HALF) = acc[ai][bj][m][0] * s; *(f32x4*)(dst + col0 + bj * HALF + 4) = acc[ai][bj][m][1] * s; } }
.LBB0_562:
	s_nop 0
	v_lshlrev_b64 v[18:19], 12, v[170:171]
	v_lshl_add_u64 v[22:23], v[130:131], 0, v[18:19]
	v_pk_mul_f32 v[16:17], v[16:17], v[172:173] op_sel_hi:[1,0]
	v_pk_mul_f32 v[14:15], v[14:15], v[172:173] op_sel_hi:[1,0]
	v_pk_mul_f32 v[12:13], v[12:13], v[172:173] op_sel_hi:[1,0]
	v_pk_mul_f32 v[10:11], v[10:11], v[172:173] op_sel_hi:[1,0]
	v_cvt_pk_bf16_f32 v18, v14, v15
	v_cvt_pk_bf16_f32 v19, v16, v17
	v_pk_mul_f32 v[8:9], v[8:9], v[172:173] op_sel_hi:[1,0]
	v_cvt_pk_bf16_f32 v20, v10, v11
	v_cvt_pk_bf16_f32 v21, v12, v13
	v_pk_mul_f32 v[6:7], v[6:7], v[172:173] op_sel_hi:[1,0]
	v_pk_mul_f32 v[4:5], v[4:5], v[172:173] op_sel_hi:[1,0]
	v_pk_mul_f32 v[2:3], v[2:3], v[172:173] op_sel_hi:[1,0]
	s_and_b64 vcc, exec, s[10:11]
	global_store_dwordx4 v[22:23], v[18:21], off nt
	s_nop 1
	v_cvt_pk_bf16_f32 v18, v6, v7
	v_cvt_pk_bf16_f32 v19, v8, v9
	v_cvt_pk_bf16_f32 v20, v2, v3
	v_cvt_pk_bf16_f32 v21, v4, v5
	global_store_dwordx4 v[22:23], v[18:21], off offset:256 nt
	s_cbranch_vccnz .LBB0_568
	s_nor_b64 s[0:1], s[12:13], s[6:7]
	v_mov_b64_e32 v[18:19], 0
	s_and_saveexec_b64 s[10:11], s[0:1]
	v_ashrrev_i32_e32 v18, 4, v170
	v_mad_u64_u32 v[18:19], s[0:1], v18, 3, v[156:157]
	v_ashrrev_i32_e32 v19, 31, v18
	v_lshlrev_b64 v[18:19], 13, v[18:19]
	v_lshl_add_u64 v[18:19], s[48:49], 0, v[18:19]
	s_or_b64 exec, exec, s[10:11]
	v_cmp_ne_u64_e32 vcc, 0, v[18:19]
	s_and_saveexec_b64 s[10:11], vcc
	s_cbranch_execz .LBB0_567
	v_lshlrev_b32_e32 v150, 2, v134
	v_lshl_add_u64 v[18:19], v[18:19], 0, v[150:151]
	global_store_dwordx4 v[18:19], v[14:17], off nt
	global_store_dwordx4 v[18:19], v[10:13], off offset:16 nt
	global_store_dwordx4 v[18:19], v[6:9], off offset:512 nt
	global_store_dwordx4 v[18:19], v[2:5], off offset:528 nt
